# K-loops of up, g1 and down switched to v_mfma_f32_16x16x32_bf16 (same bf16 operands, f32 accumulate) with row-permuted LDS image and in-place permlane re-layout of the accumulators
# speedup vs baseline: 1.0095x; 1.0079x over previous
.LBB0_20:
	s_mov_b32 s18, 0x10000
	s_mov_b32 s19, 0
	v_lshl_add_u64 v[138:139], s[18:19], 0, v[132:133]
	s_mov_b32 s18, 0x20000
	s_mov_b32 s19, 0
	v_lshl_add_u64 v[194:195], s[18:19], 0, v[132:133]
	s_mov_b32 s18, 0x30000
	s_mov_b32 s19, 0
	v_lshl_add_u64 v[196:197], s[18:19], 0, v[132:133]
	s_mov_b32 s18, 0x10000
	s_mov_b32 s19, 0
	v_lshl_add_u64 v[214:215], s[18:19], 0, v[134:135]
	s_mov_b32 s18, 0x580000
	s_mov_b32 s19, 0
	v_lshl_add_u64 v[232:233], s[18:19], 0, v[134:135]
	s_mov_b32 s18, 0x590000
	s_mov_b32 s19, 0
	v_lshl_add_u64 v[234:235], s[18:19], 0, v[134:135]
	v_lshrrev_b32_e32 v168, 3, v0
	v_and_b32_e32 v170, 15, v168
	v_lshlrev_b32_e32 v169, 1, v170
	v_cmp_gt_u32_e32 vcc, 12, v170
	s_nop 1
	v_mov_b32_e32 v171, 15
	v_cndmask_b32_e64 v171, v171, 8, vcc
	v_cmp_gt_u32_e32 vcc, 4, v170
	v_sub_u32_e32 v169, v169, v171
	v_lshlrev_b32_e32 v171, 1, v170
	v_add_u32_e32 v171, 1, v171
	s_nop 1
	v_cndmask_b32_e32 v169, v169, v171, vcc
	v_and_b32_e32 v168, 16, v168
	v_add_u32_e32 v168, v168, v169
	v_mul_u32_u24_e32 v168, 0x90, v168
	v_and_b32_e32 v169, 7, v0
	v_lshl_add_u32 v236, v169, 4, v168
	v_add_u32_e32 v237, 0x9000, v236
	v_and_b32_e32 v170, 15, v0
	v_lshlrev_b32_e32 v169, 1, v170
	v_cmp_gt_u32_e32 vcc, 12, v170
	s_nop 1
	v_mov_b32_e32 v171, 15
	v_cndmask_b32_e64 v171, v171, 8, vcc
	v_cmp_gt_u32_e32 vcc, 4, v170
	v_sub_u32_e32 v169, v169, v171
	v_lshlrev_b32_e32 v171, 1, v170
	v_add_u32_e32 v171, 1, v171
	s_nop 1
	v_cndmask_b32_e32 v169, v169, v171, vcc
	v_bfe_u32 v168, v0, 4, 2
	v_and_b32_e32 v170, 1, v168
	v_lshrrev_b32_e32 v168, 1, v168
	v_lshl_or_b32 v168, v170, 1, v168
	v_lshlrev_b32_e32 v168, 4, v168
	v_lshrrev_b32_e32 v170, 1, v0
	v_and_b32_e32 v170, 64, v170
	v_add_u32_e32 v170, v170, v169
	v_mul_u32_u24_e32 v170, 0x90, v170
	v_add_u32_e32 v238, v170, v168
	v_and_b32_e32 v170, 64, v0
	v_add_u32_e32 v170, v170, v169
	v_mul_u32_u24_e32 v170, 0x90, v170
	v_add_u32_e32 v239, v170, v168
	s_barrier
	s_waitcnt vmcnt(15)
	ds_write_b128 v236, v[68:71]
	s_waitcnt vmcnt(13)
	ds_write_b128 v236, v[72:75] offset:4608
	s_waitcnt vmcnt(11)
	ds_write_b128 v236, v[76:79] offset:9216
	s_waitcnt vmcnt(9)
	ds_write_b128 v236, v[80:83] offset:13824
	s_waitcnt vmcnt(7)
	ds_write_b128 v236, v[84:87] offset:18432
	s_waitcnt vmcnt(5)
	ds_write_b128 v236, v[88:91] offset:23040
	s_waitcnt vmcnt(3)
	ds_write_b128 v236, v[92:95] offset:27648
	s_waitcnt vmcnt(1)
	ds_write_b128 v236, v[96:99] offset:32256
	global_load_dwordx4 v[68:71], v[132:133], off offset:256
	global_load_dwordx4 v[72:75], v[138:139], off offset:256
	global_load_dwordx4 v[76:79], v[194:195], off offset:256
	global_load_dwordx4 v[80:83], v[196:197], off offset:256
	global_load_dwordx4 v[84:87], v[134:135], off offset:256
	global_load_dwordx4 v[88:91], v[214:215], off offset:256
	global_load_dwordx4 v[92:95], v[232:233], off offset:256
	global_load_dwordx4 v[96:99], v[234:235], off offset:256
	s_waitcnt lgkmcnt(0)
	s_barrier
	ds_read_b128 v[140:143], v238
	ds_read_b128 v[172:175], v239 offset:18432
	ds_read_b128 v[176:179], v239 offset:20736
	ds_read_b128 v[144:147], v238 offset:2304
	ds_read_b128 v[180:183], v239 offset:23040
	ds_read_b128 v[148:151], v238 offset:4608
	ds_read_b128 v[184:187], v239 offset:25344
	ds_read_b128 v[152:155], v238 offset:6912
	s_setprio 1
	s_waitcnt lgkmcnt(6)
	v_mfma_f32_16x16x32_bf16 v[52:55], v[172:175], v[140:143], 0
	ds_write_b128 v237, v[100:103]
	s_waitcnt lgkmcnt(6)
	v_mfma_f32_16x16x32_bf16 v[60:63], v[176:179], v[140:143], 0
	s_waitcnt lgkmcnt(5)
	v_mfma_f32_16x16x32_bf16 v[56:59], v[172:175], v[144:147], 0
	ds_write_b128 v237, v[104:107] offset:4608
	v_mfma_f32_16x16x32_bf16 v[64:67], v[176:179], v[144:147], 0
	ds_read_b128 v[156:159], v238 offset:64
	s_waitcnt lgkmcnt(6)
	v_mfma_f32_16x16x32_bf16 v[36:39], v[180:183], v[140:143], 0
	ds_read_b128 v[216:219], v239 offset:18496
	ds_write_b128 v237, v[108:111] offset:9216
	global_load_dwordx4 v[100:103], v[132:133], off offset:384
	v_mfma_f32_16x16x32_bf16 v[40:43], v[180:183], v[144:147], 0
	ds_read_b128 v[220:223], v239 offset:20800
	s_waitcnt lgkmcnt(8)
	v_mfma_f32_16x16x32_bf16 v[20:23], v[172:175], v[148:151], 0
	ds_read_b128 v[160:163], v238 offset:2368
	v_mfma_f32_16x16x32_bf16 v[28:31], v[176:179], v[148:151], 0
	v_mfma_f32_16x16x32_bf16 v[4:7], v[180:183], v[148:151], 0
	ds_read_b128 v[224:227], v239 offset:23104
	s_waitcnt lgkmcnt(9)
	v_mfma_f32_16x16x32_bf16 v[44:47], v[184:187], v[140:143], 0
	ds_read_b128 v[164:167], v238 offset:4672
	v_mfma_f32_16x16x32_bf16 v[48:51], v[184:187], v[144:147], 0
	ds_write_b128 v237, v[112:115] offset:13824
	global_load_dwordx4 v[104:107], v[138:139], off offset:384
	v_mfma_f32_16x16x32_bf16 v[12:15], v[184:187], v[148:151], 0
	ds_read_b128 v[228:231], v239 offset:25408
	s_waitcnt lgkmcnt(11)
	v_mfma_f32_16x16x32_bf16 v[24:27], v[172:175], v[152:155], 0
	ds_read_b128 v[168:171], v238 offset:6976
	ds_write_b128 v237, v[116:119] offset:18432
	global_load_dwordx4 v[108:111], v[194:195], off offset:384
	v_mfma_f32_16x16x32_bf16 v[32:35], v[176:179], v[152:155], 0
	v_mfma_f32_16x16x32_bf16 v[8:11], v[180:183], v[152:155], 0
	v_mfma_f32_16x16x32_bf16 v[16:19], v[184:187], v[152:155], 0
	s_waitcnt lgkmcnt(9)
	v_mfma_f32_16x16x32_bf16 v[52:55], v[216:219], v[156:159], v[52:55]
	s_waitcnt lgkmcnt(7)
	v_mfma_f32_16x16x32_bf16 v[60:63], v[220:223], v[156:159], v[60:63]
	s_waitcnt lgkmcnt(6)
	v_mfma_f32_16x16x32_bf16 v[56:59], v[216:219], v[160:163], v[56:59]
	ds_write_b128 v237, v[120:123] offset:23040
	global_load_dwordx4 v[112:115], v[196:197], off offset:384
	v_mfma_f32_16x16x32_bf16 v[64:67], v[220:223], v[160:163], v[64:67]
	s_waitcnt lgkmcnt(6)
	v_mfma_f32_16x16x32_bf16 v[36:39], v[224:227], v[156:159], v[36:39]
	ds_write_b128 v237, v[124:127] offset:27648
	global_load_dwordx4 v[116:119], v[134:135], off offset:384
	v_mfma_f32_16x16x32_bf16 v[40:43], v[224:227], v[160:163], v[40:43]
	s_waitcnt lgkmcnt(6)
	v_mfma_f32_16x16x32_bf16 v[20:23], v[216:219], v[164:167], v[20:23]
	s_waitcnt vmcnt(13)
	ds_write_b128 v237, v[128:131] offset:32256
	global_load_dwordx4 v[120:123], v[214:215], off offset:384
	v_mfma_f32_16x16x32_bf16 v[28:31], v[220:223], v[164:167], v[28:31]
	v_mfma_f32_16x16x32_bf16 v[4:7], v[224:227], v[164:167], v[4:7]
	global_load_dwordx4 v[124:127], v[232:233], off offset:384
	s_waitcnt lgkmcnt(5)
	v_mfma_f32_16x16x32_bf16 v[44:47], v[228:231], v[156:159], v[44:47]
	v_mfma_f32_16x16x32_bf16 v[48:51], v[228:231], v[160:163], v[48:51]
	global_load_dwordx4 v[128:131], v[234:235], off offset:384
	v_mfma_f32_16x16x32_bf16 v[12:15], v[228:231], v[164:167], v[12:15]
	s_waitcnt lgkmcnt(4)
	v_mfma_f32_16x16x32_bf16 v[24:27], v[216:219], v[168:171], v[24:27]
	v_mfma_f32_16x16x32_bf16 v[32:35], v[220:223], v[168:171], v[32:35]
	v_mfma_f32_16x16x32_bf16 v[8:11], v[224:227], v[168:171], v[8:11]
	v_mfma_f32_16x16x32_bf16 v[16:19], v[228:231], v[168:171], v[16:19]
	s_setprio 0
	s_waitcnt lgkmcnt(0)
	s_barrier
	ds_read_b128 v[140:143], v238 offset:36864
	ds_read_b128 v[172:175], v239 offset:55296
	ds_read_b128 v[176:179], v239 offset:57600
	ds_read_b128 v[144:147], v238 offset:39168
	ds_read_b128 v[180:183], v239 offset:59904
	ds_read_b128 v[148:151], v238 offset:41472
	ds_read_b128 v[184:187], v239 offset:62208
	ds_read_b128 v[152:155], v238 offset:43776
	s_setprio 1
	s_waitcnt lgkmcnt(6)
	v_mfma_f32_16x16x32_bf16 v[52:55], v[172:175], v[140:143], v[52:55]
	s_waitcnt vmcnt(15)
	ds_write_b128 v236, v[68:71]
	s_waitcnt lgkmcnt(6)
	v_mfma_f32_16x16x32_bf16 v[60:63], v[176:179], v[140:143], v[60:63]
	s_waitcnt lgkmcnt(5)
	v_mfma_f32_16x16x32_bf16 v[56:59], v[172:175], v[144:147], v[56:59]
	s_waitcnt vmcnt(14)
	ds_write_b128 v236, v[72:75] offset:4608
	v_mfma_f32_16x16x32_bf16 v[64:67], v[176:179], v[144:147], v[64:67]
	ds_read_b128 v[156:159], v238 offset:36928
	s_waitcnt lgkmcnt(6)
	v_mfma_f32_16x16x32_bf16 v[36:39], v[180:183], v[140:143], v[36:39]
	ds_read_b128 v[216:219], v239 offset:55360
	s_waitcnt vmcnt(13)
	ds_write_b128 v236, v[76:79] offset:9216
	global_load_dwordx4 v[68:71], v[132:133], off offset:512
	v_mfma_f32_16x16x32_bf16 v[40:43], v[180:183], v[144:147], v[40:43]
	ds_read_b128 v[220:223], v239 offset:57664
	s_waitcnt lgkmcnt(8)
	v_mfma_f32_16x16x32_bf16 v[20:23], v[172:175], v[148:151], v[20:23]
	ds_read_b128 v[160:163], v238 offset:39232
	v_mfma_f32_16x16x32_bf16 v[28:31], v[176:179], v[148:151], v[28:31]
	v_mfma_f32_16x16x32_bf16 v[4:7], v[180:183], v[148:151], v[4:7]
	ds_read_b128 v[224:227], v239 offset:59968
	s_waitcnt lgkmcnt(9)
	v_mfma_f32_16x16x32_bf16 v[44:47], v[184:187], v[140:143], v[44:47]
	ds_read_b128 v[164:167], v238 offset:41536
	v_mfma_f32_16x16x32_bf16 v[48:51], v[184:187], v[144:147], v[48:51]
	s_waitcnt vmcnt(13)
	ds_write_b128 v236, v[80:83] offset:13824
	global_load_dwordx4 v[72:75], v[138:139], off offset:512
	v_mfma_f32_16x16x32_bf16 v[12:15], v[184:187], v[148:151], v[12:15]
	ds_read_b128 v[228:231], v239 offset:62272
	s_waitcnt lgkmcnt(11)
	v_mfma_f32_16x16x32_bf16 v[24:27], v[172:175], v[152:155], v[24:27]
	ds_read_b128 v[168:171], v238 offset:43840
	s_waitcnt vmcnt(13)
	ds_write_b128 v236, v[84:87] offset:18432
	global_load_dwordx4 v[76:79], v[194:195], off offset:512
	v_mfma_f32_16x16x32_bf16 v[32:35], v[176:179], v[152:155], v[32:35]
	v_mfma_f32_16x16x32_bf16 v[8:11], v[180:183], v[152:155], v[8:11]
	v_mfma_f32_16x16x32_bf16 v[16:19], v[184:187], v[152:155], v[16:19]
	s_waitcnt lgkmcnt(9)
	v_mfma_f32_16x16x32_bf16 v[52:55], v[216:219], v[156:159], v[52:55]
	s_waitcnt lgkmcnt(7)
	v_mfma_f32_16x16x32_bf16 v[60:63], v[220:223], v[156:159], v[60:63]
	s_waitcnt lgkmcnt(6)
	v_mfma_f32_16x16x32_bf16 v[56:59], v[216:219], v[160:163], v[56:59]
	s_waitcnt vmcnt(13)
	ds_write_b128 v236, v[88:91] offset:23040
	global_load_dwordx4 v[80:83], v[196:197], off offset:512
	v_mfma_f32_16x16x32_bf16 v[64:67], v[220:223], v[160:163], v[64:67]
	s_waitcnt lgkmcnt(6)
	v_mfma_f32_16x16x32_bf16 v[36:39], v[224:227], v[156:159], v[36:39]
	s_waitcnt vmcnt(13)
	ds_write_b128 v236, v[92:95] offset:27648
	global_load_dwordx4 v[84:87], v[134:135], off offset:512
	v_mfma_f32_16x16x32_bf16 v[40:43], v[224:227], v[160:163], v[40:43]
	s_waitcnt lgkmcnt(6)
	v_mfma_f32_16x16x32_bf16 v[20:23], v[216:219], v[164:167], v[20:23]
	s_waitcnt vmcnt(13)
	ds_write_b128 v236, v[96:99] offset:32256
	global_load_dwordx4 v[88:91], v[214:215], off offset:512
	v_mfma_f32_16x16x32_bf16 v[28:31], v[220:223], v[164:167], v[28:31]
	v_mfma_f32_16x16x32_bf16 v[4:7], v[224:227], v[164:167], v[4:7]
	global_load_dwordx4 v[92:95], v[232:233], off offset:512
	s_waitcnt lgkmcnt(5)
	v_mfma_f32_16x16x32_bf16 v[44:47], v[228:231], v[156:159], v[44:47]
	v_mfma_f32_16x16x32_bf16 v[48:51], v[228:231], v[160:163], v[48:51]
	global_load_dwordx4 v[96:99], v[234:235], off offset:512
	v_mfma_f32_16x16x32_bf16 v[12:15], v[228:231], v[164:167], v[12:15]
	s_waitcnt lgkmcnt(4)
	v_mfma_f32_16x16x32_bf16 v[24:27], v[216:219], v[168:171], v[24:27]
	v_mfma_f32_16x16x32_bf16 v[32:35], v[220:223], v[168:171], v[32:35]
	v_mfma_f32_16x16x32_bf16 v[8:11], v[224:227], v[168:171], v[8:11]
	v_mfma_f32_16x16x32_bf16 v[16:19], v[228:231], v[168:171], v[16:19]
	s_setprio 0
	s_waitcnt lgkmcnt(0)
	s_barrier
	ds_read_b128 v[140:143], v238
	ds_read_b128 v[172:175], v239 offset:18432
	ds_read_b128 v[176:179], v239 offset:20736
	ds_read_b128 v[144:147], v238 offset:2304
	ds_read_b128 v[180:183], v239 offset:23040
	ds_read_b128 v[148:151], v238 offset:4608
	ds_read_b128 v[184:187], v239 offset:25344
	ds_read_b128 v[152:155], v238 offset:6912
	s_setprio 1
	s_waitcnt lgkmcnt(6)
	v_mfma_f32_16x16x32_bf16 v[52:55], v[172:175], v[140:143], v[52:55]
	s_waitcnt vmcnt(15)
	ds_write_b128 v237, v[100:103]
	s_waitcnt lgkmcnt(6)
	v_mfma_f32_16x16x32_bf16 v[60:63], v[176:179], v[140:143], v[60:63]
	s_waitcnt lgkmcnt(5)
	v_mfma_f32_16x16x32_bf16 v[56:59], v[172:175], v[144:147], v[56:59]
	s_waitcnt vmcnt(14)
	ds_write_b128 v237, v[104:107] offset:4608
	v_mfma_f32_16x16x32_bf16 v[64:67], v[176:179], v[144:147], v[64:67]
	ds_read_b128 v[156:159], v238 offset:64
	s_waitcnt lgkmcnt(6)
	v_mfma_f32_16x16x32_bf16 v[36:39], v[180:183], v[140:143], v[36:39]
	ds_read_b128 v[216:219], v239 offset:18496
	s_waitcnt vmcnt(13)
	ds_write_b128 v237, v[108:111] offset:9216
	global_load_dwordx4 v[100:103], v[132:133], off offset:640
	v_mfma_f32_16x16x32_bf16 v[40:43], v[180:183], v[144:147], v[40:43]
	ds_read_b128 v[220:223], v239 offset:20800
	s_waitcnt lgkmcnt(8)
	v_mfma_f32_16x16x32_bf16 v[20:23], v[172:175], v[148:151], v[20:23]
	ds_read_b128 v[160:163], v238 offset:2368
	v_mfma_f32_16x16x32_bf16 v[28:31], v[176:179], v[148:151], v[28:31]
	v_mfma_f32_16x16x32_bf16 v[4:7], v[180:183], v[148:151], v[4:7]
	ds_read_b128 v[224:227], v239 offset:23104
	s_waitcnt lgkmcnt(9)
	v_mfma_f32_16x16x32_bf16 v[44:47], v[184:187], v[140:143], v[44:47]
	ds_read_b128 v[164:167], v238 offset:4672
	v_mfma_f32_16x16x32_bf16 v[48:51], v[184:187], v[144:147], v[48:51]
	s_waitcnt vmcnt(13)
	ds_write_b128 v237, v[112:115] offset:13824
	global_load_dwordx4 v[104:107], v[138:139], off offset:640
	v_mfma_f32_16x16x32_bf16 v[12:15], v[184:187], v[148:151], v[12:15]
	ds_read_b128 v[228:231], v239 offset:25408
	s_waitcnt lgkmcnt(11)
	v_mfma_f32_16x16x32_bf16 v[24:27], v[172:175], v[152:155], v[24:27]
	ds_read_b128 v[168:171], v238 offset:6976
	s_waitcnt vmcnt(13)
	ds_write_b128 v237, v[116:119] offset:18432
	global_load_dwordx4 v[108:111], v[194:195], off offset:640
	v_mfma_f32_16x16x32_bf16 v[32:35], v[176:179], v[152:155], v[32:35]
	v_mfma_f32_16x16x32_bf16 v[8:11], v[180:183], v[152:155], v[8:11]
	v_mfma_f32_16x16x32_bf16 v[16:19], v[184:187], v[152:155], v[16:19]
	s_waitcnt lgkmcnt(9)
	v_mfma_f32_16x16x32_bf16 v[52:55], v[216:219], v[156:159], v[52:55]
	s_waitcnt lgkmcnt(7)
	v_mfma_f32_16x16x32_bf16 v[60:63], v[220:223], v[156:159], v[60:63]
	s_waitcnt lgkmcnt(6)
	v_mfma_f32_16x16x32_bf16 v[56:59], v[216:219], v[160:163], v[56:59]
	s_waitcnt vmcnt(13)
	ds_write_b128 v237, v[120:123] offset:23040
	global_load_dwordx4 v[112:115], v[196:197], off offset:640
	v_mfma_f32_16x16x32_bf16 v[64:67], v[220:223], v[160:163], v[64:67]
	s_waitcnt lgkmcnt(6)
	v_mfma_f32_16x16x32_bf16 v[36:39], v[224:227], v[156:159], v[36:39]
	s_waitcnt vmcnt(13)
	ds_write_b128 v237, v[124:127] offset:27648
	global_load_dwordx4 v[116:119], v[134:135], off offset:640
	v_mfma_f32_16x16x32_bf16 v[40:43], v[224:227], v[160:163], v[40:43]
	s_waitcnt lgkmcnt(6)
	v_mfma_f32_16x16x32_bf16 v[20:23], v[216:219], v[164:167], v[20:23]
	s_waitcnt vmcnt(13)
	ds_write_b128 v237, v[128:131] offset:32256
	global_load_dwordx4 v[120:123], v[214:215], off offset:640
	v_mfma_f32_16x16x32_bf16 v[28:31], v[220:223], v[164:167], v[28:31]
	v_mfma_f32_16x16x32_bf16 v[4:7], v[224:227], v[164:167], v[4:7]
	global_load_dwordx4 v[124:127], v[232:233], off offset:640
	s_waitcnt lgkmcnt(5)
	v_mfma_f32_16x16x32_bf16 v[44:47], v[228:231], v[156:159], v[44:47]
	v_mfma_f32_16x16x32_bf16 v[48:51], v[228:231], v[160:163], v[48:51]
	global_load_dwordx4 v[128:131], v[234:235], off offset:640
	v_mfma_f32_16x16x32_bf16 v[12:15], v[228:231], v[164:167], v[12:15]
	s_waitcnt lgkmcnt(4)
	v_mfma_f32_16x16x32_bf16 v[24:27], v[216:219], v[168:171], v[24:27]
	v_mfma_f32_16x16x32_bf16 v[32:35], v[220:223], v[168:171], v[32:35]
	v_mfma_f32_16x16x32_bf16 v[8:11], v[224:227], v[168:171], v[8:11]
	v_mfma_f32_16x16x32_bf16 v[16:19], v[228:231], v[168:171], v[16:19]
	s_setprio 0
	s_waitcnt lgkmcnt(0)
	s_barrier
	ds_read_b128 v[140:143], v238 offset:36864
	ds_read_b128 v[172:175], v239 offset:55296
	ds_read_b128 v[176:179], v239 offset:57600
	ds_read_b128 v[144:147], v238 offset:39168
	ds_read_b128 v[180:183], v239 offset:59904
	ds_read_b128 v[148:151], v238 offset:41472
	ds_read_b128 v[184:187], v239 offset:62208
	ds_read_b128 v[152:155], v238 offset:43776
	s_setprio 1
	s_waitcnt lgkmcnt(6)
	v_mfma_f32_16x16x32_bf16 v[52:55], v[172:175], v[140:143], v[52:55]
	s_waitcnt vmcnt(15)
	ds_write_b128 v236, v[68:71]
	s_waitcnt lgkmcnt(6)
	v_mfma_f32_16x16x32_bf16 v[60:63], v[176:179], v[140:143], v[60:63]
	s_waitcnt lgkmcnt(5)
	v_mfma_f32_16x16x32_bf16 v[56:59], v[172:175], v[144:147], v[56:59]
	s_waitcnt vmcnt(14)
	ds_write_b128 v236, v[72:75] offset:4608
	v_mfma_f32_16x16x32_bf16 v[64:67], v[176:179], v[144:147], v[64:67]
	ds_read_b128 v[156:159], v238 offset:36928
	s_waitcnt lgkmcnt(6)
	v_mfma_f32_16x16x32_bf16 v[36:39], v[180:183], v[140:143], v[36:39]
	ds_read_b128 v[216:219], v239 offset:55360
	s_waitcnt vmcnt(13)
	ds_write_b128 v236, v[76:79] offset:9216
	global_load_dwordx4 v[68:71], v[132:133], off offset:768
	v_mfma_f32_16x16x32_bf16 v[40:43], v[180:183], v[144:147], v[40:43]
	ds_read_b128 v[220:223], v239 offset:57664
	s_waitcnt lgkmcnt(8)
	v_mfma_f32_16x16x32_bf16 v[20:23], v[172:175], v[148:151], v[20:23]
	ds_read_b128 v[160:163], v238 offset:39232
	v_mfma_f32_16x16x32_bf16 v[28:31], v[176:179], v[148:151], v[28:31]
	v_mfma_f32_16x16x32_bf16 v[4:7], v[180:183], v[148:151], v[4:7]
	ds_read_b128 v[224:227], v239 offset:59968
	s_waitcnt lgkmcnt(9)
	v_mfma_f32_16x16x32_bf16 v[44:47], v[184:187], v[140:143], v[44:47]
	ds_read_b128 v[164:167], v238 offset:41536
	v_mfma_f32_16x16x32_bf16 v[48:51], v[184:187], v[144:147], v[48:51]
	s_waitcnt vmcnt(13)
	ds_write_b128 v236, v[80:83] offset:13824
	global_load_dwordx4 v[72:75], v[138:139], off offset:768
	v_mfma_f32_16x16x32_bf16 v[12:15], v[184:187], v[148:151], v[12:15]
	ds_read_b128 v[228:231], v239 offset:62272
	s_waitcnt lgkmcnt(11)
	v_mfma_f32_16x16x32_bf16 v[24:27], v[172:175], v[152:155], v[24:27]
	ds_read_b128 v[168:171], v238 offset:43840
	s_waitcnt vmcnt(13)
	ds_write_b128 v236, v[84:87] offset:18432
	global_load_dwordx4 v[76:79], v[194:195], off offset:768
	v_mfma_f32_16x16x32_bf16 v[32:35], v[176:179], v[152:155], v[32:35]
	v_mfma_f32_16x16x32_bf16 v[8:11], v[180:183], v[152:155], v[8:11]
	v_mfma_f32_16x16x32_bf16 v[16:19], v[184:187], v[152:155], v[16:19]
	s_waitcnt lgkmcnt(9)
	v_mfma_f32_16x16x32_bf16 v[52:55], v[216:219], v[156:159], v[52:55]
	s_waitcnt lgkmcnt(7)
	v_mfma_f32_16x16x32_bf16 v[60:63], v[220:223], v[156:159], v[60:63]
	s_waitcnt lgkmcnt(6)
	v_mfma_f32_16x16x32_bf16 v[56:59], v[216:219], v[160:163], v[56:59]
	s_waitcnt vmcnt(13)
	ds_write_b128 v236, v[88:91] offset:23040
	global_load_dwordx4 v[80:83], v[196:197], off offset:768
	v_mfma_f32_16x16x32_bf16 v[64:67], v[220:223], v[160:163], v[64:67]
	s_waitcnt lgkmcnt(6)
	v_mfma_f32_16x16x32_bf16 v[36:39], v[224:227], v[156:159], v[36:39]
	s_waitcnt vmcnt(13)
	ds_write_b128 v236, v[92:95] offset:27648
	global_load_dwordx4 v[84:87], v[134:135], off offset:768
	v_mfma_f32_16x16x32_bf16 v[40:43], v[224:227], v[160:163], v[40:43]
	s_waitcnt lgkmcnt(6)
	v_mfma_f32_16x16x32_bf16 v[20:23], v[216:219], v[164:167], v[20:23]
	s_waitcnt vmcnt(13)
	ds_write_b128 v236, v[96:99] offset:32256
	global_load_dwordx4 v[88:91], v[214:215], off offset:768
	v_mfma_f32_16x16x32_bf16 v[28:31], v[220:223], v[164:167], v[28:31]
	v_mfma_f32_16x16x32_bf16 v[4:7], v[224:227], v[164:167], v[4:7]
	global_load_dwordx4 v[92:95], v[232:233], off offset:768
	s_waitcnt lgkmcnt(5)
	v_mfma_f32_16x16x32_bf16 v[44:47], v[228:231], v[156:159], v[44:47]
	v_mfma_f32_16x16x32_bf16 v[48:51], v[228:231], v[160:163], v[48:51]
	global_load_dwordx4 v[96:99], v[234:235], off offset:768
	v_mfma_f32_16x16x32_bf16 v[12:15], v[228:231], v[164:167], v[12:15]
	s_waitcnt lgkmcnt(4)
	v_mfma_f32_16x16x32_bf16 v[24:27], v[216:219], v[168:171], v[24:27]
	v_mfma_f32_16x16x32_bf16 v[32:35], v[220:223], v[168:171], v[32:35]
	v_mfma_f32_16x16x32_bf16 v[8:11], v[224:227], v[168:171], v[8:11]
	v_mfma_f32_16x16x32_bf16 v[16:19], v[228:231], v[168:171], v[16:19]
	s_setprio 0
	s_waitcnt lgkmcnt(0)
	s_barrier
	ds_read_b128 v[140:143], v238
	ds_read_b128 v[172:175], v239 offset:18432
	ds_read_b128 v[176:179], v239 offset:20736
	ds_read_b128 v[144:147], v238 offset:2304
	ds_read_b128 v[180:183], v239 offset:23040
	ds_read_b128 v[148:151], v238 offset:4608
	ds_read_b128 v[184:187], v239 offset:25344
	ds_read_b128 v[152:155], v238 offset:6912
	s_setprio 1
	s_waitcnt lgkmcnt(6)
	v_mfma_f32_16x16x32_bf16 v[52:55], v[172:175], v[140:143], v[52:55]
	s_waitcnt vmcnt(15)
	ds_write_b128 v237, v[100:103]
	s_waitcnt lgkmcnt(6)
	v_mfma_f32_16x16x32_bf16 v[60:63], v[176:179], v[140:143], v[60:63]
	s_waitcnt lgkmcnt(5)
	v_mfma_f32_16x16x32_bf16 v[56:59], v[172:175], v[144:147], v[56:59]
	s_waitcnt vmcnt(14)
	ds_write_b128 v237, v[104:107] offset:4608
	v_mfma_f32_16x16x32_bf16 v[64:67], v[176:179], v[144:147], v[64:67]
	ds_read_b128 v[156:159], v238 offset:64
	s_waitcnt lgkmcnt(6)
	v_mfma_f32_16x16x32_bf16 v[36:39], v[180:183], v[140:143], v[36:39]
	ds_read_b128 v[216:219], v239 offset:18496
	s_waitcnt vmcnt(13)
	ds_write_b128 v237, v[108:111] offset:9216
	global_load_dwordx4 v[100:103], v[132:133], off offset:896
	v_mfma_f32_16x16x32_bf16 v[40:43], v[180:183], v[144:147], v[40:43]
	ds_read_b128 v[220:223], v239 offset:20800
	s_waitcnt lgkmcnt(8)
	v_mfma_f32_16x16x32_bf16 v[20:23], v[172:175], v[148:151], v[20:23]
	ds_read_b128 v[160:163], v238 offset:2368
	v_mfma_f32_16x16x32_bf16 v[28:31], v[176:179], v[148:151], v[28:31]
	v_mfma_f32_16x16x32_bf16 v[4:7], v[180:183], v[148:151], v[4:7]
	ds_read_b128 v[224:227], v239 offset:23104
	s_waitcnt lgkmcnt(9)
	v_mfma_f32_16x16x32_bf16 v[44:47], v[184:187], v[140:143], v[44:47]
	ds_read_b128 v[164:167], v238 offset:4672
	v_mfma_f32_16x16x32_bf16 v[48:51], v[184:187], v[144:147], v[48:51]
	s_waitcnt vmcnt(13)
	ds_write_b128 v237, v[112:115] offset:13824
	global_load_dwordx4 v[104:107], v[138:139], off offset:896
	v_mfma_f32_16x16x32_bf16 v[12:15], v[184:187], v[148:151], v[12:15]
	ds_read_b128 v[228:231], v239 offset:25408
	s_waitcnt lgkmcnt(11)
	v_mfma_f32_16x16x32_bf16 v[24:27], v[172:175], v[152:155], v[24:27]
	ds_read_b128 v[168:171], v238 offset:6976
	s_waitcnt vmcnt(13)
	ds_write_b128 v237, v[116:119] offset:18432
	global_load_dwordx4 v[108:111], v[194:195], off offset:896
	v_mfma_f32_16x16x32_bf16 v[32:35], v[176:179], v[152:155], v[32:35]
	v_mfma_f32_16x16x32_bf16 v[8:11], v[180:183], v[152:155], v[8:11]
	v_mfma_f32_16x16x32_bf16 v[16:19], v[184:187], v[152:155], v[16:19]
	s_waitcnt lgkmcnt(9)
	v_mfma_f32_16x16x32_bf16 v[52:55], v[216:219], v[156:159], v[52:55]
	s_waitcnt lgkmcnt(7)
	v_mfma_f32_16x16x32_bf16 v[60:63], v[220:223], v[156:159], v[60:63]
	s_waitcnt lgkmcnt(6)
	v_mfma_f32_16x16x32_bf16 v[56:59], v[216:219], v[160:163], v[56:59]
	s_waitcnt vmcnt(13)
	ds_write_b128 v237, v[120:123] offset:23040
	global_load_dwordx4 v[112:115], v[196:197], off offset:896
	v_mfma_f32_16x16x32_bf16 v[64:67], v[220:223], v[160:163], v[64:67]
	s_waitcnt lgkmcnt(6)
	v_mfma_f32_16x16x32_bf16 v[36:39], v[224:227], v[156:159], v[36:39]
	s_waitcnt vmcnt(13)
	ds_write_b128 v237, v[124:127] offset:27648
	global_load_dwordx4 v[116:119], v[134:135], off offset:896
	v_mfma_f32_16x16x32_bf16 v[40:43], v[224:227], v[160:163], v[40:43]
	s_waitcnt lgkmcnt(6)
	v_mfma_f32_16x16x32_bf16 v[20:23], v[216:219], v[164:167], v[20:23]
	s_waitcnt vmcnt(13)
	ds_write_b128 v237, v[128:131] offset:32256
	global_load_dwordx4 v[120:123], v[214:215], off offset:896
	v_mfma_f32_16x16x32_bf16 v[28:31], v[220:223], v[164:167], v[28:31]
	v_mfma_f32_16x16x32_bf16 v[4:7], v[224:227], v[164:167], v[4:7]
	global_load_dwordx4 v[124:127], v[232:233], off offset:896
	s_waitcnt lgkmcnt(5)
	v_mfma_f32_16x16x32_bf16 v[44:47], v[228:231], v[156:159], v[44:47]
	v_mfma_f32_16x16x32_bf16 v[48:51], v[228:231], v[160:163], v[48:51]
	global_load_dwordx4 v[128:131], v[234:235], off offset:896
	v_mfma_f32_16x16x32_bf16 v[12:15], v[228:231], v[164:167], v[12:15]
	s_waitcnt lgkmcnt(4)
	v_mfma_f32_16x16x32_bf16 v[24:27], v[216:219], v[168:171], v[24:27]
	v_mfma_f32_16x16x32_bf16 v[32:35], v[220:223], v[168:171], v[32:35]
	v_mfma_f32_16x16x32_bf16 v[8:11], v[224:227], v[168:171], v[8:11]
	v_mfma_f32_16x16x32_bf16 v[16:19], v[228:231], v[168:171], v[16:19]
	s_setprio 0
	s_waitcnt lgkmcnt(0)
	s_barrier
	ds_read_b128 v[140:143], v238 offset:36864
	ds_read_b128 v[172:175], v239 offset:55296
	ds_read_b128 v[176:179], v239 offset:57600
	ds_read_b128 v[144:147], v238 offset:39168
	ds_read_b128 v[180:183], v239 offset:59904
	ds_read_b128 v[148:151], v238 offset:41472
	ds_read_b128 v[184:187], v239 offset:62208
	ds_read_b128 v[152:155], v238 offset:43776
	s_setprio 1
	s_waitcnt lgkmcnt(6)
	v_mfma_f32_16x16x32_bf16 v[52:55], v[172:175], v[140:143], v[52:55]
	s_waitcnt vmcnt(15)
	ds_write_b128 v236, v[68:71]
	s_waitcnt lgkmcnt(6)
	v_mfma_f32_16x16x32_bf16 v[60:63], v[176:179], v[140:143], v[60:63]
	s_waitcnt lgkmcnt(5)
	v_mfma_f32_16x16x32_bf16 v[56:59], v[172:175], v[144:147], v[56:59]
	s_waitcnt vmcnt(14)
	ds_write_b128 v236, v[72:75] offset:4608
	v_mfma_f32_16x16x32_bf16 v[64:67], v[176:179], v[144:147], v[64:67]
	ds_read_b128 v[156:159], v238 offset:36928
	s_waitcnt lgkmcnt(6)
	v_mfma_f32_16x16x32_bf16 v[36:39], v[180:183], v[140:143], v[36:39]
	ds_read_b128 v[216:219], v239 offset:55360
	s_waitcnt vmcnt(13)
	ds_write_b128 v236, v[76:79] offset:9216
	global_load_dwordx4 v[68:71], v[132:133], off offset:1024
	v_mfma_f32_16x16x32_bf16 v[40:43], v[180:183], v[144:147], v[40:43]
	ds_read_b128 v[220:223], v239 offset:57664
	s_waitcnt lgkmcnt(8)
	v_mfma_f32_16x16x32_bf16 v[20:23], v[172:175], v[148:151], v[20:23]
	ds_read_b128 v[160:163], v238 offset:39232
	v_mfma_f32_16x16x32_bf16 v[28:31], v[176:179], v[148:151], v[28:31]
	v_mfma_f32_16x16x32_bf16 v[4:7], v[180:183], v[148:151], v[4:7]
	ds_read_b128 v[224:227], v239 offset:59968
	s_waitcnt lgkmcnt(9)
	v_mfma_f32_16x16x32_bf16 v[44:47], v[184:187], v[140:143], v[44:47]
	ds_read_b128 v[164:167], v238 offset:41536
	v_mfma_f32_16x16x32_bf16 v[48:51], v[184:187], v[144:147], v[48:51]
	s_waitcnt vmcnt(13)
	ds_write_b128 v236, v[80:83] offset:13824
	global_load_dwordx4 v[72:75], v[138:139], off offset:1024
	v_mfma_f32_16x16x32_bf16 v[12:15], v[184:187], v[148:151], v[12:15]
	ds_read_b128 v[228:231], v239 offset:62272
	s_waitcnt lgkmcnt(11)
	v_mfma_f32_16x16x32_bf16 v[24:27], v[172:175], v[152:155], v[24:27]
	ds_read_b128 v[168:171], v238 offset:43840
	s_waitcnt vmcnt(13)
	ds_write_b128 v236, v[84:87] offset:18432
	global_load_dwordx4 v[76:79], v[194:195], off offset:1024
	v_mfma_f32_16x16x32_bf16 v[32:35], v[176:179], v[152:155], v[32:35]
	v_mfma_f32_16x16x32_bf16 v[8:11], v[180:183], v[152:155], v[8:11]
	v_mfma_f32_16x16x32_bf16 v[16:19], v[184:187], v[152:155], v[16:19]
	s_waitcnt lgkmcnt(9)
	v_mfma_f32_16x16x32_bf16 v[52:55], v[216:219], v[156:159], v[52:55]
	s_waitcnt lgkmcnt(7)
	v_mfma_f32_16x16x32_bf16 v[60:63], v[220:223], v[156:159], v[60:63]
	s_waitcnt lgkmcnt(6)
	v_mfma_f32_16x16x32_bf16 v[56:59], v[216:219], v[160:163], v[56:59]
	s_waitcnt vmcnt(13)
	ds_write_b128 v236, v[88:91] offset:23040
	global_load_dwordx4 v[80:83], v[196:197], off offset:1024
	v_mfma_f32_16x16x32_bf16 v[64:67], v[220:223], v[160:163], v[64:67]
	s_waitcnt lgkmcnt(6)
	v_mfma_f32_16x16x32_bf16 v[36:39], v[224:227], v[156:159], v[36:39]
	s_waitcnt vmcnt(13)
	ds_write_b128 v236, v[92:95] offset:27648
	global_load_dwordx4 v[84:87], v[134:135], off offset:1024
	v_mfma_f32_16x16x32_bf16 v[40:43], v[224:227], v[160:163], v[40:43]
	s_waitcnt lgkmcnt(6)
	v_mfma_f32_16x16x32_bf16 v[20:23], v[216:219], v[164:167], v[20:23]
	s_waitcnt vmcnt(13)
	ds_write_b128 v236, v[96:99] offset:32256
	global_load_dwordx4 v[88:91], v[214:215], off offset:1024
	v_mfma_f32_16x16x32_bf16 v[28:31], v[220:223], v[164:167], v[28:31]
	v_mfma_f32_16x16x32_bf16 v[4:7], v[224:227], v[164:167], v[4:7]
	global_load_dwordx4 v[92:95], v[232:233], off offset:1024
	s_waitcnt lgkmcnt(5)
	v_mfma_f32_16x16x32_bf16 v[44:47], v[228:231], v[156:159], v[44:47]
	v_mfma_f32_16x16x32_bf16 v[48:51], v[228:231], v[160:163], v[48:51]
	global_load_dwordx4 v[96:99], v[234:235], off offset:1024
	v_mfma_f32_16x16x32_bf16 v[12:15], v[228:231], v[164:167], v[12:15]
	s_waitcnt lgkmcnt(4)
	v_mfma_f32_16x16x32_bf16 v[24:27], v[216:219], v[168:171], v[24:27]
	v_mfma_f32_16x16x32_bf16 v[32:35], v[220:223], v[168:171], v[32:35]
	v_mfma_f32_16x16x32_bf16 v[8:11], v[224:227], v[168:171], v[8:11]
	v_mfma_f32_16x16x32_bf16 v[16:19], v[228:231], v[168:171], v[16:19]
	s_setprio 0
	s_waitcnt lgkmcnt(0)
	s_barrier
	ds_read_b128 v[140:143], v238
	ds_read_b128 v[172:175], v239 offset:18432
	ds_read_b128 v[176:179], v239 offset:20736
	ds_read_b128 v[144:147], v238 offset:2304
	ds_read_b128 v[180:183], v239 offset:23040
	ds_read_b128 v[148:151], v238 offset:4608
	ds_read_b128 v[184:187], v239 offset:25344
	ds_read_b128 v[152:155], v238 offset:6912
	s_setprio 1
	s_waitcnt lgkmcnt(6)
	v_mfma_f32_16x16x32_bf16 v[52:55], v[172:175], v[140:143], v[52:55]
	s_waitcnt vmcnt(15)
	ds_write_b128 v237, v[100:103]
	s_waitcnt lgkmcnt(6)
	v_mfma_f32_16x16x32_bf16 v[60:63], v[176:179], v[140:143], v[60:63]
	s_waitcnt lgkmcnt(5)
	v_mfma_f32_16x16x32_bf16 v[56:59], v[172:175], v[144:147], v[56:59]
	s_waitcnt vmcnt(14)
	ds_write_b128 v237, v[104:107] offset:4608
	v_mfma_f32_16x16x32_bf16 v[64:67], v[176:179], v[144:147], v[64:67]
	ds_read_b128 v[156:159], v238 offset:64
	s_waitcnt lgkmcnt(6)
	v_mfma_f32_16x16x32_bf16 v[36:39], v[180:183], v[140:143], v[36:39]
	ds_read_b128 v[216:219], v239 offset:18496
	s_waitcnt vmcnt(13)
	ds_write_b128 v237, v[108:111] offset:9216
	global_load_dwordx4 v[100:103], v[132:133], off offset:1152
	v_mfma_f32_16x16x32_bf16 v[40:43], v[180:183], v[144:147], v[40:43]
	ds_read_b128 v[220:223], v239 offset:20800
	s_waitcnt lgkmcnt(8)
	v_mfma_f32_16x16x32_bf16 v[20:23], v[172:175], v[148:151], v[20:23]
	ds_read_b128 v[160:163], v238 offset:2368
	v_mfma_f32_16x16x32_bf16 v[28:31], v[176:179], v[148:151], v[28:31]
	v_mfma_f32_16x16x32_bf16 v[4:7], v[180:183], v[148:151], v[4:7]
	ds_read_b128 v[224:227], v239 offset:23104
	s_waitcnt lgkmcnt(9)
	v_mfma_f32_16x16x32_bf16 v[44:47], v[184:187], v[140:143], v[44:47]
	ds_read_b128 v[164:167], v238 offset:4672
	v_mfma_f32_16x16x32_bf16 v[48:51], v[184:187], v[144:147], v[48:51]
	s_waitcnt vmcnt(13)
	ds_write_b128 v237, v[112:115] offset:13824
	global_load_dwordx4 v[104:107], v[138:139], off offset:1152
	v_mfma_f32_16x16x32_bf16 v[12:15], v[184:187], v[148:151], v[12:15]
	ds_read_b128 v[228:231], v239 offset:25408
	s_waitcnt lgkmcnt(11)
	v_mfma_f32_16x16x32_bf16 v[24:27], v[172:175], v[152:155], v[24:27]
	ds_read_b128 v[168:171], v238 offset:6976
	s_waitcnt vmcnt(13)
	ds_write_b128 v237, v[116:119] offset:18432
	global_load_dwordx4 v[108:111], v[194:195], off offset:1152
	v_mfma_f32_16x16x32_bf16 v[32:35], v[176:179], v[152:155], v[32:35]
	v_mfma_f32_16x16x32_bf16 v[8:11], v[180:183], v[152:155], v[8:11]
	v_mfma_f32_16x16x32_bf16 v[16:19], v[184:187], v[152:155], v[16:19]
	s_waitcnt lgkmcnt(9)
	v_mfma_f32_16x16x32_bf16 v[52:55], v[216:219], v[156:159], v[52:55]
	s_waitcnt lgkmcnt(7)
	v_mfma_f32_16x16x32_bf16 v[60:63], v[220:223], v[156:159], v[60:63]
	s_waitcnt lgkmcnt(6)
	v_mfma_f32_16x16x32_bf16 v[56:59], v[216:219], v[160:163], v[56:59]
	s_waitcnt vmcnt(13)
	ds_write_b128 v237, v[120:123] offset:23040
	global_load_dwordx4 v[112:115], v[196:197], off offset:1152
	v_mfma_f32_16x16x32_bf16 v[64:67], v[220:223], v[160:163], v[64:67]
	s_waitcnt lgkmcnt(6)
	v_mfma_f32_16x16x32_bf16 v[36:39], v[224:227], v[156:159], v[36:39]
	s_waitcnt vmcnt(13)
	ds_write_b128 v237, v[124:127] offset:27648
	global_load_dwordx4 v[116:119], v[134:135], off offset:1152
	v_mfma_f32_16x16x32_bf16 v[40:43], v[224:227], v[160:163], v[40:43]
	s_waitcnt lgkmcnt(6)
	v_mfma_f32_16x16x32_bf16 v[20:23], v[216:219], v[164:167], v[20:23]
	s_waitcnt vmcnt(13)
	ds_write_b128 v237, v[128:131] offset:32256
	global_load_dwordx4 v[120:123], v[214:215], off offset:1152
	v_mfma_f32_16x16x32_bf16 v[28:31], v[220:223], v[164:167], v[28:31]
	v_mfma_f32_16x16x32_bf16 v[4:7], v[224:227], v[164:167], v[4:7]
	global_load_dwordx4 v[124:127], v[232:233], off offset:1152
	s_waitcnt lgkmcnt(5)
	v_mfma_f32_16x16x32_bf16 v[44:47], v[228:231], v[156:159], v[44:47]
	v_mfma_f32_16x16x32_bf16 v[48:51], v[228:231], v[160:163], v[48:51]
	global_load_dwordx4 v[128:131], v[234:235], off offset:1152
	v_mfma_f32_16x16x32_bf16 v[12:15], v[228:231], v[164:167], v[12:15]
	s_waitcnt lgkmcnt(4)
	v_mfma_f32_16x16x32_bf16 v[24:27], v[216:219], v[168:171], v[24:27]
	v_mfma_f32_16x16x32_bf16 v[32:35], v[220:223], v[168:171], v[32:35]
	v_mfma_f32_16x16x32_bf16 v[8:11], v[224:227], v[168:171], v[8:11]
	v_mfma_f32_16x16x32_bf16 v[16:19], v[228:231], v[168:171], v[16:19]
	s_setprio 0
	s_waitcnt lgkmcnt(0)
	s_barrier
	ds_read_b128 v[140:143], v238 offset:36864
	ds_read_b128 v[172:175], v239 offset:55296
	ds_read_b128 v[176:179], v239 offset:57600
	ds_read_b128 v[144:147], v238 offset:39168
	ds_read_b128 v[180:183], v239 offset:59904
	ds_read_b128 v[148:151], v238 offset:41472
	ds_read_b128 v[184:187], v239 offset:62208
	ds_read_b128 v[152:155], v238 offset:43776
	s_setprio 1
	s_waitcnt lgkmcnt(6)
	v_mfma_f32_16x16x32_bf16 v[52:55], v[172:175], v[140:143], v[52:55]
	s_waitcnt vmcnt(15)
	ds_write_b128 v236, v[68:71]
	s_waitcnt lgkmcnt(6)
	v_mfma_f32_16x16x32_bf16 v[60:63], v[176:179], v[140:143], v[60:63]
	s_waitcnt lgkmcnt(5)
	v_mfma_f32_16x16x32_bf16 v[56:59], v[172:175], v[144:147], v[56:59]
	s_waitcnt vmcnt(14)
	ds_write_b128 v236, v[72:75] offset:4608
	v_mfma_f32_16x16x32_bf16 v[64:67], v[176:179], v[144:147], v[64:67]
	ds_read_b128 v[156:159], v238 offset:36928
	s_waitcnt lgkmcnt(6)
	v_mfma_f32_16x16x32_bf16 v[36:39], v[180:183], v[140:143], v[36:39]
	ds_read_b128 v[216:219], v239 offset:55360
	s_waitcnt vmcnt(13)
	ds_write_b128 v236, v[76:79] offset:9216
	global_load_dwordx4 v[68:71], v[132:133], off offset:1280
	v_mfma_f32_16x16x32_bf16 v[40:43], v[180:183], v[144:147], v[40:43]
	ds_read_b128 v[220:223], v239 offset:57664
	s_waitcnt lgkmcnt(8)
	v_mfma_f32_16x16x32_bf16 v[20:23], v[172:175], v[148:151], v[20:23]
	ds_read_b128 v[160:163], v238 offset:39232
	v_mfma_f32_16x16x32_bf16 v[28:31], v[176:179], v[148:151], v[28:31]
	v_mfma_f32_16x16x32_bf16 v[4:7], v[180:183], v[148:151], v[4:7]
	ds_read_b128 v[224:227], v239 offset:59968
	s_waitcnt lgkmcnt(9)
	v_mfma_f32_16x16x32_bf16 v[44:47], v[184:187], v[140:143], v[44:47]
	ds_read_b128 v[164:167], v238 offset:41536
	v_mfma_f32_16x16x32_bf16 v[48:51], v[184:187], v[144:147], v[48:51]
	s_waitcnt vmcnt(13)
	ds_write_b128 v236, v[80:83] offset:13824
	global_load_dwordx4 v[72:75], v[138:139], off offset:1280
	v_mfma_f32_16x16x32_bf16 v[12:15], v[184:187], v[148:151], v[12:15]
	ds_read_b128 v[228:231], v239 offset:62272
	s_waitcnt lgkmcnt(11)
	v_mfma_f32_16x16x32_bf16 v[24:27], v[172:175], v[152:155], v[24:27]
	ds_read_b128 v[168:171], v238 offset:43840
	s_waitcnt vmcnt(13)
	ds_write_b128 v236, v[84:87] offset:18432
	global_load_dwordx4 v[76:79], v[194:195], off offset:1280
	v_mfma_f32_16x16x32_bf16 v[32:35], v[176:179], v[152:155], v[32:35]
	v_mfma_f32_16x16x32_bf16 v[8:11], v[180:183], v[152:155], v[8:11]
	v_mfma_f32_16x16x32_bf16 v[16:19], v[184:187], v[152:155], v[16:19]
	s_waitcnt lgkmcnt(9)
	v_mfma_f32_16x16x32_bf16 v[52:55], v[216:219], v[156:159], v[52:55]
	s_waitcnt lgkmcnt(7)
	v_mfma_f32_16x16x32_bf16 v[60:63], v[220:223], v[156:159], v[60:63]
	s_waitcnt lgkmcnt(6)
	v_mfma_f32_16x16x32_bf16 v[56:59], v[216:219], v[160:163], v[56:59]
	s_waitcnt vmcnt(13)
	ds_write_b128 v236, v[88:91] offset:23040
	global_load_dwordx4 v[80:83], v[196:197], off offset:1280
	v_mfma_f32_16x16x32_bf16 v[64:67], v[220:223], v[160:163], v[64:67]
	s_waitcnt lgkmcnt(6)
	v_mfma_f32_16x16x32_bf16 v[36:39], v[224:227], v[156:159], v[36:39]
	s_waitcnt vmcnt(13)
	ds_write_b128 v236, v[92:95] offset:27648
	global_load_dwordx4 v[84:87], v[134:135], off offset:1280
	v_mfma_f32_16x16x32_bf16 v[40:43], v[224:227], v[160:163], v[40:43]
	s_waitcnt lgkmcnt(6)
	v_mfma_f32_16x16x32_bf16 v[20:23], v[216:219], v[164:167], v[20:23]
	s_waitcnt vmcnt(13)
	ds_write_b128 v236, v[96:99] offset:32256
	global_load_dwordx4 v[88:91], v[214:215], off offset:1280
	v_mfma_f32_16x16x32_bf16 v[28:31], v[220:223], v[164:167], v[28:31]
	v_mfma_f32_16x16x32_bf16 v[4:7], v[224:227], v[164:167], v[4:7]
	global_load_dwordx4 v[92:95], v[232:233], off offset:1280
	s_waitcnt lgkmcnt(5)
	v_mfma_f32_16x16x32_bf16 v[44:47], v[228:231], v[156:159], v[44:47]
	v_mfma_f32_16x16x32_bf16 v[48:51], v[228:231], v[160:163], v[48:51]
	global_load_dwordx4 v[96:99], v[234:235], off offset:1280
	v_mfma_f32_16x16x32_bf16 v[12:15], v[228:231], v[164:167], v[12:15]
	s_waitcnt lgkmcnt(4)
	v_mfma_f32_16x16x32_bf16 v[24:27], v[216:219], v[168:171], v[24:27]
	v_mfma_f32_16x16x32_bf16 v[32:35], v[220:223], v[168:171], v[32:35]
	v_mfma_f32_16x16x32_bf16 v[8:11], v[224:227], v[168:171], v[8:11]
	v_mfma_f32_16x16x32_bf16 v[16:19], v[228:231], v[168:171], v[16:19]
	s_setprio 0
	s_waitcnt lgkmcnt(0)
	s_barrier
	ds_read_b128 v[140:143], v238
	ds_read_b128 v[172:175], v239 offset:18432
	ds_read_b128 v[176:179], v239 offset:20736
	ds_read_b128 v[144:147], v238 offset:2304
	ds_read_b128 v[180:183], v239 offset:23040
	ds_read_b128 v[148:151], v238 offset:4608
	ds_read_b128 v[184:187], v239 offset:25344
	ds_read_b128 v[152:155], v238 offset:6912
	s_setprio 1
	s_waitcnt lgkmcnt(6)
	v_mfma_f32_16x16x32_bf16 v[52:55], v[172:175], v[140:143], v[52:55]
	s_waitcnt vmcnt(15)
	ds_write_b128 v237, v[100:103]
	s_waitcnt lgkmcnt(6)
	v_mfma_f32_16x16x32_bf16 v[60:63], v[176:179], v[140:143], v[60:63]
	s_waitcnt lgkmcnt(5)
	v_mfma_f32_16x16x32_bf16 v[56:59], v[172:175], v[144:147], v[56:59]
	s_waitcnt vmcnt(14)
	ds_write_b128 v237, v[104:107] offset:4608
	v_mfma_f32_16x16x32_bf16 v[64:67], v[176:179], v[144:147], v[64:67]
	ds_read_b128 v[156:159], v238 offset:64
	s_waitcnt lgkmcnt(6)
	v_mfma_f32_16x16x32_bf16 v[36:39], v[180:183], v[140:143], v[36:39]
	ds_read_b128 v[216:219], v239 offset:18496
	s_waitcnt vmcnt(13)
	ds_write_b128 v237, v[108:111] offset:9216
	global_load_dwordx4 v[100:103], v[132:133], off offset:1408
	v_mfma_f32_16x16x32_bf16 v[40:43], v[180:183], v[144:147], v[40:43]
	ds_read_b128 v[220:223], v239 offset:20800
	s_waitcnt lgkmcnt(8)
	v_mfma_f32_16x16x32_bf16 v[20:23], v[172:175], v[148:151], v[20:23]
	ds_read_b128 v[160:163], v238 offset:2368
	v_mfma_f32_16x16x32_bf16 v[28:31], v[176:179], v[148:151], v[28:31]
	v_mfma_f32_16x16x32_bf16 v[4:7], v[180:183], v[148:151], v[4:7]
	ds_read_b128 v[224:227], v239 offset:23104
	s_waitcnt lgkmcnt(9)
	v_mfma_f32_16x16x32_bf16 v[44:47], v[184:187], v[140:143], v[44:47]
	ds_read_b128 v[164:167], v238 offset:4672
	v_mfma_f32_16x16x32_bf16 v[48:51], v[184:187], v[144:147], v[48:51]
	s_waitcnt vmcnt(13)
	ds_write_b128 v237, v[112:115] offset:13824
	global_load_dwordx4 v[104:107], v[138:139], off offset:1408
	v_mfma_f32_16x16x32_bf16 v[12:15], v[184:187], v[148:151], v[12:15]
	ds_read_b128 v[228:231], v239 offset:25408
	s_waitcnt lgkmcnt(11)
	v_mfma_f32_16x16x32_bf16 v[24:27], v[172:175], v[152:155], v[24:27]
	ds_read_b128 v[168:171], v238 offset:6976
	s_waitcnt vmcnt(13)
	ds_write_b128 v237, v[116:119] offset:18432
	global_load_dwordx4 v[108:111], v[194:195], off offset:1408
	v_mfma_f32_16x16x32_bf16 v[32:35], v[176:179], v[152:155], v[32:35]
	v_mfma_f32_16x16x32_bf16 v[8:11], v[180:183], v[152:155], v[8:11]
	v_mfma_f32_16x16x32_bf16 v[16:19], v[184:187], v[152:155], v[16:19]
	s_waitcnt lgkmcnt(9)
	v_mfma_f32_16x16x32_bf16 v[52:55], v[216:219], v[156:159], v[52:55]
	s_waitcnt lgkmcnt(7)
	v_mfma_f32_16x16x32_bf16 v[60:63], v[220:223], v[156:159], v[60:63]
	s_waitcnt lgkmcnt(6)
	v_mfma_f32_16x16x32_bf16 v[56:59], v[216:219], v[160:163], v[56:59]
	s_waitcnt vmcnt(13)
	ds_write_b128 v237, v[120:123] offset:23040
	global_load_dwordx4 v[112:115], v[196:197], off offset:1408
	v_mfma_f32_16x16x32_bf16 v[64:67], v[220:223], v[160:163], v[64:67]
	s_waitcnt lgkmcnt(6)
	v_mfma_f32_16x16x32_bf16 v[36:39], v[224:227], v[156:159], v[36:39]
	s_waitcnt vmcnt(13)
	ds_write_b128 v237, v[124:127] offset:27648
	global_load_dwordx4 v[116:119], v[134:135], off offset:1408
	v_mfma_f32_16x16x32_bf16 v[40:43], v[224:227], v[160:163], v[40:43]
	s_waitcnt lgkmcnt(6)
	v_mfma_f32_16x16x32_bf16 v[20:23], v[216:219], v[164:167], v[20:23]
	s_waitcnt vmcnt(13)
	ds_write_b128 v237, v[128:131] offset:32256
	global_load_dwordx4 v[120:123], v[214:215], off offset:1408
	v_mfma_f32_16x16x32_bf16 v[28:31], v[220:223], v[164:167], v[28:31]
	v_mfma_f32_16x16x32_bf16 v[4:7], v[224:227], v[164:167], v[4:7]
	global_load_dwordx4 v[124:127], v[232:233], off offset:1408
	s_waitcnt lgkmcnt(5)
	v_mfma_f32_16x16x32_bf16 v[44:47], v[228:231], v[156:159], v[44:47]
	v_mfma_f32_16x16x32_bf16 v[48:51], v[228:231], v[160:163], v[48:51]
	global_load_dwordx4 v[128:131], v[234:235], off offset:1408
	v_mfma_f32_16x16x32_bf16 v[12:15], v[228:231], v[164:167], v[12:15]
	s_waitcnt lgkmcnt(4)
	v_mfma_f32_16x16x32_bf16 v[24:27], v[216:219], v[168:171], v[24:27]
	v_mfma_f32_16x16x32_bf16 v[32:35], v[220:223], v[168:171], v[32:35]
	v_mfma_f32_16x16x32_bf16 v[8:11], v[224:227], v[168:171], v[8:11]
	v_mfma_f32_16x16x32_bf16 v[16:19], v[228:231], v[168:171], v[16:19]
	s_setprio 0
	s_waitcnt lgkmcnt(0)
	s_barrier
	ds_read_b128 v[140:143], v238 offset:36864
	ds_read_b128 v[172:175], v239 offset:55296
	ds_read_b128 v[176:179], v239 offset:57600
	ds_read_b128 v[144:147], v238 offset:39168
	ds_read_b128 v[180:183], v239 offset:59904
	ds_read_b128 v[148:151], v238 offset:41472
	ds_read_b128 v[184:187], v239 offset:62208
	ds_read_b128 v[152:155], v238 offset:43776
	s_setprio 1
	s_waitcnt lgkmcnt(6)
	v_mfma_f32_16x16x32_bf16 v[52:55], v[172:175], v[140:143], v[52:55]
	s_waitcnt vmcnt(15)
	ds_write_b128 v236, v[68:71]
	s_waitcnt lgkmcnt(6)
	v_mfma_f32_16x16x32_bf16 v[60:63], v[176:179], v[140:143], v[60:63]
	s_waitcnt lgkmcnt(5)
	v_mfma_f32_16x16x32_bf16 v[56:59], v[172:175], v[144:147], v[56:59]
	s_waitcnt vmcnt(14)
	ds_write_b128 v236, v[72:75] offset:4608
	v_mfma_f32_16x16x32_bf16 v[64:67], v[176:179], v[144:147], v[64:67]
	ds_read_b128 v[156:159], v238 offset:36928
	s_waitcnt lgkmcnt(6)
	v_mfma_f32_16x16x32_bf16 v[36:39], v[180:183], v[140:143], v[36:39]
	ds_read_b128 v[216:219], v239 offset:55360
	s_waitcnt vmcnt(13)
	ds_write_b128 v236, v[76:79] offset:9216
	global_load_dwordx4 v[68:71], v[132:133], off offset:1536
	v_mfma_f32_16x16x32_bf16 v[40:43], v[180:183], v[144:147], v[40:43]
	ds_read_b128 v[220:223], v239 offset:57664
	s_waitcnt lgkmcnt(8)
	v_mfma_f32_16x16x32_bf16 v[20:23], v[172:175], v[148:151], v[20:23]
	ds_read_b128 v[160:163], v238 offset:39232
	v_mfma_f32_16x16x32_bf16 v[28:31], v[176:179], v[148:151], v[28:31]
	v_mfma_f32_16x16x32_bf16 v[4:7], v[180:183], v[148:151], v[4:7]
	ds_read_b128 v[224:227], v239 offset:59968
	s_waitcnt lgkmcnt(9)
	v_mfma_f32_16x16x32_bf16 v[44:47], v[184:187], v[140:143], v[44:47]
	ds_read_b128 v[164:167], v238 offset:41536
	v_mfma_f32_16x16x32_bf16 v[48:51], v[184:187], v[144:147], v[48:51]
	s_waitcnt vmcnt(13)
	ds_write_b128 v236, v[80:83] offset:13824
	global_load_dwordx4 v[72:75], v[138:139], off offset:1536
	v_mfma_f32_16x16x32_bf16 v[12:15], v[184:187], v[148:151], v[12:15]
	ds_read_b128 v[228:231], v239 offset:62272
	s_waitcnt lgkmcnt(11)
	v_mfma_f32_16x16x32_bf16 v[24:27], v[172:175], v[152:155], v[24:27]
	ds_read_b128 v[168:171], v238 offset:43840
	s_waitcnt vmcnt(13)
	ds_write_b128 v236, v[84:87] offset:18432
	global_load_dwordx4 v[76:79], v[194:195], off offset:1536
	v_mfma_f32_16x16x32_bf16 v[32:35], v[176:179], v[152:155], v[32:35]
	v_mfma_f32_16x16x32_bf16 v[8:11], v[180:183], v[152:155], v[8:11]
	v_mfma_f32_16x16x32_bf16 v[16:19], v[184:187], v[152:155], v[16:19]
	s_waitcnt lgkmcnt(9)
	v_mfma_f32_16x16x32_bf16 v[52:55], v[216:219], v[156:159], v[52:55]
	s_waitcnt lgkmcnt(7)
	v_mfma_f32_16x16x32_bf16 v[60:63], v[220:223], v[156:159], v[60:63]
	s_waitcnt lgkmcnt(6)
	v_mfma_f32_16x16x32_bf16 v[56:59], v[216:219], v[160:163], v[56:59]
	s_waitcnt vmcnt(13)
	ds_write_b128 v236, v[88:91] offset:23040
	global_load_dwordx4 v[80:83], v[196:197], off offset:1536
	v_mfma_f32_16x16x32_bf16 v[64:67], v[220:223], v[160:163], v[64:67]
	s_waitcnt lgkmcnt(6)
	v_mfma_f32_16x16x32_bf16 v[36:39], v[224:227], v[156:159], v[36:39]
	s_waitcnt vmcnt(13)
	ds_write_b128 v236, v[92:95] offset:27648
	global_load_dwordx4 v[84:87], v[134:135], off offset:1536
	v_mfma_f32_16x16x32_bf16 v[40:43], v[224:227], v[160:163], v[40:43]
	s_waitcnt lgkmcnt(6)
	v_mfma_f32_16x16x32_bf16 v[20:23], v[216:219], v[164:167], v[20:23]
	s_waitcnt vmcnt(13)
	ds_write_b128 v236, v[96:99] offset:32256
	global_load_dwordx4 v[88:91], v[214:215], off offset:1536
	v_mfma_f32_16x16x32_bf16 v[28:31], v[220:223], v[164:167], v[28:31]
	v_mfma_f32_16x16x32_bf16 v[4:7], v[224:227], v[164:167], v[4:7]
	global_load_dwordx4 v[92:95], v[232:233], off offset:1536
	s_waitcnt lgkmcnt(5)
	v_mfma_f32_16x16x32_bf16 v[44:47], v[228:231], v[156:159], v[44:47]
	v_mfma_f32_16x16x32_bf16 v[48:51], v[228:231], v[160:163], v[48:51]
	global_load_dwordx4 v[96:99], v[234:235], off offset:1536
	v_mfma_f32_16x16x32_bf16 v[12:15], v[228:231], v[164:167], v[12:15]
	s_waitcnt lgkmcnt(4)
	v_mfma_f32_16x16x32_bf16 v[24:27], v[216:219], v[168:171], v[24:27]
	v_mfma_f32_16x16x32_bf16 v[32:35], v[220:223], v[168:171], v[32:35]
	v_mfma_f32_16x16x32_bf16 v[8:11], v[224:227], v[168:171], v[8:11]
	v_mfma_f32_16x16x32_bf16 v[16:19], v[228:231], v[168:171], v[16:19]
	s_setprio 0
	s_waitcnt lgkmcnt(0)
	s_barrier
	ds_read_b128 v[140:143], v238
	ds_read_b128 v[172:175], v239 offset:18432
	ds_read_b128 v[176:179], v239 offset:20736
	ds_read_b128 v[144:147], v238 offset:2304
	ds_read_b128 v[180:183], v239 offset:23040
	ds_read_b128 v[148:151], v238 offset:4608
	ds_read_b128 v[184:187], v239 offset:25344
	ds_read_b128 v[152:155], v238 offset:6912
	s_setprio 1
	s_waitcnt lgkmcnt(6)
	v_mfma_f32_16x16x32_bf16 v[52:55], v[172:175], v[140:143], v[52:55]
	s_waitcnt vmcnt(15)
	ds_write_b128 v237, v[100:103]
	s_waitcnt lgkmcnt(6)
	v_mfma_f32_16x16x32_bf16 v[60:63], v[176:179], v[140:143], v[60:63]
	s_waitcnt lgkmcnt(5)
	v_mfma_f32_16x16x32_bf16 v[56:59], v[172:175], v[144:147], v[56:59]
	s_waitcnt vmcnt(14)
	ds_write_b128 v237, v[104:107] offset:4608
	v_mfma_f32_16x16x32_bf16 v[64:67], v[176:179], v[144:147], v[64:67]
	ds_read_b128 v[156:159], v238 offset:64
	s_waitcnt lgkmcnt(6)
	v_mfma_f32_16x16x32_bf16 v[36:39], v[180:183], v[140:143], v[36:39]
	ds_read_b128 v[216:219], v239 offset:18496
	s_waitcnt vmcnt(13)
	ds_write_b128 v237, v[108:111] offset:9216
	global_load_dwordx4 v[100:103], v[132:133], off offset:1664
	v_mfma_f32_16x16x32_bf16 v[40:43], v[180:183], v[144:147], v[40:43]
	ds_read_b128 v[220:223], v239 offset:20800
	s_waitcnt lgkmcnt(8)
	v_mfma_f32_16x16x32_bf16 v[20:23], v[172:175], v[148:151], v[20:23]
	ds_read_b128 v[160:163], v238 offset:2368
	v_mfma_f32_16x16x32_bf16 v[28:31], v[176:179], v[148:151], v[28:31]
	v_mfma_f32_16x16x32_bf16 v[4:7], v[180:183], v[148:151], v[4:7]
	ds_read_b128 v[224:227], v239 offset:23104
	s_waitcnt lgkmcnt(9)
	v_mfma_f32_16x16x32_bf16 v[44:47], v[184:187], v[140:143], v[44:47]
	ds_read_b128 v[164:167], v238 offset:4672
	v_mfma_f32_16x16x32_bf16 v[48:51], v[184:187], v[144:147], v[48:51]
	s_waitcnt vmcnt(13)
	ds_write_b128 v237, v[112:115] offset:13824
	global_load_dwordx4 v[104:107], v[138:139], off offset:1664
	v_mfma_f32_16x16x32_bf16 v[12:15], v[184:187], v[148:151], v[12:15]
	ds_read_b128 v[228:231], v239 offset:25408
	s_waitcnt lgkmcnt(11)
	v_mfma_f32_16x16x32_bf16 v[24:27], v[172:175], v[152:155], v[24:27]
	ds_read_b128 v[168:171], v238 offset:6976
	s_waitcnt vmcnt(13)
	ds_write_b128 v237, v[116:119] offset:18432
	global_load_dwordx4 v[108:111], v[194:195], off offset:1664
	v_mfma_f32_16x16x32_bf16 v[32:35], v[176:179], v[152:155], v[32:35]
	v_mfma_f32_16x16x32_bf16 v[8:11], v[180:183], v[152:155], v[8:11]
	v_mfma_f32_16x16x32_bf16 v[16:19], v[184:187], v[152:155], v[16:19]
	s_waitcnt lgkmcnt(9)
	v_mfma_f32_16x16x32_bf16 v[52:55], v[216:219], v[156:159], v[52:55]
	s_waitcnt lgkmcnt(7)
	v_mfma_f32_16x16x32_bf16 v[60:63], v[220:223], v[156:159], v[60:63]
	s_waitcnt lgkmcnt(6)
	v_mfma_f32_16x16x32_bf16 v[56:59], v[216:219], v[160:163], v[56:59]
	s_waitcnt vmcnt(13)
	ds_write_b128 v237, v[120:123] offset:23040
	global_load_dwordx4 v[112:115], v[196:197], off offset:1664
	v_mfma_f32_16x16x32_bf16 v[64:67], v[220:223], v[160:163], v[64:67]
	s_waitcnt lgkmcnt(6)
	v_mfma_f32_16x16x32_bf16 v[36:39], v[224:227], v[156:159], v[36:39]
	s_waitcnt vmcnt(13)
	ds_write_b128 v237, v[124:127] offset:27648
	global_load_dwordx4 v[116:119], v[134:135], off offset:1664
	v_mfma_f32_16x16x32_bf16 v[40:43], v[224:227], v[160:163], v[40:43]
	s_waitcnt lgkmcnt(6)
	v_mfma_f32_16x16x32_bf16 v[20:23], v[216:219], v[164:167], v[20:23]
	s_waitcnt vmcnt(13)
	ds_write_b128 v237, v[128:131] offset:32256
	global_load_dwordx4 v[120:123], v[214:215], off offset:1664
	v_mfma_f32_16x16x32_bf16 v[28:31], v[220:223], v[164:167], v[28:31]
	v_mfma_f32_16x16x32_bf16 v[4:7], v[224:227], v[164:167], v[4:7]
	global_load_dwordx4 v[124:127], v[232:233], off offset:1664
	s_waitcnt lgkmcnt(5)
	v_mfma_f32_16x16x32_bf16 v[44:47], v[228:231], v[156:159], v[44:47]
	v_mfma_f32_16x16x32_bf16 v[48:51], v[228:231], v[160:163], v[48:51]
	global_load_dwordx4 v[128:131], v[234:235], off offset:1664
	v_mfma_f32_16x16x32_bf16 v[12:15], v[228:231], v[164:167], v[12:15]
	s_waitcnt lgkmcnt(4)
	v_mfma_f32_16x16x32_bf16 v[24:27], v[216:219], v[168:171], v[24:27]
	v_mfma_f32_16x16x32_bf16 v[32:35], v[220:223], v[168:171], v[32:35]
	v_mfma_f32_16x16x32_bf16 v[8:11], v[224:227], v[168:171], v[8:11]
	v_mfma_f32_16x16x32_bf16 v[16:19], v[228:231], v[168:171], v[16:19]
	s_setprio 0
	s_waitcnt lgkmcnt(0)
	s_barrier
	ds_read_b128 v[140:143], v238 offset:36864
	ds_read_b128 v[172:175], v239 offset:55296
	ds_read_b128 v[176:179], v239 offset:57600
	ds_read_b128 v[144:147], v238 offset:39168
	ds_read_b128 v[180:183], v239 offset:59904
	ds_read_b128 v[148:151], v238 offset:41472
	ds_read_b128 v[184:187], v239 offset:62208
	ds_read_b128 v[152:155], v238 offset:43776
	s_setprio 1
	s_waitcnt lgkmcnt(6)
	v_mfma_f32_16x16x32_bf16 v[52:55], v[172:175], v[140:143], v[52:55]
	s_waitcnt vmcnt(15)
	ds_write_b128 v236, v[68:71]
	s_waitcnt lgkmcnt(6)
	v_mfma_f32_16x16x32_bf16 v[60:63], v[176:179], v[140:143], v[60:63]
	s_waitcnt lgkmcnt(5)
	v_mfma_f32_16x16x32_bf16 v[56:59], v[172:175], v[144:147], v[56:59]
	s_waitcnt vmcnt(14)
	ds_write_b128 v236, v[72:75] offset:4608
	v_mfma_f32_16x16x32_bf16 v[64:67], v[176:179], v[144:147], v[64:67]
	ds_read_b128 v[156:159], v238 offset:36928
	s_waitcnt lgkmcnt(6)
	v_mfma_f32_16x16x32_bf16 v[36:39], v[180:183], v[140:143], v[36:39]
	ds_read_b128 v[216:219], v239 offset:55360
	s_waitcnt vmcnt(13)
	ds_write_b128 v236, v[76:79] offset:9216
	global_load_dwordx4 v[68:71], v[132:133], off offset:1792
	v_mfma_f32_16x16x32_bf16 v[40:43], v[180:183], v[144:147], v[40:43]
	ds_read_b128 v[220:223], v239 offset:57664
	s_waitcnt lgkmcnt(8)
	v_mfma_f32_16x16x32_bf16 v[20:23], v[172:175], v[148:151], v[20:23]
	ds_read_b128 v[160:163], v238 offset:39232
	v_mfma_f32_16x16x32_bf16 v[28:31], v[176:179], v[148:151], v[28:31]
	v_mfma_f32_16x16x32_bf16 v[4:7], v[180:183], v[148:151], v[4:7]
	ds_read_b128 v[224:227], v239 offset:59968
	s_waitcnt lgkmcnt(9)
	v_mfma_f32_16x16x32_bf16 v[44:47], v[184:187], v[140:143], v[44:47]
	ds_read_b128 v[164:167], v238 offset:41536
	v_mfma_f32_16x16x32_bf16 v[48:51], v[184:187], v[144:147], v[48:51]
	s_waitcnt vmcnt(13)
	ds_write_b128 v236, v[80:83] offset:13824
	global_load_dwordx4 v[72:75], v[138:139], off offset:1792
	v_mfma_f32_16x16x32_bf16 v[12:15], v[184:187], v[148:151], v[12:15]
	ds_read_b128 v[228:231], v239 offset:62272
	s_waitcnt lgkmcnt(11)
	v_mfma_f32_16x16x32_bf16 v[24:27], v[172:175], v[152:155], v[24:27]
	ds_read_b128 v[168:171], v238 offset:43840
	s_waitcnt vmcnt(13)
	ds_write_b128 v236, v[84:87] offset:18432
	global_load_dwordx4 v[76:79], v[194:195], off offset:1792
	v_mfma_f32_16x16x32_bf16 v[32:35], v[176:179], v[152:155], v[32:35]
	v_mfma_f32_16x16x32_bf16 v[8:11], v[180:183], v[152:155], v[8:11]
	v_mfma_f32_16x16x32_bf16 v[16:19], v[184:187], v[152:155], v[16:19]
	s_waitcnt lgkmcnt(9)
	v_mfma_f32_16x16x32_bf16 v[52:55], v[216:219], v[156:159], v[52:55]
	s_waitcnt lgkmcnt(7)
	v_mfma_f32_16x16x32_bf16 v[60:63], v[220:223], v[156:159], v[60:63]
	s_waitcnt lgkmcnt(6)
	v_mfma_f32_16x16x32_bf16 v[56:59], v[216:219], v[160:163], v[56:59]
	s_waitcnt vmcnt(13)
	ds_write_b128 v236, v[88:91] offset:23040
	global_load_dwordx4 v[80:83], v[196:197], off offset:1792
	v_mfma_f32_16x16x32_bf16 v[64:67], v[220:223], v[160:163], v[64:67]
	s_waitcnt lgkmcnt(6)
	v_mfma_f32_16x16x32_bf16 v[36:39], v[224:227], v[156:159], v[36:39]
	s_waitcnt vmcnt(13)
	ds_write_b128 v236, v[92:95] offset:27648
	global_load_dwordx4 v[84:87], v[134:135], off offset:1792
	v_mfma_f32_16x16x32_bf16 v[40:43], v[224:227], v[160:163], v[40:43]
	s_waitcnt lgkmcnt(6)
	v_mfma_f32_16x16x32_bf16 v[20:23], v[216:219], v[164:167], v[20:23]
	s_waitcnt vmcnt(13)
	ds_write_b128 v236, v[96:99] offset:32256
	global_load_dwordx4 v[88:91], v[214:215], off offset:1792
	v_mfma_f32_16x16x32_bf16 v[28:31], v[220:223], v[164:167], v[28:31]
	v_mfma_f32_16x16x32_bf16 v[4:7], v[224:227], v[164:167], v[4:7]
	global_load_dwordx4 v[92:95], v[232:233], off offset:1792
	s_waitcnt lgkmcnt(5)
	v_mfma_f32_16x16x32_bf16 v[44:47], v[228:231], v[156:159], v[44:47]
	v_mfma_f32_16x16x32_bf16 v[48:51], v[228:231], v[160:163], v[48:51]
	global_load_dwordx4 v[96:99], v[234:235], off offset:1792
	v_mfma_f32_16x16x32_bf16 v[12:15], v[228:231], v[164:167], v[12:15]
	s_waitcnt lgkmcnt(4)
	v_mfma_f32_16x16x32_bf16 v[24:27], v[216:219], v[168:171], v[24:27]
	v_mfma_f32_16x16x32_bf16 v[32:35], v[220:223], v[168:171], v[32:35]
	v_mfma_f32_16x16x32_bf16 v[8:11], v[224:227], v[168:171], v[8:11]
	v_mfma_f32_16x16x32_bf16 v[16:19], v[228:231], v[168:171], v[16:19]
	s_setprio 0
	s_waitcnt lgkmcnt(0)
	s_barrier
	ds_read_b128 v[140:143], v238
	ds_read_b128 v[172:175], v239 offset:18432
	ds_read_b128 v[176:179], v239 offset:20736
	ds_read_b128 v[144:147], v238 offset:2304
	ds_read_b128 v[180:183], v239 offset:23040
	ds_read_b128 v[148:151], v238 offset:4608
	ds_read_b128 v[184:187], v239 offset:25344
	ds_read_b128 v[152:155], v238 offset:6912
	s_setprio 1
	s_waitcnt lgkmcnt(6)
	v_mfma_f32_16x16x32_bf16 v[52:55], v[172:175], v[140:143], v[52:55]
	s_waitcnt vmcnt(15)
	ds_write_b128 v237, v[100:103]
	s_waitcnt lgkmcnt(6)
	v_mfma_f32_16x16x32_bf16 v[60:63], v[176:179], v[140:143], v[60:63]
	s_waitcnt lgkmcnt(5)
	v_mfma_f32_16x16x32_bf16 v[56:59], v[172:175], v[144:147], v[56:59]
	s_waitcnt vmcnt(14)
	ds_write_b128 v237, v[104:107] offset:4608
	v_mfma_f32_16x16x32_bf16 v[64:67], v[176:179], v[144:147], v[64:67]
	ds_read_b128 v[156:159], v238 offset:64
	s_waitcnt lgkmcnt(6)
	v_mfma_f32_16x16x32_bf16 v[36:39], v[180:183], v[140:143], v[36:39]
	ds_read_b128 v[216:219], v239 offset:18496
	s_waitcnt vmcnt(13)
	ds_write_b128 v237, v[108:111] offset:9216
	global_load_dwordx4 v[100:103], v[132:133], off offset:1920
	v_mfma_f32_16x16x32_bf16 v[40:43], v[180:183], v[144:147], v[40:43]
	ds_read_b128 v[220:223], v239 offset:20800
	s_waitcnt lgkmcnt(8)
	v_mfma_f32_16x16x32_bf16 v[20:23], v[172:175], v[148:151], v[20:23]
	ds_read_b128 v[160:163], v238 offset:2368
	v_mfma_f32_16x16x32_bf16 v[28:31], v[176:179], v[148:151], v[28:31]
	v_mfma_f32_16x16x32_bf16 v[4:7], v[180:183], v[148:151], v[4:7]
	ds_read_b128 v[224:227], v239 offset:23104
	s_waitcnt lgkmcnt(9)
	v_mfma_f32_16x16x32_bf16 v[44:47], v[184:187], v[140:143], v[44:47]
	ds_read_b128 v[164:167], v238 offset:4672
	v_mfma_f32_16x16x32_bf16 v[48:51], v[184:187], v[144:147], v[48:51]
	s_waitcnt vmcnt(13)
	ds_write_b128 v237, v[112:115] offset:13824
	global_load_dwordx4 v[104:107], v[138:139], off offset:1920
	v_mfma_f32_16x16x32_bf16 v[12:15], v[184:187], v[148:151], v[12:15]
	ds_read_b128 v[228:231], v239 offset:25408
	s_waitcnt lgkmcnt(11)
	v_mfma_f32_16x16x32_bf16 v[24:27], v[172:175], v[152:155], v[24:27]
	ds_read_b128 v[168:171], v238 offset:6976
	s_waitcnt vmcnt(13)
	ds_write_b128 v237, v[116:119] offset:18432
	global_load_dwordx4 v[108:111], v[194:195], off offset:1920
	v_mfma_f32_16x16x32_bf16 v[32:35], v[176:179], v[152:155], v[32:35]
	v_mfma_f32_16x16x32_bf16 v[8:11], v[180:183], v[152:155], v[8:11]
	v_mfma_f32_16x16x32_bf16 v[16:19], v[184:187], v[152:155], v[16:19]
	s_waitcnt lgkmcnt(9)
	v_mfma_f32_16x16x32_bf16 v[52:55], v[216:219], v[156:159], v[52:55]
	s_waitcnt lgkmcnt(7)
	v_mfma_f32_16x16x32_bf16 v[60:63], v[220:223], v[156:159], v[60:63]
	s_waitcnt lgkmcnt(6)
	v_mfma_f32_16x16x32_bf16 v[56:59], v[216:219], v[160:163], v[56:59]
	s_waitcnt vmcnt(13)
	ds_write_b128 v237, v[120:123] offset:23040
	global_load_dwordx4 v[112:115], v[196:197], off offset:1920
	v_mfma_f32_16x16x32_bf16 v[64:67], v[220:223], v[160:163], v[64:67]
	s_waitcnt lgkmcnt(6)
	v_mfma_f32_16x16x32_bf16 v[36:39], v[224:227], v[156:159], v[36:39]
	s_waitcnt vmcnt(13)
	ds_write_b128 v237, v[124:127] offset:27648
	global_load_dwordx4 v[116:119], v[134:135], off offset:1920
	v_mfma_f32_16x16x32_bf16 v[40:43], v[224:227], v[160:163], v[40:43]
	s_waitcnt lgkmcnt(6)
	v_mfma_f32_16x16x32_bf16 v[20:23], v[216:219], v[164:167], v[20:23]
	s_waitcnt vmcnt(13)
	ds_write_b128 v237, v[128:131] offset:32256
	global_load_dwordx4 v[120:123], v[214:215], off offset:1920
	v_mfma_f32_16x16x32_bf16 v[28:31], v[220:223], v[164:167], v[28:31]
	v_mfma_f32_16x16x32_bf16 v[4:7], v[224:227], v[164:167], v[4:7]
	global_load_dwordx4 v[124:127], v[232:233], off offset:1920
	s_waitcnt lgkmcnt(5)
	v_mfma_f32_16x16x32_bf16 v[44:47], v[228:231], v[156:159], v[44:47]
	v_mfma_f32_16x16x32_bf16 v[48:51], v[228:231], v[160:163], v[48:51]
	global_load_dwordx4 v[128:131], v[234:235], off offset:1920
	v_mfma_f32_16x16x32_bf16 v[12:15], v[228:231], v[164:167], v[12:15]
	s_waitcnt lgkmcnt(4)
	v_mfma_f32_16x16x32_bf16 v[24:27], v[216:219], v[168:171], v[24:27]
	v_mfma_f32_16x16x32_bf16 v[32:35], v[220:223], v[168:171], v[32:35]
	v_mfma_f32_16x16x32_bf16 v[8:11], v[224:227], v[168:171], v[8:11]
	v_mfma_f32_16x16x32_bf16 v[16:19], v[228:231], v[168:171], v[16:19]
	s_setprio 0
	s_waitcnt lgkmcnt(0)
	s_barrier
	ds_read_b128 v[140:143], v238 offset:36864
	ds_read_b128 v[172:175], v239 offset:55296
	ds_read_b128 v[176:179], v239 offset:57600
	ds_read_b128 v[144:147], v238 offset:39168
	ds_read_b128 v[180:183], v239 offset:59904
	ds_read_b128 v[148:151], v238 offset:41472
	ds_read_b128 v[184:187], v239 offset:62208
	ds_read_b128 v[152:155], v238 offset:43776
	s_setprio 1
	s_waitcnt lgkmcnt(6)
	v_mfma_f32_16x16x32_bf16 v[52:55], v[172:175], v[140:143], v[52:55]
	s_waitcnt vmcnt(15)
	ds_write_b128 v236, v[68:71]
	s_waitcnt lgkmcnt(6)
	v_mfma_f32_16x16x32_bf16 v[60:63], v[176:179], v[140:143], v[60:63]
	s_waitcnt lgkmcnt(5)
	v_mfma_f32_16x16x32_bf16 v[56:59], v[172:175], v[144:147], v[56:59]
	s_waitcnt vmcnt(14)
	ds_write_b128 v236, v[72:75] offset:4608
	v_mfma_f32_16x16x32_bf16 v[64:67], v[176:179], v[144:147], v[64:67]
	ds_read_b128 v[156:159], v238 offset:36928
	s_waitcnt lgkmcnt(6)
	v_mfma_f32_16x16x32_bf16 v[36:39], v[180:183], v[140:143], v[36:39]
	ds_read_b128 v[216:219], v239 offset:55360
	s_waitcnt vmcnt(13)
	ds_write_b128 v236, v[76:79] offset:9216
	v_mfma_f32_16x16x32_bf16 v[40:43], v[180:183], v[144:147], v[40:43]
	ds_read_b128 v[220:223], v239 offset:57664
	s_waitcnt lgkmcnt(8)
	v_mfma_f32_16x16x32_bf16 v[20:23], v[172:175], v[148:151], v[20:23]
	ds_read_b128 v[160:163], v238 offset:39232
	v_mfma_f32_16x16x32_bf16 v[28:31], v[176:179], v[148:151], v[28:31]
	v_mfma_f32_16x16x32_bf16 v[4:7], v[180:183], v[148:151], v[4:7]
	ds_read_b128 v[224:227], v239 offset:59968
	s_waitcnt lgkmcnt(9)
	v_mfma_f32_16x16x32_bf16 v[44:47], v[184:187], v[140:143], v[44:47]
	ds_read_b128 v[164:167], v238 offset:41536
	v_mfma_f32_16x16x32_bf16 v[48:51], v[184:187], v[144:147], v[48:51]
	s_waitcnt vmcnt(12)
	ds_write_b128 v236, v[80:83] offset:13824
	v_mfma_f32_16x16x32_bf16 v[12:15], v[184:187], v[148:151], v[12:15]
	ds_read_b128 v[228:231], v239 offset:62272
	s_waitcnt lgkmcnt(11)
	v_mfma_f32_16x16x32_bf16 v[24:27], v[172:175], v[152:155], v[24:27]
	ds_read_b128 v[168:171], v238 offset:43840
	s_waitcnt vmcnt(11)
	ds_write_b128 v236, v[84:87] offset:18432
	v_mfma_f32_16x16x32_bf16 v[32:35], v[176:179], v[152:155], v[32:35]
	v_mfma_f32_16x16x32_bf16 v[8:11], v[180:183], v[152:155], v[8:11]
	v_mfma_f32_16x16x32_bf16 v[16:19], v[184:187], v[152:155], v[16:19]
	s_waitcnt lgkmcnt(9)
	v_mfma_f32_16x16x32_bf16 v[52:55], v[216:219], v[156:159], v[52:55]
	s_waitcnt lgkmcnt(7)
	v_mfma_f32_16x16x32_bf16 v[60:63], v[220:223], v[156:159], v[60:63]
	s_waitcnt lgkmcnt(6)
	v_mfma_f32_16x16x32_bf16 v[56:59], v[216:219], v[160:163], v[56:59]
	s_waitcnt vmcnt(10)
	ds_write_b128 v236, v[88:91] offset:23040
	v_mfma_f32_16x16x32_bf16 v[64:67], v[220:223], v[160:163], v[64:67]
	s_waitcnt lgkmcnt(6)
	v_mfma_f32_16x16x32_bf16 v[36:39], v[224:227], v[156:159], v[36:39]
	s_waitcnt vmcnt(9)
	ds_write_b128 v236, v[92:95] offset:27648
	v_mfma_f32_16x16x32_bf16 v[40:43], v[224:227], v[160:163], v[40:43]
	s_waitcnt lgkmcnt(6)
	v_mfma_f32_16x16x32_bf16 v[20:23], v[216:219], v[164:167], v[20:23]
	s_waitcnt vmcnt(8)
	ds_write_b128 v236, v[96:99] offset:32256
	v_mfma_f32_16x16x32_bf16 v[28:31], v[220:223], v[164:167], v[28:31]
	v_mfma_f32_16x16x32_bf16 v[4:7], v[224:227], v[164:167], v[4:7]
	s_waitcnt lgkmcnt(5)
	v_mfma_f32_16x16x32_bf16 v[44:47], v[228:231], v[156:159], v[44:47]
	v_mfma_f32_16x16x32_bf16 v[48:51], v[228:231], v[160:163], v[48:51]
	v_mfma_f32_16x16x32_bf16 v[12:15], v[228:231], v[164:167], v[12:15]
	s_waitcnt lgkmcnt(4)
	v_mfma_f32_16x16x32_bf16 v[24:27], v[216:219], v[168:171], v[24:27]
	v_mfma_f32_16x16x32_bf16 v[32:35], v[220:223], v[168:171], v[32:35]
	v_mfma_f32_16x16x32_bf16 v[8:11], v[224:227], v[168:171], v[8:11]
	v_mfma_f32_16x16x32_bf16 v[16:19], v[228:231], v[168:171], v[16:19]
	s_setprio 0
	s_waitcnt lgkmcnt(0)
	s_barrier
	ds_read_b128 v[140:143], v238
	ds_read_b128 v[172:175], v239 offset:18432
	ds_read_b128 v[176:179], v239 offset:20736
	ds_read_b128 v[144:147], v238 offset:2304
	ds_read_b128 v[180:183], v239 offset:23040
	ds_read_b128 v[148:151], v238 offset:4608
	ds_read_b128 v[184:187], v239 offset:25344
	ds_read_b128 v[152:155], v238 offset:6912
	s_setprio 1
	s_waitcnt lgkmcnt(6)
	v_mfma_f32_16x16x32_bf16 v[52:55], v[172:175], v[140:143], v[52:55]
	s_waitcnt vmcnt(7)
	ds_write_b128 v237, v[100:103]
	s_waitcnt lgkmcnt(6)
	v_mfma_f32_16x16x32_bf16 v[60:63], v[176:179], v[140:143], v[60:63]
	s_waitcnt lgkmcnt(5)
	v_mfma_f32_16x16x32_bf16 v[56:59], v[172:175], v[144:147], v[56:59]
	s_waitcnt vmcnt(6)
	ds_write_b128 v237, v[104:107] offset:4608
	v_mfma_f32_16x16x32_bf16 v[64:67], v[176:179], v[144:147], v[64:67]
	ds_read_b128 v[156:159], v238 offset:64
	s_waitcnt lgkmcnt(6)
	v_mfma_f32_16x16x32_bf16 v[36:39], v[180:183], v[140:143], v[36:39]
	ds_read_b128 v[216:219], v239 offset:18496
	s_waitcnt vmcnt(5)
	ds_write_b128 v237, v[108:111] offset:9216
	v_mfma_f32_16x16x32_bf16 v[40:43], v[180:183], v[144:147], v[40:43]
	ds_read_b128 v[220:223], v239 offset:20800
	s_waitcnt lgkmcnt(8)
	v_mfma_f32_16x16x32_bf16 v[20:23], v[172:175], v[148:151], v[20:23]
	ds_read_b128 v[160:163], v238 offset:2368
	v_mfma_f32_16x16x32_bf16 v[28:31], v[176:179], v[148:151], v[28:31]
	v_mfma_f32_16x16x32_bf16 v[4:7], v[180:183], v[148:151], v[4:7]
	ds_read_b128 v[224:227], v239 offset:23104
	s_waitcnt lgkmcnt(9)
	v_mfma_f32_16x16x32_bf16 v[44:47], v[184:187], v[140:143], v[44:47]
	ds_read_b128 v[164:167], v238 offset:4672
	v_mfma_f32_16x16x32_bf16 v[48:51], v[184:187], v[144:147], v[48:51]
	s_waitcnt vmcnt(4)
	ds_write_b128 v237, v[112:115] offset:13824
	v_mfma_f32_16x16x32_bf16 v[12:15], v[184:187], v[148:151], v[12:15]
	ds_read_b128 v[228:231], v239 offset:25408
	s_waitcnt lgkmcnt(11)
	v_mfma_f32_16x16x32_bf16 v[24:27], v[172:175], v[152:155], v[24:27]
	ds_read_b128 v[168:171], v238 offset:6976
	s_waitcnt vmcnt(3)
	ds_write_b128 v237, v[116:119] offset:18432
	v_mfma_f32_16x16x32_bf16 v[32:35], v[176:179], v[152:155], v[32:35]
	v_mfma_f32_16x16x32_bf16 v[8:11], v[180:183], v[152:155], v[8:11]
	v_mfma_f32_16x16x32_bf16 v[16:19], v[184:187], v[152:155], v[16:19]
	s_waitcnt lgkmcnt(9)
	v_mfma_f32_16x16x32_bf16 v[52:55], v[216:219], v[156:159], v[52:55]
	s_waitcnt lgkmcnt(7)
	v_mfma_f32_16x16x32_bf16 v[60:63], v[220:223], v[156:159], v[60:63]
	s_waitcnt lgkmcnt(6)
	v_mfma_f32_16x16x32_bf16 v[56:59], v[216:219], v[160:163], v[56:59]
	s_waitcnt vmcnt(2)
	ds_write_b128 v237, v[120:123] offset:23040
	v_mfma_f32_16x16x32_bf16 v[64:67], v[220:223], v[160:163], v[64:67]
	s_waitcnt lgkmcnt(6)
	v_mfma_f32_16x16x32_bf16 v[36:39], v[224:227], v[156:159], v[36:39]
	s_waitcnt vmcnt(1)
	ds_write_b128 v237, v[124:127] offset:27648
	v_mfma_f32_16x16x32_bf16 v[40:43], v[224:227], v[160:163], v[40:43]
	s_waitcnt lgkmcnt(6)
	v_mfma_f32_16x16x32_bf16 v[20:23], v[216:219], v[164:167], v[20:23]
	s_waitcnt vmcnt(0)
	ds_write_b128 v237, v[128:131] offset:32256
	v_mfma_f32_16x16x32_bf16 v[28:31], v[220:223], v[164:167], v[28:31]
	v_mfma_f32_16x16x32_bf16 v[4:7], v[224:227], v[164:167], v[4:7]
	s_waitcnt lgkmcnt(5)
	v_mfma_f32_16x16x32_bf16 v[44:47], v[228:231], v[156:159], v[44:47]
	v_mfma_f32_16x16x32_bf16 v[48:51], v[228:231], v[160:163], v[48:51]
	v_mfma_f32_16x16x32_bf16 v[12:15], v[228:231], v[164:167], v[12:15]
	s_waitcnt lgkmcnt(4)
	v_mfma_f32_16x16x32_bf16 v[24:27], v[216:219], v[168:171], v[24:27]
	v_mfma_f32_16x16x32_bf16 v[32:35], v[220:223], v[168:171], v[32:35]
	v_mfma_f32_16x16x32_bf16 v[8:11], v[224:227], v[168:171], v[8:11]
	v_mfma_f32_16x16x32_bf16 v[16:19], v[228:231], v[168:171], v[16:19]
	s_setprio 0
	s_waitcnt lgkmcnt(0)
	s_barrier
	ds_read_b128 v[140:143], v238 offset:36864
	ds_read_b128 v[172:175], v239 offset:55296
	ds_read_b128 v[176:179], v239 offset:57600
	ds_read_b128 v[144:147], v238 offset:39168
	ds_read_b128 v[180:183], v239 offset:59904
	ds_read_b128 v[148:151], v238 offset:41472
	ds_read_b128 v[184:187], v239 offset:62208
	ds_read_b128 v[152:155], v238 offset:43776
	s_setprio 1
	s_waitcnt lgkmcnt(6)
	v_mfma_f32_16x16x32_bf16 v[52:55], v[172:175], v[140:143], v[52:55]
	s_waitcnt lgkmcnt(5)
	v_mfma_f32_16x16x32_bf16 v[60:63], v[176:179], v[140:143], v[60:63]
	s_waitcnt lgkmcnt(4)
	v_mfma_f32_16x16x32_bf16 v[56:59], v[172:175], v[144:147], v[56:59]
	v_mfma_f32_16x16x32_bf16 v[64:67], v[176:179], v[144:147], v[64:67]
	ds_read_b128 v[156:159], v238 offset:36928
	s_waitcnt lgkmcnt(4)
	v_mfma_f32_16x16x32_bf16 v[36:39], v[180:183], v[140:143], v[36:39]
	ds_read_b128 v[216:219], v239 offset:55360
	v_mfma_f32_16x16x32_bf16 v[40:43], v[180:183], v[144:147], v[40:43]
	ds_read_b128 v[220:223], v239 offset:57664
	s_waitcnt lgkmcnt(5)
	v_mfma_f32_16x16x32_bf16 v[20:23], v[172:175], v[148:151], v[20:23]
	ds_read_b128 v[160:163], v238 offset:39232
	v_mfma_f32_16x16x32_bf16 v[28:31], v[176:179], v[148:151], v[28:31]
	v_mfma_f32_16x16x32_bf16 v[4:7], v[180:183], v[148:151], v[4:7]
	ds_read_b128 v[224:227], v239 offset:59968
	s_waitcnt lgkmcnt(6)
	v_mfma_f32_16x16x32_bf16 v[44:47], v[184:187], v[140:143], v[44:47]
	ds_read_b128 v[164:167], v238 offset:41536
	v_mfma_f32_16x16x32_bf16 v[48:51], v[184:187], v[144:147], v[48:51]
	v_mfma_f32_16x16x32_bf16 v[12:15], v[184:187], v[148:151], v[12:15]
	ds_read_b128 v[228:231], v239 offset:62272
	s_waitcnt lgkmcnt(7)
	v_mfma_f32_16x16x32_bf16 v[24:27], v[172:175], v[152:155], v[24:27]
	ds_read_b128 v[168:171], v238 offset:43840
	v_mfma_f32_16x16x32_bf16 v[32:35], v[176:179], v[152:155], v[32:35]
	v_mfma_f32_16x16x32_bf16 v[8:11], v[180:183], v[152:155], v[8:11]
	v_mfma_f32_16x16x32_bf16 v[16:19], v[184:187], v[152:155], v[16:19]
	s_waitcnt lgkmcnt(6)
	v_mfma_f32_16x16x32_bf16 v[52:55], v[216:219], v[156:159], v[52:55]
	s_waitcnt lgkmcnt(5)
	v_mfma_f32_16x16x32_bf16 v[60:63], v[220:223], v[156:159], v[60:63]
	s_waitcnt lgkmcnt(4)
	v_mfma_f32_16x16x32_bf16 v[56:59], v[216:219], v[160:163], v[56:59]
	v_mfma_f32_16x16x32_bf16 v[64:67], v[220:223], v[160:163], v[64:67]
	s_waitcnt lgkmcnt(3)
	v_mfma_f32_16x16x32_bf16 v[36:39], v[224:227], v[156:159], v[36:39]
	v_mfma_f32_16x16x32_bf16 v[40:43], v[224:227], v[160:163], v[40:43]
	s_waitcnt lgkmcnt(2)
	v_mfma_f32_16x16x32_bf16 v[20:23], v[216:219], v[164:167], v[20:23]
	v_mfma_f32_16x16x32_bf16 v[28:31], v[220:223], v[164:167], v[28:31]
	v_mfma_f32_16x16x32_bf16 v[4:7], v[224:227], v[164:167], v[4:7]
	s_waitcnt lgkmcnt(1)
	v_mfma_f32_16x16x32_bf16 v[44:47], v[228:231], v[156:159], v[44:47]
	v_mfma_f32_16x16x32_bf16 v[48:51], v[228:231], v[160:163], v[48:51]
	v_mfma_f32_16x16x32_bf16 v[12:15], v[228:231], v[164:167], v[12:15]
	s_waitcnt lgkmcnt(0)
	v_mfma_f32_16x16x32_bf16 v[24:27], v[216:219], v[168:171], v[24:27]
	v_mfma_f32_16x16x32_bf16 v[32:35], v[220:223], v[168:171], v[32:35]
	v_mfma_f32_16x16x32_bf16 v[8:11], v[224:227], v[168:171], v[8:11]
	v_mfma_f32_16x16x32_bf16 v[16:19], v[228:231], v[168:171], v[16:19]
	s_setprio 0
	s_nop 7
	s_nop 4
	s_nop 4
	v_permlane16_swap_b32_e32 v52, v56
	v_permlane16_swap_b32_e32 v53, v57
	v_permlane16_swap_b32_e32 v54, v58
	v_permlane16_swap_b32_e32 v55, v59
	v_permlane16_swap_b32_e32 v60, v64
	v_permlane16_swap_b32_e32 v61, v65
	v_permlane16_swap_b32_e32 v62, v66
	v_permlane16_swap_b32_e32 v63, v67
	v_permlane16_swap_b32_e32 v36, v40
	v_permlane16_swap_b32_e32 v37, v41
	v_permlane16_swap_b32_e32 v38, v42
	v_permlane16_swap_b32_e32 v39, v43
	v_permlane16_swap_b32_e32 v44, v48
	v_permlane16_swap_b32_e32 v45, v49
	v_permlane16_swap_b32_e32 v46, v50
	v_permlane16_swap_b32_e32 v47, v51
	v_permlane16_swap_b32_e32 v20, v24
	v_permlane16_swap_b32_e32 v21, v25
	v_permlane16_swap_b32_e32 v22, v26
	v_permlane16_swap_b32_e32 v23, v27
	v_permlane16_swap_b32_e32 v28, v32
	v_permlane16_swap_b32_e32 v29, v33
	v_permlane16_swap_b32_e32 v30, v34
	v_permlane16_swap_b32_e32 v31, v35
	v_permlane16_swap_b32_e32 v4, v8
	v_permlane16_swap_b32_e32 v5, v9
	v_permlane16_swap_b32_e32 v6, v10
	v_permlane16_swap_b32_e32 v7, v11
	v_permlane16_swap_b32_e32 v12, v16
	v_permlane16_swap_b32_e32 v13, v17
	v_permlane16_swap_b32_e32 v14, v18
	v_permlane16_swap_b32_e32 v15, v19
	s_nop 1
	v_permlane32_swap_b32_e32 v52, v56
	v_permlane32_swap_b32_e32 v53, v57
	v_permlane32_swap_b32_e32 v54, v58
	v_permlane32_swap_b32_e32 v55, v59
	v_permlane32_swap_b32_e32 v60, v64
	v_permlane32_swap_b32_e32 v61, v65
	v_permlane32_swap_b32_e32 v62, v66
	v_permlane32_swap_b32_e32 v63, v67
	v_permlane32_swap_b32_e32 v36, v40
	v_permlane32_swap_b32_e32 v37, v41
	v_permlane32_swap_b32_e32 v38, v42
	v_permlane32_swap_b32_e32 v39, v43
	v_permlane32_swap_b32_e32 v44, v48
	v_permlane32_swap_b32_e32 v45, v49
	v_permlane32_swap_b32_e32 v46, v50
	v_permlane32_swap_b32_e32 v47, v51
	v_permlane32_swap_b32_e32 v20, v24
	v_permlane32_swap_b32_e32 v21, v25
	v_permlane32_swap_b32_e32 v22, v26
	v_permlane32_swap_b32_e32 v23, v27
	v_permlane32_swap_b32_e32 v28, v32
	v_permlane32_swap_b32_e32 v29, v33
	v_permlane32_swap_b32_e32 v30, v34
	v_permlane32_swap_b32_e32 v31, v35
	v_permlane32_swap_b32_e32 v4, v8
	v_permlane32_swap_b32_e32 v5, v9
	v_permlane32_swap_b32_e32 v6, v10
	v_permlane32_swap_b32_e32 v7, v11
	v_permlane32_swap_b32_e32 v12, v16
	v_permlane32_swap_b32_e32 v13, v17
	v_permlane32_swap_b32_e32 v14, v18
	v_permlane32_swap_b32_e32 v15, v19
	s_nop 1
	s_barrier
	s_load_dword s34, s[62:63], 0x0
	s_waitcnt lgkmcnt(0)
	s_add_i32 s34, s34, s21
	s_cmpk_gt_i32 s34, 0xaff
	s_cselect_b64 s[18:19], -1, 0
	s_and_b64 vcc, exec, s[18:19]
	s_cbranch_vccnz .LBB0_22
	s_lshl_b32 s20, s34, 18
	v_readlane_b32 s24, v252, 47
	v_mov_b32_e32 v2, v0
	s_and_b32 s20, s20, 0xfc0000
	v_readlane_b32 s30, v252, 53
	v_readlane_b32 s31, v252, 54
	v_ashrrev_i32_e32 v68, 3, v2
	s_add_u32 s22, s30, s20
	v_ashrrev_i32_e32 v69, 31, v68
	s_addc_u32 s23, s31, 0
	v_lshlrev_b64 v[68:69], 11, v[68:69]
	v_lshlrev_b32_e32 v2, 4, v2
	v_lshl_add_u64 v[70:71], s[22:23], 0, v[68:69]
	v_and_b32_e32 v2, 0x70, v2
	v_readlane_b32 s25, v252, 48
	s_ashr_i32 s24, s34, 6
	v_lshl_add_u64 v[132:133], v[70:71], 0, v[2:3]
	s_ashr_i32 s25, s24, 31
	v_add_co_u32_e32 v76, vcc, s33, v132
	s_lshl_b64 s[24:25], s[24:25], 17
	s_nop 0
	v_addc_co_u32_e32 v77, vcc, 0, v133, vcc
	s_add_u32 s24, s37, s24
	v_add_co_u32_e32 v80, vcc, s78, v132
	s_addc_u32 s25, s40, s25
	s_nop 0
	v_addc_co_u32_e32 v81, vcc, 0, v133, vcc
	v_lshl_add_u64 v[68:69], s[24:25], 0, v[68:69]
	v_add_co_u32_e32 v84, vcc, s79, v132
	v_lshl_add_u64 v[134:135], v[68:69], 0, v[2:3]
	s_nop 0
	v_addc_co_u32_e32 v85, vcc, 0, v133, vcc
	v_add_co_u32_e32 v92, vcc, s33, v134
	v_readlane_b32 s26, v252, 49
	s_nop 0
	v_addc_co_u32_e32 v93, vcc, 0, v135, vcc
	v_add_co_u32_e32 v96, vcc, 0x580000, v134
	v_readlane_b32 s27, v252, 50
	s_nop 0
	v_addc_co_u32_e32 v97, vcc, 0, v135, vcc
	v_add_co_u32_e32 v128, vcc, 0x590000, v134
	v_readlane_b32 s28, v252, 51
	s_nop 0
	v_addc_co_u32_e32 v129, vcc, 0, v135, vcc
	global_load_dwordx4 v[68:71], v[132:133], off
	global_load_dwordx4 v[100:103], v[132:133], off offset:128
	global_load_dwordx4 v[72:75], v[76:77], off
	global_load_dwordx4 v[104:107], v[76:77], off offset:128
	s_nop 0
	global_load_dwordx4 v[76:79], v[80:81], off
	global_load_dwordx4 v[108:111], v[80:81], off offset:128
	s_nop 0
	global_load_dwordx4 v[80:83], v[84:85], off
	global_load_dwordx4 v[112:115], v[84:85], off offset:128
	s_nop 0
	global_load_dwordx4 v[84:87], v[134:135], off
	global_load_dwordx4 v[116:119], v[134:135], off offset:128
	global_load_dwordx4 v[88:91], v[92:93], off
	global_load_dwordx4 v[120:123], v[92:93], off offset:128
	s_nop 0
	global_load_dwordx4 v[92:95], v[96:97], off
	global_load_dwordx4 v[124:127], v[96:97], off offset:128
	s_nop 0
	global_load_dwordx4 v[96:99], v[128:129], off
	s_nop 0
	global_load_dwordx4 v[128:131], v[128:129], off offset:128
	v_readlane_b32 s29, v252, 52

.LBB0_300:
	s_and_b32 s0, s76, 0xfffffe00
	s_cmpk_eq_i32 s0, 0xc00
	s_cselect_b64 s[0:1], -1, 0
	s_and_b64 s[0:1], s[26:27], s[0:1]
	s_cmpk_lt_i32 s76, 0xd00
	s_movk_i32 s2, 0xff00
	s_cselect_b32 s2, 0x100, s2
	s_and_b64 s[0:1], s[0:1], exec
	s_cselect_b32 s77, s2, 0
	s_add_i32 s77, s77, s76
	s_cmpk_lt_i32 s77, 0xd00
	s_mov_b64 s[0:1], -1
	s_cbranch_scc0 .LBB0_423
	s_mov_b32 s0, 0x10000
	s_mov_b32 s1, 0
	v_lshl_add_u64 v[134:135], s[0:1], 0, v[148:149]
	s_mov_b32 s0, 0x20000
	s_mov_b32 s1, 0
	v_lshl_add_u64 v[194:195], s[0:1], 0, v[148:149]
	s_mov_b32 s0, 0x30000
	s_mov_b32 s1, 0
	v_lshl_add_u64 v[196:197], s[0:1], 0, v[148:149]
	s_mov_b32 s0, 0x10000
	s_mov_b32 s1, 0
	v_lshl_add_u64 v[214:215], s[0:1], 0, v[150:151]
	s_mov_b32 s0, 0x20000
	s_mov_b32 s1, 0
	v_lshl_add_u64 v[236:237], s[0:1], 0, v[150:151]
	s_mov_b32 s0, 0x30000
	s_mov_b32 s1, 0
	v_lshl_add_u64 v[238:239], s[0:1], 0, v[150:151]
	v_lshrrev_b32_e32 v172, 3, v0
	v_and_b32_e32 v174, 15, v172
	v_lshlrev_b32_e32 v173, 1, v174
	v_cmp_gt_u32_e32 vcc, 12, v174
	s_nop 1
	v_mov_b32_e32 v175, 15
	v_cndmask_b32_e64 v175, v175, 8, vcc
	v_cmp_gt_u32_e32 vcc, 4, v174
	v_sub_u32_e32 v173, v173, v175
	v_lshlrev_b32_e32 v175, 1, v174
	v_add_u32_e32 v175, 1, v175
	s_nop 1
	v_cndmask_b32_e32 v173, v173, v175, vcc
	v_and_b32_e32 v172, 16, v172
	v_add_u32_e32 v172, v172, v173
	v_mul_u32_u24_e32 v172, 0x90, v172
	v_and_b32_e32 v173, 7, v0
	v_lshl_add_u32 v240, v173, 4, v172
	v_add_u32_e32 v241, 0x9000, v240
	v_and_b32_e32 v174, 15, v0
	v_lshlrev_b32_e32 v173, 1, v174
	v_cmp_gt_u32_e32 vcc, 12, v174
	s_nop 1
	v_mov_b32_e32 v175, 15
	v_cndmask_b32_e64 v175, v175, 8, vcc
	v_cmp_gt_u32_e32 vcc, 4, v174
	v_sub_u32_e32 v173, v173, v175
	v_lshlrev_b32_e32 v175, 1, v174
	v_add_u32_e32 v175, 1, v175
	s_nop 1
	v_cndmask_b32_e32 v173, v173, v175, vcc
	v_bfe_u32 v172, v0, 4, 2
	v_and_b32_e32 v174, 1, v172
	v_lshrrev_b32_e32 v172, 1, v172
	v_lshl_or_b32 v172, v174, 1, v172
	v_lshlrev_b32_e32 v172, 4, v172
	v_lshrrev_b32_e32 v174, 1, v0
	v_and_b32_e32 v174, 64, v174
	v_add_u32_e32 v174, v174, v173
	v_mul_u32_u24_e32 v174, 0x90, v174
	v_add_u32_e32 v242, v174, v172
	v_and_b32_e32 v174, 64, v0
	v_add_u32_e32 v174, v174, v173
	v_mul_u32_u24_e32 v174, 0x90, v174
	v_add_u32_e32 v243, v174, v172
	s_barrier
	s_waitcnt vmcnt(15)
	ds_write_b128 v240, v[68:71]
	s_waitcnt vmcnt(13)
	ds_write_b128 v240, v[72:75] offset:4608
	s_waitcnt vmcnt(11)
	ds_write_b128 v240, v[76:79] offset:9216
	s_waitcnt vmcnt(9)
	ds_write_b128 v240, v[80:83] offset:13824
	s_waitcnt vmcnt(7)
	ds_write_b128 v240, v[84:87] offset:18432
	s_waitcnt vmcnt(5)
	ds_write_b128 v240, v[88:91] offset:23040
	s_waitcnt vmcnt(3)
	ds_write_b128 v240, v[92:95] offset:27648
	s_waitcnt vmcnt(1)
	ds_write_b128 v240, v[96:99] offset:32256
	global_load_dwordx4 v[68:71], v[148:149], off offset:256
	global_load_dwordx4 v[72:75], v[134:135], off offset:256
	global_load_dwordx4 v[76:79], v[194:195], off offset:256
	global_load_dwordx4 v[80:83], v[196:197], off offset:256
	global_load_dwordx4 v[84:87], v[150:151], off offset:256
	global_load_dwordx4 v[88:91], v[214:215], off offset:256
	global_load_dwordx4 v[92:95], v[236:237], off offset:256
	global_load_dwordx4 v[96:99], v[238:239], off offset:256
	s_waitcnt lgkmcnt(0)
	s_barrier
	ds_read_b128 v[136:139], v242
	ds_read_b128 v[176:179], v243 offset:18432
	ds_read_b128 v[180:183], v243 offset:20736
	ds_read_b128 v[140:143], v242 offset:2304
	ds_read_b128 v[184:187], v243 offset:23040
	ds_read_b128 v[152:155], v242 offset:4608
	ds_read_b128 v[216:219], v243 offset:25344
	ds_read_b128 v[156:159], v242 offset:6912
	s_setprio 1
	s_waitcnt lgkmcnt(6)
	v_mfma_f32_16x16x32_bf16 v[52:55], v[176:179], v[136:139], 0
	ds_write_b128 v241, v[100:103]
	s_waitcnt lgkmcnt(6)
	v_mfma_f32_16x16x32_bf16 v[60:63], v[180:183], v[136:139], 0
	s_waitcnt lgkmcnt(5)
	v_mfma_f32_16x16x32_bf16 v[56:59], v[176:179], v[140:143], 0
	ds_write_b128 v241, v[104:107] offset:4608
	v_mfma_f32_16x16x32_bf16 v[64:67], v[180:183], v[140:143], 0
	ds_read_b128 v[160:163], v242 offset:64
	s_waitcnt lgkmcnt(6)
	v_mfma_f32_16x16x32_bf16 v[36:39], v[184:187], v[136:139], 0
	ds_read_b128 v[220:223], v243 offset:18496
	ds_write_b128 v241, v[108:111] offset:9216
	global_load_dwordx4 v[100:103], v[148:149], off offset:384
	v_mfma_f32_16x16x32_bf16 v[40:43], v[184:187], v[140:143], 0
	ds_read_b128 v[224:227], v243 offset:20800
	s_waitcnt lgkmcnt(8)
	v_mfma_f32_16x16x32_bf16 v[20:23], v[176:179], v[152:155], 0
	ds_read_b128 v[164:167], v242 offset:2368
	v_mfma_f32_16x16x32_bf16 v[28:31], v[180:183], v[152:155], 0
	v_mfma_f32_16x16x32_bf16 v[4:7], v[184:187], v[152:155], 0
	ds_read_b128 v[228:231], v243 offset:23104
	s_waitcnt lgkmcnt(9)
	v_mfma_f32_16x16x32_bf16 v[44:47], v[216:219], v[136:139], 0
	ds_read_b128 v[168:171], v242 offset:4672
	v_mfma_f32_16x16x32_bf16 v[48:51], v[216:219], v[140:143], 0
	ds_write_b128 v241, v[112:115] offset:13824
	global_load_dwordx4 v[104:107], v[134:135], off offset:384
	v_mfma_f32_16x16x32_bf16 v[12:15], v[216:219], v[152:155], 0
	ds_read_b128 v[232:235], v243 offset:25408
	s_waitcnt lgkmcnt(11)
	v_mfma_f32_16x16x32_bf16 v[24:27], v[176:179], v[156:159], 0
	ds_read_b128 v[172:175], v242 offset:6976
	ds_write_b128 v241, v[116:119] offset:18432
	global_load_dwordx4 v[108:111], v[194:195], off offset:384
	v_mfma_f32_16x16x32_bf16 v[32:35], v[180:183], v[156:159], 0
	v_mfma_f32_16x16x32_bf16 v[8:11], v[184:187], v[156:159], 0
	v_mfma_f32_16x16x32_bf16 v[16:19], v[216:219], v[156:159], 0
	s_waitcnt lgkmcnt(9)
	v_mfma_f32_16x16x32_bf16 v[52:55], v[220:223], v[160:163], v[52:55]
	s_waitcnt lgkmcnt(7)
	v_mfma_f32_16x16x32_bf16 v[60:63], v[224:227], v[160:163], v[60:63]
	s_waitcnt lgkmcnt(6)
	v_mfma_f32_16x16x32_bf16 v[56:59], v[220:223], v[164:167], v[56:59]
	ds_write_b128 v241, v[120:123] offset:23040
	global_load_dwordx4 v[112:115], v[196:197], off offset:384
	v_mfma_f32_16x16x32_bf16 v[64:67], v[224:227], v[164:167], v[64:67]
	s_waitcnt lgkmcnt(6)
	v_mfma_f32_16x16x32_bf16 v[36:39], v[228:231], v[160:163], v[36:39]
	ds_write_b128 v241, v[124:127] offset:27648
	global_load_dwordx4 v[116:119], v[150:151], off offset:384
	v_mfma_f32_16x16x32_bf16 v[40:43], v[228:231], v[164:167], v[40:43]
	s_waitcnt lgkmcnt(6)
	v_mfma_f32_16x16x32_bf16 v[20:23], v[220:223], v[168:171], v[20:23]
	s_waitcnt vmcnt(13)
	ds_write_b128 v241, v[128:131] offset:32256
	global_load_dwordx4 v[120:123], v[214:215], off offset:384
	v_mfma_f32_16x16x32_bf16 v[28:31], v[224:227], v[168:171], v[28:31]
	v_mfma_f32_16x16x32_bf16 v[4:7], v[228:231], v[168:171], v[4:7]
	global_load_dwordx4 v[124:127], v[236:237], off offset:384
	s_waitcnt lgkmcnt(5)
	v_mfma_f32_16x16x32_bf16 v[44:47], v[232:235], v[160:163], v[44:47]
	v_mfma_f32_16x16x32_bf16 v[48:51], v[232:235], v[164:167], v[48:51]
	global_load_dwordx4 v[128:131], v[238:239], off offset:384
	v_mfma_f32_16x16x32_bf16 v[12:15], v[232:235], v[168:171], v[12:15]
	s_waitcnt lgkmcnt(4)
	v_mfma_f32_16x16x32_bf16 v[24:27], v[220:223], v[172:175], v[24:27]
	v_mfma_f32_16x16x32_bf16 v[32:35], v[224:227], v[172:175], v[32:35]
	v_mfma_f32_16x16x32_bf16 v[8:11], v[228:231], v[172:175], v[8:11]
	v_mfma_f32_16x16x32_bf16 v[16:19], v[232:235], v[172:175], v[16:19]
	s_setprio 0
	s_waitcnt lgkmcnt(0)
	s_barrier
	ds_read_b128 v[136:139], v242 offset:36864
	ds_read_b128 v[176:179], v243 offset:55296
	ds_read_b128 v[180:183], v243 offset:57600
	ds_read_b128 v[140:143], v242 offset:39168
	ds_read_b128 v[184:187], v243 offset:59904
	ds_read_b128 v[152:155], v242 offset:41472
	ds_read_b128 v[216:219], v243 offset:62208
	ds_read_b128 v[156:159], v242 offset:43776
	s_setprio 1
	s_waitcnt lgkmcnt(6)
	v_mfma_f32_16x16x32_bf16 v[52:55], v[176:179], v[136:139], v[52:55]
	s_waitcnt vmcnt(15)
	ds_write_b128 v240, v[68:71]
	s_waitcnt lgkmcnt(6)
	v_mfma_f32_16x16x32_bf16 v[60:63], v[180:183], v[136:139], v[60:63]
	s_waitcnt lgkmcnt(5)
	v_mfma_f32_16x16x32_bf16 v[56:59], v[176:179], v[140:143], v[56:59]
	s_waitcnt vmcnt(14)
	ds_write_b128 v240, v[72:75] offset:4608
	v_mfma_f32_16x16x32_bf16 v[64:67], v[180:183], v[140:143], v[64:67]
	ds_read_b128 v[160:163], v242 offset:36928
	s_waitcnt lgkmcnt(6)
	v_mfma_f32_16x16x32_bf16 v[36:39], v[184:187], v[136:139], v[36:39]
	ds_read_b128 v[220:223], v243 offset:55360
	s_waitcnt vmcnt(13)
	ds_write_b128 v240, v[76:79] offset:9216
	global_load_dwordx4 v[68:71], v[148:149], off offset:512
	v_mfma_f32_16x16x32_bf16 v[40:43], v[184:187], v[140:143], v[40:43]
	ds_read_b128 v[224:227], v243 offset:57664
	s_waitcnt lgkmcnt(8)
	v_mfma_f32_16x16x32_bf16 v[20:23], v[176:179], v[152:155], v[20:23]
	ds_read_b128 v[164:167], v242 offset:39232
	v_mfma_f32_16x16x32_bf16 v[28:31], v[180:183], v[152:155], v[28:31]
	v_mfma_f32_16x16x32_bf16 v[4:7], v[184:187], v[152:155], v[4:7]
	ds_read_b128 v[228:231], v243 offset:59968
	s_waitcnt lgkmcnt(9)
	v_mfma_f32_16x16x32_bf16 v[44:47], v[216:219], v[136:139], v[44:47]
	ds_read_b128 v[168:171], v242 offset:41536
	v_mfma_f32_16x16x32_bf16 v[48:51], v[216:219], v[140:143], v[48:51]
	s_waitcnt vmcnt(13)
	ds_write_b128 v240, v[80:83] offset:13824
	global_load_dwordx4 v[72:75], v[134:135], off offset:512
	v_mfma_f32_16x16x32_bf16 v[12:15], v[216:219], v[152:155], v[12:15]
	ds_read_b128 v[232:235], v243 offset:62272
	s_waitcnt lgkmcnt(11)
	v_mfma_f32_16x16x32_bf16 v[24:27], v[176:179], v[156:159], v[24:27]
	ds_read_b128 v[172:175], v242 offset:43840
	s_waitcnt vmcnt(13)
	ds_write_b128 v240, v[84:87] offset:18432
	global_load_dwordx4 v[76:79], v[194:195], off offset:512
	v_mfma_f32_16x16x32_bf16 v[32:35], v[180:183], v[156:159], v[32:35]
	v_mfma_f32_16x16x32_bf16 v[8:11], v[184:187], v[156:159], v[8:11]
	v_mfma_f32_16x16x32_bf16 v[16:19], v[216:219], v[156:159], v[16:19]
	s_waitcnt lgkmcnt(9)
	v_mfma_f32_16x16x32_bf16 v[52:55], v[220:223], v[160:163], v[52:55]
	s_waitcnt lgkmcnt(7)
	v_mfma_f32_16x16x32_bf16 v[60:63], v[224:227], v[160:163], v[60:63]
	s_waitcnt lgkmcnt(6)
	v_mfma_f32_16x16x32_bf16 v[56:59], v[220:223], v[164:167], v[56:59]
	s_waitcnt vmcnt(13)
	ds_write_b128 v240, v[88:91] offset:23040
	global_load_dwordx4 v[80:83], v[196:197], off offset:512
	v_mfma_f32_16x16x32_bf16 v[64:67], v[224:227], v[164:167], v[64:67]
	s_waitcnt lgkmcnt(6)
	v_mfma_f32_16x16x32_bf16 v[36:39], v[228:231], v[160:163], v[36:39]
	s_waitcnt vmcnt(13)
	ds_write_b128 v240, v[92:95] offset:27648
	global_load_dwordx4 v[84:87], v[150:151], off offset:512
	v_mfma_f32_16x16x32_bf16 v[40:43], v[228:231], v[164:167], v[40:43]
	s_waitcnt lgkmcnt(6)
	v_mfma_f32_16x16x32_bf16 v[20:23], v[220:223], v[168:171], v[20:23]
	s_waitcnt vmcnt(13)
	ds_write_b128 v240, v[96:99] offset:32256
	global_load_dwordx4 v[88:91], v[214:215], off offset:512
	v_mfma_f32_16x16x32_bf16 v[28:31], v[224:227], v[168:171], v[28:31]
	v_mfma_f32_16x16x32_bf16 v[4:7], v[228:231], v[168:171], v[4:7]
	global_load_dwordx4 v[92:95], v[236:237], off offset:512
	s_waitcnt lgkmcnt(5)
	v_mfma_f32_16x16x32_bf16 v[44:47], v[232:235], v[160:163], v[44:47]
	v_mfma_f32_16x16x32_bf16 v[48:51], v[232:235], v[164:167], v[48:51]
	global_load_dwordx4 v[96:99], v[238:239], off offset:512
	v_mfma_f32_16x16x32_bf16 v[12:15], v[232:235], v[168:171], v[12:15]
	s_waitcnt lgkmcnt(4)
	v_mfma_f32_16x16x32_bf16 v[24:27], v[220:223], v[172:175], v[24:27]
	v_mfma_f32_16x16x32_bf16 v[32:35], v[224:227], v[172:175], v[32:35]
	v_mfma_f32_16x16x32_bf16 v[8:11], v[228:231], v[172:175], v[8:11]
	v_mfma_f32_16x16x32_bf16 v[16:19], v[232:235], v[172:175], v[16:19]
	s_setprio 0
	s_waitcnt lgkmcnt(0)
	s_barrier
	ds_read_b128 v[136:139], v242
	ds_read_b128 v[176:179], v243 offset:18432
	ds_read_b128 v[180:183], v243 offset:20736
	ds_read_b128 v[140:143], v242 offset:2304
	ds_read_b128 v[184:187], v243 offset:23040
	ds_read_b128 v[152:155], v242 offset:4608
	ds_read_b128 v[216:219], v243 offset:25344
	ds_read_b128 v[156:159], v242 offset:6912
	s_setprio 1
	s_waitcnt lgkmcnt(6)
	v_mfma_f32_16x16x32_bf16 v[52:55], v[176:179], v[136:139], v[52:55]
	s_waitcnt vmcnt(15)
	ds_write_b128 v241, v[100:103]
	s_waitcnt lgkmcnt(6)
	v_mfma_f32_16x16x32_bf16 v[60:63], v[180:183], v[136:139], v[60:63]
	s_waitcnt lgkmcnt(5)
	v_mfma_f32_16x16x32_bf16 v[56:59], v[176:179], v[140:143], v[56:59]
	s_waitcnt vmcnt(14)
	ds_write_b128 v241, v[104:107] offset:4608
	v_mfma_f32_16x16x32_bf16 v[64:67], v[180:183], v[140:143], v[64:67]
	ds_read_b128 v[160:163], v242 offset:64
	s_waitcnt lgkmcnt(6)
	v_mfma_f32_16x16x32_bf16 v[36:39], v[184:187], v[136:139], v[36:39]
	ds_read_b128 v[220:223], v243 offset:18496
	s_waitcnt vmcnt(13)
	ds_write_b128 v241, v[108:111] offset:9216
	global_load_dwordx4 v[100:103], v[148:149], off offset:640
	v_mfma_f32_16x16x32_bf16 v[40:43], v[184:187], v[140:143], v[40:43]
	ds_read_b128 v[224:227], v243 offset:20800
	s_waitcnt lgkmcnt(8)
	v_mfma_f32_16x16x32_bf16 v[20:23], v[176:179], v[152:155], v[20:23]
	ds_read_b128 v[164:167], v242 offset:2368
	v_mfma_f32_16x16x32_bf16 v[28:31], v[180:183], v[152:155], v[28:31]
	v_mfma_f32_16x16x32_bf16 v[4:7], v[184:187], v[152:155], v[4:7]
	ds_read_b128 v[228:231], v243 offset:23104
	s_waitcnt lgkmcnt(9)
	v_mfma_f32_16x16x32_bf16 v[44:47], v[216:219], v[136:139], v[44:47]
	ds_read_b128 v[168:171], v242 offset:4672
	v_mfma_f32_16x16x32_bf16 v[48:51], v[216:219], v[140:143], v[48:51]
	s_waitcnt vmcnt(13)
	ds_write_b128 v241, v[112:115] offset:13824
	global_load_dwordx4 v[104:107], v[134:135], off offset:640
	v_mfma_f32_16x16x32_bf16 v[12:15], v[216:219], v[152:155], v[12:15]
	ds_read_b128 v[232:235], v243 offset:25408
	s_waitcnt lgkmcnt(11)
	v_mfma_f32_16x16x32_bf16 v[24:27], v[176:179], v[156:159], v[24:27]
	ds_read_b128 v[172:175], v242 offset:6976
	s_waitcnt vmcnt(13)
	ds_write_b128 v241, v[116:119] offset:18432
	global_load_dwordx4 v[108:111], v[194:195], off offset:640
	v_mfma_f32_16x16x32_bf16 v[32:35], v[180:183], v[156:159], v[32:35]
	v_mfma_f32_16x16x32_bf16 v[8:11], v[184:187], v[156:159], v[8:11]
	v_mfma_f32_16x16x32_bf16 v[16:19], v[216:219], v[156:159], v[16:19]
	s_waitcnt lgkmcnt(9)
	v_mfma_f32_16x16x32_bf16 v[52:55], v[220:223], v[160:163], v[52:55]
	s_waitcnt lgkmcnt(7)
	v_mfma_f32_16x16x32_bf16 v[60:63], v[224:227], v[160:163], v[60:63]
	s_waitcnt lgkmcnt(6)
	v_mfma_f32_16x16x32_bf16 v[56:59], v[220:223], v[164:167], v[56:59]
	s_waitcnt vmcnt(13)
	ds_write_b128 v241, v[120:123] offset:23040
	global_load_dwordx4 v[112:115], v[196:197], off offset:640
	v_mfma_f32_16x16x32_bf16 v[64:67], v[224:227], v[164:167], v[64:67]
	s_waitcnt lgkmcnt(6)
	v_mfma_f32_16x16x32_bf16 v[36:39], v[228:231], v[160:163], v[36:39]
	s_waitcnt vmcnt(13)
	ds_write_b128 v241, v[124:127] offset:27648
	global_load_dwordx4 v[116:119], v[150:151], off offset:640
	v_mfma_f32_16x16x32_bf16 v[40:43], v[228:231], v[164:167], v[40:43]
	s_waitcnt lgkmcnt(6)
	v_mfma_f32_16x16x32_bf16 v[20:23], v[220:223], v[168:171], v[20:23]
	s_waitcnt vmcnt(13)
	ds_write_b128 v241, v[128:131] offset:32256
	global_load_dwordx4 v[120:123], v[214:215], off offset:640
	v_mfma_f32_16x16x32_bf16 v[28:31], v[224:227], v[168:171], v[28:31]
	v_mfma_f32_16x16x32_bf16 v[4:7], v[228:231], v[168:171], v[4:7]
	global_load_dwordx4 v[124:127], v[236:237], off offset:640
	s_waitcnt lgkmcnt(5)
	v_mfma_f32_16x16x32_bf16 v[44:47], v[232:235], v[160:163], v[44:47]
	v_mfma_f32_16x16x32_bf16 v[48:51], v[232:235], v[164:167], v[48:51]
	global_load_dwordx4 v[128:131], v[238:239], off offset:640
	v_mfma_f32_16x16x32_bf16 v[12:15], v[232:235], v[168:171], v[12:15]
	s_waitcnt lgkmcnt(4)
	v_mfma_f32_16x16x32_bf16 v[24:27], v[220:223], v[172:175], v[24:27]
	v_mfma_f32_16x16x32_bf16 v[32:35], v[224:227], v[172:175], v[32:35]
	v_mfma_f32_16x16x32_bf16 v[8:11], v[228:231], v[172:175], v[8:11]
	v_mfma_f32_16x16x32_bf16 v[16:19], v[232:235], v[172:175], v[16:19]
	s_setprio 0
	s_waitcnt lgkmcnt(0)
	s_barrier
	ds_read_b128 v[136:139], v242 offset:36864
	ds_read_b128 v[176:179], v243 offset:55296
	ds_read_b128 v[180:183], v243 offset:57600
	ds_read_b128 v[140:143], v242 offset:39168
	ds_read_b128 v[184:187], v243 offset:59904
	ds_read_b128 v[152:155], v242 offset:41472
	ds_read_b128 v[216:219], v243 offset:62208
	ds_read_b128 v[156:159], v242 offset:43776
	s_setprio 1
	s_waitcnt lgkmcnt(6)
	v_mfma_f32_16x16x32_bf16 v[52:55], v[176:179], v[136:139], v[52:55]
	s_waitcnt vmcnt(15)
	ds_write_b128 v240, v[68:71]
	s_waitcnt lgkmcnt(6)
	v_mfma_f32_16x16x32_bf16 v[60:63], v[180:183], v[136:139], v[60:63]
	s_waitcnt lgkmcnt(5)
	v_mfma_f32_16x16x32_bf16 v[56:59], v[176:179], v[140:143], v[56:59]
	s_waitcnt vmcnt(14)
	ds_write_b128 v240, v[72:75] offset:4608
	v_mfma_f32_16x16x32_bf16 v[64:67], v[180:183], v[140:143], v[64:67]
	ds_read_b128 v[160:163], v242 offset:36928
	s_waitcnt lgkmcnt(6)
	v_mfma_f32_16x16x32_bf16 v[36:39], v[184:187], v[136:139], v[36:39]
	ds_read_b128 v[220:223], v243 offset:55360
	s_waitcnt vmcnt(13)
	ds_write_b128 v240, v[76:79] offset:9216
	global_load_dwordx4 v[68:71], v[148:149], off offset:768
	v_mfma_f32_16x16x32_bf16 v[40:43], v[184:187], v[140:143], v[40:43]
	ds_read_b128 v[224:227], v243 offset:57664
	s_waitcnt lgkmcnt(8)
	v_mfma_f32_16x16x32_bf16 v[20:23], v[176:179], v[152:155], v[20:23]
	ds_read_b128 v[164:167], v242 offset:39232
	v_mfma_f32_16x16x32_bf16 v[28:31], v[180:183], v[152:155], v[28:31]
	v_mfma_f32_16x16x32_bf16 v[4:7], v[184:187], v[152:155], v[4:7]
	ds_read_b128 v[228:231], v243 offset:59968
	s_waitcnt lgkmcnt(9)
	v_mfma_f32_16x16x32_bf16 v[44:47], v[216:219], v[136:139], v[44:47]
	ds_read_b128 v[168:171], v242 offset:41536
	v_mfma_f32_16x16x32_bf16 v[48:51], v[216:219], v[140:143], v[48:51]
	s_waitcnt vmcnt(13)
	ds_write_b128 v240, v[80:83] offset:13824
	global_load_dwordx4 v[72:75], v[134:135], off offset:768
	v_mfma_f32_16x16x32_bf16 v[12:15], v[216:219], v[152:155], v[12:15]
	ds_read_b128 v[232:235], v243 offset:62272
	s_waitcnt lgkmcnt(11)
	v_mfma_f32_16x16x32_bf16 v[24:27], v[176:179], v[156:159], v[24:27]
	ds_read_b128 v[172:175], v242 offset:43840
	s_waitcnt vmcnt(13)
	ds_write_b128 v240, v[84:87] offset:18432
	global_load_dwordx4 v[76:79], v[194:195], off offset:768
	v_mfma_f32_16x16x32_bf16 v[32:35], v[180:183], v[156:159], v[32:35]
	v_mfma_f32_16x16x32_bf16 v[8:11], v[184:187], v[156:159], v[8:11]
	v_mfma_f32_16x16x32_bf16 v[16:19], v[216:219], v[156:159], v[16:19]
	s_waitcnt lgkmcnt(9)
	v_mfma_f32_16x16x32_bf16 v[52:55], v[220:223], v[160:163], v[52:55]
	s_waitcnt lgkmcnt(7)
	v_mfma_f32_16x16x32_bf16 v[60:63], v[224:227], v[160:163], v[60:63]
	s_waitcnt lgkmcnt(6)
	v_mfma_f32_16x16x32_bf16 v[56:59], v[220:223], v[164:167], v[56:59]
	s_waitcnt vmcnt(13)
	ds_write_b128 v240, v[88:91] offset:23040
	global_load_dwordx4 v[80:83], v[196:197], off offset:768
	v_mfma_f32_16x16x32_bf16 v[64:67], v[224:227], v[164:167], v[64:67]
	s_waitcnt lgkmcnt(6)
	v_mfma_f32_16x16x32_bf16 v[36:39], v[228:231], v[160:163], v[36:39]
	s_waitcnt vmcnt(13)
	ds_write_b128 v240, v[92:95] offset:27648
	global_load_dwordx4 v[84:87], v[150:151], off offset:768
	v_mfma_f32_16x16x32_bf16 v[40:43], v[228:231], v[164:167], v[40:43]
	s_waitcnt lgkmcnt(6)
	v_mfma_f32_16x16x32_bf16 v[20:23], v[220:223], v[168:171], v[20:23]
	s_waitcnt vmcnt(13)
	ds_write_b128 v240, v[96:99] offset:32256
	global_load_dwordx4 v[88:91], v[214:215], off offset:768
	v_mfma_f32_16x16x32_bf16 v[28:31], v[224:227], v[168:171], v[28:31]
	v_mfma_f32_16x16x32_bf16 v[4:7], v[228:231], v[168:171], v[4:7]
	global_load_dwordx4 v[92:95], v[236:237], off offset:768
	s_waitcnt lgkmcnt(5)
	v_mfma_f32_16x16x32_bf16 v[44:47], v[232:235], v[160:163], v[44:47]
	v_mfma_f32_16x16x32_bf16 v[48:51], v[232:235], v[164:167], v[48:51]
	global_load_dwordx4 v[96:99], v[238:239], off offset:768
	v_mfma_f32_16x16x32_bf16 v[12:15], v[232:235], v[168:171], v[12:15]
	s_waitcnt lgkmcnt(4)
	v_mfma_f32_16x16x32_bf16 v[24:27], v[220:223], v[172:175], v[24:27]
	v_mfma_f32_16x16x32_bf16 v[32:35], v[224:227], v[172:175], v[32:35]
	v_mfma_f32_16x16x32_bf16 v[8:11], v[228:231], v[172:175], v[8:11]
	v_mfma_f32_16x16x32_bf16 v[16:19], v[232:235], v[172:175], v[16:19]
	s_setprio 0
	s_waitcnt lgkmcnt(0)
	s_barrier
	ds_read_b128 v[136:139], v242
	ds_read_b128 v[176:179], v243 offset:18432
	ds_read_b128 v[180:183], v243 offset:20736
	ds_read_b128 v[140:143], v242 offset:2304
	ds_read_b128 v[184:187], v243 offset:23040
	ds_read_b128 v[152:155], v242 offset:4608
	ds_read_b128 v[216:219], v243 offset:25344
	ds_read_b128 v[156:159], v242 offset:6912
	s_setprio 1
	s_waitcnt lgkmcnt(6)
	v_mfma_f32_16x16x32_bf16 v[52:55], v[176:179], v[136:139], v[52:55]
	s_waitcnt vmcnt(15)
	ds_write_b128 v241, v[100:103]
	s_waitcnt lgkmcnt(6)
	v_mfma_f32_16x16x32_bf16 v[60:63], v[180:183], v[136:139], v[60:63]
	s_waitcnt lgkmcnt(5)
	v_mfma_f32_16x16x32_bf16 v[56:59], v[176:179], v[140:143], v[56:59]
	s_waitcnt vmcnt(14)
	ds_write_b128 v241, v[104:107] offset:4608
	v_mfma_f32_16x16x32_bf16 v[64:67], v[180:183], v[140:143], v[64:67]
	ds_read_b128 v[160:163], v242 offset:64
	s_waitcnt lgkmcnt(6)
	v_mfma_f32_16x16x32_bf16 v[36:39], v[184:187], v[136:139], v[36:39]
	ds_read_b128 v[220:223], v243 offset:18496
	s_waitcnt vmcnt(13)
	ds_write_b128 v241, v[108:111] offset:9216
	global_load_dwordx4 v[100:103], v[148:149], off offset:896
	v_mfma_f32_16x16x32_bf16 v[40:43], v[184:187], v[140:143], v[40:43]
	ds_read_b128 v[224:227], v243 offset:20800
	s_waitcnt lgkmcnt(8)
	v_mfma_f32_16x16x32_bf16 v[20:23], v[176:179], v[152:155], v[20:23]
	ds_read_b128 v[164:167], v242 offset:2368
	v_mfma_f32_16x16x32_bf16 v[28:31], v[180:183], v[152:155], v[28:31]
	v_mfma_f32_16x16x32_bf16 v[4:7], v[184:187], v[152:155], v[4:7]
	ds_read_b128 v[228:231], v243 offset:23104
	s_waitcnt lgkmcnt(9)
	v_mfma_f32_16x16x32_bf16 v[44:47], v[216:219], v[136:139], v[44:47]
	ds_read_b128 v[168:171], v242 offset:4672
	v_mfma_f32_16x16x32_bf16 v[48:51], v[216:219], v[140:143], v[48:51]
	s_waitcnt vmcnt(13)
	ds_write_b128 v241, v[112:115] offset:13824
	global_load_dwordx4 v[104:107], v[134:135], off offset:896
	v_mfma_f32_16x16x32_bf16 v[12:15], v[216:219], v[152:155], v[12:15]
	ds_read_b128 v[232:235], v243 offset:25408
	s_waitcnt lgkmcnt(11)
	v_mfma_f32_16x16x32_bf16 v[24:27], v[176:179], v[156:159], v[24:27]
	ds_read_b128 v[172:175], v242 offset:6976
	s_waitcnt vmcnt(13)
	ds_write_b128 v241, v[116:119] offset:18432
	global_load_dwordx4 v[108:111], v[194:195], off offset:896
	v_mfma_f32_16x16x32_bf16 v[32:35], v[180:183], v[156:159], v[32:35]
	v_mfma_f32_16x16x32_bf16 v[8:11], v[184:187], v[156:159], v[8:11]
	v_mfma_f32_16x16x32_bf16 v[16:19], v[216:219], v[156:159], v[16:19]
	s_waitcnt lgkmcnt(9)
	v_mfma_f32_16x16x32_bf16 v[52:55], v[220:223], v[160:163], v[52:55]
	s_waitcnt lgkmcnt(7)
	v_mfma_f32_16x16x32_bf16 v[60:63], v[224:227], v[160:163], v[60:63]
	s_waitcnt lgkmcnt(6)
	v_mfma_f32_16x16x32_bf16 v[56:59], v[220:223], v[164:167], v[56:59]
	s_waitcnt vmcnt(13)
	ds_write_b128 v241, v[120:123] offset:23040
	global_load_dwordx4 v[112:115], v[196:197], off offset:896
	v_mfma_f32_16x16x32_bf16 v[64:67], v[224:227], v[164:167], v[64:67]
	s_waitcnt lgkmcnt(6)
	v_mfma_f32_16x16x32_bf16 v[36:39], v[228:231], v[160:163], v[36:39]
	s_waitcnt vmcnt(13)
	ds_write_b128 v241, v[124:127] offset:27648
	global_load_dwordx4 v[116:119], v[150:151], off offset:896
	v_mfma_f32_16x16x32_bf16 v[40:43], v[228:231], v[164:167], v[40:43]
	s_waitcnt lgkmcnt(6)
	v_mfma_f32_16x16x32_bf16 v[20:23], v[220:223], v[168:171], v[20:23]
	s_waitcnt vmcnt(13)
	ds_write_b128 v241, v[128:131] offset:32256
	global_load_dwordx4 v[120:123], v[214:215], off offset:896
	v_mfma_f32_16x16x32_bf16 v[28:31], v[224:227], v[168:171], v[28:31]
	v_mfma_f32_16x16x32_bf16 v[4:7], v[228:231], v[168:171], v[4:7]
	global_load_dwordx4 v[124:127], v[236:237], off offset:896
	s_waitcnt lgkmcnt(5)
	v_mfma_f32_16x16x32_bf16 v[44:47], v[232:235], v[160:163], v[44:47]
	v_mfma_f32_16x16x32_bf16 v[48:51], v[232:235], v[164:167], v[48:51]
	global_load_dwordx4 v[128:131], v[238:239], off offset:896
	v_mfma_f32_16x16x32_bf16 v[12:15], v[232:235], v[168:171], v[12:15]
	s_waitcnt lgkmcnt(4)
	v_mfma_f32_16x16x32_bf16 v[24:27], v[220:223], v[172:175], v[24:27]
	v_mfma_f32_16x16x32_bf16 v[32:35], v[224:227], v[172:175], v[32:35]
	v_mfma_f32_16x16x32_bf16 v[8:11], v[228:231], v[172:175], v[8:11]
	v_mfma_f32_16x16x32_bf16 v[16:19], v[232:235], v[172:175], v[16:19]
	s_setprio 0
	s_waitcnt lgkmcnt(0)
	s_barrier
	ds_read_b128 v[136:139], v242 offset:36864
	ds_read_b128 v[176:179], v243 offset:55296
	ds_read_b128 v[180:183], v243 offset:57600
	ds_read_b128 v[140:143], v242 offset:39168
	ds_read_b128 v[184:187], v243 offset:59904
	ds_read_b128 v[152:155], v242 offset:41472
	ds_read_b128 v[216:219], v243 offset:62208
	ds_read_b128 v[156:159], v242 offset:43776
	s_setprio 1
	s_waitcnt lgkmcnt(6)
	v_mfma_f32_16x16x32_bf16 v[52:55], v[176:179], v[136:139], v[52:55]
	s_waitcnt vmcnt(15)
	ds_write_b128 v240, v[68:71]
	s_waitcnt lgkmcnt(6)
	v_mfma_f32_16x16x32_bf16 v[60:63], v[180:183], v[136:139], v[60:63]
	s_waitcnt lgkmcnt(5)
	v_mfma_f32_16x16x32_bf16 v[56:59], v[176:179], v[140:143], v[56:59]
	s_waitcnt vmcnt(14)
	ds_write_b128 v240, v[72:75] offset:4608
	v_mfma_f32_16x16x32_bf16 v[64:67], v[180:183], v[140:143], v[64:67]
	ds_read_b128 v[160:163], v242 offset:36928
	s_waitcnt lgkmcnt(6)
	v_mfma_f32_16x16x32_bf16 v[36:39], v[184:187], v[136:139], v[36:39]
	ds_read_b128 v[220:223], v243 offset:55360
	s_waitcnt vmcnt(13)
	ds_write_b128 v240, v[76:79] offset:9216
	global_load_dwordx4 v[68:71], v[148:149], off offset:1024
	v_mfma_f32_16x16x32_bf16 v[40:43], v[184:187], v[140:143], v[40:43]
	ds_read_b128 v[224:227], v243 offset:57664
	s_waitcnt lgkmcnt(8)
	v_mfma_f32_16x16x32_bf16 v[20:23], v[176:179], v[152:155], v[20:23]
	ds_read_b128 v[164:167], v242 offset:39232
	v_mfma_f32_16x16x32_bf16 v[28:31], v[180:183], v[152:155], v[28:31]
	v_mfma_f32_16x16x32_bf16 v[4:7], v[184:187], v[152:155], v[4:7]
	ds_read_b128 v[228:231], v243 offset:59968
	s_waitcnt lgkmcnt(9)
	v_mfma_f32_16x16x32_bf16 v[44:47], v[216:219], v[136:139], v[44:47]
	ds_read_b128 v[168:171], v242 offset:41536
	v_mfma_f32_16x16x32_bf16 v[48:51], v[216:219], v[140:143], v[48:51]
	s_waitcnt vmcnt(13)
	ds_write_b128 v240, v[80:83] offset:13824
	global_load_dwordx4 v[72:75], v[134:135], off offset:1024
	v_mfma_f32_16x16x32_bf16 v[12:15], v[216:219], v[152:155], v[12:15]
	ds_read_b128 v[232:235], v243 offset:62272
	s_waitcnt lgkmcnt(11)
	v_mfma_f32_16x16x32_bf16 v[24:27], v[176:179], v[156:159], v[24:27]
	ds_read_b128 v[172:175], v242 offset:43840
	s_waitcnt vmcnt(13)
	ds_write_b128 v240, v[84:87] offset:18432
	global_load_dwordx4 v[76:79], v[194:195], off offset:1024
	v_mfma_f32_16x16x32_bf16 v[32:35], v[180:183], v[156:159], v[32:35]
	v_mfma_f32_16x16x32_bf16 v[8:11], v[184:187], v[156:159], v[8:11]
	v_mfma_f32_16x16x32_bf16 v[16:19], v[216:219], v[156:159], v[16:19]
	s_waitcnt lgkmcnt(9)
	v_mfma_f32_16x16x32_bf16 v[52:55], v[220:223], v[160:163], v[52:55]
	s_waitcnt lgkmcnt(7)
	v_mfma_f32_16x16x32_bf16 v[60:63], v[224:227], v[160:163], v[60:63]
	s_waitcnt lgkmcnt(6)
	v_mfma_f32_16x16x32_bf16 v[56:59], v[220:223], v[164:167], v[56:59]
	s_waitcnt vmcnt(13)
	ds_write_b128 v240, v[88:91] offset:23040
	global_load_dwordx4 v[80:83], v[196:197], off offset:1024
	v_mfma_f32_16x16x32_bf16 v[64:67], v[224:227], v[164:167], v[64:67]
	s_waitcnt lgkmcnt(6)
	v_mfma_f32_16x16x32_bf16 v[36:39], v[228:231], v[160:163], v[36:39]
	s_waitcnt vmcnt(13)
	ds_write_b128 v240, v[92:95] offset:27648
	global_load_dwordx4 v[84:87], v[150:151], off offset:1024
	v_mfma_f32_16x16x32_bf16 v[40:43], v[228:231], v[164:167], v[40:43]
	s_waitcnt lgkmcnt(6)
	v_mfma_f32_16x16x32_bf16 v[20:23], v[220:223], v[168:171], v[20:23]
	s_waitcnt vmcnt(13)
	ds_write_b128 v240, v[96:99] offset:32256
	global_load_dwordx4 v[88:91], v[214:215], off offset:1024
	v_mfma_f32_16x16x32_bf16 v[28:31], v[224:227], v[168:171], v[28:31]
	v_mfma_f32_16x16x32_bf16 v[4:7], v[228:231], v[168:171], v[4:7]
	global_load_dwordx4 v[92:95], v[236:237], off offset:1024
	s_waitcnt lgkmcnt(5)
	v_mfma_f32_16x16x32_bf16 v[44:47], v[232:235], v[160:163], v[44:47]
	v_mfma_f32_16x16x32_bf16 v[48:51], v[232:235], v[164:167], v[48:51]
	global_load_dwordx4 v[96:99], v[238:239], off offset:1024
	v_mfma_f32_16x16x32_bf16 v[12:15], v[232:235], v[168:171], v[12:15]
	s_waitcnt lgkmcnt(4)
	v_mfma_f32_16x16x32_bf16 v[24:27], v[220:223], v[172:175], v[24:27]
	v_mfma_f32_16x16x32_bf16 v[32:35], v[224:227], v[172:175], v[32:35]
	v_mfma_f32_16x16x32_bf16 v[8:11], v[228:231], v[172:175], v[8:11]
	v_mfma_f32_16x16x32_bf16 v[16:19], v[232:235], v[172:175], v[16:19]
	s_setprio 0
	s_waitcnt lgkmcnt(0)
	s_barrier
	ds_read_b128 v[136:139], v242
	ds_read_b128 v[176:179], v243 offset:18432
	ds_read_b128 v[180:183], v243 offset:20736
	ds_read_b128 v[140:143], v242 offset:2304
	ds_read_b128 v[184:187], v243 offset:23040
	ds_read_b128 v[152:155], v242 offset:4608
	ds_read_b128 v[216:219], v243 offset:25344
	ds_read_b128 v[156:159], v242 offset:6912
	s_setprio 1
	s_waitcnt lgkmcnt(6)
	v_mfma_f32_16x16x32_bf16 v[52:55], v[176:179], v[136:139], v[52:55]
	s_waitcnt vmcnt(15)
	ds_write_b128 v241, v[100:103]
	s_waitcnt lgkmcnt(6)
	v_mfma_f32_16x16x32_bf16 v[60:63], v[180:183], v[136:139], v[60:63]
	s_waitcnt lgkmcnt(5)
	v_mfma_f32_16x16x32_bf16 v[56:59], v[176:179], v[140:143], v[56:59]
	s_waitcnt vmcnt(14)
	ds_write_b128 v241, v[104:107] offset:4608
	v_mfma_f32_16x16x32_bf16 v[64:67], v[180:183], v[140:143], v[64:67]
	ds_read_b128 v[160:163], v242 offset:64
	s_waitcnt lgkmcnt(6)
	v_mfma_f32_16x16x32_bf16 v[36:39], v[184:187], v[136:139], v[36:39]
	ds_read_b128 v[220:223], v243 offset:18496
	s_waitcnt vmcnt(13)
	ds_write_b128 v241, v[108:111] offset:9216
	global_load_dwordx4 v[100:103], v[148:149], off offset:1152
	v_mfma_f32_16x16x32_bf16 v[40:43], v[184:187], v[140:143], v[40:43]
	ds_read_b128 v[224:227], v243 offset:20800
	s_waitcnt lgkmcnt(8)
	v_mfma_f32_16x16x32_bf16 v[20:23], v[176:179], v[152:155], v[20:23]
	ds_read_b128 v[164:167], v242 offset:2368
	v_mfma_f32_16x16x32_bf16 v[28:31], v[180:183], v[152:155], v[28:31]
	v_mfma_f32_16x16x32_bf16 v[4:7], v[184:187], v[152:155], v[4:7]
	ds_read_b128 v[228:231], v243 offset:23104
	s_waitcnt lgkmcnt(9)
	v_mfma_f32_16x16x32_bf16 v[44:47], v[216:219], v[136:139], v[44:47]
	ds_read_b128 v[168:171], v242 offset:4672
	v_mfma_f32_16x16x32_bf16 v[48:51], v[216:219], v[140:143], v[48:51]
	s_waitcnt vmcnt(13)
	ds_write_b128 v241, v[112:115] offset:13824
	global_load_dwordx4 v[104:107], v[134:135], off offset:1152
	v_mfma_f32_16x16x32_bf16 v[12:15], v[216:219], v[152:155], v[12:15]
	ds_read_b128 v[232:235], v243 offset:25408
	s_waitcnt lgkmcnt(11)
	v_mfma_f32_16x16x32_bf16 v[24:27], v[176:179], v[156:159], v[24:27]
	ds_read_b128 v[172:175], v242 offset:6976
	s_waitcnt vmcnt(13)
	ds_write_b128 v241, v[116:119] offset:18432
	global_load_dwordx4 v[108:111], v[194:195], off offset:1152
	v_mfma_f32_16x16x32_bf16 v[32:35], v[180:183], v[156:159], v[32:35]
	v_mfma_f32_16x16x32_bf16 v[8:11], v[184:187], v[156:159], v[8:11]
	v_mfma_f32_16x16x32_bf16 v[16:19], v[216:219], v[156:159], v[16:19]
	s_waitcnt lgkmcnt(9)
	v_mfma_f32_16x16x32_bf16 v[52:55], v[220:223], v[160:163], v[52:55]
	s_waitcnt lgkmcnt(7)
	v_mfma_f32_16x16x32_bf16 v[60:63], v[224:227], v[160:163], v[60:63]
	s_waitcnt lgkmcnt(6)
	v_mfma_f32_16x16x32_bf16 v[56:59], v[220:223], v[164:167], v[56:59]
	s_waitcnt vmcnt(13)
	ds_write_b128 v241, v[120:123] offset:23040
	global_load_dwordx4 v[112:115], v[196:197], off offset:1152
	v_mfma_f32_16x16x32_bf16 v[64:67], v[224:227], v[164:167], v[64:67]
	s_waitcnt lgkmcnt(6)
	v_mfma_f32_16x16x32_bf16 v[36:39], v[228:231], v[160:163], v[36:39]
	s_waitcnt vmcnt(13)
	ds_write_b128 v241, v[124:127] offset:27648
	global_load_dwordx4 v[116:119], v[150:151], off offset:1152
	v_mfma_f32_16x16x32_bf16 v[40:43], v[228:231], v[164:167], v[40:43]
	s_waitcnt lgkmcnt(6)
	v_mfma_f32_16x16x32_bf16 v[20:23], v[220:223], v[168:171], v[20:23]
	s_waitcnt vmcnt(13)
	ds_write_b128 v241, v[128:131] offset:32256
	global_load_dwordx4 v[120:123], v[214:215], off offset:1152
	v_mfma_f32_16x16x32_bf16 v[28:31], v[224:227], v[168:171], v[28:31]
	v_mfma_f32_16x16x32_bf16 v[4:7], v[228:231], v[168:171], v[4:7]
	global_load_dwordx4 v[124:127], v[236:237], off offset:1152
	s_waitcnt lgkmcnt(5)
	v_mfma_f32_16x16x32_bf16 v[44:47], v[232:235], v[160:163], v[44:47]
	v_mfma_f32_16x16x32_bf16 v[48:51], v[232:235], v[164:167], v[48:51]
	global_load_dwordx4 v[128:131], v[238:239], off offset:1152
	v_mfma_f32_16x16x32_bf16 v[12:15], v[232:235], v[168:171], v[12:15]
	s_waitcnt lgkmcnt(4)
	v_mfma_f32_16x16x32_bf16 v[24:27], v[220:223], v[172:175], v[24:27]
	v_mfma_f32_16x16x32_bf16 v[32:35], v[224:227], v[172:175], v[32:35]
	v_mfma_f32_16x16x32_bf16 v[8:11], v[228:231], v[172:175], v[8:11]
	v_mfma_f32_16x16x32_bf16 v[16:19], v[232:235], v[172:175], v[16:19]
	s_setprio 0
	s_waitcnt lgkmcnt(0)
	s_barrier
	ds_read_b128 v[136:139], v242 offset:36864
	ds_read_b128 v[176:179], v243 offset:55296
	ds_read_b128 v[180:183], v243 offset:57600
	ds_read_b128 v[140:143], v242 offset:39168
	ds_read_b128 v[184:187], v243 offset:59904
	ds_read_b128 v[152:155], v242 offset:41472
	ds_read_b128 v[216:219], v243 offset:62208
	ds_read_b128 v[156:159], v242 offset:43776
	s_setprio 1
	s_waitcnt lgkmcnt(6)
	v_mfma_f32_16x16x32_bf16 v[52:55], v[176:179], v[136:139], v[52:55]
	s_waitcnt vmcnt(15)
	ds_write_b128 v240, v[68:71]
	s_waitcnt lgkmcnt(6)
	v_mfma_f32_16x16x32_bf16 v[60:63], v[180:183], v[136:139], v[60:63]
	s_waitcnt lgkmcnt(5)
	v_mfma_f32_16x16x32_bf16 v[56:59], v[176:179], v[140:143], v[56:59]
	s_waitcnt vmcnt(14)
	ds_write_b128 v240, v[72:75] offset:4608
	v_mfma_f32_16x16x32_bf16 v[64:67], v[180:183], v[140:143], v[64:67]
	ds_read_b128 v[160:163], v242 offset:36928
	s_waitcnt lgkmcnt(6)
	v_mfma_f32_16x16x32_bf16 v[36:39], v[184:187], v[136:139], v[36:39]
	ds_read_b128 v[220:223], v243 offset:55360
	s_waitcnt vmcnt(13)
	ds_write_b128 v240, v[76:79] offset:9216
	global_load_dwordx4 v[68:71], v[148:149], off offset:1280
	v_mfma_f32_16x16x32_bf16 v[40:43], v[184:187], v[140:143], v[40:43]
	ds_read_b128 v[224:227], v243 offset:57664
	s_waitcnt lgkmcnt(8)
	v_mfma_f32_16x16x32_bf16 v[20:23], v[176:179], v[152:155], v[20:23]
	ds_read_b128 v[164:167], v242 offset:39232
	v_mfma_f32_16x16x32_bf16 v[28:31], v[180:183], v[152:155], v[28:31]
	v_mfma_f32_16x16x32_bf16 v[4:7], v[184:187], v[152:155], v[4:7]
	ds_read_b128 v[228:231], v243 offset:59968
	s_waitcnt lgkmcnt(9)
	v_mfma_f32_16x16x32_bf16 v[44:47], v[216:219], v[136:139], v[44:47]
	ds_read_b128 v[168:171], v242 offset:41536
	v_mfma_f32_16x16x32_bf16 v[48:51], v[216:219], v[140:143], v[48:51]
	s_waitcnt vmcnt(13)
	ds_write_b128 v240, v[80:83] offset:13824
	global_load_dwordx4 v[72:75], v[134:135], off offset:1280
	v_mfma_f32_16x16x32_bf16 v[12:15], v[216:219], v[152:155], v[12:15]
	ds_read_b128 v[232:235], v243 offset:62272
	s_waitcnt lgkmcnt(11)
	v_mfma_f32_16x16x32_bf16 v[24:27], v[176:179], v[156:159], v[24:27]
	ds_read_b128 v[172:175], v242 offset:43840
	s_waitcnt vmcnt(13)
	ds_write_b128 v240, v[84:87] offset:18432
	global_load_dwordx4 v[76:79], v[194:195], off offset:1280
	v_mfma_f32_16x16x32_bf16 v[32:35], v[180:183], v[156:159], v[32:35]
	v_mfma_f32_16x16x32_bf16 v[8:11], v[184:187], v[156:159], v[8:11]
	v_mfma_f32_16x16x32_bf16 v[16:19], v[216:219], v[156:159], v[16:19]
	s_waitcnt lgkmcnt(9)
	v_mfma_f32_16x16x32_bf16 v[52:55], v[220:223], v[160:163], v[52:55]
	s_waitcnt lgkmcnt(7)
	v_mfma_f32_16x16x32_bf16 v[60:63], v[224:227], v[160:163], v[60:63]
	s_waitcnt lgkmcnt(6)
	v_mfma_f32_16x16x32_bf16 v[56:59], v[220:223], v[164:167], v[56:59]
	s_waitcnt vmcnt(13)
	ds_write_b128 v240, v[88:91] offset:23040
	global_load_dwordx4 v[80:83], v[196:197], off offset:1280
	v_mfma_f32_16x16x32_bf16 v[64:67], v[224:227], v[164:167], v[64:67]
	s_waitcnt lgkmcnt(6)
	v_mfma_f32_16x16x32_bf16 v[36:39], v[228:231], v[160:163], v[36:39]
	s_waitcnt vmcnt(13)
	ds_write_b128 v240, v[92:95] offset:27648
	global_load_dwordx4 v[84:87], v[150:151], off offset:1280
	v_mfma_f32_16x16x32_bf16 v[40:43], v[228:231], v[164:167], v[40:43]
	s_waitcnt lgkmcnt(6)
	v_mfma_f32_16x16x32_bf16 v[20:23], v[220:223], v[168:171], v[20:23]
	s_waitcnt vmcnt(13)
	ds_write_b128 v240, v[96:99] offset:32256
	global_load_dwordx4 v[88:91], v[214:215], off offset:1280
	v_mfma_f32_16x16x32_bf16 v[28:31], v[224:227], v[168:171], v[28:31]
	v_mfma_f32_16x16x32_bf16 v[4:7], v[228:231], v[168:171], v[4:7]
	global_load_dwordx4 v[92:95], v[236:237], off offset:1280
	s_waitcnt lgkmcnt(5)
	v_mfma_f32_16x16x32_bf16 v[44:47], v[232:235], v[160:163], v[44:47]
	v_mfma_f32_16x16x32_bf16 v[48:51], v[232:235], v[164:167], v[48:51]
	global_load_dwordx4 v[96:99], v[238:239], off offset:1280
	v_mfma_f32_16x16x32_bf16 v[12:15], v[232:235], v[168:171], v[12:15]
	s_waitcnt lgkmcnt(4)
	v_mfma_f32_16x16x32_bf16 v[24:27], v[220:223], v[172:175], v[24:27]
	v_mfma_f32_16x16x32_bf16 v[32:35], v[224:227], v[172:175], v[32:35]
	v_mfma_f32_16x16x32_bf16 v[8:11], v[228:231], v[172:175], v[8:11]
	v_mfma_f32_16x16x32_bf16 v[16:19], v[232:235], v[172:175], v[16:19]
	s_setprio 0
	s_waitcnt lgkmcnt(0)
	s_barrier
	ds_read_b128 v[136:139], v242
	ds_read_b128 v[176:179], v243 offset:18432
	ds_read_b128 v[180:183], v243 offset:20736
	ds_read_b128 v[140:143], v242 offset:2304
	ds_read_b128 v[184:187], v243 offset:23040
	ds_read_b128 v[152:155], v242 offset:4608
	ds_read_b128 v[216:219], v243 offset:25344
	ds_read_b128 v[156:159], v242 offset:6912
	s_setprio 1
	s_waitcnt lgkmcnt(6)
	v_mfma_f32_16x16x32_bf16 v[52:55], v[176:179], v[136:139], v[52:55]
	s_waitcnt vmcnt(15)
	ds_write_b128 v241, v[100:103]
	s_waitcnt lgkmcnt(6)
	v_mfma_f32_16x16x32_bf16 v[60:63], v[180:183], v[136:139], v[60:63]
	s_waitcnt lgkmcnt(5)
	v_mfma_f32_16x16x32_bf16 v[56:59], v[176:179], v[140:143], v[56:59]
	s_waitcnt vmcnt(14)
	ds_write_b128 v241, v[104:107] offset:4608
	v_mfma_f32_16x16x32_bf16 v[64:67], v[180:183], v[140:143], v[64:67]
	ds_read_b128 v[160:163], v242 offset:64
	s_waitcnt lgkmcnt(6)
	v_mfma_f32_16x16x32_bf16 v[36:39], v[184:187], v[136:139], v[36:39]
	ds_read_b128 v[220:223], v243 offset:18496
	s_waitcnt vmcnt(13)
	ds_write_b128 v241, v[108:111] offset:9216
	global_load_dwordx4 v[100:103], v[148:149], off offset:1408
	v_mfma_f32_16x16x32_bf16 v[40:43], v[184:187], v[140:143], v[40:43]
	ds_read_b128 v[224:227], v243 offset:20800
	s_waitcnt lgkmcnt(8)
	v_mfma_f32_16x16x32_bf16 v[20:23], v[176:179], v[152:155], v[20:23]
	ds_read_b128 v[164:167], v242 offset:2368
	v_mfma_f32_16x16x32_bf16 v[28:31], v[180:183], v[152:155], v[28:31]
	v_mfma_f32_16x16x32_bf16 v[4:7], v[184:187], v[152:155], v[4:7]
	ds_read_b128 v[228:231], v243 offset:23104
	s_waitcnt lgkmcnt(9)
	v_mfma_f32_16x16x32_bf16 v[44:47], v[216:219], v[136:139], v[44:47]
	ds_read_b128 v[168:171], v242 offset:4672
	v_mfma_f32_16x16x32_bf16 v[48:51], v[216:219], v[140:143], v[48:51]
	s_waitcnt vmcnt(13)
	ds_write_b128 v241, v[112:115] offset:13824
	global_load_dwordx4 v[104:107], v[134:135], off offset:1408
	v_mfma_f32_16x16x32_bf16 v[12:15], v[216:219], v[152:155], v[12:15]
	ds_read_b128 v[232:235], v243 offset:25408
	s_waitcnt lgkmcnt(11)
	v_mfma_f32_16x16x32_bf16 v[24:27], v[176:179], v[156:159], v[24:27]
	ds_read_b128 v[172:175], v242 offset:6976
	s_waitcnt vmcnt(13)
	ds_write_b128 v241, v[116:119] offset:18432
	global_load_dwordx4 v[108:111], v[194:195], off offset:1408
	v_mfma_f32_16x16x32_bf16 v[32:35], v[180:183], v[156:159], v[32:35]
	v_mfma_f32_16x16x32_bf16 v[8:11], v[184:187], v[156:159], v[8:11]
	v_mfma_f32_16x16x32_bf16 v[16:19], v[216:219], v[156:159], v[16:19]
	s_waitcnt lgkmcnt(9)
	v_mfma_f32_16x16x32_bf16 v[52:55], v[220:223], v[160:163], v[52:55]
	s_waitcnt lgkmcnt(7)
	v_mfma_f32_16x16x32_bf16 v[60:63], v[224:227], v[160:163], v[60:63]
	s_waitcnt lgkmcnt(6)
	v_mfma_f32_16x16x32_bf16 v[56:59], v[220:223], v[164:167], v[56:59]
	s_waitcnt vmcnt(13)
	ds_write_b128 v241, v[120:123] offset:23040
	global_load_dwordx4 v[112:115], v[196:197], off offset:1408
	v_mfma_f32_16x16x32_bf16 v[64:67], v[224:227], v[164:167], v[64:67]
	s_waitcnt lgkmcnt(6)
	v_mfma_f32_16x16x32_bf16 v[36:39], v[228:231], v[160:163], v[36:39]
	s_waitcnt vmcnt(13)
	ds_write_b128 v241, v[124:127] offset:27648
	global_load_dwordx4 v[116:119], v[150:151], off offset:1408
	v_mfma_f32_16x16x32_bf16 v[40:43], v[228:231], v[164:167], v[40:43]
	s_waitcnt lgkmcnt(6)
	v_mfma_f32_16x16x32_bf16 v[20:23], v[220:223], v[168:171], v[20:23]
	s_waitcnt vmcnt(13)
	ds_write_b128 v241, v[128:131] offset:32256
	global_load_dwordx4 v[120:123], v[214:215], off offset:1408
	v_mfma_f32_16x16x32_bf16 v[28:31], v[224:227], v[168:171], v[28:31]
	v_mfma_f32_16x16x32_bf16 v[4:7], v[228:231], v[168:171], v[4:7]
	global_load_dwordx4 v[124:127], v[236:237], off offset:1408
	s_waitcnt lgkmcnt(5)
	v_mfma_f32_16x16x32_bf16 v[44:47], v[232:235], v[160:163], v[44:47]
	v_mfma_f32_16x16x32_bf16 v[48:51], v[232:235], v[164:167], v[48:51]
	global_load_dwordx4 v[128:131], v[238:239], off offset:1408
	v_mfma_f32_16x16x32_bf16 v[12:15], v[232:235], v[168:171], v[12:15]
	s_waitcnt lgkmcnt(4)
	v_mfma_f32_16x16x32_bf16 v[24:27], v[220:223], v[172:175], v[24:27]
	v_mfma_f32_16x16x32_bf16 v[32:35], v[224:227], v[172:175], v[32:35]
	v_mfma_f32_16x16x32_bf16 v[8:11], v[228:231], v[172:175], v[8:11]
	v_mfma_f32_16x16x32_bf16 v[16:19], v[232:235], v[172:175], v[16:19]
	s_setprio 0
	s_waitcnt lgkmcnt(0)
	s_barrier
	ds_read_b128 v[136:139], v242 offset:36864
	ds_read_b128 v[176:179], v243 offset:55296
	ds_read_b128 v[180:183], v243 offset:57600
	ds_read_b128 v[140:143], v242 offset:39168
	ds_read_b128 v[184:187], v243 offset:59904
	ds_read_b128 v[152:155], v242 offset:41472
	ds_read_b128 v[216:219], v243 offset:62208
	ds_read_b128 v[156:159], v242 offset:43776
	s_setprio 1
	s_waitcnt lgkmcnt(6)
	v_mfma_f32_16x16x32_bf16 v[52:55], v[176:179], v[136:139], v[52:55]
	s_waitcnt vmcnt(15)
	ds_write_b128 v240, v[68:71]
	s_waitcnt lgkmcnt(6)
	v_mfma_f32_16x16x32_bf16 v[60:63], v[180:183], v[136:139], v[60:63]
	s_waitcnt lgkmcnt(5)
	v_mfma_f32_16x16x32_bf16 v[56:59], v[176:179], v[140:143], v[56:59]
	s_waitcnt vmcnt(14)
	ds_write_b128 v240, v[72:75] offset:4608
	v_mfma_f32_16x16x32_bf16 v[64:67], v[180:183], v[140:143], v[64:67]
	ds_read_b128 v[160:163], v242 offset:36928
	s_waitcnt lgkmcnt(6)
	v_mfma_f32_16x16x32_bf16 v[36:39], v[184:187], v[136:139], v[36:39]
	ds_read_b128 v[220:223], v243 offset:55360
	s_waitcnt vmcnt(13)
	ds_write_b128 v240, v[76:79] offset:9216
	global_load_dwordx4 v[68:71], v[148:149], off offset:1536
	v_mfma_f32_16x16x32_bf16 v[40:43], v[184:187], v[140:143], v[40:43]
	ds_read_b128 v[224:227], v243 offset:57664
	s_waitcnt lgkmcnt(8)
	v_mfma_f32_16x16x32_bf16 v[20:23], v[176:179], v[152:155], v[20:23]
	ds_read_b128 v[164:167], v242 offset:39232
	v_mfma_f32_16x16x32_bf16 v[28:31], v[180:183], v[152:155], v[28:31]
	v_mfma_f32_16x16x32_bf16 v[4:7], v[184:187], v[152:155], v[4:7]
	ds_read_b128 v[228:231], v243 offset:59968
	s_waitcnt lgkmcnt(9)
	v_mfma_f32_16x16x32_bf16 v[44:47], v[216:219], v[136:139], v[44:47]
	ds_read_b128 v[168:171], v242 offset:41536
	v_mfma_f32_16x16x32_bf16 v[48:51], v[216:219], v[140:143], v[48:51]
	s_waitcnt vmcnt(13)
	ds_write_b128 v240, v[80:83] offset:13824
	global_load_dwordx4 v[72:75], v[134:135], off offset:1536
	v_mfma_f32_16x16x32_bf16 v[12:15], v[216:219], v[152:155], v[12:15]
	ds_read_b128 v[232:235], v243 offset:62272
	s_waitcnt lgkmcnt(11)
	v_mfma_f32_16x16x32_bf16 v[24:27], v[176:179], v[156:159], v[24:27]
	ds_read_b128 v[172:175], v242 offset:43840
	s_waitcnt vmcnt(13)
	ds_write_b128 v240, v[84:87] offset:18432
	global_load_dwordx4 v[76:79], v[194:195], off offset:1536
	v_mfma_f32_16x16x32_bf16 v[32:35], v[180:183], v[156:159], v[32:35]
	v_mfma_f32_16x16x32_bf16 v[8:11], v[184:187], v[156:159], v[8:11]
	v_mfma_f32_16x16x32_bf16 v[16:19], v[216:219], v[156:159], v[16:19]
	s_waitcnt lgkmcnt(9)
	v_mfma_f32_16x16x32_bf16 v[52:55], v[220:223], v[160:163], v[52:55]
	s_waitcnt lgkmcnt(7)
	v_mfma_f32_16x16x32_bf16 v[60:63], v[224:227], v[160:163], v[60:63]
	s_waitcnt lgkmcnt(6)
	v_mfma_f32_16x16x32_bf16 v[56:59], v[220:223], v[164:167], v[56:59]
	s_waitcnt vmcnt(13)
	ds_write_b128 v240, v[88:91] offset:23040
	global_load_dwordx4 v[80:83], v[196:197], off offset:1536
	v_mfma_f32_16x16x32_bf16 v[64:67], v[224:227], v[164:167], v[64:67]
	s_waitcnt lgkmcnt(6)
	v_mfma_f32_16x16x32_bf16 v[36:39], v[228:231], v[160:163], v[36:39]
	s_waitcnt vmcnt(13)
	ds_write_b128 v240, v[92:95] offset:27648
	global_load_dwordx4 v[84:87], v[150:151], off offset:1536
	v_mfma_f32_16x16x32_bf16 v[40:43], v[228:231], v[164:167], v[40:43]
	s_waitcnt lgkmcnt(6)
	v_mfma_f32_16x16x32_bf16 v[20:23], v[220:223], v[168:171], v[20:23]
	s_waitcnt vmcnt(13)
	ds_write_b128 v240, v[96:99] offset:32256
	global_load_dwordx4 v[88:91], v[214:215], off offset:1536
	v_mfma_f32_16x16x32_bf16 v[28:31], v[224:227], v[168:171], v[28:31]
	v_mfma_f32_16x16x32_bf16 v[4:7], v[228:231], v[168:171], v[4:7]
	global_load_dwordx4 v[92:95], v[236:237], off offset:1536
	s_waitcnt lgkmcnt(5)
	v_mfma_f32_16x16x32_bf16 v[44:47], v[232:235], v[160:163], v[44:47]
	v_mfma_f32_16x16x32_bf16 v[48:51], v[232:235], v[164:167], v[48:51]
	global_load_dwordx4 v[96:99], v[238:239], off offset:1536
	v_mfma_f32_16x16x32_bf16 v[12:15], v[232:235], v[168:171], v[12:15]
	s_waitcnt lgkmcnt(4)
	v_mfma_f32_16x16x32_bf16 v[24:27], v[220:223], v[172:175], v[24:27]
	v_mfma_f32_16x16x32_bf16 v[32:35], v[224:227], v[172:175], v[32:35]
	v_mfma_f32_16x16x32_bf16 v[8:11], v[228:231], v[172:175], v[8:11]
	v_mfma_f32_16x16x32_bf16 v[16:19], v[232:235], v[172:175], v[16:19]
	s_setprio 0
	s_waitcnt lgkmcnt(0)
	s_barrier
	ds_read_b128 v[136:139], v242
	ds_read_b128 v[176:179], v243 offset:18432
	ds_read_b128 v[180:183], v243 offset:20736
	ds_read_b128 v[140:143], v242 offset:2304
	ds_read_b128 v[184:187], v243 offset:23040
	ds_read_b128 v[152:155], v242 offset:4608
	ds_read_b128 v[216:219], v243 offset:25344
	ds_read_b128 v[156:159], v242 offset:6912
	s_setprio 1
	s_waitcnt lgkmcnt(6)
	v_mfma_f32_16x16x32_bf16 v[52:55], v[176:179], v[136:139], v[52:55]
	s_waitcnt vmcnt(15)
	ds_write_b128 v241, v[100:103]
	s_waitcnt lgkmcnt(6)
	v_mfma_f32_16x16x32_bf16 v[60:63], v[180:183], v[136:139], v[60:63]
	s_waitcnt lgkmcnt(5)
	v_mfma_f32_16x16x32_bf16 v[56:59], v[176:179], v[140:143], v[56:59]
	s_waitcnt vmcnt(14)
	ds_write_b128 v241, v[104:107] offset:4608
	v_mfma_f32_16x16x32_bf16 v[64:67], v[180:183], v[140:143], v[64:67]
	ds_read_b128 v[160:163], v242 offset:64
	s_waitcnt lgkmcnt(6)
	v_mfma_f32_16x16x32_bf16 v[36:39], v[184:187], v[136:139], v[36:39]
	ds_read_b128 v[220:223], v243 offset:18496
	s_waitcnt vmcnt(13)
	ds_write_b128 v241, v[108:111] offset:9216
	global_load_dwordx4 v[100:103], v[148:149], off offset:1664
	v_mfma_f32_16x16x32_bf16 v[40:43], v[184:187], v[140:143], v[40:43]
	ds_read_b128 v[224:227], v243 offset:20800
	s_waitcnt lgkmcnt(8)
	v_mfma_f32_16x16x32_bf16 v[20:23], v[176:179], v[152:155], v[20:23]
	ds_read_b128 v[164:167], v242 offset:2368
	v_mfma_f32_16x16x32_bf16 v[28:31], v[180:183], v[152:155], v[28:31]
	v_mfma_f32_16x16x32_bf16 v[4:7], v[184:187], v[152:155], v[4:7]
	ds_read_b128 v[228:231], v243 offset:23104
	s_waitcnt lgkmcnt(9)
	v_mfma_f32_16x16x32_bf16 v[44:47], v[216:219], v[136:139], v[44:47]
	ds_read_b128 v[168:171], v242 offset:4672
	v_mfma_f32_16x16x32_bf16 v[48:51], v[216:219], v[140:143], v[48:51]
	s_waitcnt vmcnt(13)
	ds_write_b128 v241, v[112:115] offset:13824
	global_load_dwordx4 v[104:107], v[134:135], off offset:1664
	v_mfma_f32_16x16x32_bf16 v[12:15], v[216:219], v[152:155], v[12:15]
	ds_read_b128 v[232:235], v243 offset:25408
	s_waitcnt lgkmcnt(11)
	v_mfma_f32_16x16x32_bf16 v[24:27], v[176:179], v[156:159], v[24:27]
	ds_read_b128 v[172:175], v242 offset:6976
	s_waitcnt vmcnt(13)
	ds_write_b128 v241, v[116:119] offset:18432
	global_load_dwordx4 v[108:111], v[194:195], off offset:1664
	v_mfma_f32_16x16x32_bf16 v[32:35], v[180:183], v[156:159], v[32:35]
	v_mfma_f32_16x16x32_bf16 v[8:11], v[184:187], v[156:159], v[8:11]
	v_mfma_f32_16x16x32_bf16 v[16:19], v[216:219], v[156:159], v[16:19]
	s_waitcnt lgkmcnt(9)
	v_mfma_f32_16x16x32_bf16 v[52:55], v[220:223], v[160:163], v[52:55]
	s_waitcnt lgkmcnt(7)
	v_mfma_f32_16x16x32_bf16 v[60:63], v[224:227], v[160:163], v[60:63]
	s_waitcnt lgkmcnt(6)
	v_mfma_f32_16x16x32_bf16 v[56:59], v[220:223], v[164:167], v[56:59]
	s_waitcnt vmcnt(13)
	ds_write_b128 v241, v[120:123] offset:23040
	global_load_dwordx4 v[112:115], v[196:197], off offset:1664
	v_mfma_f32_16x16x32_bf16 v[64:67], v[224:227], v[164:167], v[64:67]
	s_waitcnt lgkmcnt(6)
	v_mfma_f32_16x16x32_bf16 v[36:39], v[228:231], v[160:163], v[36:39]
	s_waitcnt vmcnt(13)
	ds_write_b128 v241, v[124:127] offset:27648
	global_load_dwordx4 v[116:119], v[150:151], off offset:1664
	v_mfma_f32_16x16x32_bf16 v[40:43], v[228:231], v[164:167], v[40:43]
	s_waitcnt lgkmcnt(6)
	v_mfma_f32_16x16x32_bf16 v[20:23], v[220:223], v[168:171], v[20:23]
	s_waitcnt vmcnt(13)
	ds_write_b128 v241, v[128:131] offset:32256
	global_load_dwordx4 v[120:123], v[214:215], off offset:1664
	v_mfma_f32_16x16x32_bf16 v[28:31], v[224:227], v[168:171], v[28:31]
	v_mfma_f32_16x16x32_bf16 v[4:7], v[228:231], v[168:171], v[4:7]
	global_load_dwordx4 v[124:127], v[236:237], off offset:1664
	s_waitcnt lgkmcnt(5)
	v_mfma_f32_16x16x32_bf16 v[44:47], v[232:235], v[160:163], v[44:47]
	v_mfma_f32_16x16x32_bf16 v[48:51], v[232:235], v[164:167], v[48:51]
	global_load_dwordx4 v[128:131], v[238:239], off offset:1664
	v_mfma_f32_16x16x32_bf16 v[12:15], v[232:235], v[168:171], v[12:15]
	s_waitcnt lgkmcnt(4)
	v_mfma_f32_16x16x32_bf16 v[24:27], v[220:223], v[172:175], v[24:27]
	v_mfma_f32_16x16x32_bf16 v[32:35], v[224:227], v[172:175], v[32:35]
	v_mfma_f32_16x16x32_bf16 v[8:11], v[228:231], v[172:175], v[8:11]
	v_mfma_f32_16x16x32_bf16 v[16:19], v[232:235], v[172:175], v[16:19]
	s_setprio 0
	s_waitcnt lgkmcnt(0)
	s_barrier
	ds_read_b128 v[136:139], v242 offset:36864
	ds_read_b128 v[176:179], v243 offset:55296
	ds_read_b128 v[180:183], v243 offset:57600
	ds_read_b128 v[140:143], v242 offset:39168
	ds_read_b128 v[184:187], v243 offset:59904
	ds_read_b128 v[152:155], v242 offset:41472
	ds_read_b128 v[216:219], v243 offset:62208
	ds_read_b128 v[156:159], v242 offset:43776
	s_setprio 1
	s_waitcnt lgkmcnt(6)
	v_mfma_f32_16x16x32_bf16 v[52:55], v[176:179], v[136:139], v[52:55]
	s_waitcnt vmcnt(15)
	ds_write_b128 v240, v[68:71]
	s_waitcnt lgkmcnt(6)
	v_mfma_f32_16x16x32_bf16 v[60:63], v[180:183], v[136:139], v[60:63]
	s_waitcnt lgkmcnt(5)
	v_mfma_f32_16x16x32_bf16 v[56:59], v[176:179], v[140:143], v[56:59]
	s_waitcnt vmcnt(14)
	ds_write_b128 v240, v[72:75] offset:4608
	v_mfma_f32_16x16x32_bf16 v[64:67], v[180:183], v[140:143], v[64:67]
	ds_read_b128 v[160:163], v242 offset:36928
	s_waitcnt lgkmcnt(6)
	v_mfma_f32_16x16x32_bf16 v[36:39], v[184:187], v[136:139], v[36:39]
	ds_read_b128 v[220:223], v243 offset:55360
	s_waitcnt vmcnt(13)
	ds_write_b128 v240, v[76:79] offset:9216
	global_load_dwordx4 v[68:71], v[148:149], off offset:1792
	v_mfma_f32_16x16x32_bf16 v[40:43], v[184:187], v[140:143], v[40:43]
	ds_read_b128 v[224:227], v243 offset:57664
	s_waitcnt lgkmcnt(8)
	v_mfma_f32_16x16x32_bf16 v[20:23], v[176:179], v[152:155], v[20:23]
	ds_read_b128 v[164:167], v242 offset:39232
	v_mfma_f32_16x16x32_bf16 v[28:31], v[180:183], v[152:155], v[28:31]
	v_mfma_f32_16x16x32_bf16 v[4:7], v[184:187], v[152:155], v[4:7]
	ds_read_b128 v[228:231], v243 offset:59968
	s_waitcnt lgkmcnt(9)
	v_mfma_f32_16x16x32_bf16 v[44:47], v[216:219], v[136:139], v[44:47]
	ds_read_b128 v[168:171], v242 offset:41536
	v_mfma_f32_16x16x32_bf16 v[48:51], v[216:219], v[140:143], v[48:51]
	s_waitcnt vmcnt(13)
	ds_write_b128 v240, v[80:83] offset:13824
	global_load_dwordx4 v[72:75], v[134:135], off offset:1792
	v_mfma_f32_16x16x32_bf16 v[12:15], v[216:219], v[152:155], v[12:15]
	ds_read_b128 v[232:235], v243 offset:62272
	s_waitcnt lgkmcnt(11)
	v_mfma_f32_16x16x32_bf16 v[24:27], v[176:179], v[156:159], v[24:27]
	ds_read_b128 v[172:175], v242 offset:43840
	s_waitcnt vmcnt(13)
	ds_write_b128 v240, v[84:87] offset:18432
	global_load_dwordx4 v[76:79], v[194:195], off offset:1792
	v_mfma_f32_16x16x32_bf16 v[32:35], v[180:183], v[156:159], v[32:35]
	v_mfma_f32_16x16x32_bf16 v[8:11], v[184:187], v[156:159], v[8:11]
	v_mfma_f32_16x16x32_bf16 v[16:19], v[216:219], v[156:159], v[16:19]
	s_waitcnt lgkmcnt(9)
	v_mfma_f32_16x16x32_bf16 v[52:55], v[220:223], v[160:163], v[52:55]
	s_waitcnt lgkmcnt(7)
	v_mfma_f32_16x16x32_bf16 v[60:63], v[224:227], v[160:163], v[60:63]
	s_waitcnt lgkmcnt(6)
	v_mfma_f32_16x16x32_bf16 v[56:59], v[220:223], v[164:167], v[56:59]
	s_waitcnt vmcnt(13)
	ds_write_b128 v240, v[88:91] offset:23040
	global_load_dwordx4 v[80:83], v[196:197], off offset:1792
	v_mfma_f32_16x16x32_bf16 v[64:67], v[224:227], v[164:167], v[64:67]
	s_waitcnt lgkmcnt(6)
	v_mfma_f32_16x16x32_bf16 v[36:39], v[228:231], v[160:163], v[36:39]
	s_waitcnt vmcnt(13)
	ds_write_b128 v240, v[92:95] offset:27648
	global_load_dwordx4 v[84:87], v[150:151], off offset:1792
	v_mfma_f32_16x16x32_bf16 v[40:43], v[228:231], v[164:167], v[40:43]
	s_waitcnt lgkmcnt(6)
	v_mfma_f32_16x16x32_bf16 v[20:23], v[220:223], v[168:171], v[20:23]
	s_waitcnt vmcnt(13)
	ds_write_b128 v240, v[96:99] offset:32256
	global_load_dwordx4 v[88:91], v[214:215], off offset:1792
	v_mfma_f32_16x16x32_bf16 v[28:31], v[224:227], v[168:171], v[28:31]
	v_mfma_f32_16x16x32_bf16 v[4:7], v[228:231], v[168:171], v[4:7]
	global_load_dwordx4 v[92:95], v[236:237], off offset:1792
	s_waitcnt lgkmcnt(5)
	v_mfma_f32_16x16x32_bf16 v[44:47], v[232:235], v[160:163], v[44:47]
	v_mfma_f32_16x16x32_bf16 v[48:51], v[232:235], v[164:167], v[48:51]
	global_load_dwordx4 v[96:99], v[238:239], off offset:1792
	v_mfma_f32_16x16x32_bf16 v[12:15], v[232:235], v[168:171], v[12:15]
	s_waitcnt lgkmcnt(4)
	v_mfma_f32_16x16x32_bf16 v[24:27], v[220:223], v[172:175], v[24:27]
	v_mfma_f32_16x16x32_bf16 v[32:35], v[224:227], v[172:175], v[32:35]
	v_mfma_f32_16x16x32_bf16 v[8:11], v[228:231], v[172:175], v[8:11]
	v_mfma_f32_16x16x32_bf16 v[16:19], v[232:235], v[172:175], v[16:19]
	s_setprio 0
	s_waitcnt lgkmcnt(0)
	s_barrier
	ds_read_b128 v[136:139], v242
	ds_read_b128 v[176:179], v243 offset:18432
	ds_read_b128 v[180:183], v243 offset:20736
	ds_read_b128 v[140:143], v242 offset:2304
	ds_read_b128 v[184:187], v243 offset:23040
	ds_read_b128 v[152:155], v242 offset:4608
	ds_read_b128 v[216:219], v243 offset:25344
	ds_read_b128 v[156:159], v242 offset:6912
	s_setprio 1
	s_waitcnt lgkmcnt(6)
	v_mfma_f32_16x16x32_bf16 v[52:55], v[176:179], v[136:139], v[52:55]
	s_waitcnt vmcnt(15)
	ds_write_b128 v241, v[100:103]
	s_waitcnt lgkmcnt(6)
	v_mfma_f32_16x16x32_bf16 v[60:63], v[180:183], v[136:139], v[60:63]
	s_waitcnt lgkmcnt(5)
	v_mfma_f32_16x16x32_bf16 v[56:59], v[176:179], v[140:143], v[56:59]
	s_waitcnt vmcnt(14)
	ds_write_b128 v241, v[104:107] offset:4608
	v_mfma_f32_16x16x32_bf16 v[64:67], v[180:183], v[140:143], v[64:67]
	ds_read_b128 v[160:163], v242 offset:64
	s_waitcnt lgkmcnt(6)
	v_mfma_f32_16x16x32_bf16 v[36:39], v[184:187], v[136:139], v[36:39]
	ds_read_b128 v[220:223], v243 offset:18496
	s_waitcnt vmcnt(13)
	ds_write_b128 v241, v[108:111] offset:9216
	global_load_dwordx4 v[100:103], v[148:149], off offset:1920
	v_mfma_f32_16x16x32_bf16 v[40:43], v[184:187], v[140:143], v[40:43]
	ds_read_b128 v[224:227], v243 offset:20800
	s_waitcnt lgkmcnt(8)
	v_mfma_f32_16x16x32_bf16 v[20:23], v[176:179], v[152:155], v[20:23]
	ds_read_b128 v[164:167], v242 offset:2368
	v_mfma_f32_16x16x32_bf16 v[28:31], v[180:183], v[152:155], v[28:31]
	v_mfma_f32_16x16x32_bf16 v[4:7], v[184:187], v[152:155], v[4:7]
	ds_read_b128 v[228:231], v243 offset:23104
	s_waitcnt lgkmcnt(9)
	v_mfma_f32_16x16x32_bf16 v[44:47], v[216:219], v[136:139], v[44:47]
	ds_read_b128 v[168:171], v242 offset:4672
	v_mfma_f32_16x16x32_bf16 v[48:51], v[216:219], v[140:143], v[48:51]
	s_waitcnt vmcnt(13)
	ds_write_b128 v241, v[112:115] offset:13824
	global_load_dwordx4 v[104:107], v[134:135], off offset:1920
	v_mfma_f32_16x16x32_bf16 v[12:15], v[216:219], v[152:155], v[12:15]
	ds_read_b128 v[232:235], v243 offset:25408
	s_waitcnt lgkmcnt(11)
	v_mfma_f32_16x16x32_bf16 v[24:27], v[176:179], v[156:159], v[24:27]
	ds_read_b128 v[172:175], v242 offset:6976
	s_waitcnt vmcnt(13)
	ds_write_b128 v241, v[116:119] offset:18432
	global_load_dwordx4 v[108:111], v[194:195], off offset:1920
	v_mfma_f32_16x16x32_bf16 v[32:35], v[180:183], v[156:159], v[32:35]
	v_mfma_f32_16x16x32_bf16 v[8:11], v[184:187], v[156:159], v[8:11]
	v_mfma_f32_16x16x32_bf16 v[16:19], v[216:219], v[156:159], v[16:19]
	s_waitcnt lgkmcnt(9)
	v_mfma_f32_16x16x32_bf16 v[52:55], v[220:223], v[160:163], v[52:55]
	s_waitcnt lgkmcnt(7)
	v_mfma_f32_16x16x32_bf16 v[60:63], v[224:227], v[160:163], v[60:63]
	s_waitcnt lgkmcnt(6)
	v_mfma_f32_16x16x32_bf16 v[56:59], v[220:223], v[164:167], v[56:59]
	s_waitcnt vmcnt(13)
	ds_write_b128 v241, v[120:123] offset:23040
	global_load_dwordx4 v[112:115], v[196:197], off offset:1920
	v_mfma_f32_16x16x32_bf16 v[64:67], v[224:227], v[164:167], v[64:67]
	s_waitcnt lgkmcnt(6)
	v_mfma_f32_16x16x32_bf16 v[36:39], v[228:231], v[160:163], v[36:39]
	s_waitcnt vmcnt(13)
	ds_write_b128 v241, v[124:127] offset:27648
	global_load_dwordx4 v[116:119], v[150:151], off offset:1920
	v_mfma_f32_16x16x32_bf16 v[40:43], v[228:231], v[164:167], v[40:43]
	s_waitcnt lgkmcnt(6)
	v_mfma_f32_16x16x32_bf16 v[20:23], v[220:223], v[168:171], v[20:23]
	s_waitcnt vmcnt(13)
	ds_write_b128 v241, v[128:131] offset:32256
	global_load_dwordx4 v[120:123], v[214:215], off offset:1920
	v_mfma_f32_16x16x32_bf16 v[28:31], v[224:227], v[168:171], v[28:31]
	v_mfma_f32_16x16x32_bf16 v[4:7], v[228:231], v[168:171], v[4:7]
	global_load_dwordx4 v[124:127], v[236:237], off offset:1920
	s_waitcnt lgkmcnt(5)
	v_mfma_f32_16x16x32_bf16 v[44:47], v[232:235], v[160:163], v[44:47]
	v_mfma_f32_16x16x32_bf16 v[48:51], v[232:235], v[164:167], v[48:51]
	global_load_dwordx4 v[128:131], v[238:239], off offset:1920
	v_mfma_f32_16x16x32_bf16 v[12:15], v[232:235], v[168:171], v[12:15]
	s_waitcnt lgkmcnt(4)
	v_mfma_f32_16x16x32_bf16 v[24:27], v[220:223], v[172:175], v[24:27]
	v_mfma_f32_16x16x32_bf16 v[32:35], v[224:227], v[172:175], v[32:35]
	v_mfma_f32_16x16x32_bf16 v[8:11], v[228:231], v[172:175], v[8:11]
	v_mfma_f32_16x16x32_bf16 v[16:19], v[232:235], v[172:175], v[16:19]
	s_setprio 0
	s_waitcnt lgkmcnt(0)
	s_barrier
	ds_read_b128 v[136:139], v242 offset:36864
	ds_read_b128 v[176:179], v243 offset:55296
	ds_read_b128 v[180:183], v243 offset:57600
	ds_read_b128 v[140:143], v242 offset:39168
	ds_read_b128 v[184:187], v243 offset:59904
	ds_read_b128 v[152:155], v242 offset:41472
	ds_read_b128 v[216:219], v243 offset:62208
	ds_read_b128 v[156:159], v242 offset:43776
	s_setprio 1
	s_waitcnt lgkmcnt(6)
	v_mfma_f32_16x16x32_bf16 v[52:55], v[176:179], v[136:139], v[52:55]
	s_waitcnt vmcnt(15)
	ds_write_b128 v240, v[68:71]
	s_waitcnt lgkmcnt(6)
	v_mfma_f32_16x16x32_bf16 v[60:63], v[180:183], v[136:139], v[60:63]
	s_waitcnt lgkmcnt(5)
	v_mfma_f32_16x16x32_bf16 v[56:59], v[176:179], v[140:143], v[56:59]
	s_waitcnt vmcnt(14)
	ds_write_b128 v240, v[72:75] offset:4608
	v_mfma_f32_16x16x32_bf16 v[64:67], v[180:183], v[140:143], v[64:67]
	ds_read_b128 v[160:163], v242 offset:36928
	s_waitcnt lgkmcnt(6)
	v_mfma_f32_16x16x32_bf16 v[36:39], v[184:187], v[136:139], v[36:39]
	ds_read_b128 v[220:223], v243 offset:55360
	s_waitcnt vmcnt(13)
	ds_write_b128 v240, v[76:79] offset:9216
	v_mfma_f32_16x16x32_bf16 v[40:43], v[184:187], v[140:143], v[40:43]
	ds_read_b128 v[224:227], v243 offset:57664
	s_waitcnt lgkmcnt(8)
	v_mfma_f32_16x16x32_bf16 v[20:23], v[176:179], v[152:155], v[20:23]
	ds_read_b128 v[164:167], v242 offset:39232
	v_mfma_f32_16x16x32_bf16 v[28:31], v[180:183], v[152:155], v[28:31]
	v_mfma_f32_16x16x32_bf16 v[4:7], v[184:187], v[152:155], v[4:7]
	ds_read_b128 v[228:231], v243 offset:59968
	s_waitcnt lgkmcnt(9)
	v_mfma_f32_16x16x32_bf16 v[44:47], v[216:219], v[136:139], v[44:47]
	ds_read_b128 v[168:171], v242 offset:41536
	v_mfma_f32_16x16x32_bf16 v[48:51], v[216:219], v[140:143], v[48:51]
	s_waitcnt vmcnt(12)
	ds_write_b128 v240, v[80:83] offset:13824
	v_mfma_f32_16x16x32_bf16 v[12:15], v[216:219], v[152:155], v[12:15]
	ds_read_b128 v[232:235], v243 offset:62272
	s_waitcnt lgkmcnt(11)
	v_mfma_f32_16x16x32_bf16 v[24:27], v[176:179], v[156:159], v[24:27]
	ds_read_b128 v[172:175], v242 offset:43840
	s_waitcnt vmcnt(11)
	ds_write_b128 v240, v[84:87] offset:18432
	v_mfma_f32_16x16x32_bf16 v[32:35], v[180:183], v[156:159], v[32:35]
	v_mfma_f32_16x16x32_bf16 v[8:11], v[184:187], v[156:159], v[8:11]
	v_mfma_f32_16x16x32_bf16 v[16:19], v[216:219], v[156:159], v[16:19]
	s_waitcnt lgkmcnt(9)
	v_mfma_f32_16x16x32_bf16 v[52:55], v[220:223], v[160:163], v[52:55]
	s_waitcnt lgkmcnt(7)
	v_mfma_f32_16x16x32_bf16 v[60:63], v[224:227], v[160:163], v[60:63]
	s_waitcnt lgkmcnt(6)
	v_mfma_f32_16x16x32_bf16 v[56:59], v[220:223], v[164:167], v[56:59]
	s_waitcnt vmcnt(10)
	ds_write_b128 v240, v[88:91] offset:23040
	v_mfma_f32_16x16x32_bf16 v[64:67], v[224:227], v[164:167], v[64:67]
	s_waitcnt lgkmcnt(6)
	v_mfma_f32_16x16x32_bf16 v[36:39], v[228:231], v[160:163], v[36:39]
	s_waitcnt vmcnt(9)
	ds_write_b128 v240, v[92:95] offset:27648
	v_mfma_f32_16x16x32_bf16 v[40:43], v[228:231], v[164:167], v[40:43]
	s_waitcnt lgkmcnt(6)
	v_mfma_f32_16x16x32_bf16 v[20:23], v[220:223], v[168:171], v[20:23]
	s_waitcnt vmcnt(8)
	ds_write_b128 v240, v[96:99] offset:32256
	v_mfma_f32_16x16x32_bf16 v[28:31], v[224:227], v[168:171], v[28:31]
	v_mfma_f32_16x16x32_bf16 v[4:7], v[228:231], v[168:171], v[4:7]
	s_waitcnt lgkmcnt(5)
	v_mfma_f32_16x16x32_bf16 v[44:47], v[232:235], v[160:163], v[44:47]
	v_mfma_f32_16x16x32_bf16 v[48:51], v[232:235], v[164:167], v[48:51]
	v_mfma_f32_16x16x32_bf16 v[12:15], v[232:235], v[168:171], v[12:15]
	s_waitcnt lgkmcnt(4)
	v_mfma_f32_16x16x32_bf16 v[24:27], v[220:223], v[172:175], v[24:27]
	v_mfma_f32_16x16x32_bf16 v[32:35], v[224:227], v[172:175], v[32:35]
	v_mfma_f32_16x16x32_bf16 v[8:11], v[228:231], v[172:175], v[8:11]
	v_mfma_f32_16x16x32_bf16 v[16:19], v[232:235], v[172:175], v[16:19]
	s_setprio 0
	s_waitcnt lgkmcnt(0)
	s_barrier
	ds_read_b128 v[136:139], v242
	ds_read_b128 v[176:179], v243 offset:18432
	ds_read_b128 v[180:183], v243 offset:20736
	ds_read_b128 v[140:143], v242 offset:2304
	ds_read_b128 v[184:187], v243 offset:23040
	ds_read_b128 v[152:155], v242 offset:4608
	ds_read_b128 v[216:219], v243 offset:25344
	ds_read_b128 v[156:159], v242 offset:6912
	s_setprio 1
	s_waitcnt lgkmcnt(6)
	v_mfma_f32_16x16x32_bf16 v[52:55], v[176:179], v[136:139], v[52:55]
	s_waitcnt vmcnt(7)
	ds_write_b128 v241, v[100:103]
	s_waitcnt lgkmcnt(6)
	v_mfma_f32_16x16x32_bf16 v[60:63], v[180:183], v[136:139], v[60:63]
	s_waitcnt lgkmcnt(5)
	v_mfma_f32_16x16x32_bf16 v[56:59], v[176:179], v[140:143], v[56:59]
	s_waitcnt vmcnt(6)
	ds_write_b128 v241, v[104:107] offset:4608
	v_mfma_f32_16x16x32_bf16 v[64:67], v[180:183], v[140:143], v[64:67]
	ds_read_b128 v[160:163], v242 offset:64
	s_waitcnt lgkmcnt(6)
	v_mfma_f32_16x16x32_bf16 v[36:39], v[184:187], v[136:139], v[36:39]
	ds_read_b128 v[220:223], v243 offset:18496
	s_waitcnt vmcnt(5)
	ds_write_b128 v241, v[108:111] offset:9216
	v_mfma_f32_16x16x32_bf16 v[40:43], v[184:187], v[140:143], v[40:43]
	ds_read_b128 v[224:227], v243 offset:20800
	s_waitcnt lgkmcnt(8)
	v_mfma_f32_16x16x32_bf16 v[20:23], v[176:179], v[152:155], v[20:23]
	ds_read_b128 v[164:167], v242 offset:2368
	v_mfma_f32_16x16x32_bf16 v[28:31], v[180:183], v[152:155], v[28:31]
	v_mfma_f32_16x16x32_bf16 v[4:7], v[184:187], v[152:155], v[4:7]
	ds_read_b128 v[228:231], v243 offset:23104
	s_waitcnt lgkmcnt(9)
	v_mfma_f32_16x16x32_bf16 v[44:47], v[216:219], v[136:139], v[44:47]
	ds_read_b128 v[168:171], v242 offset:4672
	v_mfma_f32_16x16x32_bf16 v[48:51], v[216:219], v[140:143], v[48:51]
	s_waitcnt vmcnt(4)
	ds_write_b128 v241, v[112:115] offset:13824
	v_mfma_f32_16x16x32_bf16 v[12:15], v[216:219], v[152:155], v[12:15]
	ds_read_b128 v[232:235], v243 offset:25408
	s_waitcnt lgkmcnt(11)
	v_mfma_f32_16x16x32_bf16 v[24:27], v[176:179], v[156:159], v[24:27]
	ds_read_b128 v[172:175], v242 offset:6976
	s_waitcnt vmcnt(3)
	ds_write_b128 v241, v[116:119] offset:18432
	v_mfma_f32_16x16x32_bf16 v[32:35], v[180:183], v[156:159], v[32:35]
	v_mfma_f32_16x16x32_bf16 v[8:11], v[184:187], v[156:159], v[8:11]
	v_mfma_f32_16x16x32_bf16 v[16:19], v[216:219], v[156:159], v[16:19]
	s_waitcnt lgkmcnt(9)
	v_mfma_f32_16x16x32_bf16 v[52:55], v[220:223], v[160:163], v[52:55]
	s_waitcnt lgkmcnt(7)
	v_mfma_f32_16x16x32_bf16 v[60:63], v[224:227], v[160:163], v[60:63]
	s_waitcnt lgkmcnt(6)
	v_mfma_f32_16x16x32_bf16 v[56:59], v[220:223], v[164:167], v[56:59]
	s_waitcnt vmcnt(2)
	ds_write_b128 v241, v[120:123] offset:23040
	v_mfma_f32_16x16x32_bf16 v[64:67], v[224:227], v[164:167], v[64:67]
	s_waitcnt lgkmcnt(6)
	v_mfma_f32_16x16x32_bf16 v[36:39], v[228:231], v[160:163], v[36:39]
	s_waitcnt vmcnt(1)
	ds_write_b128 v241, v[124:127] offset:27648
	v_mfma_f32_16x16x32_bf16 v[40:43], v[228:231], v[164:167], v[40:43]
	s_waitcnt lgkmcnt(6)
	v_mfma_f32_16x16x32_bf16 v[20:23], v[220:223], v[168:171], v[20:23]
	s_waitcnt vmcnt(0)
	ds_write_b128 v241, v[128:131] offset:32256
	v_mfma_f32_16x16x32_bf16 v[28:31], v[224:227], v[168:171], v[28:31]
	v_mfma_f32_16x16x32_bf16 v[4:7], v[228:231], v[168:171], v[4:7]
	s_waitcnt lgkmcnt(5)
	v_mfma_f32_16x16x32_bf16 v[44:47], v[232:235], v[160:163], v[44:47]
	v_mfma_f32_16x16x32_bf16 v[48:51], v[232:235], v[164:167], v[48:51]
	v_mfma_f32_16x16x32_bf16 v[12:15], v[232:235], v[168:171], v[12:15]
	s_waitcnt lgkmcnt(4)
	v_mfma_f32_16x16x32_bf16 v[24:27], v[220:223], v[172:175], v[24:27]
	v_mfma_f32_16x16x32_bf16 v[32:35], v[224:227], v[172:175], v[32:35]
	v_mfma_f32_16x16x32_bf16 v[8:11], v[228:231], v[172:175], v[8:11]
	v_mfma_f32_16x16x32_bf16 v[16:19], v[232:235], v[172:175], v[16:19]
	s_setprio 0
	s_waitcnt lgkmcnt(0)
	s_barrier
	ds_read_b128 v[136:139], v242 offset:36864
	ds_read_b128 v[176:179], v243 offset:55296
	ds_read_b128 v[180:183], v243 offset:57600
	ds_read_b128 v[140:143], v242 offset:39168
	ds_read_b128 v[184:187], v243 offset:59904
	ds_read_b128 v[152:155], v242 offset:41472
	ds_read_b128 v[216:219], v243 offset:62208
	ds_read_b128 v[156:159], v242 offset:43776
	s_setprio 1
	s_waitcnt lgkmcnt(6)
	v_mfma_f32_16x16x32_bf16 v[52:55], v[176:179], v[136:139], v[52:55]
	s_waitcnt lgkmcnt(5)
	v_mfma_f32_16x16x32_bf16 v[60:63], v[180:183], v[136:139], v[60:63]
	s_waitcnt lgkmcnt(4)
	v_mfma_f32_16x16x32_bf16 v[56:59], v[176:179], v[140:143], v[56:59]
	v_mfma_f32_16x16x32_bf16 v[64:67], v[180:183], v[140:143], v[64:67]
	ds_read_b128 v[160:163], v242 offset:36928
	s_waitcnt lgkmcnt(4)
	v_mfma_f32_16x16x32_bf16 v[36:39], v[184:187], v[136:139], v[36:39]
	ds_read_b128 v[220:223], v243 offset:55360
	v_mfma_f32_16x16x32_bf16 v[40:43], v[184:187], v[140:143], v[40:43]
	ds_read_b128 v[224:227], v243 offset:57664
	s_waitcnt lgkmcnt(5)
	v_mfma_f32_16x16x32_bf16 v[20:23], v[176:179], v[152:155], v[20:23]
	ds_read_b128 v[164:167], v242 offset:39232
	v_mfma_f32_16x16x32_bf16 v[28:31], v[180:183], v[152:155], v[28:31]
	v_mfma_f32_16x16x32_bf16 v[4:7], v[184:187], v[152:155], v[4:7]
	ds_read_b128 v[228:231], v243 offset:59968
	s_waitcnt lgkmcnt(6)
	v_mfma_f32_16x16x32_bf16 v[44:47], v[216:219], v[136:139], v[44:47]
	ds_read_b128 v[168:171], v242 offset:41536
	v_mfma_f32_16x16x32_bf16 v[48:51], v[216:219], v[140:143], v[48:51]
	v_mfma_f32_16x16x32_bf16 v[12:15], v[216:219], v[152:155], v[12:15]
	ds_read_b128 v[232:235], v243 offset:62272
	s_waitcnt lgkmcnt(7)
	v_mfma_f32_16x16x32_bf16 v[24:27], v[176:179], v[156:159], v[24:27]
	ds_read_b128 v[172:175], v242 offset:43840
	v_mfma_f32_16x16x32_bf16 v[32:35], v[180:183], v[156:159], v[32:35]
	v_mfma_f32_16x16x32_bf16 v[8:11], v[184:187], v[156:159], v[8:11]
	v_mfma_f32_16x16x32_bf16 v[16:19], v[216:219], v[156:159], v[16:19]
	s_waitcnt lgkmcnt(6)
	v_mfma_f32_16x16x32_bf16 v[52:55], v[220:223], v[160:163], v[52:55]
	s_waitcnt lgkmcnt(5)
	v_mfma_f32_16x16x32_bf16 v[60:63], v[224:227], v[160:163], v[60:63]
	s_waitcnt lgkmcnt(4)
	v_mfma_f32_16x16x32_bf16 v[56:59], v[220:223], v[164:167], v[56:59]
	v_mfma_f32_16x16x32_bf16 v[64:67], v[224:227], v[164:167], v[64:67]
	s_waitcnt lgkmcnt(3)
	v_mfma_f32_16x16x32_bf16 v[36:39], v[228:231], v[160:163], v[36:39]
	v_mfma_f32_16x16x32_bf16 v[40:43], v[228:231], v[164:167], v[40:43]
	s_waitcnt lgkmcnt(2)
	v_mfma_f32_16x16x32_bf16 v[20:23], v[220:223], v[168:171], v[20:23]
	v_mfma_f32_16x16x32_bf16 v[28:31], v[224:227], v[168:171], v[28:31]
	v_mfma_f32_16x16x32_bf16 v[4:7], v[228:231], v[168:171], v[4:7]
	s_waitcnt lgkmcnt(1)
	v_mfma_f32_16x16x32_bf16 v[44:47], v[232:235], v[160:163], v[44:47]
	v_mfma_f32_16x16x32_bf16 v[48:51], v[232:235], v[164:167], v[48:51]
	v_mfma_f32_16x16x32_bf16 v[12:15], v[232:235], v[168:171], v[12:15]
	s_waitcnt lgkmcnt(0)
	v_mfma_f32_16x16x32_bf16 v[24:27], v[220:223], v[172:175], v[24:27]
	v_mfma_f32_16x16x32_bf16 v[32:35], v[224:227], v[172:175], v[32:35]
	v_mfma_f32_16x16x32_bf16 v[8:11], v[228:231], v[172:175], v[8:11]
	v_mfma_f32_16x16x32_bf16 v[16:19], v[232:235], v[172:175], v[16:19]
	s_setprio 0
	s_nop 7
	s_nop 4
	s_nop 4
	v_permlane16_swap_b32_e32 v52, v56
	v_permlane16_swap_b32_e32 v53, v57
	v_permlane16_swap_b32_e32 v54, v58
	v_permlane16_swap_b32_e32 v55, v59
	v_permlane16_swap_b32_e32 v60, v64
	v_permlane16_swap_b32_e32 v61, v65
	v_permlane16_swap_b32_e32 v62, v66
	v_permlane16_swap_b32_e32 v63, v67
	v_permlane16_swap_b32_e32 v36, v40
	v_permlane16_swap_b32_e32 v37, v41
	v_permlane16_swap_b32_e32 v38, v42
	v_permlane16_swap_b32_e32 v39, v43
	v_permlane16_swap_b32_e32 v44, v48
	v_permlane16_swap_b32_e32 v45, v49
	v_permlane16_swap_b32_e32 v46, v50
	v_permlane16_swap_b32_e32 v47, v51
	v_permlane16_swap_b32_e32 v20, v24
	v_permlane16_swap_b32_e32 v21, v25
	v_permlane16_swap_b32_e32 v22, v26
	v_permlane16_swap_b32_e32 v23, v27
	v_permlane16_swap_b32_e32 v28, v32
	v_permlane16_swap_b32_e32 v29, v33
	v_permlane16_swap_b32_e32 v30, v34
	v_permlane16_swap_b32_e32 v31, v35
	v_permlane16_swap_b32_e32 v4, v8
	v_permlane16_swap_b32_e32 v5, v9
	v_permlane16_swap_b32_e32 v6, v10
	v_permlane16_swap_b32_e32 v7, v11
	v_permlane16_swap_b32_e32 v12, v16
	v_permlane16_swap_b32_e32 v13, v17
	v_permlane16_swap_b32_e32 v14, v18
	v_permlane16_swap_b32_e32 v15, v19
	s_nop 1
	v_permlane32_swap_b32_e32 v52, v56
	v_permlane32_swap_b32_e32 v53, v57
	v_permlane32_swap_b32_e32 v54, v58
	v_permlane32_swap_b32_e32 v55, v59
	v_permlane32_swap_b32_e32 v60, v64
	v_permlane32_swap_b32_e32 v61, v65
	v_permlane32_swap_b32_e32 v62, v66
	v_permlane32_swap_b32_e32 v63, v67
	v_permlane32_swap_b32_e32 v36, v40
	v_permlane32_swap_b32_e32 v37, v41
	v_permlane32_swap_b32_e32 v38, v42
	v_permlane32_swap_b32_e32 v39, v43
	v_permlane32_swap_b32_e32 v44, v48
	v_permlane32_swap_b32_e32 v45, v49
	v_permlane32_swap_b32_e32 v46, v50
	v_permlane32_swap_b32_e32 v47, v51
	v_permlane32_swap_b32_e32 v20, v24
	v_permlane32_swap_b32_e32 v21, v25
	v_permlane32_swap_b32_e32 v22, v26
	v_permlane32_swap_b32_e32 v23, v27
	v_permlane32_swap_b32_e32 v28, v32
	v_permlane32_swap_b32_e32 v29, v33
	v_permlane32_swap_b32_e32 v30, v34
	v_permlane32_swap_b32_e32 v31, v35
	v_permlane32_swap_b32_e32 v4, v8
	v_permlane32_swap_b32_e32 v5, v9
	v_permlane32_swap_b32_e32 v6, v10
	v_permlane32_swap_b32_e32 v7, v11
	v_permlane32_swap_b32_e32 v12, v16
	v_permlane32_swap_b32_e32 v13, v17
	v_permlane32_swap_b32_e32 v14, v18
	v_permlane32_swap_b32_e32 v15, v19
	s_nop 1
	v_mov_b32_e32 v188, 0x12010
	s_add_i32 s2, s76, s70
	s_and_b32 s0, s2, 0xfffffe00
	s_cmpk_eq_i32 s0, 0xc00
	s_cselect_b64 s[0:1], -1, 0
	s_and_b64 s[0:1], s[26:27], s[0:1]
	s_cmpk_lt_i32 s2, 0xd00
	s_movk_i32 s3, 0xff00
	s_cselect_b32 s3, 0x100, s3
	s_and_b64 s[0:1], s[0:1], exec
	s_cselect_b32 s0, s3, 0
	s_add_i32 s0, s0, s2
	s_cmpk_lt_i32 s2, 0xe10
	s_cselect_b32 s0, s0, 0xd00
	s_cmpk_gt_i32 s0, 0xcff
	v_mov_b64_e32 v[146:147], v[150:151]
	v_mov_b64_e32 v[144:145], v[148:149]
	s_barrier
	s_cbranch_scc1 .LBB0_303
	s_lshl_b32 s1, s0, 18
	v_readlane_b32 s12, v252, 47
	v_mov_b32_e32 v2, v0
	s_and_b32 s1, s1, 0xfc0000
	v_readlane_b32 s18, v252, 53
	v_readlane_b32 s19, v252, 54
	v_ashrrev_i32_e32 v68, 3, v2
	s_add_u32 s2, s18, s1
	v_ashrrev_i32_e32 v69, 31, v68
	s_addc_u32 s3, s19, 0
	v_lshlrev_b64 v[68:69], 11, v[68:69]
	v_lshlrev_b32_e32 v2, 4, v2
	v_lshl_add_u64 v[70:71], s[2:3], 0, v[68:69]
	v_and_b32_e32 v2, 0x70, v2
	s_ashr_i32 s0, s0, 6
	v_lshl_add_u64 v[144:145], v[70:71], 0, v[2:3]
	s_ashr_i32 s1, s0, 31
	v_add_co_u32_e32 v76, vcc, s33, v144
	s_lshl_b64 s[0:1], s[0:1], 18
	s_nop 0
	v_addc_co_u32_e32 v77, vcc, 0, v145, vcc
	s_add_u32 s0, s68, s0
	v_add_co_u32_e32 v80, vcc, s78, v144
	s_addc_u32 s1, s69, s1
	s_nop 0
	v_addc_co_u32_e32 v81, vcc, 0, v145, vcc
	v_lshl_add_u64 v[68:69], s[0:1], 0, v[68:69]
	v_add_co_u32_e32 v84, vcc, s79, v144
	v_lshl_add_u64 v[146:147], v[68:69], 0, v[2:3]
	s_nop 0
	v_addc_co_u32_e32 v85, vcc, 0, v145, vcc
	v_add_co_u32_e32 v92, vcc, s33, v146
	v_readlane_b32 s13, v252, 48
	s_nop 0
	v_addc_co_u32_e32 v93, vcc, 0, v147, vcc
	v_add_co_u32_e32 v96, vcc, s78, v146
	v_readlane_b32 s14, v252, 49
	s_nop 0
	v_addc_co_u32_e32 v97, vcc, 0, v147, vcc
	v_add_co_u32_e32 v128, vcc, 0x30000, v146
	v_readlane_b32 s15, v252, 50
	s_nop 0
	v_addc_co_u32_e32 v129, vcc, 0, v147, vcc
	global_load_dwordx4 v[68:71], v[144:145], off
	global_load_dwordx4 v[100:103], v[144:145], off offset:128
	global_load_dwordx4 v[72:75], v[76:77], off
	global_load_dwordx4 v[104:107], v[76:77], off offset:128
	s_nop 0
	global_load_dwordx4 v[76:79], v[80:81], off
	global_load_dwordx4 v[108:111], v[80:81], off offset:128
	s_nop 0
	global_load_dwordx4 v[80:83], v[84:85], off
	global_load_dwordx4 v[112:115], v[84:85], off offset:128
	s_nop 0
	global_load_dwordx4 v[84:87], v[146:147], off
	global_load_dwordx4 v[116:119], v[146:147], off offset:128
	global_load_dwordx4 v[88:91], v[92:93], off
	global_load_dwordx4 v[120:123], v[92:93], off offset:128
	s_nop 0
	global_load_dwordx4 v[92:95], v[96:97], off
	global_load_dwordx4 v[124:127], v[96:97], off offset:128
	s_nop 0
	global_load_dwordx4 v[96:99], v[128:129], off
	s_nop 0
	global_load_dwordx4 v[128:131], v[128:129], off offset:128
	v_readlane_b32 s16, v252, 51
	v_readlane_b32 s17, v252, 52

.LBB0_360:
	s_and_saveexec_b64 s[36:37], s[0:1]
	s_cbranch_execz .LBB0_355
	s_mov_b32 s12, 0x3e16c740
	v_pk_mul_f32 v[138:139], v[154:155], s[12:13] op_sel_hi:[1,0]
	v_pk_mul_f32 v[136:137], v[136:137], s[12:13] op_sel_hi:[1,0]
	v_cvt_pk_bf16_f32 v138, v138, v139
	v_cvt_pk_bf16_f32 v139, v136, v137
	global_store_dwordx2 v[152:153], v[138:139], off
	s_branch .LBB0_355
.Ltramp_9:
	s_branch .LBB0_9
.Ltramp_LBB0_10:
	s_branch .LBB0_10
.Ltramp_LBB0_11:
	s_branch .LBB0_11

.LBB0_581:
	s_or_b64 exec, exec, s[20:21]
	s_lshl_b32 s0, s36, 1
	s_and_b32 s20, s0, 0xffffff80
	s_mul_i32 s0, s37, 0x1600
	v_readlane_b32 s22, v252, 60
	v_readlane_b32 s23, v252, 61
	s_add_u32 s0, s22, s0
	s_addc_u32 s1, s23, 0
	s_mul_i32 s22, s20, 0x1600
	s_mul_hi_i32 s21, s20, 0x1600
	s_add_u32 s22, s34, s22
	v_mov_b32_e32 v141, v0
	s_waitcnt vmcnt(0)
	s_addc_u32 s23, s35, s21
	v_mov_b64_e32 v[4:5], s[0:1]
	v_ashrrev_i32_e32 v6, 3, v141
	v_mad_i64_i32 v[132:133], s[0:1], v6, s73, v[4:5]
	v_lshlrev_b32_e32 v2, 4, v141
	v_mov_b64_e32 v[4:5], s[22:23]
	v_and_b32_e32 v2, 0x70, v2
	v_mad_i64_i32 v[134:135], s[0:1], v6, s73, v[4:5]
	s_waitcnt vmcnt(13)
	v_lshl_add_u64 v[72:73], v[132:133], 0, v[2:3]
	s_mov_b32 s0, 0x2c000
	s_waitcnt vmcnt(9)
	v_add_co_u32_e32 v80, vcc, s0, v72
	s_mov_b32 s1, 0x58000
	s_nop 0
	v_addc_co_u32_e32 v81, vcc, 0, v73, vcc
	s_waitcnt vmcnt(5)
	v_add_co_u32_e32 v88, vcc, s1, v72
	s_mov_b32 s21, 0x84000
	s_nop 0
	v_addc_co_u32_e32 v89, vcc, 0, v73, vcc
	s_waitcnt vmcnt(1)
	v_add_co_u32_e32 v96, vcc, s21, v72
	v_lshl_add_u64 v[104:105], v[134:135], 0, v[2:3]
	s_nop 0
	v_addc_co_u32_e32 v97, vcc, 0, v73, vcc
	s_mov_b32 s0, 0x2c000
	s_mov_b32 s1, 0
	v_lshl_add_u64 v[74:75], s[0:1], 0, v[72:73]
	s_mov_b32 s0, 0x58000
	s_mov_b32 s1, 0
	v_lshl_add_u64 v[106:107], s[0:1], 0, v[72:73]
	s_mov_b32 s0, 0x84000
	s_mov_b32 s1, 0
	v_lshl_add_u64 v[188:189], s[0:1], 0, v[72:73]
	s_mov_b32 s0, 0x2c000
	s_mov_b32 s1, 0
	v_lshl_add_u64 v[214:215], s[0:1], 0, v[104:105]
	s_mov_b32 s0, 0x58000
	s_mov_b32 s1, 0
	v_lshl_add_u64 v[236:237], s[0:1], 0, v[104:105]
	s_mov_b32 s0, 0x84000
	s_mov_b32 s1, 0
	v_lshl_add_u64 v[238:239], s[0:1], 0, v[104:105]
	v_lshrrev_b32_e32 v172, 3, v0
	v_and_b32_e32 v174, 15, v172
	v_lshlrev_b32_e32 v173, 1, v174
	v_cmp_gt_u32_e32 vcc, 12, v174
	s_nop 1
	v_mov_b32_e32 v175, 15
	v_cndmask_b32_e64 v175, v175, 8, vcc
	v_cmp_gt_u32_e32 vcc, 4, v174
	v_sub_u32_e32 v173, v173, v175
	v_lshlrev_b32_e32 v175, 1, v174
	v_add_u32_e32 v175, 1, v175
	s_nop 1
	v_cndmask_b32_e32 v173, v173, v175, vcc
	v_and_b32_e32 v172, 16, v172
	v_add_u32_e32 v172, v172, v173
	v_mul_u32_u24_e32 v172, 0x90, v172
	v_and_b32_e32 v173, 7, v0
	v_lshl_add_u32 v213, v173, 4, v172
	v_add_u32_e32 v240, 0x9000, v213
	v_and_b32_e32 v174, 15, v0
	v_lshlrev_b32_e32 v173, 1, v174
	v_cmp_gt_u32_e32 vcc, 12, v174
	s_nop 1
	v_mov_b32_e32 v175, 15
	v_cndmask_b32_e64 v175, v175, 8, vcc
	v_cmp_gt_u32_e32 vcc, 4, v174
	v_sub_u32_e32 v173, v173, v175
	v_lshlrev_b32_e32 v175, 1, v174
	v_add_u32_e32 v175, 1, v175
	s_nop 1
	v_cndmask_b32_e32 v173, v173, v175, vcc
	v_bfe_u32 v172, v0, 4, 2
	v_and_b32_e32 v174, 1, v172
	v_lshrrev_b32_e32 v172, 1, v172
	v_lshl_or_b32 v172, v174, 1, v172
	v_lshlrev_b32_e32 v172, 4, v172
	v_lshrrev_b32_e32 v174, 1, v0
	v_and_b32_e32 v174, 64, v174
	v_add_u32_e32 v174, v174, v173
	v_mul_u32_u24_e32 v174, 0x90, v174
	v_add_u32_e32 v241, v174, v172
	v_and_b32_e32 v174, 64, v0
	v_add_u32_e32 v174, v174, v173
	v_mul_u32_u24_e32 v174, 0x90, v174
	v_add_u32_e32 v242, v174, v172
	global_load_dwordx4 v[68:71], v[72:73], off
	global_load_dwordx4 v[76:79], v[74:75], off
	global_load_dwordx4 v[80:83], v[106:107], off
	global_load_dwordx4 v[84:87], v[188:189], off
	global_load_dwordx4 v[88:91], v[104:105], off
	global_load_dwordx4 v[92:95], v[214:215], off
	global_load_dwordx4 v[96:99], v[236:237], off
	global_load_dwordx4 v[100:103], v[238:239], off
	global_load_dwordx4 v[108:111], v[72:73], off offset:128
	global_load_dwordx4 v[112:115], v[74:75], off offset:128
	global_load_dwordx4 v[116:119], v[106:107], off offset:128
	global_load_dwordx4 v[120:123], v[188:189], off offset:128
	global_load_dwordx4 v[124:127], v[104:105], off offset:128
	global_load_dwordx4 v[128:131], v[214:215], off offset:128
	global_load_dwordx4 v[136:139], v[236:237], off offset:128
	global_load_dwordx4 v[140:143], v[238:239], off offset:128
	s_barrier
	s_waitcnt vmcnt(15)
	ds_write_b128 v213, v[68:71]
	s_waitcnt vmcnt(14)
	ds_write_b128 v213, v[76:79] offset:4608
	s_waitcnt vmcnt(13)
	ds_write_b128 v213, v[80:83] offset:9216
	s_waitcnt vmcnt(12)
	ds_write_b128 v213, v[84:87] offset:13824
	s_waitcnt vmcnt(11)
	ds_write_b128 v213, v[88:91] offset:18432
	s_waitcnt vmcnt(10)
	ds_write_b128 v213, v[92:95] offset:23040
	s_waitcnt vmcnt(9)
	ds_write_b128 v213, v[96:99] offset:27648
	s_waitcnt vmcnt(8)
	ds_write_b128 v213, v[100:103] offset:32256
	global_load_dwordx4 v[68:71], v[72:73], off offset:256
	global_load_dwordx4 v[76:79], v[74:75], off offset:256
	global_load_dwordx4 v[80:83], v[106:107], off offset:256
	global_load_dwordx4 v[84:87], v[188:189], off offset:256
	global_load_dwordx4 v[88:91], v[104:105], off offset:256
	global_load_dwordx4 v[92:95], v[214:215], off offset:256
	global_load_dwordx4 v[96:99], v[236:237], off offset:256
	global_load_dwordx4 v[100:103], v[238:239], off offset:256
	s_waitcnt lgkmcnt(0)
	s_barrier
	ds_read_b128 v[144:147], v241
	ds_read_b128 v[176:179], v242 offset:18432
	ds_read_b128 v[180:183], v242 offset:20736
	ds_read_b128 v[148:151], v241 offset:2304
	ds_read_b128 v[184:187], v242 offset:23040
	ds_read_b128 v[152:155], v241 offset:4608
	ds_read_b128 v[216:219], v242 offset:25344
	ds_read_b128 v[156:159], v241 offset:6912
	s_setprio 1
	s_waitcnt lgkmcnt(6)
	v_mfma_f32_16x16x32_bf16 v[52:55], v[176:179], v[144:147], 0
	s_waitcnt vmcnt(15)
	ds_write_b128 v240, v[108:111]
	s_waitcnt lgkmcnt(6)
	v_mfma_f32_16x16x32_bf16 v[60:63], v[180:183], v[144:147], 0
	s_waitcnt lgkmcnt(5)
	v_mfma_f32_16x16x32_bf16 v[56:59], v[176:179], v[148:151], 0
	s_waitcnt vmcnt(14)
	ds_write_b128 v240, v[112:115] offset:4608
	v_mfma_f32_16x16x32_bf16 v[64:67], v[180:183], v[148:151], 0
	ds_read_b128 v[160:163], v241 offset:64
	s_waitcnt lgkmcnt(6)
	v_mfma_f32_16x16x32_bf16 v[36:39], v[184:187], v[144:147], 0
	ds_read_b128 v[220:223], v242 offset:18496
	s_waitcnt vmcnt(13)
	ds_write_b128 v240, v[116:119] offset:9216
	global_load_dwordx4 v[108:111], v[72:73], off offset:384
	v_mfma_f32_16x16x32_bf16 v[40:43], v[184:187], v[148:151], 0
	ds_read_b128 v[224:227], v242 offset:20800
	s_waitcnt lgkmcnt(8)
	v_mfma_f32_16x16x32_bf16 v[20:23], v[176:179], v[152:155], 0
	ds_read_b128 v[164:167], v241 offset:2368
	v_mfma_f32_16x16x32_bf16 v[28:31], v[180:183], v[152:155], 0
	v_mfma_f32_16x16x32_bf16 v[4:7], v[184:187], v[152:155], 0
	ds_read_b128 v[228:231], v242 offset:23104
	s_waitcnt lgkmcnt(9)
	v_mfma_f32_16x16x32_bf16 v[44:47], v[216:219], v[144:147], 0
	ds_read_b128 v[168:171], v241 offset:4672
	v_mfma_f32_16x16x32_bf16 v[48:51], v[216:219], v[148:151], 0
	s_waitcnt vmcnt(13)
	ds_write_b128 v240, v[120:123] offset:13824
	global_load_dwordx4 v[112:115], v[74:75], off offset:384
	v_mfma_f32_16x16x32_bf16 v[12:15], v[216:219], v[152:155], 0
	ds_read_b128 v[232:235], v242 offset:25408
	s_waitcnt lgkmcnt(11)
	v_mfma_f32_16x16x32_bf16 v[24:27], v[176:179], v[156:159], 0
	ds_read_b128 v[172:175], v241 offset:6976
	s_waitcnt vmcnt(13)
	ds_write_b128 v240, v[124:127] offset:18432
	global_load_dwordx4 v[116:119], v[106:107], off offset:384
	v_mfma_f32_16x16x32_bf16 v[32:35], v[180:183], v[156:159], 0
	v_mfma_f32_16x16x32_bf16 v[8:11], v[184:187], v[156:159], 0
	v_mfma_f32_16x16x32_bf16 v[16:19], v[216:219], v[156:159], 0
	s_waitcnt lgkmcnt(9)
	v_mfma_f32_16x16x32_bf16 v[52:55], v[220:223], v[160:163], v[52:55]
	s_waitcnt lgkmcnt(7)
	v_mfma_f32_16x16x32_bf16 v[60:63], v[224:227], v[160:163], v[60:63]
	s_waitcnt lgkmcnt(6)
	v_mfma_f32_16x16x32_bf16 v[56:59], v[220:223], v[164:167], v[56:59]
	s_waitcnt vmcnt(13)
	ds_write_b128 v240, v[128:131] offset:23040
	global_load_dwordx4 v[120:123], v[188:189], off offset:384
	v_mfma_f32_16x16x32_bf16 v[64:67], v[224:227], v[164:167], v[64:67]
	s_waitcnt lgkmcnt(6)
	v_mfma_f32_16x16x32_bf16 v[36:39], v[228:231], v[160:163], v[36:39]
	s_waitcnt vmcnt(13)
	ds_write_b128 v240, v[136:139] offset:27648
	global_load_dwordx4 v[124:127], v[104:105], off offset:384
	v_mfma_f32_16x16x32_bf16 v[40:43], v[228:231], v[164:167], v[40:43]
	s_waitcnt lgkmcnt(6)
	v_mfma_f32_16x16x32_bf16 v[20:23], v[220:223], v[168:171], v[20:23]
	s_waitcnt vmcnt(13)
	ds_write_b128 v240, v[140:143] offset:32256
	global_load_dwordx4 v[128:131], v[214:215], off offset:384
	v_mfma_f32_16x16x32_bf16 v[28:31], v[224:227], v[168:171], v[28:31]
	v_mfma_f32_16x16x32_bf16 v[4:7], v[228:231], v[168:171], v[4:7]
	global_load_dwordx4 v[136:139], v[236:237], off offset:384
	s_waitcnt lgkmcnt(5)
	v_mfma_f32_16x16x32_bf16 v[44:47], v[232:235], v[160:163], v[44:47]
	v_mfma_f32_16x16x32_bf16 v[48:51], v[232:235], v[164:167], v[48:51]
	global_load_dwordx4 v[140:143], v[238:239], off offset:384
	v_mfma_f32_16x16x32_bf16 v[12:15], v[232:235], v[168:171], v[12:15]
	s_waitcnt lgkmcnt(4)
	v_mfma_f32_16x16x32_bf16 v[24:27], v[220:223], v[172:175], v[24:27]
	v_mfma_f32_16x16x32_bf16 v[32:35], v[224:227], v[172:175], v[32:35]
	v_mfma_f32_16x16x32_bf16 v[8:11], v[228:231], v[172:175], v[8:11]
	v_mfma_f32_16x16x32_bf16 v[16:19], v[232:235], v[172:175], v[16:19]
	s_setprio 0
	s_waitcnt lgkmcnt(0)
	s_barrier
	ds_read_b128 v[144:147], v241 offset:36864
	ds_read_b128 v[176:179], v242 offset:55296
	ds_read_b128 v[180:183], v242 offset:57600
	ds_read_b128 v[148:151], v241 offset:39168
	ds_read_b128 v[184:187], v242 offset:59904
	ds_read_b128 v[152:155], v241 offset:41472
	ds_read_b128 v[216:219], v242 offset:62208
	ds_read_b128 v[156:159], v241 offset:43776
	s_setprio 1
	s_waitcnt lgkmcnt(6)
	v_mfma_f32_16x16x32_bf16 v[52:55], v[176:179], v[144:147], v[52:55]
	s_waitcnt vmcnt(15)
	ds_write_b128 v213, v[68:71]
	s_waitcnt lgkmcnt(6)
	v_mfma_f32_16x16x32_bf16 v[60:63], v[180:183], v[144:147], v[60:63]
	s_waitcnt lgkmcnt(5)
	v_mfma_f32_16x16x32_bf16 v[56:59], v[176:179], v[148:151], v[56:59]
	s_waitcnt vmcnt(14)
	ds_write_b128 v213, v[76:79] offset:4608
	v_mfma_f32_16x16x32_bf16 v[64:67], v[180:183], v[148:151], v[64:67]
	ds_read_b128 v[160:163], v241 offset:36928
	s_waitcnt lgkmcnt(6)
	v_mfma_f32_16x16x32_bf16 v[36:39], v[184:187], v[144:147], v[36:39]
	ds_read_b128 v[220:223], v242 offset:55360
	s_waitcnt vmcnt(13)
	ds_write_b128 v213, v[80:83] offset:9216
	global_load_dwordx4 v[68:71], v[72:73], off offset:512
	v_mfma_f32_16x16x32_bf16 v[40:43], v[184:187], v[148:151], v[40:43]
	ds_read_b128 v[224:227], v242 offset:57664
	s_waitcnt lgkmcnt(8)
	v_mfma_f32_16x16x32_bf16 v[20:23], v[176:179], v[152:155], v[20:23]
	ds_read_b128 v[164:167], v241 offset:39232
	v_mfma_f32_16x16x32_bf16 v[28:31], v[180:183], v[152:155], v[28:31]
	v_mfma_f32_16x16x32_bf16 v[4:7], v[184:187], v[152:155], v[4:7]
	ds_read_b128 v[228:231], v242 offset:59968
	s_waitcnt lgkmcnt(9)
	v_mfma_f32_16x16x32_bf16 v[44:47], v[216:219], v[144:147], v[44:47]
	ds_read_b128 v[168:171], v241 offset:41536
	v_mfma_f32_16x16x32_bf16 v[48:51], v[216:219], v[148:151], v[48:51]
	s_waitcnt vmcnt(13)
	ds_write_b128 v213, v[84:87] offset:13824
	global_load_dwordx4 v[76:79], v[74:75], off offset:512
	v_mfma_f32_16x16x32_bf16 v[12:15], v[216:219], v[152:155], v[12:15]
	ds_read_b128 v[232:235], v242 offset:62272
	s_waitcnt lgkmcnt(11)
	v_mfma_f32_16x16x32_bf16 v[24:27], v[176:179], v[156:159], v[24:27]
	ds_read_b128 v[172:175], v241 offset:43840
	s_waitcnt vmcnt(13)
	ds_write_b128 v213, v[88:91] offset:18432
	global_load_dwordx4 v[80:83], v[106:107], off offset:512
	v_mfma_f32_16x16x32_bf16 v[32:35], v[180:183], v[156:159], v[32:35]
	v_mfma_f32_16x16x32_bf16 v[8:11], v[184:187], v[156:159], v[8:11]
	v_mfma_f32_16x16x32_bf16 v[16:19], v[216:219], v[156:159], v[16:19]
	s_waitcnt lgkmcnt(9)
	v_mfma_f32_16x16x32_bf16 v[52:55], v[220:223], v[160:163], v[52:55]
	s_waitcnt lgkmcnt(7)
	v_mfma_f32_16x16x32_bf16 v[60:63], v[224:227], v[160:163], v[60:63]
	s_waitcnt lgkmcnt(6)
	v_mfma_f32_16x16x32_bf16 v[56:59], v[220:223], v[164:167], v[56:59]
	s_waitcnt vmcnt(13)
	ds_write_b128 v213, v[92:95] offset:23040
	global_load_dwordx4 v[84:87], v[188:189], off offset:512
	v_mfma_f32_16x16x32_bf16 v[64:67], v[224:227], v[164:167], v[64:67]
	s_waitcnt lgkmcnt(6)
	v_mfma_f32_16x16x32_bf16 v[36:39], v[228:231], v[160:163], v[36:39]
	s_waitcnt vmcnt(13)
	ds_write_b128 v213, v[96:99] offset:27648
	global_load_dwordx4 v[88:91], v[104:105], off offset:512
	v_mfma_f32_16x16x32_bf16 v[40:43], v[228:231], v[164:167], v[40:43]
	s_waitcnt lgkmcnt(6)
	v_mfma_f32_16x16x32_bf16 v[20:23], v[220:223], v[168:171], v[20:23]
	s_waitcnt vmcnt(13)
	ds_write_b128 v213, v[100:103] offset:32256
	global_load_dwordx4 v[92:95], v[214:215], off offset:512
	v_mfma_f32_16x16x32_bf16 v[28:31], v[224:227], v[168:171], v[28:31]
	v_mfma_f32_16x16x32_bf16 v[4:7], v[228:231], v[168:171], v[4:7]
	global_load_dwordx4 v[96:99], v[236:237], off offset:512
	s_waitcnt lgkmcnt(5)
	v_mfma_f32_16x16x32_bf16 v[44:47], v[232:235], v[160:163], v[44:47]
	v_mfma_f32_16x16x32_bf16 v[48:51], v[232:235], v[164:167], v[48:51]
	global_load_dwordx4 v[100:103], v[238:239], off offset:512
	v_mfma_f32_16x16x32_bf16 v[12:15], v[232:235], v[168:171], v[12:15]
	s_waitcnt lgkmcnt(4)
	v_mfma_f32_16x16x32_bf16 v[24:27], v[220:223], v[172:175], v[24:27]
	v_mfma_f32_16x16x32_bf16 v[32:35], v[224:227], v[172:175], v[32:35]
	v_mfma_f32_16x16x32_bf16 v[8:11], v[228:231], v[172:175], v[8:11]
	v_mfma_f32_16x16x32_bf16 v[16:19], v[232:235], v[172:175], v[16:19]
	s_setprio 0
	s_waitcnt lgkmcnt(0)
	s_barrier
	ds_read_b128 v[144:147], v241
	ds_read_b128 v[176:179], v242 offset:18432
	ds_read_b128 v[180:183], v242 offset:20736
	ds_read_b128 v[148:151], v241 offset:2304
	ds_read_b128 v[184:187], v242 offset:23040
	ds_read_b128 v[152:155], v241 offset:4608
	ds_read_b128 v[216:219], v242 offset:25344
	ds_read_b128 v[156:159], v241 offset:6912
	s_setprio 1
	s_waitcnt lgkmcnt(6)
	v_mfma_f32_16x16x32_bf16 v[52:55], v[176:179], v[144:147], v[52:55]
	s_waitcnt vmcnt(15)
	ds_write_b128 v240, v[108:111]
	s_waitcnt lgkmcnt(6)
	v_mfma_f32_16x16x32_bf16 v[60:63], v[180:183], v[144:147], v[60:63]
	s_waitcnt lgkmcnt(5)
	v_mfma_f32_16x16x32_bf16 v[56:59], v[176:179], v[148:151], v[56:59]
	s_waitcnt vmcnt(14)
	ds_write_b128 v240, v[112:115] offset:4608
	v_mfma_f32_16x16x32_bf16 v[64:67], v[180:183], v[148:151], v[64:67]
	ds_read_b128 v[160:163], v241 offset:64
	s_waitcnt lgkmcnt(6)
	v_mfma_f32_16x16x32_bf16 v[36:39], v[184:187], v[144:147], v[36:39]
	ds_read_b128 v[220:223], v242 offset:18496
	s_waitcnt vmcnt(13)
	ds_write_b128 v240, v[116:119] offset:9216
	global_load_dwordx4 v[108:111], v[72:73], off offset:640
	v_mfma_f32_16x16x32_bf16 v[40:43], v[184:187], v[148:151], v[40:43]
	ds_read_b128 v[224:227], v242 offset:20800
	s_waitcnt lgkmcnt(8)
	v_mfma_f32_16x16x32_bf16 v[20:23], v[176:179], v[152:155], v[20:23]
	ds_read_b128 v[164:167], v241 offset:2368
	v_mfma_f32_16x16x32_bf16 v[28:31], v[180:183], v[152:155], v[28:31]
	v_mfma_f32_16x16x32_bf16 v[4:7], v[184:187], v[152:155], v[4:7]
	ds_read_b128 v[228:231], v242 offset:23104
	s_waitcnt lgkmcnt(9)
	v_mfma_f32_16x16x32_bf16 v[44:47], v[216:219], v[144:147], v[44:47]
	ds_read_b128 v[168:171], v241 offset:4672
	v_mfma_f32_16x16x32_bf16 v[48:51], v[216:219], v[148:151], v[48:51]
	s_waitcnt vmcnt(13)
	ds_write_b128 v240, v[120:123] offset:13824
	global_load_dwordx4 v[112:115], v[74:75], off offset:640
	v_mfma_f32_16x16x32_bf16 v[12:15], v[216:219], v[152:155], v[12:15]
	ds_read_b128 v[232:235], v242 offset:25408
	s_waitcnt lgkmcnt(11)
	v_mfma_f32_16x16x32_bf16 v[24:27], v[176:179], v[156:159], v[24:27]
	ds_read_b128 v[172:175], v241 offset:6976
	s_waitcnt vmcnt(13)
	ds_write_b128 v240, v[124:127] offset:18432
	global_load_dwordx4 v[116:119], v[106:107], off offset:640
	v_mfma_f32_16x16x32_bf16 v[32:35], v[180:183], v[156:159], v[32:35]
	v_mfma_f32_16x16x32_bf16 v[8:11], v[184:187], v[156:159], v[8:11]
	v_mfma_f32_16x16x32_bf16 v[16:19], v[216:219], v[156:159], v[16:19]
	s_waitcnt lgkmcnt(9)
	v_mfma_f32_16x16x32_bf16 v[52:55], v[220:223], v[160:163], v[52:55]
	s_waitcnt lgkmcnt(7)
	v_mfma_f32_16x16x32_bf16 v[60:63], v[224:227], v[160:163], v[60:63]
	s_waitcnt lgkmcnt(6)
	v_mfma_f32_16x16x32_bf16 v[56:59], v[220:223], v[164:167], v[56:59]
	s_waitcnt vmcnt(13)
	ds_write_b128 v240, v[128:131] offset:23040
	global_load_dwordx4 v[120:123], v[188:189], off offset:640
	v_mfma_f32_16x16x32_bf16 v[64:67], v[224:227], v[164:167], v[64:67]
	s_waitcnt lgkmcnt(6)
	v_mfma_f32_16x16x32_bf16 v[36:39], v[228:231], v[160:163], v[36:39]
	s_waitcnt vmcnt(13)
	ds_write_b128 v240, v[136:139] offset:27648
	global_load_dwordx4 v[124:127], v[104:105], off offset:640
	v_mfma_f32_16x16x32_bf16 v[40:43], v[228:231], v[164:167], v[40:43]
	s_waitcnt lgkmcnt(6)
	v_mfma_f32_16x16x32_bf16 v[20:23], v[220:223], v[168:171], v[20:23]
	s_waitcnt vmcnt(13)
	ds_write_b128 v240, v[140:143] offset:32256
	global_load_dwordx4 v[128:131], v[214:215], off offset:640
	v_mfma_f32_16x16x32_bf16 v[28:31], v[224:227], v[168:171], v[28:31]
	v_mfma_f32_16x16x32_bf16 v[4:7], v[228:231], v[168:171], v[4:7]
	global_load_dwordx4 v[136:139], v[236:237], off offset:640
	s_waitcnt lgkmcnt(5)
	v_mfma_f32_16x16x32_bf16 v[44:47], v[232:235], v[160:163], v[44:47]
	v_mfma_f32_16x16x32_bf16 v[48:51], v[232:235], v[164:167], v[48:51]
	global_load_dwordx4 v[140:143], v[238:239], off offset:640
	v_mfma_f32_16x16x32_bf16 v[12:15], v[232:235], v[168:171], v[12:15]
	s_waitcnt lgkmcnt(4)
	v_mfma_f32_16x16x32_bf16 v[24:27], v[220:223], v[172:175], v[24:27]
	v_mfma_f32_16x16x32_bf16 v[32:35], v[224:227], v[172:175], v[32:35]
	v_mfma_f32_16x16x32_bf16 v[8:11], v[228:231], v[172:175], v[8:11]
	v_mfma_f32_16x16x32_bf16 v[16:19], v[232:235], v[172:175], v[16:19]
	s_setprio 0
	s_waitcnt lgkmcnt(0)
	s_barrier
	ds_read_b128 v[144:147], v241 offset:36864
	ds_read_b128 v[176:179], v242 offset:55296
	ds_read_b128 v[180:183], v242 offset:57600
	ds_read_b128 v[148:151], v241 offset:39168
	ds_read_b128 v[184:187], v242 offset:59904
	ds_read_b128 v[152:155], v241 offset:41472
	ds_read_b128 v[216:219], v242 offset:62208
	ds_read_b128 v[156:159], v241 offset:43776
	s_setprio 1
	s_waitcnt lgkmcnt(6)
	v_mfma_f32_16x16x32_bf16 v[52:55], v[176:179], v[144:147], v[52:55]
	s_waitcnt vmcnt(15)
	ds_write_b128 v213, v[68:71]
	s_waitcnt lgkmcnt(6)
	v_mfma_f32_16x16x32_bf16 v[60:63], v[180:183], v[144:147], v[60:63]
	s_waitcnt lgkmcnt(5)
	v_mfma_f32_16x16x32_bf16 v[56:59], v[176:179], v[148:151], v[56:59]
	s_waitcnt vmcnt(14)
	ds_write_b128 v213, v[76:79] offset:4608
	v_mfma_f32_16x16x32_bf16 v[64:67], v[180:183], v[148:151], v[64:67]
	ds_read_b128 v[160:163], v241 offset:36928
	s_waitcnt lgkmcnt(6)
	v_mfma_f32_16x16x32_bf16 v[36:39], v[184:187], v[144:147], v[36:39]
	ds_read_b128 v[220:223], v242 offset:55360
	s_waitcnt vmcnt(13)
	ds_write_b128 v213, v[80:83] offset:9216
	global_load_dwordx4 v[68:71], v[72:73], off offset:768
	v_mfma_f32_16x16x32_bf16 v[40:43], v[184:187], v[148:151], v[40:43]
	ds_read_b128 v[224:227], v242 offset:57664
	s_waitcnt lgkmcnt(8)
	v_mfma_f32_16x16x32_bf16 v[20:23], v[176:179], v[152:155], v[20:23]
	ds_read_b128 v[164:167], v241 offset:39232
	v_mfma_f32_16x16x32_bf16 v[28:31], v[180:183], v[152:155], v[28:31]
	v_mfma_f32_16x16x32_bf16 v[4:7], v[184:187], v[152:155], v[4:7]
	ds_read_b128 v[228:231], v242 offset:59968
	s_waitcnt lgkmcnt(9)
	v_mfma_f32_16x16x32_bf16 v[44:47], v[216:219], v[144:147], v[44:47]
	ds_read_b128 v[168:171], v241 offset:41536
	v_mfma_f32_16x16x32_bf16 v[48:51], v[216:219], v[148:151], v[48:51]
	s_waitcnt vmcnt(13)
	ds_write_b128 v213, v[84:87] offset:13824
	global_load_dwordx4 v[76:79], v[74:75], off offset:768
	v_mfma_f32_16x16x32_bf16 v[12:15], v[216:219], v[152:155], v[12:15]
	ds_read_b128 v[232:235], v242 offset:62272
	s_waitcnt lgkmcnt(11)
	v_mfma_f32_16x16x32_bf16 v[24:27], v[176:179], v[156:159], v[24:27]
	ds_read_b128 v[172:175], v241 offset:43840
	s_waitcnt vmcnt(13)
	ds_write_b128 v213, v[88:91] offset:18432
	global_load_dwordx4 v[80:83], v[106:107], off offset:768
	v_mfma_f32_16x16x32_bf16 v[32:35], v[180:183], v[156:159], v[32:35]
	v_mfma_f32_16x16x32_bf16 v[8:11], v[184:187], v[156:159], v[8:11]
	v_mfma_f32_16x16x32_bf16 v[16:19], v[216:219], v[156:159], v[16:19]
	s_waitcnt lgkmcnt(9)
	v_mfma_f32_16x16x32_bf16 v[52:55], v[220:223], v[160:163], v[52:55]
	s_waitcnt lgkmcnt(7)
	v_mfma_f32_16x16x32_bf16 v[60:63], v[224:227], v[160:163], v[60:63]
	s_waitcnt lgkmcnt(6)
	v_mfma_f32_16x16x32_bf16 v[56:59], v[220:223], v[164:167], v[56:59]
	s_waitcnt vmcnt(13)
	ds_write_b128 v213, v[92:95] offset:23040
	global_load_dwordx4 v[84:87], v[188:189], off offset:768
	v_mfma_f32_16x16x32_bf16 v[64:67], v[224:227], v[164:167], v[64:67]
	s_waitcnt lgkmcnt(6)
	v_mfma_f32_16x16x32_bf16 v[36:39], v[228:231], v[160:163], v[36:39]
	s_waitcnt vmcnt(13)
	ds_write_b128 v213, v[96:99] offset:27648
	global_load_dwordx4 v[88:91], v[104:105], off offset:768
	v_mfma_f32_16x16x32_bf16 v[40:43], v[228:231], v[164:167], v[40:43]
	s_waitcnt lgkmcnt(6)
	v_mfma_f32_16x16x32_bf16 v[20:23], v[220:223], v[168:171], v[20:23]
	s_waitcnt vmcnt(13)
	ds_write_b128 v213, v[100:103] offset:32256
	global_load_dwordx4 v[92:95], v[214:215], off offset:768
	v_mfma_f32_16x16x32_bf16 v[28:31], v[224:227], v[168:171], v[28:31]
	v_mfma_f32_16x16x32_bf16 v[4:7], v[228:231], v[168:171], v[4:7]
	global_load_dwordx4 v[96:99], v[236:237], off offset:768
	s_waitcnt lgkmcnt(5)
	v_mfma_f32_16x16x32_bf16 v[44:47], v[232:235], v[160:163], v[44:47]
	v_mfma_f32_16x16x32_bf16 v[48:51], v[232:235], v[164:167], v[48:51]
	global_load_dwordx4 v[100:103], v[238:239], off offset:768
	v_mfma_f32_16x16x32_bf16 v[12:15], v[232:235], v[168:171], v[12:15]
	s_waitcnt lgkmcnt(4)
	v_mfma_f32_16x16x32_bf16 v[24:27], v[220:223], v[172:175], v[24:27]
	v_mfma_f32_16x16x32_bf16 v[32:35], v[224:227], v[172:175], v[32:35]
	v_mfma_f32_16x16x32_bf16 v[8:11], v[228:231], v[172:175], v[8:11]
	v_mfma_f32_16x16x32_bf16 v[16:19], v[232:235], v[172:175], v[16:19]
	s_setprio 0
	s_waitcnt lgkmcnt(0)
	s_barrier
	ds_read_b128 v[144:147], v241
	ds_read_b128 v[176:179], v242 offset:18432
	ds_read_b128 v[180:183], v242 offset:20736
	ds_read_b128 v[148:151], v241 offset:2304
	ds_read_b128 v[184:187], v242 offset:23040
	ds_read_b128 v[152:155], v241 offset:4608
	ds_read_b128 v[216:219], v242 offset:25344
	ds_read_b128 v[156:159], v241 offset:6912
	s_setprio 1
	s_waitcnt lgkmcnt(6)
	v_mfma_f32_16x16x32_bf16 v[52:55], v[176:179], v[144:147], v[52:55]
	s_waitcnt vmcnt(15)
	ds_write_b128 v240, v[108:111]
	s_waitcnt lgkmcnt(6)
	v_mfma_f32_16x16x32_bf16 v[60:63], v[180:183], v[144:147], v[60:63]
	s_waitcnt lgkmcnt(5)
	v_mfma_f32_16x16x32_bf16 v[56:59], v[176:179], v[148:151], v[56:59]
	s_waitcnt vmcnt(14)
	ds_write_b128 v240, v[112:115] offset:4608
	v_mfma_f32_16x16x32_bf16 v[64:67], v[180:183], v[148:151], v[64:67]
	ds_read_b128 v[160:163], v241 offset:64
	s_waitcnt lgkmcnt(6)
	v_mfma_f32_16x16x32_bf16 v[36:39], v[184:187], v[144:147], v[36:39]
	ds_read_b128 v[220:223], v242 offset:18496
	s_waitcnt vmcnt(13)
	ds_write_b128 v240, v[116:119] offset:9216
	global_load_dwordx4 v[108:111], v[72:73], off offset:896
	v_mfma_f32_16x16x32_bf16 v[40:43], v[184:187], v[148:151], v[40:43]
	ds_read_b128 v[224:227], v242 offset:20800
	s_waitcnt lgkmcnt(8)
	v_mfma_f32_16x16x32_bf16 v[20:23], v[176:179], v[152:155], v[20:23]
	ds_read_b128 v[164:167], v241 offset:2368
	v_mfma_f32_16x16x32_bf16 v[28:31], v[180:183], v[152:155], v[28:31]
	v_mfma_f32_16x16x32_bf16 v[4:7], v[184:187], v[152:155], v[4:7]
	ds_read_b128 v[228:231], v242 offset:23104
	s_waitcnt lgkmcnt(9)
	v_mfma_f32_16x16x32_bf16 v[44:47], v[216:219], v[144:147], v[44:47]
	ds_read_b128 v[168:171], v241 offset:4672
	v_mfma_f32_16x16x32_bf16 v[48:51], v[216:219], v[148:151], v[48:51]
	s_waitcnt vmcnt(13)
	ds_write_b128 v240, v[120:123] offset:13824
	global_load_dwordx4 v[112:115], v[74:75], off offset:896
	v_mfma_f32_16x16x32_bf16 v[12:15], v[216:219], v[152:155], v[12:15]
	ds_read_b128 v[232:235], v242 offset:25408
	s_waitcnt lgkmcnt(11)
	v_mfma_f32_16x16x32_bf16 v[24:27], v[176:179], v[156:159], v[24:27]
	ds_read_b128 v[172:175], v241 offset:6976
	s_waitcnt vmcnt(13)
	ds_write_b128 v240, v[124:127] offset:18432
	global_load_dwordx4 v[116:119], v[106:107], off offset:896
	v_mfma_f32_16x16x32_bf16 v[32:35], v[180:183], v[156:159], v[32:35]
	v_mfma_f32_16x16x32_bf16 v[8:11], v[184:187], v[156:159], v[8:11]
	v_mfma_f32_16x16x32_bf16 v[16:19], v[216:219], v[156:159], v[16:19]
	s_waitcnt lgkmcnt(9)
	v_mfma_f32_16x16x32_bf16 v[52:55], v[220:223], v[160:163], v[52:55]
	s_waitcnt lgkmcnt(7)
	v_mfma_f32_16x16x32_bf16 v[60:63], v[224:227], v[160:163], v[60:63]
	s_waitcnt lgkmcnt(6)
	v_mfma_f32_16x16x32_bf16 v[56:59], v[220:223], v[164:167], v[56:59]
	s_waitcnt vmcnt(13)
	ds_write_b128 v240, v[128:131] offset:23040
	global_load_dwordx4 v[120:123], v[188:189], off offset:896
	v_mfma_f32_16x16x32_bf16 v[64:67], v[224:227], v[164:167], v[64:67]
	s_waitcnt lgkmcnt(6)
	v_mfma_f32_16x16x32_bf16 v[36:39], v[228:231], v[160:163], v[36:39]
	s_waitcnt vmcnt(13)
	ds_write_b128 v240, v[136:139] offset:27648
	global_load_dwordx4 v[124:127], v[104:105], off offset:896
	v_mfma_f32_16x16x32_bf16 v[40:43], v[228:231], v[164:167], v[40:43]
	s_waitcnt lgkmcnt(6)
	v_mfma_f32_16x16x32_bf16 v[20:23], v[220:223], v[168:171], v[20:23]
	s_waitcnt vmcnt(13)
	ds_write_b128 v240, v[140:143] offset:32256
	global_load_dwordx4 v[128:131], v[214:215], off offset:896
	v_mfma_f32_16x16x32_bf16 v[28:31], v[224:227], v[168:171], v[28:31]
	v_mfma_f32_16x16x32_bf16 v[4:7], v[228:231], v[168:171], v[4:7]
	global_load_dwordx4 v[136:139], v[236:237], off offset:896
	s_waitcnt lgkmcnt(5)
	v_mfma_f32_16x16x32_bf16 v[44:47], v[232:235], v[160:163], v[44:47]
	v_mfma_f32_16x16x32_bf16 v[48:51], v[232:235], v[164:167], v[48:51]
	global_load_dwordx4 v[140:143], v[238:239], off offset:896
	v_mfma_f32_16x16x32_bf16 v[12:15], v[232:235], v[168:171], v[12:15]
	s_waitcnt lgkmcnt(4)
	v_mfma_f32_16x16x32_bf16 v[24:27], v[220:223], v[172:175], v[24:27]
	v_mfma_f32_16x16x32_bf16 v[32:35], v[224:227], v[172:175], v[32:35]
	v_mfma_f32_16x16x32_bf16 v[8:11], v[228:231], v[172:175], v[8:11]
	v_mfma_f32_16x16x32_bf16 v[16:19], v[232:235], v[172:175], v[16:19]
	s_setprio 0
	s_waitcnt lgkmcnt(0)
	s_barrier
	ds_read_b128 v[144:147], v241 offset:36864
	ds_read_b128 v[176:179], v242 offset:55296
	ds_read_b128 v[180:183], v242 offset:57600
	ds_read_b128 v[148:151], v241 offset:39168
	ds_read_b128 v[184:187], v242 offset:59904
	ds_read_b128 v[152:155], v241 offset:41472
	ds_read_b128 v[216:219], v242 offset:62208
	ds_read_b128 v[156:159], v241 offset:43776
	s_setprio 1
	s_waitcnt lgkmcnt(6)
	v_mfma_f32_16x16x32_bf16 v[52:55], v[176:179], v[144:147], v[52:55]
	s_waitcnt vmcnt(15)
	ds_write_b128 v213, v[68:71]
	s_waitcnt lgkmcnt(6)
	v_mfma_f32_16x16x32_bf16 v[60:63], v[180:183], v[144:147], v[60:63]
	s_waitcnt lgkmcnt(5)
	v_mfma_f32_16x16x32_bf16 v[56:59], v[176:179], v[148:151], v[56:59]
	s_waitcnt vmcnt(14)
	ds_write_b128 v213, v[76:79] offset:4608
	v_mfma_f32_16x16x32_bf16 v[64:67], v[180:183], v[148:151], v[64:67]
	ds_read_b128 v[160:163], v241 offset:36928
	s_waitcnt lgkmcnt(6)
	v_mfma_f32_16x16x32_bf16 v[36:39], v[184:187], v[144:147], v[36:39]
	ds_read_b128 v[220:223], v242 offset:55360
	s_waitcnt vmcnt(13)
	ds_write_b128 v213, v[80:83] offset:9216
	global_load_dwordx4 v[68:71], v[72:73], off offset:1024
	v_mfma_f32_16x16x32_bf16 v[40:43], v[184:187], v[148:151], v[40:43]
	ds_read_b128 v[224:227], v242 offset:57664
	s_waitcnt lgkmcnt(8)
	v_mfma_f32_16x16x32_bf16 v[20:23], v[176:179], v[152:155], v[20:23]
	ds_read_b128 v[164:167], v241 offset:39232
	v_mfma_f32_16x16x32_bf16 v[28:31], v[180:183], v[152:155], v[28:31]
	v_mfma_f32_16x16x32_bf16 v[4:7], v[184:187], v[152:155], v[4:7]
	ds_read_b128 v[228:231], v242 offset:59968
	s_waitcnt lgkmcnt(9)
	v_mfma_f32_16x16x32_bf16 v[44:47], v[216:219], v[144:147], v[44:47]
	ds_read_b128 v[168:171], v241 offset:41536
	v_mfma_f32_16x16x32_bf16 v[48:51], v[216:219], v[148:151], v[48:51]
	s_waitcnt vmcnt(13)
	ds_write_b128 v213, v[84:87] offset:13824
	global_load_dwordx4 v[76:79], v[74:75], off offset:1024
	v_mfma_f32_16x16x32_bf16 v[12:15], v[216:219], v[152:155], v[12:15]
	ds_read_b128 v[232:235], v242 offset:62272
	s_waitcnt lgkmcnt(11)
	v_mfma_f32_16x16x32_bf16 v[24:27], v[176:179], v[156:159], v[24:27]
	ds_read_b128 v[172:175], v241 offset:43840
	s_waitcnt vmcnt(13)
	ds_write_b128 v213, v[88:91] offset:18432
	global_load_dwordx4 v[80:83], v[106:107], off offset:1024
	v_mfma_f32_16x16x32_bf16 v[32:35], v[180:183], v[156:159], v[32:35]
	v_mfma_f32_16x16x32_bf16 v[8:11], v[184:187], v[156:159], v[8:11]
	v_mfma_f32_16x16x32_bf16 v[16:19], v[216:219], v[156:159], v[16:19]
	s_waitcnt lgkmcnt(9)
	v_mfma_f32_16x16x32_bf16 v[52:55], v[220:223], v[160:163], v[52:55]
	s_waitcnt lgkmcnt(7)
	v_mfma_f32_16x16x32_bf16 v[60:63], v[224:227], v[160:163], v[60:63]
	s_waitcnt lgkmcnt(6)
	v_mfma_f32_16x16x32_bf16 v[56:59], v[220:223], v[164:167], v[56:59]
	s_waitcnt vmcnt(13)
	ds_write_b128 v213, v[92:95] offset:23040
	global_load_dwordx4 v[84:87], v[188:189], off offset:1024
	v_mfma_f32_16x16x32_bf16 v[64:67], v[224:227], v[164:167], v[64:67]
	s_waitcnt lgkmcnt(6)
	v_mfma_f32_16x16x32_bf16 v[36:39], v[228:231], v[160:163], v[36:39]
	s_waitcnt vmcnt(13)
	ds_write_b128 v213, v[96:99] offset:27648
	global_load_dwordx4 v[88:91], v[104:105], off offset:1024
	v_mfma_f32_16x16x32_bf16 v[40:43], v[228:231], v[164:167], v[40:43]
	s_waitcnt lgkmcnt(6)
	v_mfma_f32_16x16x32_bf16 v[20:23], v[220:223], v[168:171], v[20:23]
	s_waitcnt vmcnt(13)
	ds_write_b128 v213, v[100:103] offset:32256
	global_load_dwordx4 v[92:95], v[214:215], off offset:1024
	v_mfma_f32_16x16x32_bf16 v[28:31], v[224:227], v[168:171], v[28:31]
	v_mfma_f32_16x16x32_bf16 v[4:7], v[228:231], v[168:171], v[4:7]
	global_load_dwordx4 v[96:99], v[236:237], off offset:1024
	s_waitcnt lgkmcnt(5)
	v_mfma_f32_16x16x32_bf16 v[44:47], v[232:235], v[160:163], v[44:47]
	v_mfma_f32_16x16x32_bf16 v[48:51], v[232:235], v[164:167], v[48:51]
	global_load_dwordx4 v[100:103], v[238:239], off offset:1024
	v_mfma_f32_16x16x32_bf16 v[12:15], v[232:235], v[168:171], v[12:15]
	s_waitcnt lgkmcnt(4)
	v_mfma_f32_16x16x32_bf16 v[24:27], v[220:223], v[172:175], v[24:27]
	v_mfma_f32_16x16x32_bf16 v[32:35], v[224:227], v[172:175], v[32:35]
	v_mfma_f32_16x16x32_bf16 v[8:11], v[228:231], v[172:175], v[8:11]
	v_mfma_f32_16x16x32_bf16 v[16:19], v[232:235], v[172:175], v[16:19]
	s_setprio 0
	s_waitcnt lgkmcnt(0)
	s_barrier
	ds_read_b128 v[144:147], v241
	ds_read_b128 v[176:179], v242 offset:18432
	ds_read_b128 v[180:183], v242 offset:20736
	ds_read_b128 v[148:151], v241 offset:2304
	ds_read_b128 v[184:187], v242 offset:23040
	ds_read_b128 v[152:155], v241 offset:4608
	ds_read_b128 v[216:219], v242 offset:25344
	ds_read_b128 v[156:159], v241 offset:6912
	s_setprio 1
	s_waitcnt lgkmcnt(6)
	v_mfma_f32_16x16x32_bf16 v[52:55], v[176:179], v[144:147], v[52:55]
	s_waitcnt vmcnt(15)
	ds_write_b128 v240, v[108:111]
	s_waitcnt lgkmcnt(6)
	v_mfma_f32_16x16x32_bf16 v[60:63], v[180:183], v[144:147], v[60:63]
	s_waitcnt lgkmcnt(5)
	v_mfma_f32_16x16x32_bf16 v[56:59], v[176:179], v[148:151], v[56:59]
	s_waitcnt vmcnt(14)
	ds_write_b128 v240, v[112:115] offset:4608
	v_mfma_f32_16x16x32_bf16 v[64:67], v[180:183], v[148:151], v[64:67]
	ds_read_b128 v[160:163], v241 offset:64
	s_waitcnt lgkmcnt(6)
	v_mfma_f32_16x16x32_bf16 v[36:39], v[184:187], v[144:147], v[36:39]
	ds_read_b128 v[220:223], v242 offset:18496
	s_waitcnt vmcnt(13)
	ds_write_b128 v240, v[116:119] offset:9216
	global_load_dwordx4 v[108:111], v[72:73], off offset:1152
	v_mfma_f32_16x16x32_bf16 v[40:43], v[184:187], v[148:151], v[40:43]
	ds_read_b128 v[224:227], v242 offset:20800
	s_waitcnt lgkmcnt(8)
	v_mfma_f32_16x16x32_bf16 v[20:23], v[176:179], v[152:155], v[20:23]
	ds_read_b128 v[164:167], v241 offset:2368
	v_mfma_f32_16x16x32_bf16 v[28:31], v[180:183], v[152:155], v[28:31]
	v_mfma_f32_16x16x32_bf16 v[4:7], v[184:187], v[152:155], v[4:7]
	ds_read_b128 v[228:231], v242 offset:23104
	s_waitcnt lgkmcnt(9)
	v_mfma_f32_16x16x32_bf16 v[44:47], v[216:219], v[144:147], v[44:47]
	ds_read_b128 v[168:171], v241 offset:4672
	v_mfma_f32_16x16x32_bf16 v[48:51], v[216:219], v[148:151], v[48:51]
	s_waitcnt vmcnt(13)
	ds_write_b128 v240, v[120:123] offset:13824
	global_load_dwordx4 v[112:115], v[74:75], off offset:1152
	v_mfma_f32_16x16x32_bf16 v[12:15], v[216:219], v[152:155], v[12:15]
	ds_read_b128 v[232:235], v242 offset:25408
	s_waitcnt lgkmcnt(11)
	v_mfma_f32_16x16x32_bf16 v[24:27], v[176:179], v[156:159], v[24:27]
	ds_read_b128 v[172:175], v241 offset:6976
	s_waitcnt vmcnt(13)
	ds_write_b128 v240, v[124:127] offset:18432
	global_load_dwordx4 v[116:119], v[106:107], off offset:1152
	v_mfma_f32_16x16x32_bf16 v[32:35], v[180:183], v[156:159], v[32:35]
	v_mfma_f32_16x16x32_bf16 v[8:11], v[184:187], v[156:159], v[8:11]
	v_mfma_f32_16x16x32_bf16 v[16:19], v[216:219], v[156:159], v[16:19]
	s_waitcnt lgkmcnt(9)
	v_mfma_f32_16x16x32_bf16 v[52:55], v[220:223], v[160:163], v[52:55]
	s_waitcnt lgkmcnt(7)
	v_mfma_f32_16x16x32_bf16 v[60:63], v[224:227], v[160:163], v[60:63]
	s_waitcnt lgkmcnt(6)
	v_mfma_f32_16x16x32_bf16 v[56:59], v[220:223], v[164:167], v[56:59]
	s_waitcnt vmcnt(13)
	ds_write_b128 v240, v[128:131] offset:23040
	global_load_dwordx4 v[120:123], v[188:189], off offset:1152
	v_mfma_f32_16x16x32_bf16 v[64:67], v[224:227], v[164:167], v[64:67]
	s_waitcnt lgkmcnt(6)
	v_mfma_f32_16x16x32_bf16 v[36:39], v[228:231], v[160:163], v[36:39]
	s_waitcnt vmcnt(13)
	ds_write_b128 v240, v[136:139] offset:27648
	global_load_dwordx4 v[124:127], v[104:105], off offset:1152
	v_mfma_f32_16x16x32_bf16 v[40:43], v[228:231], v[164:167], v[40:43]
	s_waitcnt lgkmcnt(6)
	v_mfma_f32_16x16x32_bf16 v[20:23], v[220:223], v[168:171], v[20:23]
	s_waitcnt vmcnt(13)
	ds_write_b128 v240, v[140:143] offset:32256
	global_load_dwordx4 v[128:131], v[214:215], off offset:1152
	v_mfma_f32_16x16x32_bf16 v[28:31], v[224:227], v[168:171], v[28:31]
	v_mfma_f32_16x16x32_bf16 v[4:7], v[228:231], v[168:171], v[4:7]
	global_load_dwordx4 v[136:139], v[236:237], off offset:1152
	s_waitcnt lgkmcnt(5)
	v_mfma_f32_16x16x32_bf16 v[44:47], v[232:235], v[160:163], v[44:47]
	v_mfma_f32_16x16x32_bf16 v[48:51], v[232:235], v[164:167], v[48:51]
	global_load_dwordx4 v[140:143], v[238:239], off offset:1152
	v_mfma_f32_16x16x32_bf16 v[12:15], v[232:235], v[168:171], v[12:15]
	s_waitcnt lgkmcnt(4)
	v_mfma_f32_16x16x32_bf16 v[24:27], v[220:223], v[172:175], v[24:27]
	v_mfma_f32_16x16x32_bf16 v[32:35], v[224:227], v[172:175], v[32:35]
	v_mfma_f32_16x16x32_bf16 v[8:11], v[228:231], v[172:175], v[8:11]
	v_mfma_f32_16x16x32_bf16 v[16:19], v[232:235], v[172:175], v[16:19]
	s_setprio 0
	s_waitcnt lgkmcnt(0)
	s_barrier
	ds_read_b128 v[144:147], v241 offset:36864
	ds_read_b128 v[176:179], v242 offset:55296
	ds_read_b128 v[180:183], v242 offset:57600
	ds_read_b128 v[148:151], v241 offset:39168
	ds_read_b128 v[184:187], v242 offset:59904
	ds_read_b128 v[152:155], v241 offset:41472
	ds_read_b128 v[216:219], v242 offset:62208
	ds_read_b128 v[156:159], v241 offset:43776
	s_setprio 1
	s_waitcnt lgkmcnt(6)
	v_mfma_f32_16x16x32_bf16 v[52:55], v[176:179], v[144:147], v[52:55]
	s_waitcnt vmcnt(15)
	ds_write_b128 v213, v[68:71]
	s_waitcnt lgkmcnt(6)
	v_mfma_f32_16x16x32_bf16 v[60:63], v[180:183], v[144:147], v[60:63]
	s_waitcnt lgkmcnt(5)
	v_mfma_f32_16x16x32_bf16 v[56:59], v[176:179], v[148:151], v[56:59]
	s_waitcnt vmcnt(14)
	ds_write_b128 v213, v[76:79] offset:4608
	v_mfma_f32_16x16x32_bf16 v[64:67], v[180:183], v[148:151], v[64:67]
	ds_read_b128 v[160:163], v241 offset:36928
	s_waitcnt lgkmcnt(6)
	v_mfma_f32_16x16x32_bf16 v[36:39], v[184:187], v[144:147], v[36:39]
	ds_read_b128 v[220:223], v242 offset:55360
	s_waitcnt vmcnt(13)
	ds_write_b128 v213, v[80:83] offset:9216
	global_load_dwordx4 v[68:71], v[72:73], off offset:1280
	v_mfma_f32_16x16x32_bf16 v[40:43], v[184:187], v[148:151], v[40:43]
	ds_read_b128 v[224:227], v242 offset:57664
	s_waitcnt lgkmcnt(8)
	v_mfma_f32_16x16x32_bf16 v[20:23], v[176:179], v[152:155], v[20:23]
	ds_read_b128 v[164:167], v241 offset:39232
	v_mfma_f32_16x16x32_bf16 v[28:31], v[180:183], v[152:155], v[28:31]
	v_mfma_f32_16x16x32_bf16 v[4:7], v[184:187], v[152:155], v[4:7]
	ds_read_b128 v[228:231], v242 offset:59968
	s_waitcnt lgkmcnt(9)
	v_mfma_f32_16x16x32_bf16 v[44:47], v[216:219], v[144:147], v[44:47]
	ds_read_b128 v[168:171], v241 offset:41536
	v_mfma_f32_16x16x32_bf16 v[48:51], v[216:219], v[148:151], v[48:51]
	s_waitcnt vmcnt(13)
	ds_write_b128 v213, v[84:87] offset:13824
	global_load_dwordx4 v[76:79], v[74:75], off offset:1280
	v_mfma_f32_16x16x32_bf16 v[12:15], v[216:219], v[152:155], v[12:15]
	ds_read_b128 v[232:235], v242 offset:62272
	s_waitcnt lgkmcnt(11)
	v_mfma_f32_16x16x32_bf16 v[24:27], v[176:179], v[156:159], v[24:27]
	ds_read_b128 v[172:175], v241 offset:43840
	s_waitcnt vmcnt(13)
	ds_write_b128 v213, v[88:91] offset:18432
	global_load_dwordx4 v[80:83], v[106:107], off offset:1280
	v_mfma_f32_16x16x32_bf16 v[32:35], v[180:183], v[156:159], v[32:35]
	v_mfma_f32_16x16x32_bf16 v[8:11], v[184:187], v[156:159], v[8:11]
	v_mfma_f32_16x16x32_bf16 v[16:19], v[216:219], v[156:159], v[16:19]
	s_waitcnt lgkmcnt(9)
	v_mfma_f32_16x16x32_bf16 v[52:55], v[220:223], v[160:163], v[52:55]
	s_waitcnt lgkmcnt(7)
	v_mfma_f32_16x16x32_bf16 v[60:63], v[224:227], v[160:163], v[60:63]
	s_waitcnt lgkmcnt(6)
	v_mfma_f32_16x16x32_bf16 v[56:59], v[220:223], v[164:167], v[56:59]
	s_waitcnt vmcnt(13)
	ds_write_b128 v213, v[92:95] offset:23040
	global_load_dwordx4 v[84:87], v[188:189], off offset:1280
	v_mfma_f32_16x16x32_bf16 v[64:67], v[224:227], v[164:167], v[64:67]
	s_waitcnt lgkmcnt(6)
	v_mfma_f32_16x16x32_bf16 v[36:39], v[228:231], v[160:163], v[36:39]
	s_waitcnt vmcnt(13)
	ds_write_b128 v213, v[96:99] offset:27648
	global_load_dwordx4 v[88:91], v[104:105], off offset:1280
	v_mfma_f32_16x16x32_bf16 v[40:43], v[228:231], v[164:167], v[40:43]
	s_waitcnt lgkmcnt(6)
	v_mfma_f32_16x16x32_bf16 v[20:23], v[220:223], v[168:171], v[20:23]
	s_waitcnt vmcnt(13)
	ds_write_b128 v213, v[100:103] offset:32256
	global_load_dwordx4 v[92:95], v[214:215], off offset:1280
	v_mfma_f32_16x16x32_bf16 v[28:31], v[224:227], v[168:171], v[28:31]
	v_mfma_f32_16x16x32_bf16 v[4:7], v[228:231], v[168:171], v[4:7]
	global_load_dwordx4 v[96:99], v[236:237], off offset:1280
	s_waitcnt lgkmcnt(5)
	v_mfma_f32_16x16x32_bf16 v[44:47], v[232:235], v[160:163], v[44:47]
	v_mfma_f32_16x16x32_bf16 v[48:51], v[232:235], v[164:167], v[48:51]
	global_load_dwordx4 v[100:103], v[238:239], off offset:1280
	v_mfma_f32_16x16x32_bf16 v[12:15], v[232:235], v[168:171], v[12:15]
	s_waitcnt lgkmcnt(4)
	v_mfma_f32_16x16x32_bf16 v[24:27], v[220:223], v[172:175], v[24:27]
	v_mfma_f32_16x16x32_bf16 v[32:35], v[224:227], v[172:175], v[32:35]
	v_mfma_f32_16x16x32_bf16 v[8:11], v[228:231], v[172:175], v[8:11]
	v_mfma_f32_16x16x32_bf16 v[16:19], v[232:235], v[172:175], v[16:19]
	s_setprio 0
	s_waitcnt lgkmcnt(0)
	s_barrier
	ds_read_b128 v[144:147], v241
	ds_read_b128 v[176:179], v242 offset:18432
	ds_read_b128 v[180:183], v242 offset:20736
	ds_read_b128 v[148:151], v241 offset:2304
	ds_read_b128 v[184:187], v242 offset:23040
	ds_read_b128 v[152:155], v241 offset:4608
	ds_read_b128 v[216:219], v242 offset:25344
	ds_read_b128 v[156:159], v241 offset:6912
	s_setprio 1
	s_waitcnt lgkmcnt(6)
	v_mfma_f32_16x16x32_bf16 v[52:55], v[176:179], v[144:147], v[52:55]
	s_waitcnt vmcnt(15)
	ds_write_b128 v240, v[108:111]
	s_waitcnt lgkmcnt(6)
	v_mfma_f32_16x16x32_bf16 v[60:63], v[180:183], v[144:147], v[60:63]
	s_waitcnt lgkmcnt(5)
	v_mfma_f32_16x16x32_bf16 v[56:59], v[176:179], v[148:151], v[56:59]
	s_waitcnt vmcnt(14)
	ds_write_b128 v240, v[112:115] offset:4608
	v_mfma_f32_16x16x32_bf16 v[64:67], v[180:183], v[148:151], v[64:67]
	ds_read_b128 v[160:163], v241 offset:64
	s_waitcnt lgkmcnt(6)
	v_mfma_f32_16x16x32_bf16 v[36:39], v[184:187], v[144:147], v[36:39]
	ds_read_b128 v[220:223], v242 offset:18496
	s_waitcnt vmcnt(13)
	ds_write_b128 v240, v[116:119] offset:9216
	global_load_dwordx4 v[108:111], v[72:73], off offset:1408
	v_mfma_f32_16x16x32_bf16 v[40:43], v[184:187], v[148:151], v[40:43]
	ds_read_b128 v[224:227], v242 offset:20800
	s_waitcnt lgkmcnt(8)
	v_mfma_f32_16x16x32_bf16 v[20:23], v[176:179], v[152:155], v[20:23]
	ds_read_b128 v[164:167], v241 offset:2368
	v_mfma_f32_16x16x32_bf16 v[28:31], v[180:183], v[152:155], v[28:31]
	v_mfma_f32_16x16x32_bf16 v[4:7], v[184:187], v[152:155], v[4:7]
	ds_read_b128 v[228:231], v242 offset:23104
	s_waitcnt lgkmcnt(9)
	v_mfma_f32_16x16x32_bf16 v[44:47], v[216:219], v[144:147], v[44:47]
	ds_read_b128 v[168:171], v241 offset:4672
	v_mfma_f32_16x16x32_bf16 v[48:51], v[216:219], v[148:151], v[48:51]
	s_waitcnt vmcnt(13)
	ds_write_b128 v240, v[120:123] offset:13824
	global_load_dwordx4 v[112:115], v[74:75], off offset:1408
	v_mfma_f32_16x16x32_bf16 v[12:15], v[216:219], v[152:155], v[12:15]
	ds_read_b128 v[232:235], v242 offset:25408
	s_waitcnt lgkmcnt(11)
	v_mfma_f32_16x16x32_bf16 v[24:27], v[176:179], v[156:159], v[24:27]
	ds_read_b128 v[172:175], v241 offset:6976
	s_waitcnt vmcnt(13)
	ds_write_b128 v240, v[124:127] offset:18432
	global_load_dwordx4 v[116:119], v[106:107], off offset:1408
	v_mfma_f32_16x16x32_bf16 v[32:35], v[180:183], v[156:159], v[32:35]
	v_mfma_f32_16x16x32_bf16 v[8:11], v[184:187], v[156:159], v[8:11]
	v_mfma_f32_16x16x32_bf16 v[16:19], v[216:219], v[156:159], v[16:19]
	s_waitcnt lgkmcnt(9)
	v_mfma_f32_16x16x32_bf16 v[52:55], v[220:223], v[160:163], v[52:55]
	s_waitcnt lgkmcnt(7)
	v_mfma_f32_16x16x32_bf16 v[60:63], v[224:227], v[160:163], v[60:63]
	s_waitcnt lgkmcnt(6)
	v_mfma_f32_16x16x32_bf16 v[56:59], v[220:223], v[164:167], v[56:59]
	s_waitcnt vmcnt(13)
	ds_write_b128 v240, v[128:131] offset:23040
	global_load_dwordx4 v[120:123], v[188:189], off offset:1408
	v_mfma_f32_16x16x32_bf16 v[64:67], v[224:227], v[164:167], v[64:67]
	s_waitcnt lgkmcnt(6)
	v_mfma_f32_16x16x32_bf16 v[36:39], v[228:231], v[160:163], v[36:39]
	s_waitcnt vmcnt(13)
	ds_write_b128 v240, v[136:139] offset:27648
	global_load_dwordx4 v[124:127], v[104:105], off offset:1408
	v_mfma_f32_16x16x32_bf16 v[40:43], v[228:231], v[164:167], v[40:43]
	s_waitcnt lgkmcnt(6)
	v_mfma_f32_16x16x32_bf16 v[20:23], v[220:223], v[168:171], v[20:23]
	s_waitcnt vmcnt(13)
	ds_write_b128 v240, v[140:143] offset:32256
	global_load_dwordx4 v[128:131], v[214:215], off offset:1408
	v_mfma_f32_16x16x32_bf16 v[28:31], v[224:227], v[168:171], v[28:31]
	v_mfma_f32_16x16x32_bf16 v[4:7], v[228:231], v[168:171], v[4:7]
	global_load_dwordx4 v[136:139], v[236:237], off offset:1408
	s_waitcnt lgkmcnt(5)
	v_mfma_f32_16x16x32_bf16 v[44:47], v[232:235], v[160:163], v[44:47]
	v_mfma_f32_16x16x32_bf16 v[48:51], v[232:235], v[164:167], v[48:51]
	global_load_dwordx4 v[140:143], v[238:239], off offset:1408
	v_mfma_f32_16x16x32_bf16 v[12:15], v[232:235], v[168:171], v[12:15]
	s_waitcnt lgkmcnt(4)
	v_mfma_f32_16x16x32_bf16 v[24:27], v[220:223], v[172:175], v[24:27]
	v_mfma_f32_16x16x32_bf16 v[32:35], v[224:227], v[172:175], v[32:35]
	v_mfma_f32_16x16x32_bf16 v[8:11], v[228:231], v[172:175], v[8:11]
	v_mfma_f32_16x16x32_bf16 v[16:19], v[232:235], v[172:175], v[16:19]
	s_setprio 0
	s_waitcnt lgkmcnt(0)
	s_barrier
	ds_read_b128 v[144:147], v241 offset:36864
	ds_read_b128 v[176:179], v242 offset:55296
	ds_read_b128 v[180:183], v242 offset:57600
	ds_read_b128 v[148:151], v241 offset:39168
	ds_read_b128 v[184:187], v242 offset:59904
	ds_read_b128 v[152:155], v241 offset:41472
	ds_read_b128 v[216:219], v242 offset:62208
	ds_read_b128 v[156:159], v241 offset:43776
	s_setprio 1
	s_waitcnt lgkmcnt(6)
	v_mfma_f32_16x16x32_bf16 v[52:55], v[176:179], v[144:147], v[52:55]
	s_waitcnt vmcnt(15)
	ds_write_b128 v213, v[68:71]
	s_waitcnt lgkmcnt(6)
	v_mfma_f32_16x16x32_bf16 v[60:63], v[180:183], v[144:147], v[60:63]
	s_waitcnt lgkmcnt(5)
	v_mfma_f32_16x16x32_bf16 v[56:59], v[176:179], v[148:151], v[56:59]
	s_waitcnt vmcnt(14)
	ds_write_b128 v213, v[76:79] offset:4608
	v_mfma_f32_16x16x32_bf16 v[64:67], v[180:183], v[148:151], v[64:67]
	ds_read_b128 v[160:163], v241 offset:36928
	s_waitcnt lgkmcnt(6)
	v_mfma_f32_16x16x32_bf16 v[36:39], v[184:187], v[144:147], v[36:39]
	ds_read_b128 v[220:223], v242 offset:55360
	s_waitcnt vmcnt(13)
	ds_write_b128 v213, v[80:83] offset:9216
	global_load_dwordx4 v[68:71], v[72:73], off offset:1536
	v_mfma_f32_16x16x32_bf16 v[40:43], v[184:187], v[148:151], v[40:43]
	ds_read_b128 v[224:227], v242 offset:57664
	s_waitcnt lgkmcnt(8)
	v_mfma_f32_16x16x32_bf16 v[20:23], v[176:179], v[152:155], v[20:23]
	ds_read_b128 v[164:167], v241 offset:39232
	v_mfma_f32_16x16x32_bf16 v[28:31], v[180:183], v[152:155], v[28:31]
	v_mfma_f32_16x16x32_bf16 v[4:7], v[184:187], v[152:155], v[4:7]
	ds_read_b128 v[228:231], v242 offset:59968
	s_waitcnt lgkmcnt(9)
	v_mfma_f32_16x16x32_bf16 v[44:47], v[216:219], v[144:147], v[44:47]
	ds_read_b128 v[168:171], v241 offset:41536
	v_mfma_f32_16x16x32_bf16 v[48:51], v[216:219], v[148:151], v[48:51]
	s_waitcnt vmcnt(13)
	ds_write_b128 v213, v[84:87] offset:13824
	global_load_dwordx4 v[76:79], v[74:75], off offset:1536
	v_mfma_f32_16x16x32_bf16 v[12:15], v[216:219], v[152:155], v[12:15]
	ds_read_b128 v[232:235], v242 offset:62272
	s_waitcnt lgkmcnt(11)
	v_mfma_f32_16x16x32_bf16 v[24:27], v[176:179], v[156:159], v[24:27]
	ds_read_b128 v[172:175], v241 offset:43840
	s_waitcnt vmcnt(13)
	ds_write_b128 v213, v[88:91] offset:18432
	global_load_dwordx4 v[80:83], v[106:107], off offset:1536
	v_mfma_f32_16x16x32_bf16 v[32:35], v[180:183], v[156:159], v[32:35]
	v_mfma_f32_16x16x32_bf16 v[8:11], v[184:187], v[156:159], v[8:11]
	v_mfma_f32_16x16x32_bf16 v[16:19], v[216:219], v[156:159], v[16:19]
	s_waitcnt lgkmcnt(9)
	v_mfma_f32_16x16x32_bf16 v[52:55], v[220:223], v[160:163], v[52:55]
	s_waitcnt lgkmcnt(7)
	v_mfma_f32_16x16x32_bf16 v[60:63], v[224:227], v[160:163], v[60:63]
	s_waitcnt lgkmcnt(6)
	v_mfma_f32_16x16x32_bf16 v[56:59], v[220:223], v[164:167], v[56:59]
	s_waitcnt vmcnt(13)
	ds_write_b128 v213, v[92:95] offset:23040
	global_load_dwordx4 v[84:87], v[188:189], off offset:1536
	v_mfma_f32_16x16x32_bf16 v[64:67], v[224:227], v[164:167], v[64:67]
	s_waitcnt lgkmcnt(6)
	v_mfma_f32_16x16x32_bf16 v[36:39], v[228:231], v[160:163], v[36:39]
	s_waitcnt vmcnt(13)
	ds_write_b128 v213, v[96:99] offset:27648
	global_load_dwordx4 v[88:91], v[104:105], off offset:1536
	v_mfma_f32_16x16x32_bf16 v[40:43], v[228:231], v[164:167], v[40:43]
	s_waitcnt lgkmcnt(6)
	v_mfma_f32_16x16x32_bf16 v[20:23], v[220:223], v[168:171], v[20:23]
	s_waitcnt vmcnt(13)
	ds_write_b128 v213, v[100:103] offset:32256
	global_load_dwordx4 v[92:95], v[214:215], off offset:1536
	v_mfma_f32_16x16x32_bf16 v[28:31], v[224:227], v[168:171], v[28:31]
	v_mfma_f32_16x16x32_bf16 v[4:7], v[228:231], v[168:171], v[4:7]
	global_load_dwordx4 v[96:99], v[236:237], off offset:1536
	s_waitcnt lgkmcnt(5)
	v_mfma_f32_16x16x32_bf16 v[44:47], v[232:235], v[160:163], v[44:47]
	v_mfma_f32_16x16x32_bf16 v[48:51], v[232:235], v[164:167], v[48:51]
	global_load_dwordx4 v[100:103], v[238:239], off offset:1536
	v_mfma_f32_16x16x32_bf16 v[12:15], v[232:235], v[168:171], v[12:15]
	s_waitcnt lgkmcnt(4)
	v_mfma_f32_16x16x32_bf16 v[24:27], v[220:223], v[172:175], v[24:27]
	v_mfma_f32_16x16x32_bf16 v[32:35], v[224:227], v[172:175], v[32:35]
	v_mfma_f32_16x16x32_bf16 v[8:11], v[228:231], v[172:175], v[8:11]
	v_mfma_f32_16x16x32_bf16 v[16:19], v[232:235], v[172:175], v[16:19]
	s_setprio 0
	s_waitcnt lgkmcnt(0)
	s_barrier
	ds_read_b128 v[144:147], v241
	ds_read_b128 v[176:179], v242 offset:18432
	ds_read_b128 v[180:183], v242 offset:20736
	ds_read_b128 v[148:151], v241 offset:2304
	ds_read_b128 v[184:187], v242 offset:23040
	ds_read_b128 v[152:155], v241 offset:4608
	ds_read_b128 v[216:219], v242 offset:25344
	ds_read_b128 v[156:159], v241 offset:6912
	s_setprio 1
	s_waitcnt lgkmcnt(6)
	v_mfma_f32_16x16x32_bf16 v[52:55], v[176:179], v[144:147], v[52:55]
	s_waitcnt vmcnt(15)
	ds_write_b128 v240, v[108:111]
	s_waitcnt lgkmcnt(6)
	v_mfma_f32_16x16x32_bf16 v[60:63], v[180:183], v[144:147], v[60:63]
	s_waitcnt lgkmcnt(5)
	v_mfma_f32_16x16x32_bf16 v[56:59], v[176:179], v[148:151], v[56:59]
	s_waitcnt vmcnt(14)
	ds_write_b128 v240, v[112:115] offset:4608
	v_mfma_f32_16x16x32_bf16 v[64:67], v[180:183], v[148:151], v[64:67]
	ds_read_b128 v[160:163], v241 offset:64
	s_waitcnt lgkmcnt(6)
	v_mfma_f32_16x16x32_bf16 v[36:39], v[184:187], v[144:147], v[36:39]
	ds_read_b128 v[220:223], v242 offset:18496
	s_waitcnt vmcnt(13)
	ds_write_b128 v240, v[116:119] offset:9216
	global_load_dwordx4 v[108:111], v[72:73], off offset:1664
	v_mfma_f32_16x16x32_bf16 v[40:43], v[184:187], v[148:151], v[40:43]
	ds_read_b128 v[224:227], v242 offset:20800
	s_waitcnt lgkmcnt(8)
	v_mfma_f32_16x16x32_bf16 v[20:23], v[176:179], v[152:155], v[20:23]
	ds_read_b128 v[164:167], v241 offset:2368
	v_mfma_f32_16x16x32_bf16 v[28:31], v[180:183], v[152:155], v[28:31]
	v_mfma_f32_16x16x32_bf16 v[4:7], v[184:187], v[152:155], v[4:7]
	ds_read_b128 v[228:231], v242 offset:23104
	s_waitcnt lgkmcnt(9)
	v_mfma_f32_16x16x32_bf16 v[44:47], v[216:219], v[144:147], v[44:47]
	ds_read_b128 v[168:171], v241 offset:4672
	v_mfma_f32_16x16x32_bf16 v[48:51], v[216:219], v[148:151], v[48:51]
	s_waitcnt vmcnt(13)
	ds_write_b128 v240, v[120:123] offset:13824
	global_load_dwordx4 v[112:115], v[74:75], off offset:1664
	v_mfma_f32_16x16x32_bf16 v[12:15], v[216:219], v[152:155], v[12:15]
	ds_read_b128 v[232:235], v242 offset:25408
	s_waitcnt lgkmcnt(11)
	v_mfma_f32_16x16x32_bf16 v[24:27], v[176:179], v[156:159], v[24:27]
	ds_read_b128 v[172:175], v241 offset:6976
	s_waitcnt vmcnt(13)
	ds_write_b128 v240, v[124:127] offset:18432
	global_load_dwordx4 v[116:119], v[106:107], off offset:1664
	v_mfma_f32_16x16x32_bf16 v[32:35], v[180:183], v[156:159], v[32:35]
	v_mfma_f32_16x16x32_bf16 v[8:11], v[184:187], v[156:159], v[8:11]
	v_mfma_f32_16x16x32_bf16 v[16:19], v[216:219], v[156:159], v[16:19]
	s_waitcnt lgkmcnt(9)
	v_mfma_f32_16x16x32_bf16 v[52:55], v[220:223], v[160:163], v[52:55]
	s_waitcnt lgkmcnt(7)
	v_mfma_f32_16x16x32_bf16 v[60:63], v[224:227], v[160:163], v[60:63]
	s_waitcnt lgkmcnt(6)
	v_mfma_f32_16x16x32_bf16 v[56:59], v[220:223], v[164:167], v[56:59]
	s_waitcnt vmcnt(13)
	ds_write_b128 v240, v[128:131] offset:23040
	global_load_dwordx4 v[120:123], v[188:189], off offset:1664
	v_mfma_f32_16x16x32_bf16 v[64:67], v[224:227], v[164:167], v[64:67]
	s_waitcnt lgkmcnt(6)
	v_mfma_f32_16x16x32_bf16 v[36:39], v[228:231], v[160:163], v[36:39]
	s_waitcnt vmcnt(13)
	ds_write_b128 v240, v[136:139] offset:27648
	global_load_dwordx4 v[124:127], v[104:105], off offset:1664
	v_mfma_f32_16x16x32_bf16 v[40:43], v[228:231], v[164:167], v[40:43]
	s_waitcnt lgkmcnt(6)
	v_mfma_f32_16x16x32_bf16 v[20:23], v[220:223], v[168:171], v[20:23]
	s_waitcnt vmcnt(13)
	ds_write_b128 v240, v[140:143] offset:32256
	global_load_dwordx4 v[128:131], v[214:215], off offset:1664
	v_mfma_f32_16x16x32_bf16 v[28:31], v[224:227], v[168:171], v[28:31]
	v_mfma_f32_16x16x32_bf16 v[4:7], v[228:231], v[168:171], v[4:7]
	global_load_dwordx4 v[136:139], v[236:237], off offset:1664
	s_waitcnt lgkmcnt(5)
	v_mfma_f32_16x16x32_bf16 v[44:47], v[232:235], v[160:163], v[44:47]
	v_mfma_f32_16x16x32_bf16 v[48:51], v[232:235], v[164:167], v[48:51]
	global_load_dwordx4 v[140:143], v[238:239], off offset:1664
	v_mfma_f32_16x16x32_bf16 v[12:15], v[232:235], v[168:171], v[12:15]
	s_waitcnt lgkmcnt(4)
	v_mfma_f32_16x16x32_bf16 v[24:27], v[220:223], v[172:175], v[24:27]
	v_mfma_f32_16x16x32_bf16 v[32:35], v[224:227], v[172:175], v[32:35]
	v_mfma_f32_16x16x32_bf16 v[8:11], v[228:231], v[172:175], v[8:11]
	v_mfma_f32_16x16x32_bf16 v[16:19], v[232:235], v[172:175], v[16:19]
	s_setprio 0
	s_waitcnt lgkmcnt(0)
	s_barrier
	ds_read_b128 v[144:147], v241 offset:36864
	ds_read_b128 v[176:179], v242 offset:55296
	ds_read_b128 v[180:183], v242 offset:57600
	ds_read_b128 v[148:151], v241 offset:39168
	ds_read_b128 v[184:187], v242 offset:59904
	ds_read_b128 v[152:155], v241 offset:41472
	ds_read_b128 v[216:219], v242 offset:62208
	ds_read_b128 v[156:159], v241 offset:43776
	s_setprio 1
	s_waitcnt lgkmcnt(6)
	v_mfma_f32_16x16x32_bf16 v[52:55], v[176:179], v[144:147], v[52:55]
	s_waitcnt vmcnt(15)
	ds_write_b128 v213, v[68:71]
	s_waitcnt lgkmcnt(6)
	v_mfma_f32_16x16x32_bf16 v[60:63], v[180:183], v[144:147], v[60:63]
	s_waitcnt lgkmcnt(5)
	v_mfma_f32_16x16x32_bf16 v[56:59], v[176:179], v[148:151], v[56:59]
	s_waitcnt vmcnt(14)
	ds_write_b128 v213, v[76:79] offset:4608
	v_mfma_f32_16x16x32_bf16 v[64:67], v[180:183], v[148:151], v[64:67]
	ds_read_b128 v[160:163], v241 offset:36928
	s_waitcnt lgkmcnt(6)
	v_mfma_f32_16x16x32_bf16 v[36:39], v[184:187], v[144:147], v[36:39]
	ds_read_b128 v[220:223], v242 offset:55360
	s_waitcnt vmcnt(13)
	ds_write_b128 v213, v[80:83] offset:9216
	global_load_dwordx4 v[68:71], v[72:73], off offset:1792
	v_mfma_f32_16x16x32_bf16 v[40:43], v[184:187], v[148:151], v[40:43]
	ds_read_b128 v[224:227], v242 offset:57664
	s_waitcnt lgkmcnt(8)
	v_mfma_f32_16x16x32_bf16 v[20:23], v[176:179], v[152:155], v[20:23]
	ds_read_b128 v[164:167], v241 offset:39232
	v_mfma_f32_16x16x32_bf16 v[28:31], v[180:183], v[152:155], v[28:31]
	v_mfma_f32_16x16x32_bf16 v[4:7], v[184:187], v[152:155], v[4:7]
	ds_read_b128 v[228:231], v242 offset:59968
	s_waitcnt lgkmcnt(9)
	v_mfma_f32_16x16x32_bf16 v[44:47], v[216:219], v[144:147], v[44:47]
	ds_read_b128 v[168:171], v241 offset:41536
	v_mfma_f32_16x16x32_bf16 v[48:51], v[216:219], v[148:151], v[48:51]
	s_waitcnt vmcnt(13)
	ds_write_b128 v213, v[84:87] offset:13824
	global_load_dwordx4 v[76:79], v[74:75], off offset:1792
	v_mfma_f32_16x16x32_bf16 v[12:15], v[216:219], v[152:155], v[12:15]
	ds_read_b128 v[232:235], v242 offset:62272
	s_waitcnt lgkmcnt(11)
	v_mfma_f32_16x16x32_bf16 v[24:27], v[176:179], v[156:159], v[24:27]
	ds_read_b128 v[172:175], v241 offset:43840
	s_waitcnt vmcnt(13)
	ds_write_b128 v213, v[88:91] offset:18432
	global_load_dwordx4 v[80:83], v[106:107], off offset:1792
	v_mfma_f32_16x16x32_bf16 v[32:35], v[180:183], v[156:159], v[32:35]
	v_mfma_f32_16x16x32_bf16 v[8:11], v[184:187], v[156:159], v[8:11]
	v_mfma_f32_16x16x32_bf16 v[16:19], v[216:219], v[156:159], v[16:19]
	s_waitcnt lgkmcnt(9)
	v_mfma_f32_16x16x32_bf16 v[52:55], v[220:223], v[160:163], v[52:55]
	s_waitcnt lgkmcnt(7)
	v_mfma_f32_16x16x32_bf16 v[60:63], v[224:227], v[160:163], v[60:63]
	s_waitcnt lgkmcnt(6)
	v_mfma_f32_16x16x32_bf16 v[56:59], v[220:223], v[164:167], v[56:59]
	s_waitcnt vmcnt(13)
	ds_write_b128 v213, v[92:95] offset:23040
	global_load_dwordx4 v[84:87], v[188:189], off offset:1792
	v_mfma_f32_16x16x32_bf16 v[64:67], v[224:227], v[164:167], v[64:67]
	s_waitcnt lgkmcnt(6)
	v_mfma_f32_16x16x32_bf16 v[36:39], v[228:231], v[160:163], v[36:39]
	s_waitcnt vmcnt(13)
	ds_write_b128 v213, v[96:99] offset:27648
	global_load_dwordx4 v[88:91], v[104:105], off offset:1792
	v_mfma_f32_16x16x32_bf16 v[40:43], v[228:231], v[164:167], v[40:43]
	s_waitcnt lgkmcnt(6)
	v_mfma_f32_16x16x32_bf16 v[20:23], v[220:223], v[168:171], v[20:23]
	s_waitcnt vmcnt(13)
	ds_write_b128 v213, v[100:103] offset:32256
	global_load_dwordx4 v[92:95], v[214:215], off offset:1792
	v_mfma_f32_16x16x32_bf16 v[28:31], v[224:227], v[168:171], v[28:31]
	v_mfma_f32_16x16x32_bf16 v[4:7], v[228:231], v[168:171], v[4:7]
	global_load_dwordx4 v[96:99], v[236:237], off offset:1792
	s_waitcnt lgkmcnt(5)
	v_mfma_f32_16x16x32_bf16 v[44:47], v[232:235], v[160:163], v[44:47]
	v_mfma_f32_16x16x32_bf16 v[48:51], v[232:235], v[164:167], v[48:51]
	global_load_dwordx4 v[100:103], v[238:239], off offset:1792
	v_mfma_f32_16x16x32_bf16 v[12:15], v[232:235], v[168:171], v[12:15]
	s_waitcnt lgkmcnt(4)
	v_mfma_f32_16x16x32_bf16 v[24:27], v[220:223], v[172:175], v[24:27]
	v_mfma_f32_16x16x32_bf16 v[32:35], v[224:227], v[172:175], v[32:35]
	v_mfma_f32_16x16x32_bf16 v[8:11], v[228:231], v[172:175], v[8:11]
	v_mfma_f32_16x16x32_bf16 v[16:19], v[232:235], v[172:175], v[16:19]
	s_setprio 0
	s_waitcnt lgkmcnt(0)
	s_barrier
	ds_read_b128 v[144:147], v241
	ds_read_b128 v[176:179], v242 offset:18432
	ds_read_b128 v[180:183], v242 offset:20736
	ds_read_b128 v[148:151], v241 offset:2304
	ds_read_b128 v[184:187], v242 offset:23040
	ds_read_b128 v[152:155], v241 offset:4608
	ds_read_b128 v[216:219], v242 offset:25344
	ds_read_b128 v[156:159], v241 offset:6912
	s_setprio 1
	s_waitcnt lgkmcnt(6)
	v_mfma_f32_16x16x32_bf16 v[52:55], v[176:179], v[144:147], v[52:55]
	s_waitcnt vmcnt(15)
	ds_write_b128 v240, v[108:111]
	s_waitcnt lgkmcnt(6)
	v_mfma_f32_16x16x32_bf16 v[60:63], v[180:183], v[144:147], v[60:63]
	s_waitcnt lgkmcnt(5)
	v_mfma_f32_16x16x32_bf16 v[56:59], v[176:179], v[148:151], v[56:59]
	s_waitcnt vmcnt(14)
	ds_write_b128 v240, v[112:115] offset:4608
	v_mfma_f32_16x16x32_bf16 v[64:67], v[180:183], v[148:151], v[64:67]
	ds_read_b128 v[160:163], v241 offset:64
	s_waitcnt lgkmcnt(6)
	v_mfma_f32_16x16x32_bf16 v[36:39], v[184:187], v[144:147], v[36:39]
	ds_read_b128 v[220:223], v242 offset:18496
	s_waitcnt vmcnt(13)
	ds_write_b128 v240, v[116:119] offset:9216
	global_load_dwordx4 v[108:111], v[72:73], off offset:1920
	v_mfma_f32_16x16x32_bf16 v[40:43], v[184:187], v[148:151], v[40:43]
	ds_read_b128 v[224:227], v242 offset:20800
	s_waitcnt lgkmcnt(8)
	v_mfma_f32_16x16x32_bf16 v[20:23], v[176:179], v[152:155], v[20:23]
	ds_read_b128 v[164:167], v241 offset:2368
	v_mfma_f32_16x16x32_bf16 v[28:31], v[180:183], v[152:155], v[28:31]
	v_mfma_f32_16x16x32_bf16 v[4:7], v[184:187], v[152:155], v[4:7]
	ds_read_b128 v[228:231], v242 offset:23104
	s_waitcnt lgkmcnt(9)
	v_mfma_f32_16x16x32_bf16 v[44:47], v[216:219], v[144:147], v[44:47]
	ds_read_b128 v[168:171], v241 offset:4672
	v_mfma_f32_16x16x32_bf16 v[48:51], v[216:219], v[148:151], v[48:51]
	s_waitcnt vmcnt(13)
	ds_write_b128 v240, v[120:123] offset:13824
	global_load_dwordx4 v[112:115], v[74:75], off offset:1920
	v_mfma_f32_16x16x32_bf16 v[12:15], v[216:219], v[152:155], v[12:15]
	ds_read_b128 v[232:235], v242 offset:25408
	s_waitcnt lgkmcnt(11)
	v_mfma_f32_16x16x32_bf16 v[24:27], v[176:179], v[156:159], v[24:27]
	ds_read_b128 v[172:175], v241 offset:6976
	s_waitcnt vmcnt(13)
	ds_write_b128 v240, v[124:127] offset:18432
	global_load_dwordx4 v[116:119], v[106:107], off offset:1920
	v_mfma_f32_16x16x32_bf16 v[32:35], v[180:183], v[156:159], v[32:35]
	v_mfma_f32_16x16x32_bf16 v[8:11], v[184:187], v[156:159], v[8:11]
	v_mfma_f32_16x16x32_bf16 v[16:19], v[216:219], v[156:159], v[16:19]
	s_waitcnt lgkmcnt(9)
	v_mfma_f32_16x16x32_bf16 v[52:55], v[220:223], v[160:163], v[52:55]
	s_waitcnt lgkmcnt(7)
	v_mfma_f32_16x16x32_bf16 v[60:63], v[224:227], v[160:163], v[60:63]
	s_waitcnt lgkmcnt(6)
	v_mfma_f32_16x16x32_bf16 v[56:59], v[220:223], v[164:167], v[56:59]
	s_waitcnt vmcnt(13)
	ds_write_b128 v240, v[128:131] offset:23040
	global_load_dwordx4 v[120:123], v[188:189], off offset:1920
	v_mfma_f32_16x16x32_bf16 v[64:67], v[224:227], v[164:167], v[64:67]
	s_waitcnt lgkmcnt(6)
	v_mfma_f32_16x16x32_bf16 v[36:39], v[228:231], v[160:163], v[36:39]
	s_waitcnt vmcnt(13)
	ds_write_b128 v240, v[136:139] offset:27648
	global_load_dwordx4 v[124:127], v[104:105], off offset:1920
	v_mfma_f32_16x16x32_bf16 v[40:43], v[228:231], v[164:167], v[40:43]
	s_waitcnt lgkmcnt(6)
	v_mfma_f32_16x16x32_bf16 v[20:23], v[220:223], v[168:171], v[20:23]
	s_waitcnt vmcnt(13)
	ds_write_b128 v240, v[140:143] offset:32256
	global_load_dwordx4 v[128:131], v[214:215], off offset:1920
	v_mfma_f32_16x16x32_bf16 v[28:31], v[224:227], v[168:171], v[28:31]
	v_mfma_f32_16x16x32_bf16 v[4:7], v[228:231], v[168:171], v[4:7]
	global_load_dwordx4 v[136:139], v[236:237], off offset:1920
	s_waitcnt lgkmcnt(5)
	v_mfma_f32_16x16x32_bf16 v[44:47], v[232:235], v[160:163], v[44:47]
	v_mfma_f32_16x16x32_bf16 v[48:51], v[232:235], v[164:167], v[48:51]
	global_load_dwordx4 v[140:143], v[238:239], off offset:1920
	v_mfma_f32_16x16x32_bf16 v[12:15], v[232:235], v[168:171], v[12:15]
	s_waitcnt lgkmcnt(4)
	v_mfma_f32_16x16x32_bf16 v[24:27], v[220:223], v[172:175], v[24:27]
	v_mfma_f32_16x16x32_bf16 v[32:35], v[224:227], v[172:175], v[32:35]
	v_mfma_f32_16x16x32_bf16 v[8:11], v[228:231], v[172:175], v[8:11]
	v_mfma_f32_16x16x32_bf16 v[16:19], v[232:235], v[172:175], v[16:19]
	s_setprio 0
	s_waitcnt lgkmcnt(0)
	s_barrier
	ds_read_b128 v[144:147], v241 offset:36864
	ds_read_b128 v[176:179], v242 offset:55296
	ds_read_b128 v[180:183], v242 offset:57600
	ds_read_b128 v[148:151], v241 offset:39168
	ds_read_b128 v[184:187], v242 offset:59904
	ds_read_b128 v[152:155], v241 offset:41472
	ds_read_b128 v[216:219], v242 offset:62208
	ds_read_b128 v[156:159], v241 offset:43776
	s_setprio 1
	s_waitcnt lgkmcnt(6)
	v_mfma_f32_16x16x32_bf16 v[52:55], v[176:179], v[144:147], v[52:55]
	s_waitcnt vmcnt(15)
	ds_write_b128 v213, v[68:71]
	s_waitcnt lgkmcnt(6)
	v_mfma_f32_16x16x32_bf16 v[60:63], v[180:183], v[144:147], v[60:63]
	s_waitcnt lgkmcnt(5)
	v_mfma_f32_16x16x32_bf16 v[56:59], v[176:179], v[148:151], v[56:59]
	s_waitcnt vmcnt(14)
	ds_write_b128 v213, v[76:79] offset:4608
	v_mfma_f32_16x16x32_bf16 v[64:67], v[180:183], v[148:151], v[64:67]
	ds_read_b128 v[160:163], v241 offset:36928
	s_waitcnt lgkmcnt(6)
	v_mfma_f32_16x16x32_bf16 v[36:39], v[184:187], v[144:147], v[36:39]
	ds_read_b128 v[220:223], v242 offset:55360
	s_waitcnt vmcnt(13)
	ds_write_b128 v213, v[80:83] offset:9216
	global_load_dwordx4 v[68:71], v[72:73], off offset:2048
	v_mfma_f32_16x16x32_bf16 v[40:43], v[184:187], v[148:151], v[40:43]
	ds_read_b128 v[224:227], v242 offset:57664
	s_waitcnt lgkmcnt(8)
	v_mfma_f32_16x16x32_bf16 v[20:23], v[176:179], v[152:155], v[20:23]
	ds_read_b128 v[164:167], v241 offset:39232
	v_mfma_f32_16x16x32_bf16 v[28:31], v[180:183], v[152:155], v[28:31]
	v_mfma_f32_16x16x32_bf16 v[4:7], v[184:187], v[152:155], v[4:7]
	ds_read_b128 v[228:231], v242 offset:59968
	s_waitcnt lgkmcnt(9)
	v_mfma_f32_16x16x32_bf16 v[44:47], v[216:219], v[144:147], v[44:47]
	ds_read_b128 v[168:171], v241 offset:41536
	v_mfma_f32_16x16x32_bf16 v[48:51], v[216:219], v[148:151], v[48:51]
	s_waitcnt vmcnt(13)
	ds_write_b128 v213, v[84:87] offset:13824
	global_load_dwordx4 v[76:79], v[74:75], off offset:2048
	v_mfma_f32_16x16x32_bf16 v[12:15], v[216:219], v[152:155], v[12:15]
	ds_read_b128 v[232:235], v242 offset:62272
	s_waitcnt lgkmcnt(11)
	v_mfma_f32_16x16x32_bf16 v[24:27], v[176:179], v[156:159], v[24:27]
	ds_read_b128 v[172:175], v241 offset:43840
	s_waitcnt vmcnt(13)
	ds_write_b128 v213, v[88:91] offset:18432
	global_load_dwordx4 v[80:83], v[106:107], off offset:2048
	v_mfma_f32_16x16x32_bf16 v[32:35], v[180:183], v[156:159], v[32:35]
	v_mfma_f32_16x16x32_bf16 v[8:11], v[184:187], v[156:159], v[8:11]
	v_mfma_f32_16x16x32_bf16 v[16:19], v[216:219], v[156:159], v[16:19]
	s_waitcnt lgkmcnt(9)
	v_mfma_f32_16x16x32_bf16 v[52:55], v[220:223], v[160:163], v[52:55]
	s_waitcnt lgkmcnt(7)
	v_mfma_f32_16x16x32_bf16 v[60:63], v[224:227], v[160:163], v[60:63]
	s_waitcnt lgkmcnt(6)
	v_mfma_f32_16x16x32_bf16 v[56:59], v[220:223], v[164:167], v[56:59]
	s_waitcnt vmcnt(13)
	ds_write_b128 v213, v[92:95] offset:23040
	global_load_dwordx4 v[84:87], v[188:189], off offset:2048
	v_mfma_f32_16x16x32_bf16 v[64:67], v[224:227], v[164:167], v[64:67]
	s_waitcnt lgkmcnt(6)
	v_mfma_f32_16x16x32_bf16 v[36:39], v[228:231], v[160:163], v[36:39]
	s_waitcnt vmcnt(13)
	ds_write_b128 v213, v[96:99] offset:27648
	global_load_dwordx4 v[88:91], v[104:105], off offset:2048
	v_mfma_f32_16x16x32_bf16 v[40:43], v[228:231], v[164:167], v[40:43]
	s_waitcnt lgkmcnt(6)
	v_mfma_f32_16x16x32_bf16 v[20:23], v[220:223], v[168:171], v[20:23]
	s_waitcnt vmcnt(13)
	ds_write_b128 v213, v[100:103] offset:32256
	global_load_dwordx4 v[92:95], v[214:215], off offset:2048
	v_mfma_f32_16x16x32_bf16 v[28:31], v[224:227], v[168:171], v[28:31]
	v_mfma_f32_16x16x32_bf16 v[4:7], v[228:231], v[168:171], v[4:7]
	global_load_dwordx4 v[96:99], v[236:237], off offset:2048
	s_waitcnt lgkmcnt(5)
	v_mfma_f32_16x16x32_bf16 v[44:47], v[232:235], v[160:163], v[44:47]
	v_mfma_f32_16x16x32_bf16 v[48:51], v[232:235], v[164:167], v[48:51]
	global_load_dwordx4 v[100:103], v[238:239], off offset:2048
	v_mfma_f32_16x16x32_bf16 v[12:15], v[232:235], v[168:171], v[12:15]
	s_waitcnt lgkmcnt(4)
	v_mfma_f32_16x16x32_bf16 v[24:27], v[220:223], v[172:175], v[24:27]
	v_mfma_f32_16x16x32_bf16 v[32:35], v[224:227], v[172:175], v[32:35]
	v_mfma_f32_16x16x32_bf16 v[8:11], v[228:231], v[172:175], v[8:11]
	v_mfma_f32_16x16x32_bf16 v[16:19], v[232:235], v[172:175], v[16:19]
	s_setprio 0
	s_waitcnt lgkmcnt(0)
	s_barrier
	ds_read_b128 v[144:147], v241
	ds_read_b128 v[176:179], v242 offset:18432
	ds_read_b128 v[180:183], v242 offset:20736
	ds_read_b128 v[148:151], v241 offset:2304
	ds_read_b128 v[184:187], v242 offset:23040
	ds_read_b128 v[152:155], v241 offset:4608
	ds_read_b128 v[216:219], v242 offset:25344
	ds_read_b128 v[156:159], v241 offset:6912
	s_setprio 1
	s_waitcnt lgkmcnt(6)
	v_mfma_f32_16x16x32_bf16 v[52:55], v[176:179], v[144:147], v[52:55]
	s_waitcnt vmcnt(15)
	ds_write_b128 v240, v[108:111]
	s_waitcnt lgkmcnt(6)
	v_mfma_f32_16x16x32_bf16 v[60:63], v[180:183], v[144:147], v[60:63]
	s_waitcnt lgkmcnt(5)
	v_mfma_f32_16x16x32_bf16 v[56:59], v[176:179], v[148:151], v[56:59]
	s_waitcnt vmcnt(14)
	ds_write_b128 v240, v[112:115] offset:4608
	v_mfma_f32_16x16x32_bf16 v[64:67], v[180:183], v[148:151], v[64:67]
	ds_read_b128 v[160:163], v241 offset:64
	s_waitcnt lgkmcnt(6)
	v_mfma_f32_16x16x32_bf16 v[36:39], v[184:187], v[144:147], v[36:39]
	ds_read_b128 v[220:223], v242 offset:18496
	s_waitcnt vmcnt(13)
	ds_write_b128 v240, v[116:119] offset:9216
	global_load_dwordx4 v[108:111], v[72:73], off offset:2176
	v_mfma_f32_16x16x32_bf16 v[40:43], v[184:187], v[148:151], v[40:43]
	ds_read_b128 v[224:227], v242 offset:20800
	s_waitcnt lgkmcnt(8)
	v_mfma_f32_16x16x32_bf16 v[20:23], v[176:179], v[152:155], v[20:23]
	ds_read_b128 v[164:167], v241 offset:2368
	v_mfma_f32_16x16x32_bf16 v[28:31], v[180:183], v[152:155], v[28:31]
	v_mfma_f32_16x16x32_bf16 v[4:7], v[184:187], v[152:155], v[4:7]
	ds_read_b128 v[228:231], v242 offset:23104
	s_waitcnt lgkmcnt(9)
	v_mfma_f32_16x16x32_bf16 v[44:47], v[216:219], v[144:147], v[44:47]
	ds_read_b128 v[168:171], v241 offset:4672
	v_mfma_f32_16x16x32_bf16 v[48:51], v[216:219], v[148:151], v[48:51]
	s_waitcnt vmcnt(13)
	ds_write_b128 v240, v[120:123] offset:13824
	global_load_dwordx4 v[112:115], v[74:75], off offset:2176
	v_mfma_f32_16x16x32_bf16 v[12:15], v[216:219], v[152:155], v[12:15]
	ds_read_b128 v[232:235], v242 offset:25408
	s_waitcnt lgkmcnt(11)
	v_mfma_f32_16x16x32_bf16 v[24:27], v[176:179], v[156:159], v[24:27]
	ds_read_b128 v[172:175], v241 offset:6976
	s_waitcnt vmcnt(13)
	ds_write_b128 v240, v[124:127] offset:18432
	global_load_dwordx4 v[116:119], v[106:107], off offset:2176
	v_mfma_f32_16x16x32_bf16 v[32:35], v[180:183], v[156:159], v[32:35]
	v_mfma_f32_16x16x32_bf16 v[8:11], v[184:187], v[156:159], v[8:11]
	v_mfma_f32_16x16x32_bf16 v[16:19], v[216:219], v[156:159], v[16:19]
	s_waitcnt lgkmcnt(9)
	v_mfma_f32_16x16x32_bf16 v[52:55], v[220:223], v[160:163], v[52:55]
	s_waitcnt lgkmcnt(7)
	v_mfma_f32_16x16x32_bf16 v[60:63], v[224:227], v[160:163], v[60:63]
	s_waitcnt lgkmcnt(6)
	v_mfma_f32_16x16x32_bf16 v[56:59], v[220:223], v[164:167], v[56:59]
	s_waitcnt vmcnt(13)
	ds_write_b128 v240, v[128:131] offset:23040
	global_load_dwordx4 v[120:123], v[188:189], off offset:2176
	v_mfma_f32_16x16x32_bf16 v[64:67], v[224:227], v[164:167], v[64:67]
	s_waitcnt lgkmcnt(6)
	v_mfma_f32_16x16x32_bf16 v[36:39], v[228:231], v[160:163], v[36:39]
	s_waitcnt vmcnt(13)
	ds_write_b128 v240, v[136:139] offset:27648
	global_load_dwordx4 v[124:127], v[104:105], off offset:2176
	v_mfma_f32_16x16x32_bf16 v[40:43], v[228:231], v[164:167], v[40:43]
	s_waitcnt lgkmcnt(6)
	v_mfma_f32_16x16x32_bf16 v[20:23], v[220:223], v[168:171], v[20:23]
	s_waitcnt vmcnt(13)
	ds_write_b128 v240, v[140:143] offset:32256
	global_load_dwordx4 v[128:131], v[214:215], off offset:2176
	v_mfma_f32_16x16x32_bf16 v[28:31], v[224:227], v[168:171], v[28:31]
	v_mfma_f32_16x16x32_bf16 v[4:7], v[228:231], v[168:171], v[4:7]
	global_load_dwordx4 v[136:139], v[236:237], off offset:2176
	s_waitcnt lgkmcnt(5)
	v_mfma_f32_16x16x32_bf16 v[44:47], v[232:235], v[160:163], v[44:47]
	v_mfma_f32_16x16x32_bf16 v[48:51], v[232:235], v[164:167], v[48:51]
	global_load_dwordx4 v[140:143], v[238:239], off offset:2176
	v_mfma_f32_16x16x32_bf16 v[12:15], v[232:235], v[168:171], v[12:15]
	s_waitcnt lgkmcnt(4)
	v_mfma_f32_16x16x32_bf16 v[24:27], v[220:223], v[172:175], v[24:27]
	v_mfma_f32_16x16x32_bf16 v[32:35], v[224:227], v[172:175], v[32:35]
	v_mfma_f32_16x16x32_bf16 v[8:11], v[228:231], v[172:175], v[8:11]
	v_mfma_f32_16x16x32_bf16 v[16:19], v[232:235], v[172:175], v[16:19]
	s_setprio 0
	s_waitcnt lgkmcnt(0)
	s_barrier
	ds_read_b128 v[144:147], v241 offset:36864
	ds_read_b128 v[176:179], v242 offset:55296
	ds_read_b128 v[180:183], v242 offset:57600
	ds_read_b128 v[148:151], v241 offset:39168
	ds_read_b128 v[184:187], v242 offset:59904
	ds_read_b128 v[152:155], v241 offset:41472
	ds_read_b128 v[216:219], v242 offset:62208
	ds_read_b128 v[156:159], v241 offset:43776
	s_setprio 1
	s_waitcnt lgkmcnt(6)
	v_mfma_f32_16x16x32_bf16 v[52:55], v[176:179], v[144:147], v[52:55]
	s_waitcnt vmcnt(15)
	ds_write_b128 v213, v[68:71]
	s_waitcnt lgkmcnt(6)
	v_mfma_f32_16x16x32_bf16 v[60:63], v[180:183], v[144:147], v[60:63]
	s_waitcnt lgkmcnt(5)
	v_mfma_f32_16x16x32_bf16 v[56:59], v[176:179], v[148:151], v[56:59]
	s_waitcnt vmcnt(14)
	ds_write_b128 v213, v[76:79] offset:4608
	v_mfma_f32_16x16x32_bf16 v[64:67], v[180:183], v[148:151], v[64:67]
	ds_read_b128 v[160:163], v241 offset:36928
	s_waitcnt lgkmcnt(6)
	v_mfma_f32_16x16x32_bf16 v[36:39], v[184:187], v[144:147], v[36:39]
	ds_read_b128 v[220:223], v242 offset:55360
	s_waitcnt vmcnt(13)
	ds_write_b128 v213, v[80:83] offset:9216
	global_load_dwordx4 v[68:71], v[72:73], off offset:2304
	v_mfma_f32_16x16x32_bf16 v[40:43], v[184:187], v[148:151], v[40:43]
	ds_read_b128 v[224:227], v242 offset:57664
	s_waitcnt lgkmcnt(8)
	v_mfma_f32_16x16x32_bf16 v[20:23], v[176:179], v[152:155], v[20:23]
	ds_read_b128 v[164:167], v241 offset:39232
	v_mfma_f32_16x16x32_bf16 v[28:31], v[180:183], v[152:155], v[28:31]
	v_mfma_f32_16x16x32_bf16 v[4:7], v[184:187], v[152:155], v[4:7]
	ds_read_b128 v[228:231], v242 offset:59968
	s_waitcnt lgkmcnt(9)
	v_mfma_f32_16x16x32_bf16 v[44:47], v[216:219], v[144:147], v[44:47]
	ds_read_b128 v[168:171], v241 offset:41536
	v_mfma_f32_16x16x32_bf16 v[48:51], v[216:219], v[148:151], v[48:51]
	s_waitcnt vmcnt(13)
	ds_write_b128 v213, v[84:87] offset:13824
	global_load_dwordx4 v[76:79], v[74:75], off offset:2304
	v_mfma_f32_16x16x32_bf16 v[12:15], v[216:219], v[152:155], v[12:15]
	ds_read_b128 v[232:235], v242 offset:62272
	s_waitcnt lgkmcnt(11)
	v_mfma_f32_16x16x32_bf16 v[24:27], v[176:179], v[156:159], v[24:27]
	ds_read_b128 v[172:175], v241 offset:43840
	s_waitcnt vmcnt(13)
	ds_write_b128 v213, v[88:91] offset:18432
	global_load_dwordx4 v[80:83], v[106:107], off offset:2304
	v_mfma_f32_16x16x32_bf16 v[32:35], v[180:183], v[156:159], v[32:35]
	v_mfma_f32_16x16x32_bf16 v[8:11], v[184:187], v[156:159], v[8:11]
	v_mfma_f32_16x16x32_bf16 v[16:19], v[216:219], v[156:159], v[16:19]
	s_waitcnt lgkmcnt(9)
	v_mfma_f32_16x16x32_bf16 v[52:55], v[220:223], v[160:163], v[52:55]
	s_waitcnt lgkmcnt(7)
	v_mfma_f32_16x16x32_bf16 v[60:63], v[224:227], v[160:163], v[60:63]
	s_waitcnt lgkmcnt(6)
	v_mfma_f32_16x16x32_bf16 v[56:59], v[220:223], v[164:167], v[56:59]
	s_waitcnt vmcnt(13)
	ds_write_b128 v213, v[92:95] offset:23040
	global_load_dwordx4 v[84:87], v[188:189], off offset:2304
	v_mfma_f32_16x16x32_bf16 v[64:67], v[224:227], v[164:167], v[64:67]
	s_waitcnt lgkmcnt(6)
	v_mfma_f32_16x16x32_bf16 v[36:39], v[228:231], v[160:163], v[36:39]
	s_waitcnt vmcnt(13)
	ds_write_b128 v213, v[96:99] offset:27648
	global_load_dwordx4 v[88:91], v[104:105], off offset:2304
	v_mfma_f32_16x16x32_bf16 v[40:43], v[228:231], v[164:167], v[40:43]
	s_waitcnt lgkmcnt(6)
	v_mfma_f32_16x16x32_bf16 v[20:23], v[220:223], v[168:171], v[20:23]
	s_waitcnt vmcnt(13)
	ds_write_b128 v213, v[100:103] offset:32256
	global_load_dwordx4 v[92:95], v[214:215], off offset:2304
	v_mfma_f32_16x16x32_bf16 v[28:31], v[224:227], v[168:171], v[28:31]
	v_mfma_f32_16x16x32_bf16 v[4:7], v[228:231], v[168:171], v[4:7]
	global_load_dwordx4 v[96:99], v[236:237], off offset:2304
	s_waitcnt lgkmcnt(5)
	v_mfma_f32_16x16x32_bf16 v[44:47], v[232:235], v[160:163], v[44:47]
	v_mfma_f32_16x16x32_bf16 v[48:51], v[232:235], v[164:167], v[48:51]
	global_load_dwordx4 v[100:103], v[238:239], off offset:2304
	v_mfma_f32_16x16x32_bf16 v[12:15], v[232:235], v[168:171], v[12:15]
	s_waitcnt lgkmcnt(4)
	v_mfma_f32_16x16x32_bf16 v[24:27], v[220:223], v[172:175], v[24:27]
	v_mfma_f32_16x16x32_bf16 v[32:35], v[224:227], v[172:175], v[32:35]
	v_mfma_f32_16x16x32_bf16 v[8:11], v[228:231], v[172:175], v[8:11]
	v_mfma_f32_16x16x32_bf16 v[16:19], v[232:235], v[172:175], v[16:19]
	s_setprio 0
	s_waitcnt lgkmcnt(0)
	s_barrier
	ds_read_b128 v[144:147], v241
	ds_read_b128 v[176:179], v242 offset:18432
	ds_read_b128 v[180:183], v242 offset:20736
	ds_read_b128 v[148:151], v241 offset:2304
	ds_read_b128 v[184:187], v242 offset:23040
	ds_read_b128 v[152:155], v241 offset:4608
	ds_read_b128 v[216:219], v242 offset:25344
	ds_read_b128 v[156:159], v241 offset:6912
	s_setprio 1
	s_waitcnt lgkmcnt(6)
	v_mfma_f32_16x16x32_bf16 v[52:55], v[176:179], v[144:147], v[52:55]
	s_waitcnt vmcnt(15)
	ds_write_b128 v240, v[108:111]
	s_waitcnt lgkmcnt(6)
	v_mfma_f32_16x16x32_bf16 v[60:63], v[180:183], v[144:147], v[60:63]
	s_waitcnt lgkmcnt(5)
	v_mfma_f32_16x16x32_bf16 v[56:59], v[176:179], v[148:151], v[56:59]
	s_waitcnt vmcnt(14)
	ds_write_b128 v240, v[112:115] offset:4608
	v_mfma_f32_16x16x32_bf16 v[64:67], v[180:183], v[148:151], v[64:67]
	ds_read_b128 v[160:163], v241 offset:64
	s_waitcnt lgkmcnt(6)
	v_mfma_f32_16x16x32_bf16 v[36:39], v[184:187], v[144:147], v[36:39]
	ds_read_b128 v[220:223], v242 offset:18496
	s_waitcnt vmcnt(13)
	ds_write_b128 v240, v[116:119] offset:9216
	global_load_dwordx4 v[108:111], v[72:73], off offset:2432
	v_mfma_f32_16x16x32_bf16 v[40:43], v[184:187], v[148:151], v[40:43]
	ds_read_b128 v[224:227], v242 offset:20800
	s_waitcnt lgkmcnt(8)
	v_mfma_f32_16x16x32_bf16 v[20:23], v[176:179], v[152:155], v[20:23]
	ds_read_b128 v[164:167], v241 offset:2368
	v_mfma_f32_16x16x32_bf16 v[28:31], v[180:183], v[152:155], v[28:31]
	v_mfma_f32_16x16x32_bf16 v[4:7], v[184:187], v[152:155], v[4:7]
	ds_read_b128 v[228:231], v242 offset:23104
	s_waitcnt lgkmcnt(9)
	v_mfma_f32_16x16x32_bf16 v[44:47], v[216:219], v[144:147], v[44:47]
	ds_read_b128 v[168:171], v241 offset:4672
	v_mfma_f32_16x16x32_bf16 v[48:51], v[216:219], v[148:151], v[48:51]
	s_waitcnt vmcnt(13)
	ds_write_b128 v240, v[120:123] offset:13824
	global_load_dwordx4 v[112:115], v[74:75], off offset:2432
	v_mfma_f32_16x16x32_bf16 v[12:15], v[216:219], v[152:155], v[12:15]
	ds_read_b128 v[232:235], v242 offset:25408
	s_waitcnt lgkmcnt(11)
	v_mfma_f32_16x16x32_bf16 v[24:27], v[176:179], v[156:159], v[24:27]
	ds_read_b128 v[172:175], v241 offset:6976
	s_waitcnt vmcnt(13)
	ds_write_b128 v240, v[124:127] offset:18432
	global_load_dwordx4 v[116:119], v[106:107], off offset:2432
	v_mfma_f32_16x16x32_bf16 v[32:35], v[180:183], v[156:159], v[32:35]
	v_mfma_f32_16x16x32_bf16 v[8:11], v[184:187], v[156:159], v[8:11]
	v_mfma_f32_16x16x32_bf16 v[16:19], v[216:219], v[156:159], v[16:19]
	s_waitcnt lgkmcnt(9)
	v_mfma_f32_16x16x32_bf16 v[52:55], v[220:223], v[160:163], v[52:55]
	s_waitcnt lgkmcnt(7)
	v_mfma_f32_16x16x32_bf16 v[60:63], v[224:227], v[160:163], v[60:63]
	s_waitcnt lgkmcnt(6)
	v_mfma_f32_16x16x32_bf16 v[56:59], v[220:223], v[164:167], v[56:59]
	s_waitcnt vmcnt(13)
	ds_write_b128 v240, v[128:131] offset:23040
	global_load_dwordx4 v[120:123], v[188:189], off offset:2432
	v_mfma_f32_16x16x32_bf16 v[64:67], v[224:227], v[164:167], v[64:67]
	s_waitcnt lgkmcnt(6)
	v_mfma_f32_16x16x32_bf16 v[36:39], v[228:231], v[160:163], v[36:39]
	s_waitcnt vmcnt(13)
	ds_write_b128 v240, v[136:139] offset:27648
	global_load_dwordx4 v[124:127], v[104:105], off offset:2432
	v_mfma_f32_16x16x32_bf16 v[40:43], v[228:231], v[164:167], v[40:43]
	s_waitcnt lgkmcnt(6)
	v_mfma_f32_16x16x32_bf16 v[20:23], v[220:223], v[168:171], v[20:23]
	s_waitcnt vmcnt(13)
	ds_write_b128 v240, v[140:143] offset:32256
	global_load_dwordx4 v[128:131], v[214:215], off offset:2432
	v_mfma_f32_16x16x32_bf16 v[28:31], v[224:227], v[168:171], v[28:31]
	v_mfma_f32_16x16x32_bf16 v[4:7], v[228:231], v[168:171], v[4:7]
	global_load_dwordx4 v[136:139], v[236:237], off offset:2432
	s_waitcnt lgkmcnt(5)
	v_mfma_f32_16x16x32_bf16 v[44:47], v[232:235], v[160:163], v[44:47]
	v_mfma_f32_16x16x32_bf16 v[48:51], v[232:235], v[164:167], v[48:51]
	global_load_dwordx4 v[140:143], v[238:239], off offset:2432
	v_mfma_f32_16x16x32_bf16 v[12:15], v[232:235], v[168:171], v[12:15]
	s_waitcnt lgkmcnt(4)
	v_mfma_f32_16x16x32_bf16 v[24:27], v[220:223], v[172:175], v[24:27]
	v_mfma_f32_16x16x32_bf16 v[32:35], v[224:227], v[172:175], v[32:35]
	v_mfma_f32_16x16x32_bf16 v[8:11], v[228:231], v[172:175], v[8:11]
	v_mfma_f32_16x16x32_bf16 v[16:19], v[232:235], v[172:175], v[16:19]
	s_setprio 0
	s_waitcnt lgkmcnt(0)
	s_barrier
	ds_read_b128 v[144:147], v241 offset:36864
	ds_read_b128 v[176:179], v242 offset:55296
	ds_read_b128 v[180:183], v242 offset:57600
	ds_read_b128 v[148:151], v241 offset:39168
	ds_read_b128 v[184:187], v242 offset:59904
	ds_read_b128 v[152:155], v241 offset:41472
	ds_read_b128 v[216:219], v242 offset:62208
	ds_read_b128 v[156:159], v241 offset:43776
	s_setprio 1
	s_waitcnt lgkmcnt(6)
	v_mfma_f32_16x16x32_bf16 v[52:55], v[176:179], v[144:147], v[52:55]
	s_waitcnt vmcnt(15)
	ds_write_b128 v213, v[68:71]
	s_waitcnt lgkmcnt(6)
	v_mfma_f32_16x16x32_bf16 v[60:63], v[180:183], v[144:147], v[60:63]
	s_waitcnt lgkmcnt(5)
	v_mfma_f32_16x16x32_bf16 v[56:59], v[176:179], v[148:151], v[56:59]
	s_waitcnt vmcnt(14)
	ds_write_b128 v213, v[76:79] offset:4608
	v_mfma_f32_16x16x32_bf16 v[64:67], v[180:183], v[148:151], v[64:67]
	ds_read_b128 v[160:163], v241 offset:36928
	s_waitcnt lgkmcnt(6)
	v_mfma_f32_16x16x32_bf16 v[36:39], v[184:187], v[144:147], v[36:39]
	ds_read_b128 v[220:223], v242 offset:55360
	s_waitcnt vmcnt(13)
	ds_write_b128 v213, v[80:83] offset:9216
	global_load_dwordx4 v[68:71], v[72:73], off offset:2560
	v_mfma_f32_16x16x32_bf16 v[40:43], v[184:187], v[148:151], v[40:43]
	ds_read_b128 v[224:227], v242 offset:57664
	s_waitcnt lgkmcnt(8)
	v_mfma_f32_16x16x32_bf16 v[20:23], v[176:179], v[152:155], v[20:23]
	ds_read_b128 v[164:167], v241 offset:39232
	v_mfma_f32_16x16x32_bf16 v[28:31], v[180:183], v[152:155], v[28:31]
	v_mfma_f32_16x16x32_bf16 v[4:7], v[184:187], v[152:155], v[4:7]
	ds_read_b128 v[228:231], v242 offset:59968
	s_waitcnt lgkmcnt(9)
	v_mfma_f32_16x16x32_bf16 v[44:47], v[216:219], v[144:147], v[44:47]
	ds_read_b128 v[168:171], v241 offset:41536
	v_mfma_f32_16x16x32_bf16 v[48:51], v[216:219], v[148:151], v[48:51]
	s_waitcnt vmcnt(13)
	ds_write_b128 v213, v[84:87] offset:13824
	global_load_dwordx4 v[76:79], v[74:75], off offset:2560
	v_mfma_f32_16x16x32_bf16 v[12:15], v[216:219], v[152:155], v[12:15]
	ds_read_b128 v[232:235], v242 offset:62272
	s_waitcnt lgkmcnt(11)
	v_mfma_f32_16x16x32_bf16 v[24:27], v[176:179], v[156:159], v[24:27]
	ds_read_b128 v[172:175], v241 offset:43840
	s_waitcnt vmcnt(13)
	ds_write_b128 v213, v[88:91] offset:18432
	global_load_dwordx4 v[80:83], v[106:107], off offset:2560
	v_mfma_f32_16x16x32_bf16 v[32:35], v[180:183], v[156:159], v[32:35]
	v_mfma_f32_16x16x32_bf16 v[8:11], v[184:187], v[156:159], v[8:11]
	v_mfma_f32_16x16x32_bf16 v[16:19], v[216:219], v[156:159], v[16:19]
	s_waitcnt lgkmcnt(9)
	v_mfma_f32_16x16x32_bf16 v[52:55], v[220:223], v[160:163], v[52:55]
	s_waitcnt lgkmcnt(7)
	v_mfma_f32_16x16x32_bf16 v[60:63], v[224:227], v[160:163], v[60:63]
	s_waitcnt lgkmcnt(6)
	v_mfma_f32_16x16x32_bf16 v[56:59], v[220:223], v[164:167], v[56:59]
	s_waitcnt vmcnt(13)
	ds_write_b128 v213, v[92:95] offset:23040
	global_load_dwordx4 v[84:87], v[188:189], off offset:2560
	v_mfma_f32_16x16x32_bf16 v[64:67], v[224:227], v[164:167], v[64:67]
	s_waitcnt lgkmcnt(6)
	v_mfma_f32_16x16x32_bf16 v[36:39], v[228:231], v[160:163], v[36:39]
	s_waitcnt vmcnt(13)
	ds_write_b128 v213, v[96:99] offset:27648
	global_load_dwordx4 v[88:91], v[104:105], off offset:2560
	v_mfma_f32_16x16x32_bf16 v[40:43], v[228:231], v[164:167], v[40:43]
	s_waitcnt lgkmcnt(6)
	v_mfma_f32_16x16x32_bf16 v[20:23], v[220:223], v[168:171], v[20:23]
	s_waitcnt vmcnt(13)
	ds_write_b128 v213, v[100:103] offset:32256
	global_load_dwordx4 v[92:95], v[214:215], off offset:2560
	v_mfma_f32_16x16x32_bf16 v[28:31], v[224:227], v[168:171], v[28:31]
	v_mfma_f32_16x16x32_bf16 v[4:7], v[228:231], v[168:171], v[4:7]
	global_load_dwordx4 v[96:99], v[236:237], off offset:2560
	s_waitcnt lgkmcnt(5)
	v_mfma_f32_16x16x32_bf16 v[44:47], v[232:235], v[160:163], v[44:47]
	v_mfma_f32_16x16x32_bf16 v[48:51], v[232:235], v[164:167], v[48:51]
	global_load_dwordx4 v[100:103], v[238:239], off offset:2560
	v_mfma_f32_16x16x32_bf16 v[12:15], v[232:235], v[168:171], v[12:15]
	s_waitcnt lgkmcnt(4)
	v_mfma_f32_16x16x32_bf16 v[24:27], v[220:223], v[172:175], v[24:27]
	v_mfma_f32_16x16x32_bf16 v[32:35], v[224:227], v[172:175], v[32:35]
	v_mfma_f32_16x16x32_bf16 v[8:11], v[228:231], v[172:175], v[8:11]
	v_mfma_f32_16x16x32_bf16 v[16:19], v[232:235], v[172:175], v[16:19]
	s_setprio 0
	s_waitcnt lgkmcnt(0)
	s_barrier
	ds_read_b128 v[144:147], v241
	ds_read_b128 v[176:179], v242 offset:18432
	ds_read_b128 v[180:183], v242 offset:20736
	ds_read_b128 v[148:151], v241 offset:2304
	ds_read_b128 v[184:187], v242 offset:23040
	ds_read_b128 v[152:155], v241 offset:4608
	ds_read_b128 v[216:219], v242 offset:25344
	ds_read_b128 v[156:159], v241 offset:6912
	s_setprio 1
	s_waitcnt lgkmcnt(6)
	v_mfma_f32_16x16x32_bf16 v[52:55], v[176:179], v[144:147], v[52:55]
	s_waitcnt vmcnt(15)
	ds_write_b128 v240, v[108:111]
	s_waitcnt lgkmcnt(6)
	v_mfma_f32_16x16x32_bf16 v[60:63], v[180:183], v[144:147], v[60:63]
	s_waitcnt lgkmcnt(5)
	v_mfma_f32_16x16x32_bf16 v[56:59], v[176:179], v[148:151], v[56:59]
	s_waitcnt vmcnt(14)
	ds_write_b128 v240, v[112:115] offset:4608
	v_mfma_f32_16x16x32_bf16 v[64:67], v[180:183], v[148:151], v[64:67]
	ds_read_b128 v[160:163], v241 offset:64
	s_waitcnt lgkmcnt(6)
	v_mfma_f32_16x16x32_bf16 v[36:39], v[184:187], v[144:147], v[36:39]
	ds_read_b128 v[220:223], v242 offset:18496
	s_waitcnt vmcnt(13)
	ds_write_b128 v240, v[116:119] offset:9216
	global_load_dwordx4 v[108:111], v[72:73], off offset:2688
	v_mfma_f32_16x16x32_bf16 v[40:43], v[184:187], v[148:151], v[40:43]
	ds_read_b128 v[224:227], v242 offset:20800
	s_waitcnt lgkmcnt(8)
	v_mfma_f32_16x16x32_bf16 v[20:23], v[176:179], v[152:155], v[20:23]
	ds_read_b128 v[164:167], v241 offset:2368
	v_mfma_f32_16x16x32_bf16 v[28:31], v[180:183], v[152:155], v[28:31]
	v_mfma_f32_16x16x32_bf16 v[4:7], v[184:187], v[152:155], v[4:7]
	ds_read_b128 v[228:231], v242 offset:23104
	s_waitcnt lgkmcnt(9)
	v_mfma_f32_16x16x32_bf16 v[44:47], v[216:219], v[144:147], v[44:47]
	ds_read_b128 v[168:171], v241 offset:4672
	v_mfma_f32_16x16x32_bf16 v[48:51], v[216:219], v[148:151], v[48:51]
	s_waitcnt vmcnt(13)
	ds_write_b128 v240, v[120:123] offset:13824
	global_load_dwordx4 v[112:115], v[74:75], off offset:2688
	v_mfma_f32_16x16x32_bf16 v[12:15], v[216:219], v[152:155], v[12:15]
	ds_read_b128 v[232:235], v242 offset:25408
	s_waitcnt lgkmcnt(11)
	v_mfma_f32_16x16x32_bf16 v[24:27], v[176:179], v[156:159], v[24:27]
	ds_read_b128 v[172:175], v241 offset:6976
	s_waitcnt vmcnt(13)
	ds_write_b128 v240, v[124:127] offset:18432
	global_load_dwordx4 v[116:119], v[106:107], off offset:2688
	v_mfma_f32_16x16x32_bf16 v[32:35], v[180:183], v[156:159], v[32:35]
	v_mfma_f32_16x16x32_bf16 v[8:11], v[184:187], v[156:159], v[8:11]
	v_mfma_f32_16x16x32_bf16 v[16:19], v[216:219], v[156:159], v[16:19]
	s_waitcnt lgkmcnt(9)
	v_mfma_f32_16x16x32_bf16 v[52:55], v[220:223], v[160:163], v[52:55]
	s_waitcnt lgkmcnt(7)
	v_mfma_f32_16x16x32_bf16 v[60:63], v[224:227], v[160:163], v[60:63]
	s_waitcnt lgkmcnt(6)
	v_mfma_f32_16x16x32_bf16 v[56:59], v[220:223], v[164:167], v[56:59]
	s_waitcnt vmcnt(13)
	ds_write_b128 v240, v[128:131] offset:23040
	global_load_dwordx4 v[120:123], v[188:189], off offset:2688
	v_mfma_f32_16x16x32_bf16 v[64:67], v[224:227], v[164:167], v[64:67]
	s_waitcnt lgkmcnt(6)
	v_mfma_f32_16x16x32_bf16 v[36:39], v[228:231], v[160:163], v[36:39]
	s_waitcnt vmcnt(13)
	ds_write_b128 v240, v[136:139] offset:27648
	global_load_dwordx4 v[124:127], v[104:105], off offset:2688
	v_mfma_f32_16x16x32_bf16 v[40:43], v[228:231], v[164:167], v[40:43]
	s_waitcnt lgkmcnt(6)
	v_mfma_f32_16x16x32_bf16 v[20:23], v[220:223], v[168:171], v[20:23]
	s_waitcnt vmcnt(13)
	ds_write_b128 v240, v[140:143] offset:32256
	global_load_dwordx4 v[128:131], v[214:215], off offset:2688
	v_mfma_f32_16x16x32_bf16 v[28:31], v[224:227], v[168:171], v[28:31]
	v_mfma_f32_16x16x32_bf16 v[4:7], v[228:231], v[168:171], v[4:7]
	global_load_dwordx4 v[136:139], v[236:237], off offset:2688
	s_waitcnt lgkmcnt(5)
	v_mfma_f32_16x16x32_bf16 v[44:47], v[232:235], v[160:163], v[44:47]
	v_mfma_f32_16x16x32_bf16 v[48:51], v[232:235], v[164:167], v[48:51]
	global_load_dwordx4 v[140:143], v[238:239], off offset:2688
	v_mfma_f32_16x16x32_bf16 v[12:15], v[232:235], v[168:171], v[12:15]
	s_waitcnt lgkmcnt(4)
	v_mfma_f32_16x16x32_bf16 v[24:27], v[220:223], v[172:175], v[24:27]
	v_mfma_f32_16x16x32_bf16 v[32:35], v[224:227], v[172:175], v[32:35]
	v_mfma_f32_16x16x32_bf16 v[8:11], v[228:231], v[172:175], v[8:11]
	v_mfma_f32_16x16x32_bf16 v[16:19], v[232:235], v[172:175], v[16:19]
	s_setprio 0
	s_waitcnt lgkmcnt(0)
	s_barrier
	ds_read_b128 v[144:147], v241 offset:36864
	ds_read_b128 v[176:179], v242 offset:55296
	ds_read_b128 v[180:183], v242 offset:57600
	ds_read_b128 v[148:151], v241 offset:39168
	ds_read_b128 v[184:187], v242 offset:59904
	ds_read_b128 v[152:155], v241 offset:41472
	ds_read_b128 v[216:219], v242 offset:62208
	ds_read_b128 v[156:159], v241 offset:43776
	s_setprio 1
	s_waitcnt lgkmcnt(6)
	v_mfma_f32_16x16x32_bf16 v[52:55], v[176:179], v[144:147], v[52:55]
	s_waitcnt vmcnt(15)
	ds_write_b128 v213, v[68:71]
	s_waitcnt lgkmcnt(6)
	v_mfma_f32_16x16x32_bf16 v[60:63], v[180:183], v[144:147], v[60:63]
	s_waitcnt lgkmcnt(5)
	v_mfma_f32_16x16x32_bf16 v[56:59], v[176:179], v[148:151], v[56:59]
	s_waitcnt vmcnt(14)
	ds_write_b128 v213, v[76:79] offset:4608
	v_mfma_f32_16x16x32_bf16 v[64:67], v[180:183], v[148:151], v[64:67]
	ds_read_b128 v[160:163], v241 offset:36928
	s_waitcnt lgkmcnt(6)
	v_mfma_f32_16x16x32_bf16 v[36:39], v[184:187], v[144:147], v[36:39]
	ds_read_b128 v[220:223], v242 offset:55360
	s_waitcnt vmcnt(13)
	ds_write_b128 v213, v[80:83] offset:9216
	global_load_dwordx4 v[68:71], v[72:73], off offset:2816
	v_mfma_f32_16x16x32_bf16 v[40:43], v[184:187], v[148:151], v[40:43]
	ds_read_b128 v[224:227], v242 offset:57664
	s_waitcnt lgkmcnt(8)
	v_mfma_f32_16x16x32_bf16 v[20:23], v[176:179], v[152:155], v[20:23]
	ds_read_b128 v[164:167], v241 offset:39232
	v_mfma_f32_16x16x32_bf16 v[28:31], v[180:183], v[152:155], v[28:31]
	v_mfma_f32_16x16x32_bf16 v[4:7], v[184:187], v[152:155], v[4:7]
	ds_read_b128 v[228:231], v242 offset:59968
	s_waitcnt lgkmcnt(9)
	v_mfma_f32_16x16x32_bf16 v[44:47], v[216:219], v[144:147], v[44:47]
	ds_read_b128 v[168:171], v241 offset:41536
	v_mfma_f32_16x16x32_bf16 v[48:51], v[216:219], v[148:151], v[48:51]
	s_waitcnt vmcnt(13)
	ds_write_b128 v213, v[84:87] offset:13824
	global_load_dwordx4 v[76:79], v[74:75], off offset:2816
	v_mfma_f32_16x16x32_bf16 v[12:15], v[216:219], v[152:155], v[12:15]
	ds_read_b128 v[232:235], v242 offset:62272
	s_waitcnt lgkmcnt(11)
	v_mfma_f32_16x16x32_bf16 v[24:27], v[176:179], v[156:159], v[24:27]
	ds_read_b128 v[172:175], v241 offset:43840
	s_waitcnt vmcnt(13)
	ds_write_b128 v213, v[88:91] offset:18432
	global_load_dwordx4 v[80:83], v[106:107], off offset:2816
	v_mfma_f32_16x16x32_bf16 v[32:35], v[180:183], v[156:159], v[32:35]
	v_mfma_f32_16x16x32_bf16 v[8:11], v[184:187], v[156:159], v[8:11]
	v_mfma_f32_16x16x32_bf16 v[16:19], v[216:219], v[156:159], v[16:19]
	s_waitcnt lgkmcnt(9)
	v_mfma_f32_16x16x32_bf16 v[52:55], v[220:223], v[160:163], v[52:55]
	s_waitcnt lgkmcnt(7)
	v_mfma_f32_16x16x32_bf16 v[60:63], v[224:227], v[160:163], v[60:63]
	s_waitcnt lgkmcnt(6)
	v_mfma_f32_16x16x32_bf16 v[56:59], v[220:223], v[164:167], v[56:59]
	s_waitcnt vmcnt(13)
	ds_write_b128 v213, v[92:95] offset:23040
	global_load_dwordx4 v[84:87], v[188:189], off offset:2816
	v_mfma_f32_16x16x32_bf16 v[64:67], v[224:227], v[164:167], v[64:67]
	s_waitcnt lgkmcnt(6)
	v_mfma_f32_16x16x32_bf16 v[36:39], v[228:231], v[160:163], v[36:39]
	s_waitcnt vmcnt(13)
	ds_write_b128 v213, v[96:99] offset:27648
	global_load_dwordx4 v[88:91], v[104:105], off offset:2816
	v_mfma_f32_16x16x32_bf16 v[40:43], v[228:231], v[164:167], v[40:43]
	s_waitcnt lgkmcnt(6)
	v_mfma_f32_16x16x32_bf16 v[20:23], v[220:223], v[168:171], v[20:23]
	s_waitcnt vmcnt(13)
	ds_write_b128 v213, v[100:103] offset:32256
	global_load_dwordx4 v[92:95], v[214:215], off offset:2816
	v_mfma_f32_16x16x32_bf16 v[28:31], v[224:227], v[168:171], v[28:31]
	v_mfma_f32_16x16x32_bf16 v[4:7], v[228:231], v[168:171], v[4:7]
	global_load_dwordx4 v[96:99], v[236:237], off offset:2816
	s_waitcnt lgkmcnt(5)
	v_mfma_f32_16x16x32_bf16 v[44:47], v[232:235], v[160:163], v[44:47]
	v_mfma_f32_16x16x32_bf16 v[48:51], v[232:235], v[164:167], v[48:51]
	global_load_dwordx4 v[100:103], v[238:239], off offset:2816
	v_mfma_f32_16x16x32_bf16 v[12:15], v[232:235], v[168:171], v[12:15]
	s_waitcnt lgkmcnt(4)
	v_mfma_f32_16x16x32_bf16 v[24:27], v[220:223], v[172:175], v[24:27]
	v_mfma_f32_16x16x32_bf16 v[32:35], v[224:227], v[172:175], v[32:35]
	v_mfma_f32_16x16x32_bf16 v[8:11], v[228:231], v[172:175], v[8:11]
	v_mfma_f32_16x16x32_bf16 v[16:19], v[232:235], v[172:175], v[16:19]
	s_setprio 0
	s_waitcnt lgkmcnt(0)
	s_barrier
	ds_read_b128 v[144:147], v241
	ds_read_b128 v[176:179], v242 offset:18432
	ds_read_b128 v[180:183], v242 offset:20736
	ds_read_b128 v[148:151], v241 offset:2304
	ds_read_b128 v[184:187], v242 offset:23040
	ds_read_b128 v[152:155], v241 offset:4608
	ds_read_b128 v[216:219], v242 offset:25344
	ds_read_b128 v[156:159], v241 offset:6912
	s_setprio 1
	s_waitcnt lgkmcnt(6)
	v_mfma_f32_16x16x32_bf16 v[52:55], v[176:179], v[144:147], v[52:55]
	s_waitcnt vmcnt(15)
	ds_write_b128 v240, v[108:111]
	s_waitcnt lgkmcnt(6)
	v_mfma_f32_16x16x32_bf16 v[60:63], v[180:183], v[144:147], v[60:63]
	s_waitcnt lgkmcnt(5)
	v_mfma_f32_16x16x32_bf16 v[56:59], v[176:179], v[148:151], v[56:59]
	s_waitcnt vmcnt(14)
	ds_write_b128 v240, v[112:115] offset:4608
	v_mfma_f32_16x16x32_bf16 v[64:67], v[180:183], v[148:151], v[64:67]
	ds_read_b128 v[160:163], v241 offset:64
	s_waitcnt lgkmcnt(6)
	v_mfma_f32_16x16x32_bf16 v[36:39], v[184:187], v[144:147], v[36:39]
	ds_read_b128 v[220:223], v242 offset:18496
	s_waitcnt vmcnt(13)
	ds_write_b128 v240, v[116:119] offset:9216
	global_load_dwordx4 v[108:111], v[72:73], off offset:2944
	v_mfma_f32_16x16x32_bf16 v[40:43], v[184:187], v[148:151], v[40:43]
	ds_read_b128 v[224:227], v242 offset:20800
	s_waitcnt lgkmcnt(8)
	v_mfma_f32_16x16x32_bf16 v[20:23], v[176:179], v[152:155], v[20:23]
	ds_read_b128 v[164:167], v241 offset:2368
	v_mfma_f32_16x16x32_bf16 v[28:31], v[180:183], v[152:155], v[28:31]
	v_mfma_f32_16x16x32_bf16 v[4:7], v[184:187], v[152:155], v[4:7]
	ds_read_b128 v[228:231], v242 offset:23104
	s_waitcnt lgkmcnt(9)
	v_mfma_f32_16x16x32_bf16 v[44:47], v[216:219], v[144:147], v[44:47]
	ds_read_b128 v[168:171], v241 offset:4672
	v_mfma_f32_16x16x32_bf16 v[48:51], v[216:219], v[148:151], v[48:51]
	s_waitcnt vmcnt(13)
	ds_write_b128 v240, v[120:123] offset:13824
	global_load_dwordx4 v[112:115], v[74:75], off offset:2944
	v_mfma_f32_16x16x32_bf16 v[12:15], v[216:219], v[152:155], v[12:15]
	ds_read_b128 v[232:235], v242 offset:25408
	s_waitcnt lgkmcnt(11)
	v_mfma_f32_16x16x32_bf16 v[24:27], v[176:179], v[156:159], v[24:27]
	ds_read_b128 v[172:175], v241 offset:6976
	s_waitcnt vmcnt(13)
	ds_write_b128 v240, v[124:127] offset:18432
	global_load_dwordx4 v[116:119], v[106:107], off offset:2944
	v_mfma_f32_16x16x32_bf16 v[32:35], v[180:183], v[156:159], v[32:35]
	v_mfma_f32_16x16x32_bf16 v[8:11], v[184:187], v[156:159], v[8:11]
	v_mfma_f32_16x16x32_bf16 v[16:19], v[216:219], v[156:159], v[16:19]
	s_waitcnt lgkmcnt(9)
	v_mfma_f32_16x16x32_bf16 v[52:55], v[220:223], v[160:163], v[52:55]
	s_waitcnt lgkmcnt(7)
	v_mfma_f32_16x16x32_bf16 v[60:63], v[224:227], v[160:163], v[60:63]
	s_waitcnt lgkmcnt(6)
	v_mfma_f32_16x16x32_bf16 v[56:59], v[220:223], v[164:167], v[56:59]
	s_waitcnt vmcnt(13)
	ds_write_b128 v240, v[128:131] offset:23040
	global_load_dwordx4 v[120:123], v[188:189], off offset:2944
	v_mfma_f32_16x16x32_bf16 v[64:67], v[224:227], v[164:167], v[64:67]
	s_waitcnt lgkmcnt(6)
	v_mfma_f32_16x16x32_bf16 v[36:39], v[228:231], v[160:163], v[36:39]
	s_waitcnt vmcnt(13)
	ds_write_b128 v240, v[136:139] offset:27648
	global_load_dwordx4 v[124:127], v[104:105], off offset:2944
	v_mfma_f32_16x16x32_bf16 v[40:43], v[228:231], v[164:167], v[40:43]
	s_waitcnt lgkmcnt(6)
	v_mfma_f32_16x16x32_bf16 v[20:23], v[220:223], v[168:171], v[20:23]
	s_waitcnt vmcnt(13)
	ds_write_b128 v240, v[140:143] offset:32256
	global_load_dwordx4 v[128:131], v[214:215], off offset:2944
	v_mfma_f32_16x16x32_bf16 v[28:31], v[224:227], v[168:171], v[28:31]
	v_mfma_f32_16x16x32_bf16 v[4:7], v[228:231], v[168:171], v[4:7]
	global_load_dwordx4 v[136:139], v[236:237], off offset:2944
	s_waitcnt lgkmcnt(5)
	v_mfma_f32_16x16x32_bf16 v[44:47], v[232:235], v[160:163], v[44:47]
	v_mfma_f32_16x16x32_bf16 v[48:51], v[232:235], v[164:167], v[48:51]
	global_load_dwordx4 v[140:143], v[238:239], off offset:2944
	v_mfma_f32_16x16x32_bf16 v[12:15], v[232:235], v[168:171], v[12:15]
	s_waitcnt lgkmcnt(4)
	v_mfma_f32_16x16x32_bf16 v[24:27], v[220:223], v[172:175], v[24:27]
	v_mfma_f32_16x16x32_bf16 v[32:35], v[224:227], v[172:175], v[32:35]
	v_mfma_f32_16x16x32_bf16 v[8:11], v[228:231], v[172:175], v[8:11]
	v_mfma_f32_16x16x32_bf16 v[16:19], v[232:235], v[172:175], v[16:19]
	s_setprio 0
	s_waitcnt lgkmcnt(0)
	s_barrier
	ds_read_b128 v[144:147], v241 offset:36864
	ds_read_b128 v[176:179], v242 offset:55296
	ds_read_b128 v[180:183], v242 offset:57600
	ds_read_b128 v[148:151], v241 offset:39168
	ds_read_b128 v[184:187], v242 offset:59904
	ds_read_b128 v[152:155], v241 offset:41472
	ds_read_b128 v[216:219], v242 offset:62208
	ds_read_b128 v[156:159], v241 offset:43776
	s_setprio 1
	s_waitcnt lgkmcnt(6)
	v_mfma_f32_16x16x32_bf16 v[52:55], v[176:179], v[144:147], v[52:55]
	s_waitcnt vmcnt(15)
	ds_write_b128 v213, v[68:71]
	s_waitcnt lgkmcnt(6)
	v_mfma_f32_16x16x32_bf16 v[60:63], v[180:183], v[144:147], v[60:63]
	s_waitcnt lgkmcnt(5)
	v_mfma_f32_16x16x32_bf16 v[56:59], v[176:179], v[148:151], v[56:59]
	s_waitcnt vmcnt(14)
	ds_write_b128 v213, v[76:79] offset:4608
	v_mfma_f32_16x16x32_bf16 v[64:67], v[180:183], v[148:151], v[64:67]
	ds_read_b128 v[160:163], v241 offset:36928
	s_waitcnt lgkmcnt(6)
	v_mfma_f32_16x16x32_bf16 v[36:39], v[184:187], v[144:147], v[36:39]
	ds_read_b128 v[220:223], v242 offset:55360
	s_waitcnt vmcnt(13)
	ds_write_b128 v213, v[80:83] offset:9216
	global_load_dwordx4 v[68:71], v[72:73], off offset:3072
	v_mfma_f32_16x16x32_bf16 v[40:43], v[184:187], v[148:151], v[40:43]
	ds_read_b128 v[224:227], v242 offset:57664
	s_waitcnt lgkmcnt(8)
	v_mfma_f32_16x16x32_bf16 v[20:23], v[176:179], v[152:155], v[20:23]
	ds_read_b128 v[164:167], v241 offset:39232
	v_mfma_f32_16x16x32_bf16 v[28:31], v[180:183], v[152:155], v[28:31]
	v_mfma_f32_16x16x32_bf16 v[4:7], v[184:187], v[152:155], v[4:7]
	ds_read_b128 v[228:231], v242 offset:59968
	s_waitcnt lgkmcnt(9)
	v_mfma_f32_16x16x32_bf16 v[44:47], v[216:219], v[144:147], v[44:47]
	ds_read_b128 v[168:171], v241 offset:41536
	v_mfma_f32_16x16x32_bf16 v[48:51], v[216:219], v[148:151], v[48:51]
	s_waitcnt vmcnt(13)
	ds_write_b128 v213, v[84:87] offset:13824
	global_load_dwordx4 v[76:79], v[74:75], off offset:3072
	v_mfma_f32_16x16x32_bf16 v[12:15], v[216:219], v[152:155], v[12:15]
	ds_read_b128 v[232:235], v242 offset:62272
	s_waitcnt lgkmcnt(11)
	v_mfma_f32_16x16x32_bf16 v[24:27], v[176:179], v[156:159], v[24:27]
	ds_read_b128 v[172:175], v241 offset:43840
	s_waitcnt vmcnt(13)
	ds_write_b128 v213, v[88:91] offset:18432
	global_load_dwordx4 v[80:83], v[106:107], off offset:3072
	v_mfma_f32_16x16x32_bf16 v[32:35], v[180:183], v[156:159], v[32:35]
	v_mfma_f32_16x16x32_bf16 v[8:11], v[184:187], v[156:159], v[8:11]
	v_mfma_f32_16x16x32_bf16 v[16:19], v[216:219], v[156:159], v[16:19]
	s_waitcnt lgkmcnt(9)
	v_mfma_f32_16x16x32_bf16 v[52:55], v[220:223], v[160:163], v[52:55]
	s_waitcnt lgkmcnt(7)
	v_mfma_f32_16x16x32_bf16 v[60:63], v[224:227], v[160:163], v[60:63]
	s_waitcnt lgkmcnt(6)
	v_mfma_f32_16x16x32_bf16 v[56:59], v[220:223], v[164:167], v[56:59]
	s_waitcnt vmcnt(13)
	ds_write_b128 v213, v[92:95] offset:23040
	global_load_dwordx4 v[84:87], v[188:189], off offset:3072
	v_mfma_f32_16x16x32_bf16 v[64:67], v[224:227], v[164:167], v[64:67]
	s_waitcnt lgkmcnt(6)
	v_mfma_f32_16x16x32_bf16 v[36:39], v[228:231], v[160:163], v[36:39]
	s_waitcnt vmcnt(13)
	ds_write_b128 v213, v[96:99] offset:27648
	global_load_dwordx4 v[88:91], v[104:105], off offset:3072
	v_mfma_f32_16x16x32_bf16 v[40:43], v[228:231], v[164:167], v[40:43]
	s_waitcnt lgkmcnt(6)
	v_mfma_f32_16x16x32_bf16 v[20:23], v[220:223], v[168:171], v[20:23]
	s_waitcnt vmcnt(13)
	ds_write_b128 v213, v[100:103] offset:32256
	global_load_dwordx4 v[92:95], v[214:215], off offset:3072
	v_mfma_f32_16x16x32_bf16 v[28:31], v[224:227], v[168:171], v[28:31]
	v_mfma_f32_16x16x32_bf16 v[4:7], v[228:231], v[168:171], v[4:7]
	global_load_dwordx4 v[96:99], v[236:237], off offset:3072
	s_waitcnt lgkmcnt(5)
	v_mfma_f32_16x16x32_bf16 v[44:47], v[232:235], v[160:163], v[44:47]
	v_mfma_f32_16x16x32_bf16 v[48:51], v[232:235], v[164:167], v[48:51]
	global_load_dwordx4 v[100:103], v[238:239], off offset:3072
	v_mfma_f32_16x16x32_bf16 v[12:15], v[232:235], v[168:171], v[12:15]
	s_waitcnt lgkmcnt(4)
	v_mfma_f32_16x16x32_bf16 v[24:27], v[220:223], v[172:175], v[24:27]
	v_mfma_f32_16x16x32_bf16 v[32:35], v[224:227], v[172:175], v[32:35]
	v_mfma_f32_16x16x32_bf16 v[8:11], v[228:231], v[172:175], v[8:11]
	v_mfma_f32_16x16x32_bf16 v[16:19], v[232:235], v[172:175], v[16:19]
	s_setprio 0
	s_waitcnt lgkmcnt(0)
	s_barrier
	ds_read_b128 v[144:147], v241
	ds_read_b128 v[176:179], v242 offset:18432
	ds_read_b128 v[180:183], v242 offset:20736
	ds_read_b128 v[148:151], v241 offset:2304
	ds_read_b128 v[184:187], v242 offset:23040
	ds_read_b128 v[152:155], v241 offset:4608
	ds_read_b128 v[216:219], v242 offset:25344
	ds_read_b128 v[156:159], v241 offset:6912
	s_setprio 1
	s_waitcnt lgkmcnt(6)
	v_mfma_f32_16x16x32_bf16 v[52:55], v[176:179], v[144:147], v[52:55]
	s_waitcnt vmcnt(15)
	ds_write_b128 v240, v[108:111]
	s_waitcnt lgkmcnt(6)
	v_mfma_f32_16x16x32_bf16 v[60:63], v[180:183], v[144:147], v[60:63]
	s_waitcnt lgkmcnt(5)
	v_mfma_f32_16x16x32_bf16 v[56:59], v[176:179], v[148:151], v[56:59]
	s_waitcnt vmcnt(14)
	ds_write_b128 v240, v[112:115] offset:4608
	v_mfma_f32_16x16x32_bf16 v[64:67], v[180:183], v[148:151], v[64:67]
	ds_read_b128 v[160:163], v241 offset:64
	s_waitcnt lgkmcnt(6)
	v_mfma_f32_16x16x32_bf16 v[36:39], v[184:187], v[144:147], v[36:39]
	ds_read_b128 v[220:223], v242 offset:18496
	s_waitcnt vmcnt(13)
	ds_write_b128 v240, v[116:119] offset:9216
	global_load_dwordx4 v[108:111], v[72:73], off offset:3200
	v_mfma_f32_16x16x32_bf16 v[40:43], v[184:187], v[148:151], v[40:43]
	ds_read_b128 v[224:227], v242 offset:20800
	s_waitcnt lgkmcnt(8)
	v_mfma_f32_16x16x32_bf16 v[20:23], v[176:179], v[152:155], v[20:23]
	ds_read_b128 v[164:167], v241 offset:2368
	v_mfma_f32_16x16x32_bf16 v[28:31], v[180:183], v[152:155], v[28:31]
	v_mfma_f32_16x16x32_bf16 v[4:7], v[184:187], v[152:155], v[4:7]
	ds_read_b128 v[228:231], v242 offset:23104
	s_waitcnt lgkmcnt(9)
	v_mfma_f32_16x16x32_bf16 v[44:47], v[216:219], v[144:147], v[44:47]
	ds_read_b128 v[168:171], v241 offset:4672
	v_mfma_f32_16x16x32_bf16 v[48:51], v[216:219], v[148:151], v[48:51]
	s_waitcnt vmcnt(13)
	ds_write_b128 v240, v[120:123] offset:13824
	global_load_dwordx4 v[112:115], v[74:75], off offset:3200
	v_mfma_f32_16x16x32_bf16 v[12:15], v[216:219], v[152:155], v[12:15]
	ds_read_b128 v[232:235], v242 offset:25408
	s_waitcnt lgkmcnt(11)
	v_mfma_f32_16x16x32_bf16 v[24:27], v[176:179], v[156:159], v[24:27]
	ds_read_b128 v[172:175], v241 offset:6976
	s_waitcnt vmcnt(13)
	ds_write_b128 v240, v[124:127] offset:18432
	global_load_dwordx4 v[116:119], v[106:107], off offset:3200
	v_mfma_f32_16x16x32_bf16 v[32:35], v[180:183], v[156:159], v[32:35]
	v_mfma_f32_16x16x32_bf16 v[8:11], v[184:187], v[156:159], v[8:11]
	v_mfma_f32_16x16x32_bf16 v[16:19], v[216:219], v[156:159], v[16:19]
	s_waitcnt lgkmcnt(9)
	v_mfma_f32_16x16x32_bf16 v[52:55], v[220:223], v[160:163], v[52:55]
	s_waitcnt lgkmcnt(7)
	v_mfma_f32_16x16x32_bf16 v[60:63], v[224:227], v[160:163], v[60:63]
	s_waitcnt lgkmcnt(6)
	v_mfma_f32_16x16x32_bf16 v[56:59], v[220:223], v[164:167], v[56:59]
	s_waitcnt vmcnt(13)
	ds_write_b128 v240, v[128:131] offset:23040
	global_load_dwordx4 v[120:123], v[188:189], off offset:3200
	v_mfma_f32_16x16x32_bf16 v[64:67], v[224:227], v[164:167], v[64:67]
	s_waitcnt lgkmcnt(6)
	v_mfma_f32_16x16x32_bf16 v[36:39], v[228:231], v[160:163], v[36:39]
	s_waitcnt vmcnt(13)
	ds_write_b128 v240, v[136:139] offset:27648
	global_load_dwordx4 v[124:127], v[104:105], off offset:3200
	v_mfma_f32_16x16x32_bf16 v[40:43], v[228:231], v[164:167], v[40:43]
	s_waitcnt lgkmcnt(6)
	v_mfma_f32_16x16x32_bf16 v[20:23], v[220:223], v[168:171], v[20:23]
	s_waitcnt vmcnt(13)
	ds_write_b128 v240, v[140:143] offset:32256
	global_load_dwordx4 v[128:131], v[214:215], off offset:3200
	v_mfma_f32_16x16x32_bf16 v[28:31], v[224:227], v[168:171], v[28:31]
	v_mfma_f32_16x16x32_bf16 v[4:7], v[228:231], v[168:171], v[4:7]
	global_load_dwordx4 v[136:139], v[236:237], off offset:3200
	s_waitcnt lgkmcnt(5)
	v_mfma_f32_16x16x32_bf16 v[44:47], v[232:235], v[160:163], v[44:47]
	v_mfma_f32_16x16x32_bf16 v[48:51], v[232:235], v[164:167], v[48:51]
	global_load_dwordx4 v[140:143], v[238:239], off offset:3200
	v_mfma_f32_16x16x32_bf16 v[12:15], v[232:235], v[168:171], v[12:15]
	s_waitcnt lgkmcnt(4)
	v_mfma_f32_16x16x32_bf16 v[24:27], v[220:223], v[172:175], v[24:27]
	v_mfma_f32_16x16x32_bf16 v[32:35], v[224:227], v[172:175], v[32:35]
	v_mfma_f32_16x16x32_bf16 v[8:11], v[228:231], v[172:175], v[8:11]
	v_mfma_f32_16x16x32_bf16 v[16:19], v[232:235], v[172:175], v[16:19]
	s_setprio 0
	s_waitcnt lgkmcnt(0)
	s_barrier
	ds_read_b128 v[144:147], v241 offset:36864
	ds_read_b128 v[176:179], v242 offset:55296
	ds_read_b128 v[180:183], v242 offset:57600
	ds_read_b128 v[148:151], v241 offset:39168
	ds_read_b128 v[184:187], v242 offset:59904
	ds_read_b128 v[152:155], v241 offset:41472
	ds_read_b128 v[216:219], v242 offset:62208
	ds_read_b128 v[156:159], v241 offset:43776
	s_setprio 1
	s_waitcnt lgkmcnt(6)
	v_mfma_f32_16x16x32_bf16 v[52:55], v[176:179], v[144:147], v[52:55]
	s_waitcnt vmcnt(15)
	ds_write_b128 v213, v[68:71]
	s_waitcnt lgkmcnt(6)
	v_mfma_f32_16x16x32_bf16 v[60:63], v[180:183], v[144:147], v[60:63]
	s_waitcnt lgkmcnt(5)
	v_mfma_f32_16x16x32_bf16 v[56:59], v[176:179], v[148:151], v[56:59]
	s_waitcnt vmcnt(14)
	ds_write_b128 v213, v[76:79] offset:4608
	v_mfma_f32_16x16x32_bf16 v[64:67], v[180:183], v[148:151], v[64:67]
	ds_read_b128 v[160:163], v241 offset:36928
	s_waitcnt lgkmcnt(6)
	v_mfma_f32_16x16x32_bf16 v[36:39], v[184:187], v[144:147], v[36:39]
	ds_read_b128 v[220:223], v242 offset:55360
	s_waitcnt vmcnt(13)
	ds_write_b128 v213, v[80:83] offset:9216
	global_load_dwordx4 v[68:71], v[72:73], off offset:3328
	v_mfma_f32_16x16x32_bf16 v[40:43], v[184:187], v[148:151], v[40:43]
	ds_read_b128 v[224:227], v242 offset:57664
	s_waitcnt lgkmcnt(8)
	v_mfma_f32_16x16x32_bf16 v[20:23], v[176:179], v[152:155], v[20:23]
	ds_read_b128 v[164:167], v241 offset:39232
	v_mfma_f32_16x16x32_bf16 v[28:31], v[180:183], v[152:155], v[28:31]
	v_mfma_f32_16x16x32_bf16 v[4:7], v[184:187], v[152:155], v[4:7]
	ds_read_b128 v[228:231], v242 offset:59968
	s_waitcnt lgkmcnt(9)
	v_mfma_f32_16x16x32_bf16 v[44:47], v[216:219], v[144:147], v[44:47]
	ds_read_b128 v[168:171], v241 offset:41536
	v_mfma_f32_16x16x32_bf16 v[48:51], v[216:219], v[148:151], v[48:51]
	s_waitcnt vmcnt(13)
	ds_write_b128 v213, v[84:87] offset:13824
	global_load_dwordx4 v[76:79], v[74:75], off offset:3328
	v_mfma_f32_16x16x32_bf16 v[12:15], v[216:219], v[152:155], v[12:15]
	ds_read_b128 v[232:235], v242 offset:62272
	s_waitcnt lgkmcnt(11)
	v_mfma_f32_16x16x32_bf16 v[24:27], v[176:179], v[156:159], v[24:27]
	ds_read_b128 v[172:175], v241 offset:43840
	s_waitcnt vmcnt(13)
	ds_write_b128 v213, v[88:91] offset:18432
	global_load_dwordx4 v[80:83], v[106:107], off offset:3328
	v_mfma_f32_16x16x32_bf16 v[32:35], v[180:183], v[156:159], v[32:35]
	v_mfma_f32_16x16x32_bf16 v[8:11], v[184:187], v[156:159], v[8:11]
	v_mfma_f32_16x16x32_bf16 v[16:19], v[216:219], v[156:159], v[16:19]
	s_waitcnt lgkmcnt(9)
	v_mfma_f32_16x16x32_bf16 v[52:55], v[220:223], v[160:163], v[52:55]
	s_waitcnt lgkmcnt(7)
	v_mfma_f32_16x16x32_bf16 v[60:63], v[224:227], v[160:163], v[60:63]
	s_waitcnt lgkmcnt(6)
	v_mfma_f32_16x16x32_bf16 v[56:59], v[220:223], v[164:167], v[56:59]
	s_waitcnt vmcnt(13)
	ds_write_b128 v213, v[92:95] offset:23040
	global_load_dwordx4 v[84:87], v[188:189], off offset:3328
	v_mfma_f32_16x16x32_bf16 v[64:67], v[224:227], v[164:167], v[64:67]
	s_waitcnt lgkmcnt(6)
	v_mfma_f32_16x16x32_bf16 v[36:39], v[228:231], v[160:163], v[36:39]
	s_waitcnt vmcnt(13)
	ds_write_b128 v213, v[96:99] offset:27648
	global_load_dwordx4 v[88:91], v[104:105], off offset:3328
	v_mfma_f32_16x16x32_bf16 v[40:43], v[228:231], v[164:167], v[40:43]
	s_waitcnt lgkmcnt(6)
	v_mfma_f32_16x16x32_bf16 v[20:23], v[220:223], v[168:171], v[20:23]
	s_waitcnt vmcnt(13)
	ds_write_b128 v213, v[100:103] offset:32256
	global_load_dwordx4 v[92:95], v[214:215], off offset:3328
	v_mfma_f32_16x16x32_bf16 v[28:31], v[224:227], v[168:171], v[28:31]
	v_mfma_f32_16x16x32_bf16 v[4:7], v[228:231], v[168:171], v[4:7]
	global_load_dwordx4 v[96:99], v[236:237], off offset:3328
	s_waitcnt lgkmcnt(5)
	v_mfma_f32_16x16x32_bf16 v[44:47], v[232:235], v[160:163], v[44:47]
	v_mfma_f32_16x16x32_bf16 v[48:51], v[232:235], v[164:167], v[48:51]
	global_load_dwordx4 v[100:103], v[238:239], off offset:3328
	v_mfma_f32_16x16x32_bf16 v[12:15], v[232:235], v[168:171], v[12:15]
	s_waitcnt lgkmcnt(4)
	v_mfma_f32_16x16x32_bf16 v[24:27], v[220:223], v[172:175], v[24:27]
	v_mfma_f32_16x16x32_bf16 v[32:35], v[224:227], v[172:175], v[32:35]
	v_mfma_f32_16x16x32_bf16 v[8:11], v[228:231], v[172:175], v[8:11]
	v_mfma_f32_16x16x32_bf16 v[16:19], v[232:235], v[172:175], v[16:19]
	s_setprio 0
	s_waitcnt lgkmcnt(0)
	s_barrier
	ds_read_b128 v[144:147], v241
	ds_read_b128 v[176:179], v242 offset:18432
	ds_read_b128 v[180:183], v242 offset:20736
	ds_read_b128 v[148:151], v241 offset:2304
	ds_read_b128 v[184:187], v242 offset:23040
	ds_read_b128 v[152:155], v241 offset:4608
	ds_read_b128 v[216:219], v242 offset:25344
	ds_read_b128 v[156:159], v241 offset:6912
	s_setprio 1
	s_waitcnt lgkmcnt(6)
	v_mfma_f32_16x16x32_bf16 v[52:55], v[176:179], v[144:147], v[52:55]
	s_waitcnt vmcnt(15)
	ds_write_b128 v240, v[108:111]
	s_waitcnt lgkmcnt(6)
	v_mfma_f32_16x16x32_bf16 v[60:63], v[180:183], v[144:147], v[60:63]
	s_waitcnt lgkmcnt(5)
	v_mfma_f32_16x16x32_bf16 v[56:59], v[176:179], v[148:151], v[56:59]
	s_waitcnt vmcnt(14)
	ds_write_b128 v240, v[112:115] offset:4608
	v_mfma_f32_16x16x32_bf16 v[64:67], v[180:183], v[148:151], v[64:67]
	ds_read_b128 v[160:163], v241 offset:64
	s_waitcnt lgkmcnt(6)
	v_mfma_f32_16x16x32_bf16 v[36:39], v[184:187], v[144:147], v[36:39]
	ds_read_b128 v[220:223], v242 offset:18496
	s_waitcnt vmcnt(13)
	ds_write_b128 v240, v[116:119] offset:9216
	global_load_dwordx4 v[108:111], v[72:73], off offset:3456
	v_mfma_f32_16x16x32_bf16 v[40:43], v[184:187], v[148:151], v[40:43]
	ds_read_b128 v[224:227], v242 offset:20800
	s_waitcnt lgkmcnt(8)
	v_mfma_f32_16x16x32_bf16 v[20:23], v[176:179], v[152:155], v[20:23]
	ds_read_b128 v[164:167], v241 offset:2368
	v_mfma_f32_16x16x32_bf16 v[28:31], v[180:183], v[152:155], v[28:31]
	v_mfma_f32_16x16x32_bf16 v[4:7], v[184:187], v[152:155], v[4:7]
	ds_read_b128 v[228:231], v242 offset:23104
	s_waitcnt lgkmcnt(9)
	v_mfma_f32_16x16x32_bf16 v[44:47], v[216:219], v[144:147], v[44:47]
	ds_read_b128 v[168:171], v241 offset:4672
	v_mfma_f32_16x16x32_bf16 v[48:51], v[216:219], v[148:151], v[48:51]
	s_waitcnt vmcnt(13)
	ds_write_b128 v240, v[120:123] offset:13824
	global_load_dwordx4 v[112:115], v[74:75], off offset:3456
	v_mfma_f32_16x16x32_bf16 v[12:15], v[216:219], v[152:155], v[12:15]
	ds_read_b128 v[232:235], v242 offset:25408
	s_waitcnt lgkmcnt(11)
	v_mfma_f32_16x16x32_bf16 v[24:27], v[176:179], v[156:159], v[24:27]
	ds_read_b128 v[172:175], v241 offset:6976
	s_waitcnt vmcnt(13)
	ds_write_b128 v240, v[124:127] offset:18432
	global_load_dwordx4 v[116:119], v[106:107], off offset:3456
	v_mfma_f32_16x16x32_bf16 v[32:35], v[180:183], v[156:159], v[32:35]
	v_mfma_f32_16x16x32_bf16 v[8:11], v[184:187], v[156:159], v[8:11]
	v_mfma_f32_16x16x32_bf16 v[16:19], v[216:219], v[156:159], v[16:19]
	s_waitcnt lgkmcnt(9)
	v_mfma_f32_16x16x32_bf16 v[52:55], v[220:223], v[160:163], v[52:55]
	s_waitcnt lgkmcnt(7)
	v_mfma_f32_16x16x32_bf16 v[60:63], v[224:227], v[160:163], v[60:63]
	s_waitcnt lgkmcnt(6)
	v_mfma_f32_16x16x32_bf16 v[56:59], v[220:223], v[164:167], v[56:59]
	s_waitcnt vmcnt(13)
	ds_write_b128 v240, v[128:131] offset:23040
	global_load_dwordx4 v[120:123], v[188:189], off offset:3456
	v_mfma_f32_16x16x32_bf16 v[64:67], v[224:227], v[164:167], v[64:67]
	s_waitcnt lgkmcnt(6)
	v_mfma_f32_16x16x32_bf16 v[36:39], v[228:231], v[160:163], v[36:39]
	s_waitcnt vmcnt(13)
	ds_write_b128 v240, v[136:139] offset:27648
	global_load_dwordx4 v[124:127], v[104:105], off offset:3456
	v_mfma_f32_16x16x32_bf16 v[40:43], v[228:231], v[164:167], v[40:43]
	s_waitcnt lgkmcnt(6)
	v_mfma_f32_16x16x32_bf16 v[20:23], v[220:223], v[168:171], v[20:23]
	s_waitcnt vmcnt(13)
	ds_write_b128 v240, v[140:143] offset:32256
	global_load_dwordx4 v[128:131], v[214:215], off offset:3456
	v_mfma_f32_16x16x32_bf16 v[28:31], v[224:227], v[168:171], v[28:31]
	v_mfma_f32_16x16x32_bf16 v[4:7], v[228:231], v[168:171], v[4:7]
	global_load_dwordx4 v[136:139], v[236:237], off offset:3456
	s_waitcnt lgkmcnt(5)
	v_mfma_f32_16x16x32_bf16 v[44:47], v[232:235], v[160:163], v[44:47]
	v_mfma_f32_16x16x32_bf16 v[48:51], v[232:235], v[164:167], v[48:51]
	global_load_dwordx4 v[140:143], v[238:239], off offset:3456
	v_mfma_f32_16x16x32_bf16 v[12:15], v[232:235], v[168:171], v[12:15]
	s_waitcnt lgkmcnt(4)
	v_mfma_f32_16x16x32_bf16 v[24:27], v[220:223], v[172:175], v[24:27]
	v_mfma_f32_16x16x32_bf16 v[32:35], v[224:227], v[172:175], v[32:35]
	v_mfma_f32_16x16x32_bf16 v[8:11], v[228:231], v[172:175], v[8:11]
	v_mfma_f32_16x16x32_bf16 v[16:19], v[232:235], v[172:175], v[16:19]
	s_setprio 0
	s_waitcnt lgkmcnt(0)
	s_barrier
	ds_read_b128 v[144:147], v241 offset:36864
	ds_read_b128 v[176:179], v242 offset:55296
	ds_read_b128 v[180:183], v242 offset:57600
	ds_read_b128 v[148:151], v241 offset:39168
	ds_read_b128 v[184:187], v242 offset:59904
	ds_read_b128 v[152:155], v241 offset:41472
	ds_read_b128 v[216:219], v242 offset:62208
	ds_read_b128 v[156:159], v241 offset:43776
	s_setprio 1
	s_waitcnt lgkmcnt(6)
	v_mfma_f32_16x16x32_bf16 v[52:55], v[176:179], v[144:147], v[52:55]
	s_waitcnt vmcnt(15)
	ds_write_b128 v213, v[68:71]
	s_waitcnt lgkmcnt(6)
	v_mfma_f32_16x16x32_bf16 v[60:63], v[180:183], v[144:147], v[60:63]
	s_waitcnt lgkmcnt(5)
	v_mfma_f32_16x16x32_bf16 v[56:59], v[176:179], v[148:151], v[56:59]
	s_waitcnt vmcnt(14)
	ds_write_b128 v213, v[76:79] offset:4608
	v_mfma_f32_16x16x32_bf16 v[64:67], v[180:183], v[148:151], v[64:67]
	ds_read_b128 v[160:163], v241 offset:36928
	s_waitcnt lgkmcnt(6)
	v_mfma_f32_16x16x32_bf16 v[36:39], v[184:187], v[144:147], v[36:39]
	ds_read_b128 v[220:223], v242 offset:55360
	s_waitcnt vmcnt(13)
	ds_write_b128 v213, v[80:83] offset:9216
	global_load_dwordx4 v[68:71], v[72:73], off offset:3584
	v_mfma_f32_16x16x32_bf16 v[40:43], v[184:187], v[148:151], v[40:43]
	ds_read_b128 v[224:227], v242 offset:57664
	s_waitcnt lgkmcnt(8)
	v_mfma_f32_16x16x32_bf16 v[20:23], v[176:179], v[152:155], v[20:23]
	ds_read_b128 v[164:167], v241 offset:39232
	v_mfma_f32_16x16x32_bf16 v[28:31], v[180:183], v[152:155], v[28:31]
	v_mfma_f32_16x16x32_bf16 v[4:7], v[184:187], v[152:155], v[4:7]
	ds_read_b128 v[228:231], v242 offset:59968
	s_waitcnt lgkmcnt(9)
	v_mfma_f32_16x16x32_bf16 v[44:47], v[216:219], v[144:147], v[44:47]
	ds_read_b128 v[168:171], v241 offset:41536
	v_mfma_f32_16x16x32_bf16 v[48:51], v[216:219], v[148:151], v[48:51]
	s_waitcnt vmcnt(13)
	ds_write_b128 v213, v[84:87] offset:13824
	global_load_dwordx4 v[76:79], v[74:75], off offset:3584
	v_mfma_f32_16x16x32_bf16 v[12:15], v[216:219], v[152:155], v[12:15]
	ds_read_b128 v[232:235], v242 offset:62272
	s_waitcnt lgkmcnt(11)
	v_mfma_f32_16x16x32_bf16 v[24:27], v[176:179], v[156:159], v[24:27]
	ds_read_b128 v[172:175], v241 offset:43840
	s_waitcnt vmcnt(13)
	ds_write_b128 v213, v[88:91] offset:18432
	global_load_dwordx4 v[80:83], v[106:107], off offset:3584
	v_mfma_f32_16x16x32_bf16 v[32:35], v[180:183], v[156:159], v[32:35]
	v_mfma_f32_16x16x32_bf16 v[8:11], v[184:187], v[156:159], v[8:11]
	v_mfma_f32_16x16x32_bf16 v[16:19], v[216:219], v[156:159], v[16:19]
	s_waitcnt lgkmcnt(9)
	v_mfma_f32_16x16x32_bf16 v[52:55], v[220:223], v[160:163], v[52:55]
	s_waitcnt lgkmcnt(7)
	v_mfma_f32_16x16x32_bf16 v[60:63], v[224:227], v[160:163], v[60:63]
	s_waitcnt lgkmcnt(6)
	v_mfma_f32_16x16x32_bf16 v[56:59], v[220:223], v[164:167], v[56:59]
	s_waitcnt vmcnt(13)
	ds_write_b128 v213, v[92:95] offset:23040
	global_load_dwordx4 v[84:87], v[188:189], off offset:3584
	v_mfma_f32_16x16x32_bf16 v[64:67], v[224:227], v[164:167], v[64:67]
	s_waitcnt lgkmcnt(6)
	v_mfma_f32_16x16x32_bf16 v[36:39], v[228:231], v[160:163], v[36:39]
	s_waitcnt vmcnt(13)
	ds_write_b128 v213, v[96:99] offset:27648
	global_load_dwordx4 v[88:91], v[104:105], off offset:3584
	v_mfma_f32_16x16x32_bf16 v[40:43], v[228:231], v[164:167], v[40:43]
	s_waitcnt lgkmcnt(6)
	v_mfma_f32_16x16x32_bf16 v[20:23], v[220:223], v[168:171], v[20:23]
	s_waitcnt vmcnt(13)
	ds_write_b128 v213, v[100:103] offset:32256
	global_load_dwordx4 v[92:95], v[214:215], off offset:3584
	v_mfma_f32_16x16x32_bf16 v[28:31], v[224:227], v[168:171], v[28:31]
	v_mfma_f32_16x16x32_bf16 v[4:7], v[228:231], v[168:171], v[4:7]
	global_load_dwordx4 v[96:99], v[236:237], off offset:3584
	s_waitcnt lgkmcnt(5)
	v_mfma_f32_16x16x32_bf16 v[44:47], v[232:235], v[160:163], v[44:47]
	v_mfma_f32_16x16x32_bf16 v[48:51], v[232:235], v[164:167], v[48:51]
	global_load_dwordx4 v[100:103], v[238:239], off offset:3584
	v_mfma_f32_16x16x32_bf16 v[12:15], v[232:235], v[168:171], v[12:15]
	s_waitcnt lgkmcnt(4)
	v_mfma_f32_16x16x32_bf16 v[24:27], v[220:223], v[172:175], v[24:27]
	v_mfma_f32_16x16x32_bf16 v[32:35], v[224:227], v[172:175], v[32:35]
	v_mfma_f32_16x16x32_bf16 v[8:11], v[228:231], v[172:175], v[8:11]
	v_mfma_f32_16x16x32_bf16 v[16:19], v[232:235], v[172:175], v[16:19]
	s_setprio 0
	s_waitcnt lgkmcnt(0)
	s_barrier
	ds_read_b128 v[144:147], v241
	ds_read_b128 v[176:179], v242 offset:18432
	ds_read_b128 v[180:183], v242 offset:20736
	ds_read_b128 v[148:151], v241 offset:2304
	ds_read_b128 v[184:187], v242 offset:23040
	ds_read_b128 v[152:155], v241 offset:4608
	ds_read_b128 v[216:219], v242 offset:25344
	ds_read_b128 v[156:159], v241 offset:6912
	s_setprio 1
	s_waitcnt lgkmcnt(6)
	v_mfma_f32_16x16x32_bf16 v[52:55], v[176:179], v[144:147], v[52:55]
	s_waitcnt vmcnt(15)
	ds_write_b128 v240, v[108:111]
	s_waitcnt lgkmcnt(6)
	v_mfma_f32_16x16x32_bf16 v[60:63], v[180:183], v[144:147], v[60:63]
	s_waitcnt lgkmcnt(5)
	v_mfma_f32_16x16x32_bf16 v[56:59], v[176:179], v[148:151], v[56:59]
	s_waitcnt vmcnt(14)
	ds_write_b128 v240, v[112:115] offset:4608
	v_mfma_f32_16x16x32_bf16 v[64:67], v[180:183], v[148:151], v[64:67]
	ds_read_b128 v[160:163], v241 offset:64
	s_waitcnt lgkmcnt(6)
	v_mfma_f32_16x16x32_bf16 v[36:39], v[184:187], v[144:147], v[36:39]
	ds_read_b128 v[220:223], v242 offset:18496
	s_waitcnt vmcnt(13)
	ds_write_b128 v240, v[116:119] offset:9216
	global_load_dwordx4 v[108:111], v[72:73], off offset:3712
	v_mfma_f32_16x16x32_bf16 v[40:43], v[184:187], v[148:151], v[40:43]
	ds_read_b128 v[224:227], v242 offset:20800
	s_waitcnt lgkmcnt(8)
	v_mfma_f32_16x16x32_bf16 v[20:23], v[176:179], v[152:155], v[20:23]
	ds_read_b128 v[164:167], v241 offset:2368
	v_mfma_f32_16x16x32_bf16 v[28:31], v[180:183], v[152:155], v[28:31]
	v_mfma_f32_16x16x32_bf16 v[4:7], v[184:187], v[152:155], v[4:7]
	ds_read_b128 v[228:231], v242 offset:23104
	s_waitcnt lgkmcnt(9)
	v_mfma_f32_16x16x32_bf16 v[44:47], v[216:219], v[144:147], v[44:47]
	ds_read_b128 v[168:171], v241 offset:4672
	v_mfma_f32_16x16x32_bf16 v[48:51], v[216:219], v[148:151], v[48:51]
	s_waitcnt vmcnt(13)
	ds_write_b128 v240, v[120:123] offset:13824
	global_load_dwordx4 v[112:115], v[74:75], off offset:3712
	v_mfma_f32_16x16x32_bf16 v[12:15], v[216:219], v[152:155], v[12:15]
	ds_read_b128 v[232:235], v242 offset:25408
	s_waitcnt lgkmcnt(11)
	v_mfma_f32_16x16x32_bf16 v[24:27], v[176:179], v[156:159], v[24:27]
	ds_read_b128 v[172:175], v241 offset:6976
	s_waitcnt vmcnt(13)
	ds_write_b128 v240, v[124:127] offset:18432
	global_load_dwordx4 v[116:119], v[106:107], off offset:3712
	v_mfma_f32_16x16x32_bf16 v[32:35], v[180:183], v[156:159], v[32:35]
	v_mfma_f32_16x16x32_bf16 v[8:11], v[184:187], v[156:159], v[8:11]
	v_mfma_f32_16x16x32_bf16 v[16:19], v[216:219], v[156:159], v[16:19]
	s_waitcnt lgkmcnt(9)
	v_mfma_f32_16x16x32_bf16 v[52:55], v[220:223], v[160:163], v[52:55]
	s_waitcnt lgkmcnt(7)
	v_mfma_f32_16x16x32_bf16 v[60:63], v[224:227], v[160:163], v[60:63]
	s_waitcnt lgkmcnt(6)
	v_mfma_f32_16x16x32_bf16 v[56:59], v[220:223], v[164:167], v[56:59]
	s_waitcnt vmcnt(13)
	ds_write_b128 v240, v[128:131] offset:23040
	global_load_dwordx4 v[120:123], v[188:189], off offset:3712
	v_mfma_f32_16x16x32_bf16 v[64:67], v[224:227], v[164:167], v[64:67]
	s_waitcnt lgkmcnt(6)
	v_mfma_f32_16x16x32_bf16 v[36:39], v[228:231], v[160:163], v[36:39]
	s_waitcnt vmcnt(13)
	ds_write_b128 v240, v[136:139] offset:27648
	global_load_dwordx4 v[124:127], v[104:105], off offset:3712
	v_mfma_f32_16x16x32_bf16 v[40:43], v[228:231], v[164:167], v[40:43]
	s_waitcnt lgkmcnt(6)
	v_mfma_f32_16x16x32_bf16 v[20:23], v[220:223], v[168:171], v[20:23]
	s_waitcnt vmcnt(13)
	ds_write_b128 v240, v[140:143] offset:32256
	global_load_dwordx4 v[128:131], v[214:215], off offset:3712
	v_mfma_f32_16x16x32_bf16 v[28:31], v[224:227], v[168:171], v[28:31]
	v_mfma_f32_16x16x32_bf16 v[4:7], v[228:231], v[168:171], v[4:7]
	global_load_dwordx4 v[136:139], v[236:237], off offset:3712
	s_waitcnt lgkmcnt(5)
	v_mfma_f32_16x16x32_bf16 v[44:47], v[232:235], v[160:163], v[44:47]
	v_mfma_f32_16x16x32_bf16 v[48:51], v[232:235], v[164:167], v[48:51]
	global_load_dwordx4 v[140:143], v[238:239], off offset:3712
	v_mfma_f32_16x16x32_bf16 v[12:15], v[232:235], v[168:171], v[12:15]
	s_waitcnt lgkmcnt(4)
	v_mfma_f32_16x16x32_bf16 v[24:27], v[220:223], v[172:175], v[24:27]
	v_mfma_f32_16x16x32_bf16 v[32:35], v[224:227], v[172:175], v[32:35]
	v_mfma_f32_16x16x32_bf16 v[8:11], v[228:231], v[172:175], v[8:11]
	v_mfma_f32_16x16x32_bf16 v[16:19], v[232:235], v[172:175], v[16:19]
	s_setprio 0
	s_waitcnt lgkmcnt(0)
	s_barrier
	ds_read_b128 v[144:147], v241 offset:36864
	ds_read_b128 v[176:179], v242 offset:55296
	ds_read_b128 v[180:183], v242 offset:57600
	ds_read_b128 v[148:151], v241 offset:39168
	ds_read_b128 v[184:187], v242 offset:59904
	ds_read_b128 v[152:155], v241 offset:41472
	ds_read_b128 v[216:219], v242 offset:62208
	ds_read_b128 v[156:159], v241 offset:43776
	s_setprio 1
	s_waitcnt lgkmcnt(6)
	v_mfma_f32_16x16x32_bf16 v[52:55], v[176:179], v[144:147], v[52:55]
	s_waitcnt vmcnt(15)
	ds_write_b128 v213, v[68:71]
	s_waitcnt lgkmcnt(6)
	v_mfma_f32_16x16x32_bf16 v[60:63], v[180:183], v[144:147], v[60:63]
	s_waitcnt lgkmcnt(5)
	v_mfma_f32_16x16x32_bf16 v[56:59], v[176:179], v[148:151], v[56:59]
	s_waitcnt vmcnt(14)
	ds_write_b128 v213, v[76:79] offset:4608
	v_mfma_f32_16x16x32_bf16 v[64:67], v[180:183], v[148:151], v[64:67]
	ds_read_b128 v[160:163], v241 offset:36928
	s_waitcnt lgkmcnt(6)
	v_mfma_f32_16x16x32_bf16 v[36:39], v[184:187], v[144:147], v[36:39]
	ds_read_b128 v[220:223], v242 offset:55360
	s_waitcnt vmcnt(13)
	ds_write_b128 v213, v[80:83] offset:9216
	global_load_dwordx4 v[68:71], v[72:73], off offset:3840
	v_mfma_f32_16x16x32_bf16 v[40:43], v[184:187], v[148:151], v[40:43]
	ds_read_b128 v[224:227], v242 offset:57664
	s_waitcnt lgkmcnt(8)
	v_mfma_f32_16x16x32_bf16 v[20:23], v[176:179], v[152:155], v[20:23]
	ds_read_b128 v[164:167], v241 offset:39232
	v_mfma_f32_16x16x32_bf16 v[28:31], v[180:183], v[152:155], v[28:31]
	v_mfma_f32_16x16x32_bf16 v[4:7], v[184:187], v[152:155], v[4:7]
	ds_read_b128 v[228:231], v242 offset:59968
	s_waitcnt lgkmcnt(9)
	v_mfma_f32_16x16x32_bf16 v[44:47], v[216:219], v[144:147], v[44:47]
	ds_read_b128 v[168:171], v241 offset:41536
	v_mfma_f32_16x16x32_bf16 v[48:51], v[216:219], v[148:151], v[48:51]
	s_waitcnt vmcnt(13)
	ds_write_b128 v213, v[84:87] offset:13824
	global_load_dwordx4 v[76:79], v[74:75], off offset:3840
	v_mfma_f32_16x16x32_bf16 v[12:15], v[216:219], v[152:155], v[12:15]
	ds_read_b128 v[232:235], v242 offset:62272
	s_waitcnt lgkmcnt(11)
	v_mfma_f32_16x16x32_bf16 v[24:27], v[176:179], v[156:159], v[24:27]
	ds_read_b128 v[172:175], v241 offset:43840
	s_waitcnt vmcnt(13)
	ds_write_b128 v213, v[88:91] offset:18432
	global_load_dwordx4 v[80:83], v[106:107], off offset:3840
	v_mfma_f32_16x16x32_bf16 v[32:35], v[180:183], v[156:159], v[32:35]
	v_mfma_f32_16x16x32_bf16 v[8:11], v[184:187], v[156:159], v[8:11]
	v_mfma_f32_16x16x32_bf16 v[16:19], v[216:219], v[156:159], v[16:19]
	s_waitcnt lgkmcnt(9)
	v_mfma_f32_16x16x32_bf16 v[52:55], v[220:223], v[160:163], v[52:55]
	s_waitcnt lgkmcnt(7)
	v_mfma_f32_16x16x32_bf16 v[60:63], v[224:227], v[160:163], v[60:63]
	s_waitcnt lgkmcnt(6)
	v_mfma_f32_16x16x32_bf16 v[56:59], v[220:223], v[164:167], v[56:59]
	s_waitcnt vmcnt(13)
	ds_write_b128 v213, v[92:95] offset:23040
	global_load_dwordx4 v[84:87], v[188:189], off offset:3840
	v_mfma_f32_16x16x32_bf16 v[64:67], v[224:227], v[164:167], v[64:67]
	s_waitcnt lgkmcnt(6)
	v_mfma_f32_16x16x32_bf16 v[36:39], v[228:231], v[160:163], v[36:39]
	s_waitcnt vmcnt(13)
	ds_write_b128 v213, v[96:99] offset:27648
	global_load_dwordx4 v[88:91], v[104:105], off offset:3840
	v_mfma_f32_16x16x32_bf16 v[40:43], v[228:231], v[164:167], v[40:43]
	s_waitcnt lgkmcnt(6)
	v_mfma_f32_16x16x32_bf16 v[20:23], v[220:223], v[168:171], v[20:23]
	s_waitcnt vmcnt(13)
	ds_write_b128 v213, v[100:103] offset:32256
	global_load_dwordx4 v[92:95], v[214:215], off offset:3840
	v_mfma_f32_16x16x32_bf16 v[28:31], v[224:227], v[168:171], v[28:31]
	v_mfma_f32_16x16x32_bf16 v[4:7], v[228:231], v[168:171], v[4:7]
	global_load_dwordx4 v[96:99], v[236:237], off offset:3840
	s_waitcnt lgkmcnt(5)
	v_mfma_f32_16x16x32_bf16 v[44:47], v[232:235], v[160:163], v[44:47]
	v_mfma_f32_16x16x32_bf16 v[48:51], v[232:235], v[164:167], v[48:51]
	global_load_dwordx4 v[100:103], v[238:239], off offset:3840
	v_mfma_f32_16x16x32_bf16 v[12:15], v[232:235], v[168:171], v[12:15]
	s_waitcnt lgkmcnt(4)
	v_mfma_f32_16x16x32_bf16 v[24:27], v[220:223], v[172:175], v[24:27]
	v_mfma_f32_16x16x32_bf16 v[32:35], v[224:227], v[172:175], v[32:35]
	v_mfma_f32_16x16x32_bf16 v[8:11], v[228:231], v[172:175], v[8:11]
	v_mfma_f32_16x16x32_bf16 v[16:19], v[232:235], v[172:175], v[16:19]
	s_setprio 0
	s_waitcnt lgkmcnt(0)
	s_barrier
	ds_read_b128 v[144:147], v241
	ds_read_b128 v[176:179], v242 offset:18432
	ds_read_b128 v[180:183], v242 offset:20736
	ds_read_b128 v[148:151], v241 offset:2304
	ds_read_b128 v[184:187], v242 offset:23040
	ds_read_b128 v[152:155], v241 offset:4608
	ds_read_b128 v[216:219], v242 offset:25344
	ds_read_b128 v[156:159], v241 offset:6912
	s_setprio 1
	s_waitcnt lgkmcnt(6)
	v_mfma_f32_16x16x32_bf16 v[52:55], v[176:179], v[144:147], v[52:55]
	s_waitcnt vmcnt(15)
	ds_write_b128 v240, v[108:111]
	s_waitcnt lgkmcnt(6)
	v_mfma_f32_16x16x32_bf16 v[60:63], v[180:183], v[144:147], v[60:63]
	s_waitcnt lgkmcnt(5)
	v_mfma_f32_16x16x32_bf16 v[56:59], v[176:179], v[148:151], v[56:59]
	s_waitcnt vmcnt(14)
	ds_write_b128 v240, v[112:115] offset:4608
	v_mfma_f32_16x16x32_bf16 v[64:67], v[180:183], v[148:151], v[64:67]
	ds_read_b128 v[160:163], v241 offset:64
	s_waitcnt lgkmcnt(6)
	v_mfma_f32_16x16x32_bf16 v[36:39], v[184:187], v[144:147], v[36:39]
	ds_read_b128 v[220:223], v242 offset:18496
	s_waitcnt vmcnt(13)
	ds_write_b128 v240, v[116:119] offset:9216
	global_load_dwordx4 v[108:111], v[72:73], off offset:3968
	v_mfma_f32_16x16x32_bf16 v[40:43], v[184:187], v[148:151], v[40:43]
	ds_read_b128 v[224:227], v242 offset:20800
	s_waitcnt lgkmcnt(8)
	v_mfma_f32_16x16x32_bf16 v[20:23], v[176:179], v[152:155], v[20:23]
	ds_read_b128 v[164:167], v241 offset:2368
	v_mfma_f32_16x16x32_bf16 v[28:31], v[180:183], v[152:155], v[28:31]
	v_mfma_f32_16x16x32_bf16 v[4:7], v[184:187], v[152:155], v[4:7]
	ds_read_b128 v[228:231], v242 offset:23104
	s_waitcnt lgkmcnt(9)
	v_mfma_f32_16x16x32_bf16 v[44:47], v[216:219], v[144:147], v[44:47]
	ds_read_b128 v[168:171], v241 offset:4672
	v_mfma_f32_16x16x32_bf16 v[48:51], v[216:219], v[148:151], v[48:51]
	s_waitcnt vmcnt(13)
	ds_write_b128 v240, v[120:123] offset:13824
	global_load_dwordx4 v[112:115], v[74:75], off offset:3968
	v_mfma_f32_16x16x32_bf16 v[12:15], v[216:219], v[152:155], v[12:15]
	ds_read_b128 v[232:235], v242 offset:25408
	s_waitcnt lgkmcnt(11)
	v_mfma_f32_16x16x32_bf16 v[24:27], v[176:179], v[156:159], v[24:27]
	ds_read_b128 v[172:175], v241 offset:6976
	s_waitcnt vmcnt(13)
	ds_write_b128 v240, v[124:127] offset:18432
	global_load_dwordx4 v[116:119], v[106:107], off offset:3968
	v_mfma_f32_16x16x32_bf16 v[32:35], v[180:183], v[156:159], v[32:35]
	v_mfma_f32_16x16x32_bf16 v[8:11], v[184:187], v[156:159], v[8:11]
	v_mfma_f32_16x16x32_bf16 v[16:19], v[216:219], v[156:159], v[16:19]
	s_waitcnt lgkmcnt(9)
	v_mfma_f32_16x16x32_bf16 v[52:55], v[220:223], v[160:163], v[52:55]
	s_waitcnt lgkmcnt(7)
	v_mfma_f32_16x16x32_bf16 v[60:63], v[224:227], v[160:163], v[60:63]
	s_waitcnt lgkmcnt(6)
	v_mfma_f32_16x16x32_bf16 v[56:59], v[220:223], v[164:167], v[56:59]
	s_waitcnt vmcnt(13)
	ds_write_b128 v240, v[128:131] offset:23040
	global_load_dwordx4 v[120:123], v[188:189], off offset:3968
	v_mfma_f32_16x16x32_bf16 v[64:67], v[224:227], v[164:167], v[64:67]
	s_waitcnt lgkmcnt(6)
	v_mfma_f32_16x16x32_bf16 v[36:39], v[228:231], v[160:163], v[36:39]
	s_waitcnt vmcnt(13)
	ds_write_b128 v240, v[136:139] offset:27648
	global_load_dwordx4 v[124:127], v[104:105], off offset:3968
	v_mfma_f32_16x16x32_bf16 v[40:43], v[228:231], v[164:167], v[40:43]
	s_waitcnt lgkmcnt(6)
	v_mfma_f32_16x16x32_bf16 v[20:23], v[220:223], v[168:171], v[20:23]
	s_waitcnt vmcnt(13)
	ds_write_b128 v240, v[140:143] offset:32256
	global_load_dwordx4 v[128:131], v[214:215], off offset:3968
	v_mfma_f32_16x16x32_bf16 v[28:31], v[224:227], v[168:171], v[28:31]
	v_mfma_f32_16x16x32_bf16 v[4:7], v[228:231], v[168:171], v[4:7]
	global_load_dwordx4 v[136:139], v[236:237], off offset:3968
	s_waitcnt lgkmcnt(5)
	v_mfma_f32_16x16x32_bf16 v[44:47], v[232:235], v[160:163], v[44:47]
	v_mfma_f32_16x16x32_bf16 v[48:51], v[232:235], v[164:167], v[48:51]
	global_load_dwordx4 v[140:143], v[238:239], off offset:3968
	v_mfma_f32_16x16x32_bf16 v[12:15], v[232:235], v[168:171], v[12:15]
	s_waitcnt lgkmcnt(4)
	v_mfma_f32_16x16x32_bf16 v[24:27], v[220:223], v[172:175], v[24:27]
	v_mfma_f32_16x16x32_bf16 v[32:35], v[224:227], v[172:175], v[32:35]
	v_mfma_f32_16x16x32_bf16 v[8:11], v[228:231], v[172:175], v[8:11]
	v_mfma_f32_16x16x32_bf16 v[16:19], v[232:235], v[172:175], v[16:19]
	s_setprio 0
	s_waitcnt lgkmcnt(0)
	s_barrier
	ds_read_b128 v[144:147], v241 offset:36864
	ds_read_b128 v[176:179], v242 offset:55296
	ds_read_b128 v[180:183], v242 offset:57600
	ds_read_b128 v[148:151], v241 offset:39168
	ds_read_b128 v[184:187], v242 offset:59904
	ds_read_b128 v[152:155], v241 offset:41472
	ds_read_b128 v[216:219], v242 offset:62208
	ds_read_b128 v[156:159], v241 offset:43776
	s_setprio 1
	s_waitcnt lgkmcnt(6)
	v_mfma_f32_16x16x32_bf16 v[52:55], v[176:179], v[144:147], v[52:55]
	s_waitcnt vmcnt(15)
	ds_write_b128 v213, v[68:71]
	s_waitcnt lgkmcnt(6)
	v_mfma_f32_16x16x32_bf16 v[60:63], v[180:183], v[144:147], v[60:63]
	s_waitcnt lgkmcnt(5)
	v_mfma_f32_16x16x32_bf16 v[56:59], v[176:179], v[148:151], v[56:59]
	s_waitcnt vmcnt(14)
	ds_write_b128 v213, v[76:79] offset:4608
	v_mfma_f32_16x16x32_bf16 v[64:67], v[180:183], v[148:151], v[64:67]
	ds_read_b128 v[160:163], v241 offset:36928
	s_waitcnt lgkmcnt(6)
	v_mfma_f32_16x16x32_bf16 v[36:39], v[184:187], v[144:147], v[36:39]
	ds_read_b128 v[220:223], v242 offset:55360
	s_waitcnt vmcnt(13)
	ds_write_b128 v213, v[80:83] offset:9216
	v_add_co_u32_e32 v72, vcc, 0x1000, v72
	s_nop 1
	v_addc_co_u32_e32 v73, vcc, 0, v73, vcc
	v_add_co_u32_e32 v74, vcc, 0x1000, v74
	s_nop 1
	v_addc_co_u32_e32 v75, vcc, 0, v75, vcc
	v_add_co_u32_e32 v106, vcc, 0x1000, v106
	s_nop 1
	v_addc_co_u32_e32 v107, vcc, 0, v107, vcc
	v_add_co_u32_e32 v188, vcc, 0x1000, v188
	s_nop 1
	v_addc_co_u32_e32 v189, vcc, 0, v189, vcc
	v_add_co_u32_e32 v104, vcc, 0x1000, v104
	s_nop 1
	v_addc_co_u32_e32 v105, vcc, 0, v105, vcc
	v_add_co_u32_e32 v214, vcc, 0x1000, v214
	s_nop 1
	v_addc_co_u32_e32 v215, vcc, 0, v215, vcc
	v_add_co_u32_e32 v236, vcc, 0x1000, v236
	s_nop 1
	v_addc_co_u32_e32 v237, vcc, 0, v237, vcc
	v_add_co_u32_e32 v238, vcc, 0x1000, v238
	s_nop 1
	v_addc_co_u32_e32 v239, vcc, 0, v239, vcc
	global_load_dwordx4 v[68:71], v[72:73], off
	v_mfma_f32_16x16x32_bf16 v[40:43], v[184:187], v[148:151], v[40:43]
	ds_read_b128 v[224:227], v242 offset:57664
	s_waitcnt lgkmcnt(8)
	v_mfma_f32_16x16x32_bf16 v[20:23], v[176:179], v[152:155], v[20:23]
	ds_read_b128 v[164:167], v241 offset:39232
	v_mfma_f32_16x16x32_bf16 v[28:31], v[180:183], v[152:155], v[28:31]
	v_mfma_f32_16x16x32_bf16 v[4:7], v[184:187], v[152:155], v[4:7]
	ds_read_b128 v[228:231], v242 offset:59968
	s_waitcnt lgkmcnt(9)
	v_mfma_f32_16x16x32_bf16 v[44:47], v[216:219], v[144:147], v[44:47]
	ds_read_b128 v[168:171], v241 offset:41536
	v_mfma_f32_16x16x32_bf16 v[48:51], v[216:219], v[148:151], v[48:51]
	s_waitcnt vmcnt(13)
	ds_write_b128 v213, v[84:87] offset:13824
	global_load_dwordx4 v[76:79], v[74:75], off
	v_mfma_f32_16x16x32_bf16 v[12:15], v[216:219], v[152:155], v[12:15]
	ds_read_b128 v[232:235], v242 offset:62272
	s_waitcnt lgkmcnt(11)
	v_mfma_f32_16x16x32_bf16 v[24:27], v[176:179], v[156:159], v[24:27]
	ds_read_b128 v[172:175], v241 offset:43840
	s_waitcnt vmcnt(13)
	ds_write_b128 v213, v[88:91] offset:18432
	global_load_dwordx4 v[80:83], v[106:107], off
	v_mfma_f32_16x16x32_bf16 v[32:35], v[180:183], v[156:159], v[32:35]
	v_mfma_f32_16x16x32_bf16 v[8:11], v[184:187], v[156:159], v[8:11]
	v_mfma_f32_16x16x32_bf16 v[16:19], v[216:219], v[156:159], v[16:19]
	s_waitcnt lgkmcnt(9)
	v_mfma_f32_16x16x32_bf16 v[52:55], v[220:223], v[160:163], v[52:55]
	s_waitcnt lgkmcnt(7)
	v_mfma_f32_16x16x32_bf16 v[60:63], v[224:227], v[160:163], v[60:63]
	s_waitcnt lgkmcnt(6)
	v_mfma_f32_16x16x32_bf16 v[56:59], v[220:223], v[164:167], v[56:59]
	s_waitcnt vmcnt(13)
	ds_write_b128 v213, v[92:95] offset:23040
	global_load_dwordx4 v[84:87], v[188:189], off
	v_mfma_f32_16x16x32_bf16 v[64:67], v[224:227], v[164:167], v[64:67]
	s_waitcnt lgkmcnt(6)
	v_mfma_f32_16x16x32_bf16 v[36:39], v[228:231], v[160:163], v[36:39]
	s_waitcnt vmcnt(13)
	ds_write_b128 v213, v[96:99] offset:27648
	global_load_dwordx4 v[88:91], v[104:105], off
	v_mfma_f32_16x16x32_bf16 v[40:43], v[228:231], v[164:167], v[40:43]
	s_waitcnt lgkmcnt(6)
	v_mfma_f32_16x16x32_bf16 v[20:23], v[220:223], v[168:171], v[20:23]
	s_waitcnt vmcnt(13)
	ds_write_b128 v213, v[100:103] offset:32256
	global_load_dwordx4 v[92:95], v[214:215], off
	v_mfma_f32_16x16x32_bf16 v[28:31], v[224:227], v[168:171], v[28:31]
	v_mfma_f32_16x16x32_bf16 v[4:7], v[228:231], v[168:171], v[4:7]
	global_load_dwordx4 v[96:99], v[236:237], off
	s_waitcnt lgkmcnt(5)
	v_mfma_f32_16x16x32_bf16 v[44:47], v[232:235], v[160:163], v[44:47]
	v_mfma_f32_16x16x32_bf16 v[48:51], v[232:235], v[164:167], v[48:51]
	global_load_dwordx4 v[100:103], v[238:239], off
	v_mfma_f32_16x16x32_bf16 v[12:15], v[232:235], v[168:171], v[12:15]
	s_waitcnt lgkmcnt(4)
	v_mfma_f32_16x16x32_bf16 v[24:27], v[220:223], v[172:175], v[24:27]
	v_mfma_f32_16x16x32_bf16 v[32:35], v[224:227], v[172:175], v[32:35]
	v_mfma_f32_16x16x32_bf16 v[8:11], v[228:231], v[172:175], v[8:11]
	v_mfma_f32_16x16x32_bf16 v[16:19], v[232:235], v[172:175], v[16:19]
	s_setprio 0
	s_waitcnt lgkmcnt(0)
	s_barrier
	ds_read_b128 v[144:147], v241
	ds_read_b128 v[176:179], v242 offset:18432
	ds_read_b128 v[180:183], v242 offset:20736
	ds_read_b128 v[148:151], v241 offset:2304
	ds_read_b128 v[184:187], v242 offset:23040
	ds_read_b128 v[152:155], v241 offset:4608
	ds_read_b128 v[216:219], v242 offset:25344
	ds_read_b128 v[156:159], v241 offset:6912
	s_setprio 1
	s_waitcnt lgkmcnt(6)
	v_mfma_f32_16x16x32_bf16 v[52:55], v[176:179], v[144:147], v[52:55]
	s_waitcnt vmcnt(15)
	ds_write_b128 v240, v[108:111]
	s_waitcnt lgkmcnt(6)
	v_mfma_f32_16x16x32_bf16 v[60:63], v[180:183], v[144:147], v[60:63]
	s_waitcnt lgkmcnt(5)
	v_mfma_f32_16x16x32_bf16 v[56:59], v[176:179], v[148:151], v[56:59]
	s_waitcnt vmcnt(14)
	ds_write_b128 v240, v[112:115] offset:4608
	v_mfma_f32_16x16x32_bf16 v[64:67], v[180:183], v[148:151], v[64:67]
	ds_read_b128 v[160:163], v241 offset:64
	s_waitcnt lgkmcnt(6)
	v_mfma_f32_16x16x32_bf16 v[36:39], v[184:187], v[144:147], v[36:39]
	ds_read_b128 v[220:223], v242 offset:18496
	s_waitcnt vmcnt(13)
	ds_write_b128 v240, v[116:119] offset:9216
	global_load_dwordx4 v[108:111], v[72:73], off offset:128
	v_mfma_f32_16x16x32_bf16 v[40:43], v[184:187], v[148:151], v[40:43]
	ds_read_b128 v[224:227], v242 offset:20800
	s_waitcnt lgkmcnt(8)
	v_mfma_f32_16x16x32_bf16 v[20:23], v[176:179], v[152:155], v[20:23]
	ds_read_b128 v[164:167], v241 offset:2368
	v_mfma_f32_16x16x32_bf16 v[28:31], v[180:183], v[152:155], v[28:31]
	v_mfma_f32_16x16x32_bf16 v[4:7], v[184:187], v[152:155], v[4:7]
	ds_read_b128 v[228:231], v242 offset:23104
	s_waitcnt lgkmcnt(9)
	v_mfma_f32_16x16x32_bf16 v[44:47], v[216:219], v[144:147], v[44:47]
	ds_read_b128 v[168:171], v241 offset:4672
	v_mfma_f32_16x16x32_bf16 v[48:51], v[216:219], v[148:151], v[48:51]
	s_waitcnt vmcnt(13)
	ds_write_b128 v240, v[120:123] offset:13824
	global_load_dwordx4 v[112:115], v[74:75], off offset:128
	v_mfma_f32_16x16x32_bf16 v[12:15], v[216:219], v[152:155], v[12:15]
	ds_read_b128 v[232:235], v242 offset:25408
	s_waitcnt lgkmcnt(11)
	v_mfma_f32_16x16x32_bf16 v[24:27], v[176:179], v[156:159], v[24:27]
	ds_read_b128 v[172:175], v241 offset:6976
	s_waitcnt vmcnt(13)
	ds_write_b128 v240, v[124:127] offset:18432
	global_load_dwordx4 v[116:119], v[106:107], off offset:128
	v_mfma_f32_16x16x32_bf16 v[32:35], v[180:183], v[156:159], v[32:35]
	v_mfma_f32_16x16x32_bf16 v[8:11], v[184:187], v[156:159], v[8:11]
	v_mfma_f32_16x16x32_bf16 v[16:19], v[216:219], v[156:159], v[16:19]
	s_waitcnt lgkmcnt(9)
	v_mfma_f32_16x16x32_bf16 v[52:55], v[220:223], v[160:163], v[52:55]
	s_waitcnt lgkmcnt(7)
	v_mfma_f32_16x16x32_bf16 v[60:63], v[224:227], v[160:163], v[60:63]
	s_waitcnt lgkmcnt(6)
	v_mfma_f32_16x16x32_bf16 v[56:59], v[220:223], v[164:167], v[56:59]
	s_waitcnt vmcnt(13)
	ds_write_b128 v240, v[128:131] offset:23040
	global_load_dwordx4 v[120:123], v[188:189], off offset:128
	v_mfma_f32_16x16x32_bf16 v[64:67], v[224:227], v[164:167], v[64:67]
	s_waitcnt lgkmcnt(6)
	v_mfma_f32_16x16x32_bf16 v[36:39], v[228:231], v[160:163], v[36:39]
	s_waitcnt vmcnt(13)
	ds_write_b128 v240, v[136:139] offset:27648
	global_load_dwordx4 v[124:127], v[104:105], off offset:128
	v_mfma_f32_16x16x32_bf16 v[40:43], v[228:231], v[164:167], v[40:43]
	s_waitcnt lgkmcnt(6)
	v_mfma_f32_16x16x32_bf16 v[20:23], v[220:223], v[168:171], v[20:23]
	s_waitcnt vmcnt(13)
	ds_write_b128 v240, v[140:143] offset:32256
	global_load_dwordx4 v[128:131], v[214:215], off offset:128
	v_mfma_f32_16x16x32_bf16 v[28:31], v[224:227], v[168:171], v[28:31]
	v_mfma_f32_16x16x32_bf16 v[4:7], v[228:231], v[168:171], v[4:7]
	global_load_dwordx4 v[136:139], v[236:237], off offset:128
	s_waitcnt lgkmcnt(5)
	v_mfma_f32_16x16x32_bf16 v[44:47], v[232:235], v[160:163], v[44:47]
	v_mfma_f32_16x16x32_bf16 v[48:51], v[232:235], v[164:167], v[48:51]
	global_load_dwordx4 v[140:143], v[238:239], off offset:128
	v_mfma_f32_16x16x32_bf16 v[12:15], v[232:235], v[168:171], v[12:15]
	s_waitcnt lgkmcnt(4)
	v_mfma_f32_16x16x32_bf16 v[24:27], v[220:223], v[172:175], v[24:27]
	v_mfma_f32_16x16x32_bf16 v[32:35], v[224:227], v[172:175], v[32:35]
	v_mfma_f32_16x16x32_bf16 v[8:11], v[228:231], v[172:175], v[8:11]
	v_mfma_f32_16x16x32_bf16 v[16:19], v[232:235], v[172:175], v[16:19]
	s_setprio 0
	s_waitcnt lgkmcnt(0)
	s_barrier
	ds_read_b128 v[144:147], v241 offset:36864
	ds_read_b128 v[176:179], v242 offset:55296
	ds_read_b128 v[180:183], v242 offset:57600
	ds_read_b128 v[148:151], v241 offset:39168
	ds_read_b128 v[184:187], v242 offset:59904
	ds_read_b128 v[152:155], v241 offset:41472
	ds_read_b128 v[216:219], v242 offset:62208
	ds_read_b128 v[156:159], v241 offset:43776
	s_setprio 1
	s_waitcnt lgkmcnt(6)
	v_mfma_f32_16x16x32_bf16 v[52:55], v[176:179], v[144:147], v[52:55]
	s_waitcnt vmcnt(15)
	ds_write_b128 v213, v[68:71]
	s_waitcnt lgkmcnt(6)
	v_mfma_f32_16x16x32_bf16 v[60:63], v[180:183], v[144:147], v[60:63]
	s_waitcnt lgkmcnt(5)
	v_mfma_f32_16x16x32_bf16 v[56:59], v[176:179], v[148:151], v[56:59]
	s_waitcnt vmcnt(14)
	ds_write_b128 v213, v[76:79] offset:4608
	v_mfma_f32_16x16x32_bf16 v[64:67], v[180:183], v[148:151], v[64:67]
	ds_read_b128 v[160:163], v241 offset:36928
	s_waitcnt lgkmcnt(6)
	v_mfma_f32_16x16x32_bf16 v[36:39], v[184:187], v[144:147], v[36:39]
	ds_read_b128 v[220:223], v242 offset:55360
	s_waitcnt vmcnt(13)
	ds_write_b128 v213, v[80:83] offset:9216
	global_load_dwordx4 v[68:71], v[72:73], off offset:256
	v_mfma_f32_16x16x32_bf16 v[40:43], v[184:187], v[148:151], v[40:43]
	ds_read_b128 v[224:227], v242 offset:57664
	s_waitcnt lgkmcnt(8)
	v_mfma_f32_16x16x32_bf16 v[20:23], v[176:179], v[152:155], v[20:23]
	ds_read_b128 v[164:167], v241 offset:39232
	v_mfma_f32_16x16x32_bf16 v[28:31], v[180:183], v[152:155], v[28:31]
	v_mfma_f32_16x16x32_bf16 v[4:7], v[184:187], v[152:155], v[4:7]
	ds_read_b128 v[228:231], v242 offset:59968
	s_waitcnt lgkmcnt(9)
	v_mfma_f32_16x16x32_bf16 v[44:47], v[216:219], v[144:147], v[44:47]
	ds_read_b128 v[168:171], v241 offset:41536
	v_mfma_f32_16x16x32_bf16 v[48:51], v[216:219], v[148:151], v[48:51]
	s_waitcnt vmcnt(13)
	ds_write_b128 v213, v[84:87] offset:13824
	global_load_dwordx4 v[76:79], v[74:75], off offset:256
	v_mfma_f32_16x16x32_bf16 v[12:15], v[216:219], v[152:155], v[12:15]
	ds_read_b128 v[232:235], v242 offset:62272
	s_waitcnt lgkmcnt(11)
	v_mfma_f32_16x16x32_bf16 v[24:27], v[176:179], v[156:159], v[24:27]
	ds_read_b128 v[172:175], v241 offset:43840
	s_waitcnt vmcnt(13)
	ds_write_b128 v213, v[88:91] offset:18432
	global_load_dwordx4 v[80:83], v[106:107], off offset:256
	v_mfma_f32_16x16x32_bf16 v[32:35], v[180:183], v[156:159], v[32:35]
	v_mfma_f32_16x16x32_bf16 v[8:11], v[184:187], v[156:159], v[8:11]
	v_mfma_f32_16x16x32_bf16 v[16:19], v[216:219], v[156:159], v[16:19]
	s_waitcnt lgkmcnt(9)
	v_mfma_f32_16x16x32_bf16 v[52:55], v[220:223], v[160:163], v[52:55]
	s_waitcnt lgkmcnt(7)
	v_mfma_f32_16x16x32_bf16 v[60:63], v[224:227], v[160:163], v[60:63]
	s_waitcnt lgkmcnt(6)
	v_mfma_f32_16x16x32_bf16 v[56:59], v[220:223], v[164:167], v[56:59]
	s_waitcnt vmcnt(13)
	ds_write_b128 v213, v[92:95] offset:23040
	global_load_dwordx4 v[84:87], v[188:189], off offset:256
	v_mfma_f32_16x16x32_bf16 v[64:67], v[224:227], v[164:167], v[64:67]
	s_waitcnt lgkmcnt(6)
	v_mfma_f32_16x16x32_bf16 v[36:39], v[228:231], v[160:163], v[36:39]
	s_waitcnt vmcnt(13)
	ds_write_b128 v213, v[96:99] offset:27648
	global_load_dwordx4 v[88:91], v[104:105], off offset:256
	v_mfma_f32_16x16x32_bf16 v[40:43], v[228:231], v[164:167], v[40:43]
	s_waitcnt lgkmcnt(6)
	v_mfma_f32_16x16x32_bf16 v[20:23], v[220:223], v[168:171], v[20:23]
	s_waitcnt vmcnt(13)
	ds_write_b128 v213, v[100:103] offset:32256
	global_load_dwordx4 v[92:95], v[214:215], off offset:256
	v_mfma_f32_16x16x32_bf16 v[28:31], v[224:227], v[168:171], v[28:31]
	v_mfma_f32_16x16x32_bf16 v[4:7], v[228:231], v[168:171], v[4:7]
	global_load_dwordx4 v[96:99], v[236:237], off offset:256
	s_waitcnt lgkmcnt(5)
	v_mfma_f32_16x16x32_bf16 v[44:47], v[232:235], v[160:163], v[44:47]
	v_mfma_f32_16x16x32_bf16 v[48:51], v[232:235], v[164:167], v[48:51]
	global_load_dwordx4 v[100:103], v[238:239], off offset:256
	v_mfma_f32_16x16x32_bf16 v[12:15], v[232:235], v[168:171], v[12:15]
	s_waitcnt lgkmcnt(4)
	v_mfma_f32_16x16x32_bf16 v[24:27], v[220:223], v[172:175], v[24:27]
	v_mfma_f32_16x16x32_bf16 v[32:35], v[224:227], v[172:175], v[32:35]
	v_mfma_f32_16x16x32_bf16 v[8:11], v[228:231], v[172:175], v[8:11]
	v_mfma_f32_16x16x32_bf16 v[16:19], v[232:235], v[172:175], v[16:19]
	s_setprio 0
	s_waitcnt lgkmcnt(0)
	s_barrier
	ds_read_b128 v[144:147], v241
	ds_read_b128 v[176:179], v242 offset:18432
	ds_read_b128 v[180:183], v242 offset:20736
	ds_read_b128 v[148:151], v241 offset:2304
	ds_read_b128 v[184:187], v242 offset:23040
	ds_read_b128 v[152:155], v241 offset:4608
	ds_read_b128 v[216:219], v242 offset:25344
	ds_read_b128 v[156:159], v241 offset:6912
	s_setprio 1
	s_waitcnt lgkmcnt(6)
	v_mfma_f32_16x16x32_bf16 v[52:55], v[176:179], v[144:147], v[52:55]
	s_waitcnt vmcnt(15)
	ds_write_b128 v240, v[108:111]
	s_waitcnt lgkmcnt(6)
	v_mfma_f32_16x16x32_bf16 v[60:63], v[180:183], v[144:147], v[60:63]
	s_waitcnt lgkmcnt(5)
	v_mfma_f32_16x16x32_bf16 v[56:59], v[176:179], v[148:151], v[56:59]
	s_waitcnt vmcnt(14)
	ds_write_b128 v240, v[112:115] offset:4608
	v_mfma_f32_16x16x32_bf16 v[64:67], v[180:183], v[148:151], v[64:67]
	ds_read_b128 v[160:163], v241 offset:64
	s_waitcnt lgkmcnt(6)
	v_mfma_f32_16x16x32_bf16 v[36:39], v[184:187], v[144:147], v[36:39]
	ds_read_b128 v[220:223], v242 offset:18496
	s_waitcnt vmcnt(13)
	ds_write_b128 v240, v[116:119] offset:9216
	global_load_dwordx4 v[108:111], v[72:73], off offset:384
	v_mfma_f32_16x16x32_bf16 v[40:43], v[184:187], v[148:151], v[40:43]
	ds_read_b128 v[224:227], v242 offset:20800
	s_waitcnt lgkmcnt(8)
	v_mfma_f32_16x16x32_bf16 v[20:23], v[176:179], v[152:155], v[20:23]
	ds_read_b128 v[164:167], v241 offset:2368
	v_mfma_f32_16x16x32_bf16 v[28:31], v[180:183], v[152:155], v[28:31]
	v_mfma_f32_16x16x32_bf16 v[4:7], v[184:187], v[152:155], v[4:7]
	ds_read_b128 v[228:231], v242 offset:23104
	s_waitcnt lgkmcnt(9)
	v_mfma_f32_16x16x32_bf16 v[44:47], v[216:219], v[144:147], v[44:47]
	ds_read_b128 v[168:171], v241 offset:4672
	v_mfma_f32_16x16x32_bf16 v[48:51], v[216:219], v[148:151], v[48:51]
	s_waitcnt vmcnt(13)
	ds_write_b128 v240, v[120:123] offset:13824
	global_load_dwordx4 v[112:115], v[74:75], off offset:384
	v_mfma_f32_16x16x32_bf16 v[12:15], v[216:219], v[152:155], v[12:15]
	ds_read_b128 v[232:235], v242 offset:25408
	s_waitcnt lgkmcnt(11)
	v_mfma_f32_16x16x32_bf16 v[24:27], v[176:179], v[156:159], v[24:27]
	ds_read_b128 v[172:175], v241 offset:6976
	s_waitcnt vmcnt(13)
	ds_write_b128 v240, v[124:127] offset:18432
	global_load_dwordx4 v[116:119], v[106:107], off offset:384
	v_mfma_f32_16x16x32_bf16 v[32:35], v[180:183], v[156:159], v[32:35]
	v_mfma_f32_16x16x32_bf16 v[8:11], v[184:187], v[156:159], v[8:11]
	v_mfma_f32_16x16x32_bf16 v[16:19], v[216:219], v[156:159], v[16:19]
	s_waitcnt lgkmcnt(9)
	v_mfma_f32_16x16x32_bf16 v[52:55], v[220:223], v[160:163], v[52:55]
	s_waitcnt lgkmcnt(7)
	v_mfma_f32_16x16x32_bf16 v[60:63], v[224:227], v[160:163], v[60:63]
	s_waitcnt lgkmcnt(6)
	v_mfma_f32_16x16x32_bf16 v[56:59], v[220:223], v[164:167], v[56:59]
	s_waitcnt vmcnt(13)
	ds_write_b128 v240, v[128:131] offset:23040
	global_load_dwordx4 v[120:123], v[188:189], off offset:384
	v_mfma_f32_16x16x32_bf16 v[64:67], v[224:227], v[164:167], v[64:67]
	s_waitcnt lgkmcnt(6)
	v_mfma_f32_16x16x32_bf16 v[36:39], v[228:231], v[160:163], v[36:39]
	s_waitcnt vmcnt(13)
	ds_write_b128 v240, v[136:139] offset:27648
	global_load_dwordx4 v[124:127], v[104:105], off offset:384
	v_mfma_f32_16x16x32_bf16 v[40:43], v[228:231], v[164:167], v[40:43]
	s_waitcnt lgkmcnt(6)
	v_mfma_f32_16x16x32_bf16 v[20:23], v[220:223], v[168:171], v[20:23]
	s_waitcnt vmcnt(13)
	ds_write_b128 v240, v[140:143] offset:32256
	global_load_dwordx4 v[128:131], v[214:215], off offset:384
	v_mfma_f32_16x16x32_bf16 v[28:31], v[224:227], v[168:171], v[28:31]
	v_mfma_f32_16x16x32_bf16 v[4:7], v[228:231], v[168:171], v[4:7]
	global_load_dwordx4 v[136:139], v[236:237], off offset:384
	s_waitcnt lgkmcnt(5)
	v_mfma_f32_16x16x32_bf16 v[44:47], v[232:235], v[160:163], v[44:47]
	v_mfma_f32_16x16x32_bf16 v[48:51], v[232:235], v[164:167], v[48:51]
	global_load_dwordx4 v[140:143], v[238:239], off offset:384
	v_mfma_f32_16x16x32_bf16 v[12:15], v[232:235], v[168:171], v[12:15]
	s_waitcnt lgkmcnt(4)
	v_mfma_f32_16x16x32_bf16 v[24:27], v[220:223], v[172:175], v[24:27]
	v_mfma_f32_16x16x32_bf16 v[32:35], v[224:227], v[172:175], v[32:35]
	v_mfma_f32_16x16x32_bf16 v[8:11], v[228:231], v[172:175], v[8:11]
	v_mfma_f32_16x16x32_bf16 v[16:19], v[232:235], v[172:175], v[16:19]
	s_setprio 0
	s_waitcnt lgkmcnt(0)
	s_barrier
	ds_read_b128 v[144:147], v241 offset:36864
	ds_read_b128 v[176:179], v242 offset:55296
	ds_read_b128 v[180:183], v242 offset:57600
	ds_read_b128 v[148:151], v241 offset:39168
	ds_read_b128 v[184:187], v242 offset:59904
	ds_read_b128 v[152:155], v241 offset:41472
	ds_read_b128 v[216:219], v242 offset:62208
	ds_read_b128 v[156:159], v241 offset:43776
	s_setprio 1
	s_waitcnt lgkmcnt(6)
	v_mfma_f32_16x16x32_bf16 v[52:55], v[176:179], v[144:147], v[52:55]
	s_waitcnt vmcnt(15)
	ds_write_b128 v213, v[68:71]
	s_waitcnt lgkmcnt(6)
	v_mfma_f32_16x16x32_bf16 v[60:63], v[180:183], v[144:147], v[60:63]
	s_waitcnt lgkmcnt(5)
	v_mfma_f32_16x16x32_bf16 v[56:59], v[176:179], v[148:151], v[56:59]
	s_waitcnt vmcnt(14)
	ds_write_b128 v213, v[76:79] offset:4608
	v_mfma_f32_16x16x32_bf16 v[64:67], v[180:183], v[148:151], v[64:67]
	ds_read_b128 v[160:163], v241 offset:36928
	s_waitcnt lgkmcnt(6)
	v_mfma_f32_16x16x32_bf16 v[36:39], v[184:187], v[144:147], v[36:39]
	ds_read_b128 v[220:223], v242 offset:55360
	s_waitcnt vmcnt(13)
	ds_write_b128 v213, v[80:83] offset:9216
	global_load_dwordx4 v[68:71], v[72:73], off offset:512
	v_mfma_f32_16x16x32_bf16 v[40:43], v[184:187], v[148:151], v[40:43]
	ds_read_b128 v[224:227], v242 offset:57664
	s_waitcnt lgkmcnt(8)
	v_mfma_f32_16x16x32_bf16 v[20:23], v[176:179], v[152:155], v[20:23]
	ds_read_b128 v[164:167], v241 offset:39232
	v_mfma_f32_16x16x32_bf16 v[28:31], v[180:183], v[152:155], v[28:31]
	v_mfma_f32_16x16x32_bf16 v[4:7], v[184:187], v[152:155], v[4:7]
	ds_read_b128 v[228:231], v242 offset:59968
	s_waitcnt lgkmcnt(9)
	v_mfma_f32_16x16x32_bf16 v[44:47], v[216:219], v[144:147], v[44:47]
	ds_read_b128 v[168:171], v241 offset:41536
	v_mfma_f32_16x16x32_bf16 v[48:51], v[216:219], v[148:151], v[48:51]
	s_waitcnt vmcnt(13)
	ds_write_b128 v213, v[84:87] offset:13824
	global_load_dwordx4 v[76:79], v[74:75], off offset:512
	v_mfma_f32_16x16x32_bf16 v[12:15], v[216:219], v[152:155], v[12:15]
	ds_read_b128 v[232:235], v242 offset:62272
	s_waitcnt lgkmcnt(11)
	v_mfma_f32_16x16x32_bf16 v[24:27], v[176:179], v[156:159], v[24:27]
	ds_read_b128 v[172:175], v241 offset:43840
	s_waitcnt vmcnt(13)
	ds_write_b128 v213, v[88:91] offset:18432
	global_load_dwordx4 v[80:83], v[106:107], off offset:512
	v_mfma_f32_16x16x32_bf16 v[32:35], v[180:183], v[156:159], v[32:35]
	v_mfma_f32_16x16x32_bf16 v[8:11], v[184:187], v[156:159], v[8:11]
	v_mfma_f32_16x16x32_bf16 v[16:19], v[216:219], v[156:159], v[16:19]
	s_waitcnt lgkmcnt(9)
	v_mfma_f32_16x16x32_bf16 v[52:55], v[220:223], v[160:163], v[52:55]
	s_waitcnt lgkmcnt(7)
	v_mfma_f32_16x16x32_bf16 v[60:63], v[224:227], v[160:163], v[60:63]
	s_waitcnt lgkmcnt(6)
	v_mfma_f32_16x16x32_bf16 v[56:59], v[220:223], v[164:167], v[56:59]
	s_waitcnt vmcnt(13)
	ds_write_b128 v213, v[92:95] offset:23040
	global_load_dwordx4 v[84:87], v[188:189], off offset:512
	v_mfma_f32_16x16x32_bf16 v[64:67], v[224:227], v[164:167], v[64:67]
	s_waitcnt lgkmcnt(6)
	v_mfma_f32_16x16x32_bf16 v[36:39], v[228:231], v[160:163], v[36:39]
	s_waitcnt vmcnt(13)
	ds_write_b128 v213, v[96:99] offset:27648
	global_load_dwordx4 v[88:91], v[104:105], off offset:512
	v_mfma_f32_16x16x32_bf16 v[40:43], v[228:231], v[164:167], v[40:43]
	s_waitcnt lgkmcnt(6)
	v_mfma_f32_16x16x32_bf16 v[20:23], v[220:223], v[168:171], v[20:23]
	s_waitcnt vmcnt(13)
	ds_write_b128 v213, v[100:103] offset:32256
	global_load_dwordx4 v[92:95], v[214:215], off offset:512
	v_mfma_f32_16x16x32_bf16 v[28:31], v[224:227], v[168:171], v[28:31]
	v_mfma_f32_16x16x32_bf16 v[4:7], v[228:231], v[168:171], v[4:7]
	global_load_dwordx4 v[96:99], v[236:237], off offset:512
	s_waitcnt lgkmcnt(5)
	v_mfma_f32_16x16x32_bf16 v[44:47], v[232:235], v[160:163], v[44:47]
	v_mfma_f32_16x16x32_bf16 v[48:51], v[232:235], v[164:167], v[48:51]
	global_load_dwordx4 v[100:103], v[238:239], off offset:512
	v_mfma_f32_16x16x32_bf16 v[12:15], v[232:235], v[168:171], v[12:15]
	s_waitcnt lgkmcnt(4)
	v_mfma_f32_16x16x32_bf16 v[24:27], v[220:223], v[172:175], v[24:27]
	v_mfma_f32_16x16x32_bf16 v[32:35], v[224:227], v[172:175], v[32:35]
	v_mfma_f32_16x16x32_bf16 v[8:11], v[228:231], v[172:175], v[8:11]
	v_mfma_f32_16x16x32_bf16 v[16:19], v[232:235], v[172:175], v[16:19]
	s_setprio 0
	s_waitcnt lgkmcnt(0)
	s_barrier
	ds_read_b128 v[144:147], v241
	ds_read_b128 v[176:179], v242 offset:18432
	ds_read_b128 v[180:183], v242 offset:20736
	ds_read_b128 v[148:151], v241 offset:2304
	ds_read_b128 v[184:187], v242 offset:23040
	ds_read_b128 v[152:155], v241 offset:4608
	ds_read_b128 v[216:219], v242 offset:25344
	ds_read_b128 v[156:159], v241 offset:6912
	s_setprio 1
	s_waitcnt lgkmcnt(6)
	v_mfma_f32_16x16x32_bf16 v[52:55], v[176:179], v[144:147], v[52:55]
	s_waitcnt vmcnt(15)
	ds_write_b128 v240, v[108:111]
	s_waitcnt lgkmcnt(6)
	v_mfma_f32_16x16x32_bf16 v[60:63], v[180:183], v[144:147], v[60:63]
	s_waitcnt lgkmcnt(5)
	v_mfma_f32_16x16x32_bf16 v[56:59], v[176:179], v[148:151], v[56:59]
	s_waitcnt vmcnt(14)
	ds_write_b128 v240, v[112:115] offset:4608
	v_mfma_f32_16x16x32_bf16 v[64:67], v[180:183], v[148:151], v[64:67]
	ds_read_b128 v[160:163], v241 offset:64
	s_waitcnt lgkmcnt(6)
	v_mfma_f32_16x16x32_bf16 v[36:39], v[184:187], v[144:147], v[36:39]
	ds_read_b128 v[220:223], v242 offset:18496
	s_waitcnt vmcnt(13)
	ds_write_b128 v240, v[116:119] offset:9216
	global_load_dwordx4 v[108:111], v[72:73], off offset:640
	v_mfma_f32_16x16x32_bf16 v[40:43], v[184:187], v[148:151], v[40:43]
	ds_read_b128 v[224:227], v242 offset:20800
	s_waitcnt lgkmcnt(8)
	v_mfma_f32_16x16x32_bf16 v[20:23], v[176:179], v[152:155], v[20:23]
	ds_read_b128 v[164:167], v241 offset:2368
	v_mfma_f32_16x16x32_bf16 v[28:31], v[180:183], v[152:155], v[28:31]
	v_mfma_f32_16x16x32_bf16 v[4:7], v[184:187], v[152:155], v[4:7]
	ds_read_b128 v[228:231], v242 offset:23104
	s_waitcnt lgkmcnt(9)
	v_mfma_f32_16x16x32_bf16 v[44:47], v[216:219], v[144:147], v[44:47]
	ds_read_b128 v[168:171], v241 offset:4672
	v_mfma_f32_16x16x32_bf16 v[48:51], v[216:219], v[148:151], v[48:51]
	s_waitcnt vmcnt(13)
	ds_write_b128 v240, v[120:123] offset:13824
	global_load_dwordx4 v[112:115], v[74:75], off offset:640
	v_mfma_f32_16x16x32_bf16 v[12:15], v[216:219], v[152:155], v[12:15]
	ds_read_b128 v[232:235], v242 offset:25408
	s_waitcnt lgkmcnt(11)
	v_mfma_f32_16x16x32_bf16 v[24:27], v[176:179], v[156:159], v[24:27]
	ds_read_b128 v[172:175], v241 offset:6976
	s_waitcnt vmcnt(13)
	ds_write_b128 v240, v[124:127] offset:18432
	global_load_dwordx4 v[116:119], v[106:107], off offset:640
	v_mfma_f32_16x16x32_bf16 v[32:35], v[180:183], v[156:159], v[32:35]
	v_mfma_f32_16x16x32_bf16 v[8:11], v[184:187], v[156:159], v[8:11]
	v_mfma_f32_16x16x32_bf16 v[16:19], v[216:219], v[156:159], v[16:19]
	s_waitcnt lgkmcnt(9)
	v_mfma_f32_16x16x32_bf16 v[52:55], v[220:223], v[160:163], v[52:55]
	s_waitcnt lgkmcnt(7)
	v_mfma_f32_16x16x32_bf16 v[60:63], v[224:227], v[160:163], v[60:63]
	s_waitcnt lgkmcnt(6)
	v_mfma_f32_16x16x32_bf16 v[56:59], v[220:223], v[164:167], v[56:59]
	s_waitcnt vmcnt(13)
	ds_write_b128 v240, v[128:131] offset:23040
	global_load_dwordx4 v[120:123], v[188:189], off offset:640
	v_mfma_f32_16x16x32_bf16 v[64:67], v[224:227], v[164:167], v[64:67]
	s_waitcnt lgkmcnt(6)
	v_mfma_f32_16x16x32_bf16 v[36:39], v[228:231], v[160:163], v[36:39]
	s_waitcnt vmcnt(13)
	ds_write_b128 v240, v[136:139] offset:27648
	global_load_dwordx4 v[124:127], v[104:105], off offset:640
	v_mfma_f32_16x16x32_bf16 v[40:43], v[228:231], v[164:167], v[40:43]
	s_waitcnt lgkmcnt(6)
	v_mfma_f32_16x16x32_bf16 v[20:23], v[220:223], v[168:171], v[20:23]
	s_waitcnt vmcnt(13)
	ds_write_b128 v240, v[140:143] offset:32256
	global_load_dwordx4 v[128:131], v[214:215], off offset:640
	v_mfma_f32_16x16x32_bf16 v[28:31], v[224:227], v[168:171], v[28:31]
	v_mfma_f32_16x16x32_bf16 v[4:7], v[228:231], v[168:171], v[4:7]
	global_load_dwordx4 v[136:139], v[236:237], off offset:640
	s_waitcnt lgkmcnt(5)
	v_mfma_f32_16x16x32_bf16 v[44:47], v[232:235], v[160:163], v[44:47]
	v_mfma_f32_16x16x32_bf16 v[48:51], v[232:235], v[164:167], v[48:51]
	global_load_dwordx4 v[140:143], v[238:239], off offset:640
	v_mfma_f32_16x16x32_bf16 v[12:15], v[232:235], v[168:171], v[12:15]
	s_waitcnt lgkmcnt(4)
	v_mfma_f32_16x16x32_bf16 v[24:27], v[220:223], v[172:175], v[24:27]
	v_mfma_f32_16x16x32_bf16 v[32:35], v[224:227], v[172:175], v[32:35]
	v_mfma_f32_16x16x32_bf16 v[8:11], v[228:231], v[172:175], v[8:11]
	v_mfma_f32_16x16x32_bf16 v[16:19], v[232:235], v[172:175], v[16:19]
	s_setprio 0
	s_waitcnt lgkmcnt(0)
	s_barrier
	ds_read_b128 v[144:147], v241 offset:36864
	ds_read_b128 v[176:179], v242 offset:55296
	ds_read_b128 v[180:183], v242 offset:57600
	ds_read_b128 v[148:151], v241 offset:39168
	ds_read_b128 v[184:187], v242 offset:59904
	ds_read_b128 v[152:155], v241 offset:41472
	ds_read_b128 v[216:219], v242 offset:62208
	ds_read_b128 v[156:159], v241 offset:43776
	s_setprio 1
	s_waitcnt lgkmcnt(6)
	v_mfma_f32_16x16x32_bf16 v[52:55], v[176:179], v[144:147], v[52:55]
	s_waitcnt vmcnt(15)
	ds_write_b128 v213, v[68:71]
	s_waitcnt lgkmcnt(6)
	v_mfma_f32_16x16x32_bf16 v[60:63], v[180:183], v[144:147], v[60:63]
	s_waitcnt lgkmcnt(5)
	v_mfma_f32_16x16x32_bf16 v[56:59], v[176:179], v[148:151], v[56:59]
	s_waitcnt vmcnt(14)
	ds_write_b128 v213, v[76:79] offset:4608
	v_mfma_f32_16x16x32_bf16 v[64:67], v[180:183], v[148:151], v[64:67]
	ds_read_b128 v[160:163], v241 offset:36928
	s_waitcnt lgkmcnt(6)
	v_mfma_f32_16x16x32_bf16 v[36:39], v[184:187], v[144:147], v[36:39]
	ds_read_b128 v[220:223], v242 offset:55360
	s_waitcnt vmcnt(13)
	ds_write_b128 v213, v[80:83] offset:9216
	global_load_dwordx4 v[68:71], v[72:73], off offset:768
	v_mfma_f32_16x16x32_bf16 v[40:43], v[184:187], v[148:151], v[40:43]
	ds_read_b128 v[224:227], v242 offset:57664
	s_waitcnt lgkmcnt(8)
	v_mfma_f32_16x16x32_bf16 v[20:23], v[176:179], v[152:155], v[20:23]
	ds_read_b128 v[164:167], v241 offset:39232
	v_mfma_f32_16x16x32_bf16 v[28:31], v[180:183], v[152:155], v[28:31]
	v_mfma_f32_16x16x32_bf16 v[4:7], v[184:187], v[152:155], v[4:7]
	ds_read_b128 v[228:231], v242 offset:59968
	s_waitcnt lgkmcnt(9)
	v_mfma_f32_16x16x32_bf16 v[44:47], v[216:219], v[144:147], v[44:47]
	ds_read_b128 v[168:171], v241 offset:41536
	v_mfma_f32_16x16x32_bf16 v[48:51], v[216:219], v[148:151], v[48:51]
	s_waitcnt vmcnt(13)
	ds_write_b128 v213, v[84:87] offset:13824
	global_load_dwordx4 v[76:79], v[74:75], off offset:768
	v_mfma_f32_16x16x32_bf16 v[12:15], v[216:219], v[152:155], v[12:15]
	ds_read_b128 v[232:235], v242 offset:62272
	s_waitcnt lgkmcnt(11)
	v_mfma_f32_16x16x32_bf16 v[24:27], v[176:179], v[156:159], v[24:27]
	ds_read_b128 v[172:175], v241 offset:43840
	s_waitcnt vmcnt(13)
	ds_write_b128 v213, v[88:91] offset:18432
	global_load_dwordx4 v[80:83], v[106:107], off offset:768
	v_mfma_f32_16x16x32_bf16 v[32:35], v[180:183], v[156:159], v[32:35]
	v_mfma_f32_16x16x32_bf16 v[8:11], v[184:187], v[156:159], v[8:11]
	v_mfma_f32_16x16x32_bf16 v[16:19], v[216:219], v[156:159], v[16:19]
	s_waitcnt lgkmcnt(9)
	v_mfma_f32_16x16x32_bf16 v[52:55], v[220:223], v[160:163], v[52:55]
	s_waitcnt lgkmcnt(7)
	v_mfma_f32_16x16x32_bf16 v[60:63], v[224:227], v[160:163], v[60:63]
	s_waitcnt lgkmcnt(6)
	v_mfma_f32_16x16x32_bf16 v[56:59], v[220:223], v[164:167], v[56:59]
	s_waitcnt vmcnt(13)
	ds_write_b128 v213, v[92:95] offset:23040
	global_load_dwordx4 v[84:87], v[188:189], off offset:768
	v_mfma_f32_16x16x32_bf16 v[64:67], v[224:227], v[164:167], v[64:67]
	s_waitcnt lgkmcnt(6)
	v_mfma_f32_16x16x32_bf16 v[36:39], v[228:231], v[160:163], v[36:39]
	s_waitcnt vmcnt(13)
	ds_write_b128 v213, v[96:99] offset:27648
	global_load_dwordx4 v[88:91], v[104:105], off offset:768
	v_mfma_f32_16x16x32_bf16 v[40:43], v[228:231], v[164:167], v[40:43]
	s_waitcnt lgkmcnt(6)
	v_mfma_f32_16x16x32_bf16 v[20:23], v[220:223], v[168:171], v[20:23]
	s_waitcnt vmcnt(13)
	ds_write_b128 v213, v[100:103] offset:32256
	global_load_dwordx4 v[92:95], v[214:215], off offset:768
	v_mfma_f32_16x16x32_bf16 v[28:31], v[224:227], v[168:171], v[28:31]
	v_mfma_f32_16x16x32_bf16 v[4:7], v[228:231], v[168:171], v[4:7]
	global_load_dwordx4 v[96:99], v[236:237], off offset:768
	s_waitcnt lgkmcnt(5)
	v_mfma_f32_16x16x32_bf16 v[44:47], v[232:235], v[160:163], v[44:47]
	v_mfma_f32_16x16x32_bf16 v[48:51], v[232:235], v[164:167], v[48:51]
	global_load_dwordx4 v[100:103], v[238:239], off offset:768
	v_mfma_f32_16x16x32_bf16 v[12:15], v[232:235], v[168:171], v[12:15]
	s_waitcnt lgkmcnt(4)
	v_mfma_f32_16x16x32_bf16 v[24:27], v[220:223], v[172:175], v[24:27]
	v_mfma_f32_16x16x32_bf16 v[32:35], v[224:227], v[172:175], v[32:35]
	v_mfma_f32_16x16x32_bf16 v[8:11], v[228:231], v[172:175], v[8:11]
	v_mfma_f32_16x16x32_bf16 v[16:19], v[232:235], v[172:175], v[16:19]
	s_setprio 0
	s_waitcnt lgkmcnt(0)
	s_barrier
	ds_read_b128 v[144:147], v241
	ds_read_b128 v[176:179], v242 offset:18432
	ds_read_b128 v[180:183], v242 offset:20736
	ds_read_b128 v[148:151], v241 offset:2304
	ds_read_b128 v[184:187], v242 offset:23040
	ds_read_b128 v[152:155], v241 offset:4608
	ds_read_b128 v[216:219], v242 offset:25344
	ds_read_b128 v[156:159], v241 offset:6912
	s_setprio 1
	s_waitcnt lgkmcnt(6)
	v_mfma_f32_16x16x32_bf16 v[52:55], v[176:179], v[144:147], v[52:55]
	s_waitcnt vmcnt(15)
	ds_write_b128 v240, v[108:111]
	s_waitcnt lgkmcnt(6)
	v_mfma_f32_16x16x32_bf16 v[60:63], v[180:183], v[144:147], v[60:63]
	s_waitcnt lgkmcnt(5)
	v_mfma_f32_16x16x32_bf16 v[56:59], v[176:179], v[148:151], v[56:59]
	s_waitcnt vmcnt(14)
	ds_write_b128 v240, v[112:115] offset:4608
	v_mfma_f32_16x16x32_bf16 v[64:67], v[180:183], v[148:151], v[64:67]
	ds_read_b128 v[160:163], v241 offset:64
	s_waitcnt lgkmcnt(6)
	v_mfma_f32_16x16x32_bf16 v[36:39], v[184:187], v[144:147], v[36:39]
	ds_read_b128 v[220:223], v242 offset:18496
	s_waitcnt vmcnt(13)
	ds_write_b128 v240, v[116:119] offset:9216
	global_load_dwordx4 v[108:111], v[72:73], off offset:896
	v_mfma_f32_16x16x32_bf16 v[40:43], v[184:187], v[148:151], v[40:43]
	ds_read_b128 v[224:227], v242 offset:20800
	s_waitcnt lgkmcnt(8)
	v_mfma_f32_16x16x32_bf16 v[20:23], v[176:179], v[152:155], v[20:23]
	ds_read_b128 v[164:167], v241 offset:2368
	v_mfma_f32_16x16x32_bf16 v[28:31], v[180:183], v[152:155], v[28:31]
	v_mfma_f32_16x16x32_bf16 v[4:7], v[184:187], v[152:155], v[4:7]
	ds_read_b128 v[228:231], v242 offset:23104
	s_waitcnt lgkmcnt(9)
	v_mfma_f32_16x16x32_bf16 v[44:47], v[216:219], v[144:147], v[44:47]
	ds_read_b128 v[168:171], v241 offset:4672
	v_mfma_f32_16x16x32_bf16 v[48:51], v[216:219], v[148:151], v[48:51]
	s_waitcnt vmcnt(13)
	ds_write_b128 v240, v[120:123] offset:13824
	global_load_dwordx4 v[112:115], v[74:75], off offset:896
	v_mfma_f32_16x16x32_bf16 v[12:15], v[216:219], v[152:155], v[12:15]
	ds_read_b128 v[232:235], v242 offset:25408
	s_waitcnt lgkmcnt(11)
	v_mfma_f32_16x16x32_bf16 v[24:27], v[176:179], v[156:159], v[24:27]
	ds_read_b128 v[172:175], v241 offset:6976
	s_waitcnt vmcnt(13)
	ds_write_b128 v240, v[124:127] offset:18432
	global_load_dwordx4 v[116:119], v[106:107], off offset:896
	v_mfma_f32_16x16x32_bf16 v[32:35], v[180:183], v[156:159], v[32:35]
	v_mfma_f32_16x16x32_bf16 v[8:11], v[184:187], v[156:159], v[8:11]
	v_mfma_f32_16x16x32_bf16 v[16:19], v[216:219], v[156:159], v[16:19]
	s_waitcnt lgkmcnt(9)
	v_mfma_f32_16x16x32_bf16 v[52:55], v[220:223], v[160:163], v[52:55]
	s_waitcnt lgkmcnt(7)
	v_mfma_f32_16x16x32_bf16 v[60:63], v[224:227], v[160:163], v[60:63]
	s_waitcnt lgkmcnt(6)
	v_mfma_f32_16x16x32_bf16 v[56:59], v[220:223], v[164:167], v[56:59]
	s_waitcnt vmcnt(13)
	ds_write_b128 v240, v[128:131] offset:23040
	global_load_dwordx4 v[120:123], v[188:189], off offset:896
	v_mfma_f32_16x16x32_bf16 v[64:67], v[224:227], v[164:167], v[64:67]
	s_waitcnt lgkmcnt(6)
	v_mfma_f32_16x16x32_bf16 v[36:39], v[228:231], v[160:163], v[36:39]
	s_waitcnt vmcnt(13)
	ds_write_b128 v240, v[136:139] offset:27648
	global_load_dwordx4 v[124:127], v[104:105], off offset:896
	v_mfma_f32_16x16x32_bf16 v[40:43], v[228:231], v[164:167], v[40:43]
	s_waitcnt lgkmcnt(6)
	v_mfma_f32_16x16x32_bf16 v[20:23], v[220:223], v[168:171], v[20:23]
	s_waitcnt vmcnt(13)
	ds_write_b128 v240, v[140:143] offset:32256
	global_load_dwordx4 v[128:131], v[214:215], off offset:896
	v_mfma_f32_16x16x32_bf16 v[28:31], v[224:227], v[168:171], v[28:31]
	v_mfma_f32_16x16x32_bf16 v[4:7], v[228:231], v[168:171], v[4:7]
	global_load_dwordx4 v[136:139], v[236:237], off offset:896
	s_waitcnt lgkmcnt(5)
	v_mfma_f32_16x16x32_bf16 v[44:47], v[232:235], v[160:163], v[44:47]
	v_mfma_f32_16x16x32_bf16 v[48:51], v[232:235], v[164:167], v[48:51]
	global_load_dwordx4 v[140:143], v[238:239], off offset:896
	v_mfma_f32_16x16x32_bf16 v[12:15], v[232:235], v[168:171], v[12:15]
	s_waitcnt lgkmcnt(4)
	v_mfma_f32_16x16x32_bf16 v[24:27], v[220:223], v[172:175], v[24:27]
	v_mfma_f32_16x16x32_bf16 v[32:35], v[224:227], v[172:175], v[32:35]
	v_mfma_f32_16x16x32_bf16 v[8:11], v[228:231], v[172:175], v[8:11]
	v_mfma_f32_16x16x32_bf16 v[16:19], v[232:235], v[172:175], v[16:19]
	s_setprio 0
	s_waitcnt lgkmcnt(0)
	s_barrier
	ds_read_b128 v[144:147], v241 offset:36864
	ds_read_b128 v[176:179], v242 offset:55296
	ds_read_b128 v[180:183], v242 offset:57600
	ds_read_b128 v[148:151], v241 offset:39168
	ds_read_b128 v[184:187], v242 offset:59904
	ds_read_b128 v[152:155], v241 offset:41472
	ds_read_b128 v[216:219], v242 offset:62208
	ds_read_b128 v[156:159], v241 offset:43776
	s_setprio 1
	s_waitcnt lgkmcnt(6)
	v_mfma_f32_16x16x32_bf16 v[52:55], v[176:179], v[144:147], v[52:55]
	s_waitcnt vmcnt(15)
	ds_write_b128 v213, v[68:71]
	s_waitcnt lgkmcnt(6)
	v_mfma_f32_16x16x32_bf16 v[60:63], v[180:183], v[144:147], v[60:63]
	s_waitcnt lgkmcnt(5)
	v_mfma_f32_16x16x32_bf16 v[56:59], v[176:179], v[148:151], v[56:59]
	s_waitcnt vmcnt(14)
	ds_write_b128 v213, v[76:79] offset:4608
	v_mfma_f32_16x16x32_bf16 v[64:67], v[180:183], v[148:151], v[64:67]
	ds_read_b128 v[160:163], v241 offset:36928
	s_waitcnt lgkmcnt(6)
	v_mfma_f32_16x16x32_bf16 v[36:39], v[184:187], v[144:147], v[36:39]
	ds_read_b128 v[220:223], v242 offset:55360
	s_waitcnt vmcnt(13)
	ds_write_b128 v213, v[80:83] offset:9216
	global_load_dwordx4 v[68:71], v[72:73], off offset:1024
	v_mfma_f32_16x16x32_bf16 v[40:43], v[184:187], v[148:151], v[40:43]
	ds_read_b128 v[224:227], v242 offset:57664
	s_waitcnt lgkmcnt(8)
	v_mfma_f32_16x16x32_bf16 v[20:23], v[176:179], v[152:155], v[20:23]
	ds_read_b128 v[164:167], v241 offset:39232
	v_mfma_f32_16x16x32_bf16 v[28:31], v[180:183], v[152:155], v[28:31]
	v_mfma_f32_16x16x32_bf16 v[4:7], v[184:187], v[152:155], v[4:7]
	ds_read_b128 v[228:231], v242 offset:59968
	s_waitcnt lgkmcnt(9)
	v_mfma_f32_16x16x32_bf16 v[44:47], v[216:219], v[144:147], v[44:47]
	ds_read_b128 v[168:171], v241 offset:41536
	v_mfma_f32_16x16x32_bf16 v[48:51], v[216:219], v[148:151], v[48:51]
	s_waitcnt vmcnt(13)
	ds_write_b128 v213, v[84:87] offset:13824
	global_load_dwordx4 v[76:79], v[74:75], off offset:1024
	v_mfma_f32_16x16x32_bf16 v[12:15], v[216:219], v[152:155], v[12:15]
	ds_read_b128 v[232:235], v242 offset:62272
	s_waitcnt lgkmcnt(11)
	v_mfma_f32_16x16x32_bf16 v[24:27], v[176:179], v[156:159], v[24:27]
	ds_read_b128 v[172:175], v241 offset:43840
	s_waitcnt vmcnt(13)
	ds_write_b128 v213, v[88:91] offset:18432
	global_load_dwordx4 v[80:83], v[106:107], off offset:1024
	v_mfma_f32_16x16x32_bf16 v[32:35], v[180:183], v[156:159], v[32:35]
	v_mfma_f32_16x16x32_bf16 v[8:11], v[184:187], v[156:159], v[8:11]
	v_mfma_f32_16x16x32_bf16 v[16:19], v[216:219], v[156:159], v[16:19]
	s_waitcnt lgkmcnt(9)
	v_mfma_f32_16x16x32_bf16 v[52:55], v[220:223], v[160:163], v[52:55]
	s_waitcnt lgkmcnt(7)
	v_mfma_f32_16x16x32_bf16 v[60:63], v[224:227], v[160:163], v[60:63]
	s_waitcnt lgkmcnt(6)
	v_mfma_f32_16x16x32_bf16 v[56:59], v[220:223], v[164:167], v[56:59]
	s_waitcnt vmcnt(13)
	ds_write_b128 v213, v[92:95] offset:23040
	global_load_dwordx4 v[84:87], v[188:189], off offset:1024
	v_mfma_f32_16x16x32_bf16 v[64:67], v[224:227], v[164:167], v[64:67]
	s_waitcnt lgkmcnt(6)
	v_mfma_f32_16x16x32_bf16 v[36:39], v[228:231], v[160:163], v[36:39]
	s_waitcnt vmcnt(13)
	ds_write_b128 v213, v[96:99] offset:27648
	global_load_dwordx4 v[88:91], v[104:105], off offset:1024
	v_mfma_f32_16x16x32_bf16 v[40:43], v[228:231], v[164:167], v[40:43]
	s_waitcnt lgkmcnt(6)
	v_mfma_f32_16x16x32_bf16 v[20:23], v[220:223], v[168:171], v[20:23]
	s_waitcnt vmcnt(13)
	ds_write_b128 v213, v[100:103] offset:32256
	global_load_dwordx4 v[92:95], v[214:215], off offset:1024
	v_mfma_f32_16x16x32_bf16 v[28:31], v[224:227], v[168:171], v[28:31]
	v_mfma_f32_16x16x32_bf16 v[4:7], v[228:231], v[168:171], v[4:7]
	global_load_dwordx4 v[96:99], v[236:237], off offset:1024
	s_waitcnt lgkmcnt(5)
	v_mfma_f32_16x16x32_bf16 v[44:47], v[232:235], v[160:163], v[44:47]
	v_mfma_f32_16x16x32_bf16 v[48:51], v[232:235], v[164:167], v[48:51]
	global_load_dwordx4 v[100:103], v[238:239], off offset:1024
	v_mfma_f32_16x16x32_bf16 v[12:15], v[232:235], v[168:171], v[12:15]
	s_waitcnt lgkmcnt(4)
	v_mfma_f32_16x16x32_bf16 v[24:27], v[220:223], v[172:175], v[24:27]
	v_mfma_f32_16x16x32_bf16 v[32:35], v[224:227], v[172:175], v[32:35]
	v_mfma_f32_16x16x32_bf16 v[8:11], v[228:231], v[172:175], v[8:11]
	v_mfma_f32_16x16x32_bf16 v[16:19], v[232:235], v[172:175], v[16:19]
	s_setprio 0
	s_waitcnt lgkmcnt(0)
	s_barrier
	ds_read_b128 v[144:147], v241
	ds_read_b128 v[176:179], v242 offset:18432
	ds_read_b128 v[180:183], v242 offset:20736
	ds_read_b128 v[148:151], v241 offset:2304
	ds_read_b128 v[184:187], v242 offset:23040
	ds_read_b128 v[152:155], v241 offset:4608
	ds_read_b128 v[216:219], v242 offset:25344
	ds_read_b128 v[156:159], v241 offset:6912
	s_setprio 1
	s_waitcnt lgkmcnt(6)
	v_mfma_f32_16x16x32_bf16 v[52:55], v[176:179], v[144:147], v[52:55]
	s_waitcnt vmcnt(15)
	ds_write_b128 v240, v[108:111]
	s_waitcnt lgkmcnt(6)
	v_mfma_f32_16x16x32_bf16 v[60:63], v[180:183], v[144:147], v[60:63]
	s_waitcnt lgkmcnt(5)
	v_mfma_f32_16x16x32_bf16 v[56:59], v[176:179], v[148:151], v[56:59]
	s_waitcnt vmcnt(14)
	ds_write_b128 v240, v[112:115] offset:4608
	v_mfma_f32_16x16x32_bf16 v[64:67], v[180:183], v[148:151], v[64:67]
	ds_read_b128 v[160:163], v241 offset:64
	s_waitcnt lgkmcnt(6)
	v_mfma_f32_16x16x32_bf16 v[36:39], v[184:187], v[144:147], v[36:39]
	ds_read_b128 v[220:223], v242 offset:18496
	s_waitcnt vmcnt(13)
	ds_write_b128 v240, v[116:119] offset:9216
	global_load_dwordx4 v[108:111], v[72:73], off offset:1152
	v_mfma_f32_16x16x32_bf16 v[40:43], v[184:187], v[148:151], v[40:43]
	ds_read_b128 v[224:227], v242 offset:20800
	s_waitcnt lgkmcnt(8)
	v_mfma_f32_16x16x32_bf16 v[20:23], v[176:179], v[152:155], v[20:23]
	ds_read_b128 v[164:167], v241 offset:2368
	v_mfma_f32_16x16x32_bf16 v[28:31], v[180:183], v[152:155], v[28:31]
	v_mfma_f32_16x16x32_bf16 v[4:7], v[184:187], v[152:155], v[4:7]
	ds_read_b128 v[228:231], v242 offset:23104
	s_waitcnt lgkmcnt(9)
	v_mfma_f32_16x16x32_bf16 v[44:47], v[216:219], v[144:147], v[44:47]
	ds_read_b128 v[168:171], v241 offset:4672
	v_mfma_f32_16x16x32_bf16 v[48:51], v[216:219], v[148:151], v[48:51]
	s_waitcnt vmcnt(13)
	ds_write_b128 v240, v[120:123] offset:13824
	global_load_dwordx4 v[112:115], v[74:75], off offset:1152
	v_mfma_f32_16x16x32_bf16 v[12:15], v[216:219], v[152:155], v[12:15]
	ds_read_b128 v[232:235], v242 offset:25408
	s_waitcnt lgkmcnt(11)
	v_mfma_f32_16x16x32_bf16 v[24:27], v[176:179], v[156:159], v[24:27]
	ds_read_b128 v[172:175], v241 offset:6976
	s_waitcnt vmcnt(13)
	ds_write_b128 v240, v[124:127] offset:18432
	global_load_dwordx4 v[116:119], v[106:107], off offset:1152
	v_mfma_f32_16x16x32_bf16 v[32:35], v[180:183], v[156:159], v[32:35]
	v_mfma_f32_16x16x32_bf16 v[8:11], v[184:187], v[156:159], v[8:11]
	v_mfma_f32_16x16x32_bf16 v[16:19], v[216:219], v[156:159], v[16:19]
	s_waitcnt lgkmcnt(9)
	v_mfma_f32_16x16x32_bf16 v[52:55], v[220:223], v[160:163], v[52:55]
	s_waitcnt lgkmcnt(7)
	v_mfma_f32_16x16x32_bf16 v[60:63], v[224:227], v[160:163], v[60:63]
	s_waitcnt lgkmcnt(6)
	v_mfma_f32_16x16x32_bf16 v[56:59], v[220:223], v[164:167], v[56:59]
	s_waitcnt vmcnt(13)
	ds_write_b128 v240, v[128:131] offset:23040
	global_load_dwordx4 v[120:123], v[188:189], off offset:1152
	v_mfma_f32_16x16x32_bf16 v[64:67], v[224:227], v[164:167], v[64:67]
	s_waitcnt lgkmcnt(6)
	v_mfma_f32_16x16x32_bf16 v[36:39], v[228:231], v[160:163], v[36:39]
	s_waitcnt vmcnt(13)
	ds_write_b128 v240, v[136:139] offset:27648
	global_load_dwordx4 v[124:127], v[104:105], off offset:1152
	v_mfma_f32_16x16x32_bf16 v[40:43], v[228:231], v[164:167], v[40:43]
	s_waitcnt lgkmcnt(6)
	v_mfma_f32_16x16x32_bf16 v[20:23], v[220:223], v[168:171], v[20:23]
	s_waitcnt vmcnt(13)
	ds_write_b128 v240, v[140:143] offset:32256
	global_load_dwordx4 v[128:131], v[214:215], off offset:1152
	v_mfma_f32_16x16x32_bf16 v[28:31], v[224:227], v[168:171], v[28:31]
	v_mfma_f32_16x16x32_bf16 v[4:7], v[228:231], v[168:171], v[4:7]
	global_load_dwordx4 v[136:139], v[236:237], off offset:1152
	s_waitcnt lgkmcnt(5)
	v_mfma_f32_16x16x32_bf16 v[44:47], v[232:235], v[160:163], v[44:47]
	v_mfma_f32_16x16x32_bf16 v[48:51], v[232:235], v[164:167], v[48:51]
	global_load_dwordx4 v[140:143], v[238:239], off offset:1152
	v_mfma_f32_16x16x32_bf16 v[12:15], v[232:235], v[168:171], v[12:15]
	s_waitcnt lgkmcnt(4)
	v_mfma_f32_16x16x32_bf16 v[24:27], v[220:223], v[172:175], v[24:27]
	v_mfma_f32_16x16x32_bf16 v[32:35], v[224:227], v[172:175], v[32:35]
	v_mfma_f32_16x16x32_bf16 v[8:11], v[228:231], v[172:175], v[8:11]
	v_mfma_f32_16x16x32_bf16 v[16:19], v[232:235], v[172:175], v[16:19]
	s_setprio 0
	s_waitcnt lgkmcnt(0)
	s_barrier
	ds_read_b128 v[144:147], v241 offset:36864
	ds_read_b128 v[176:179], v242 offset:55296
	ds_read_b128 v[180:183], v242 offset:57600
	ds_read_b128 v[148:151], v241 offset:39168
	ds_read_b128 v[184:187], v242 offset:59904
	ds_read_b128 v[152:155], v241 offset:41472
	ds_read_b128 v[216:219], v242 offset:62208
	ds_read_b128 v[156:159], v241 offset:43776
	s_setprio 1
	s_waitcnt lgkmcnt(6)
	v_mfma_f32_16x16x32_bf16 v[52:55], v[176:179], v[144:147], v[52:55]
	s_waitcnt vmcnt(15)
	ds_write_b128 v213, v[68:71]
	s_waitcnt lgkmcnt(6)
	v_mfma_f32_16x16x32_bf16 v[60:63], v[180:183], v[144:147], v[60:63]
	s_waitcnt lgkmcnt(5)
	v_mfma_f32_16x16x32_bf16 v[56:59], v[176:179], v[148:151], v[56:59]
	s_waitcnt vmcnt(14)
	ds_write_b128 v213, v[76:79] offset:4608
	v_mfma_f32_16x16x32_bf16 v[64:67], v[180:183], v[148:151], v[64:67]
	ds_read_b128 v[160:163], v241 offset:36928
	s_waitcnt lgkmcnt(6)
	v_mfma_f32_16x16x32_bf16 v[36:39], v[184:187], v[144:147], v[36:39]
	ds_read_b128 v[220:223], v242 offset:55360
	s_waitcnt vmcnt(13)
	ds_write_b128 v213, v[80:83] offset:9216
	global_load_dwordx4 v[68:71], v[72:73], off offset:1280
	v_mfma_f32_16x16x32_bf16 v[40:43], v[184:187], v[148:151], v[40:43]
	ds_read_b128 v[224:227], v242 offset:57664
	s_waitcnt lgkmcnt(8)
	v_mfma_f32_16x16x32_bf16 v[20:23], v[176:179], v[152:155], v[20:23]
	ds_read_b128 v[164:167], v241 offset:39232
	v_mfma_f32_16x16x32_bf16 v[28:31], v[180:183], v[152:155], v[28:31]
	v_mfma_f32_16x16x32_bf16 v[4:7], v[184:187], v[152:155], v[4:7]
	ds_read_b128 v[228:231], v242 offset:59968
	s_waitcnt lgkmcnt(9)
	v_mfma_f32_16x16x32_bf16 v[44:47], v[216:219], v[144:147], v[44:47]
	ds_read_b128 v[168:171], v241 offset:41536
	v_mfma_f32_16x16x32_bf16 v[48:51], v[216:219], v[148:151], v[48:51]
	s_waitcnt vmcnt(13)
	ds_write_b128 v213, v[84:87] offset:13824
	global_load_dwordx4 v[76:79], v[74:75], off offset:1280
	v_mfma_f32_16x16x32_bf16 v[12:15], v[216:219], v[152:155], v[12:15]
	ds_read_b128 v[232:235], v242 offset:62272
	s_waitcnt lgkmcnt(11)
	v_mfma_f32_16x16x32_bf16 v[24:27], v[176:179], v[156:159], v[24:27]
	ds_read_b128 v[172:175], v241 offset:43840
	s_waitcnt vmcnt(13)
	ds_write_b128 v213, v[88:91] offset:18432
	global_load_dwordx4 v[80:83], v[106:107], off offset:1280
	v_mfma_f32_16x16x32_bf16 v[32:35], v[180:183], v[156:159], v[32:35]
	v_mfma_f32_16x16x32_bf16 v[8:11], v[184:187], v[156:159], v[8:11]
	v_mfma_f32_16x16x32_bf16 v[16:19], v[216:219], v[156:159], v[16:19]
	s_waitcnt lgkmcnt(9)
	v_mfma_f32_16x16x32_bf16 v[52:55], v[220:223], v[160:163], v[52:55]
	s_waitcnt lgkmcnt(7)
	v_mfma_f32_16x16x32_bf16 v[60:63], v[224:227], v[160:163], v[60:63]
	s_waitcnt lgkmcnt(6)
	v_mfma_f32_16x16x32_bf16 v[56:59], v[220:223], v[164:167], v[56:59]
	s_waitcnt vmcnt(13)
	ds_write_b128 v213, v[92:95] offset:23040
	global_load_dwordx4 v[84:87], v[188:189], off offset:1280
	v_mfma_f32_16x16x32_bf16 v[64:67], v[224:227], v[164:167], v[64:67]
	s_waitcnt lgkmcnt(6)
	v_mfma_f32_16x16x32_bf16 v[36:39], v[228:231], v[160:163], v[36:39]
	s_waitcnt vmcnt(13)
	ds_write_b128 v213, v[96:99] offset:27648
	global_load_dwordx4 v[88:91], v[104:105], off offset:1280
	v_mfma_f32_16x16x32_bf16 v[40:43], v[228:231], v[164:167], v[40:43]
	s_waitcnt lgkmcnt(6)
	v_mfma_f32_16x16x32_bf16 v[20:23], v[220:223], v[168:171], v[20:23]
	s_waitcnt vmcnt(13)
	ds_write_b128 v213, v[100:103] offset:32256
	global_load_dwordx4 v[92:95], v[214:215], off offset:1280
	v_mfma_f32_16x16x32_bf16 v[28:31], v[224:227], v[168:171], v[28:31]
	v_mfma_f32_16x16x32_bf16 v[4:7], v[228:231], v[168:171], v[4:7]
	global_load_dwordx4 v[96:99], v[236:237], off offset:1280
	s_waitcnt lgkmcnt(5)
	v_mfma_f32_16x16x32_bf16 v[44:47], v[232:235], v[160:163], v[44:47]
	v_mfma_f32_16x16x32_bf16 v[48:51], v[232:235], v[164:167], v[48:51]
	global_load_dwordx4 v[100:103], v[238:239], off offset:1280
	v_mfma_f32_16x16x32_bf16 v[12:15], v[232:235], v[168:171], v[12:15]
	s_waitcnt lgkmcnt(4)
	v_mfma_f32_16x16x32_bf16 v[24:27], v[220:223], v[172:175], v[24:27]
	v_mfma_f32_16x16x32_bf16 v[32:35], v[224:227], v[172:175], v[32:35]
	v_mfma_f32_16x16x32_bf16 v[8:11], v[228:231], v[172:175], v[8:11]
	v_mfma_f32_16x16x32_bf16 v[16:19], v[232:235], v[172:175], v[16:19]
	s_setprio 0
	s_waitcnt lgkmcnt(0)
	s_barrier
	ds_read_b128 v[144:147], v241
	ds_read_b128 v[176:179], v242 offset:18432
	ds_read_b128 v[180:183], v242 offset:20736
	ds_read_b128 v[148:151], v241 offset:2304
	ds_read_b128 v[184:187], v242 offset:23040
	ds_read_b128 v[152:155], v241 offset:4608
	ds_read_b128 v[216:219], v242 offset:25344
	ds_read_b128 v[156:159], v241 offset:6912
	s_setprio 1
	s_waitcnt lgkmcnt(6)
	v_mfma_f32_16x16x32_bf16 v[52:55], v[176:179], v[144:147], v[52:55]
	s_waitcnt vmcnt(15)
	ds_write_b128 v240, v[108:111]
	s_waitcnt lgkmcnt(6)
	v_mfma_f32_16x16x32_bf16 v[60:63], v[180:183], v[144:147], v[60:63]
	s_waitcnt lgkmcnt(5)
	v_mfma_f32_16x16x32_bf16 v[56:59], v[176:179], v[148:151], v[56:59]
	s_waitcnt vmcnt(14)
	ds_write_b128 v240, v[112:115] offset:4608
	v_mfma_f32_16x16x32_bf16 v[64:67], v[180:183], v[148:151], v[64:67]
	ds_read_b128 v[160:163], v241 offset:64
	s_waitcnt lgkmcnt(6)
	v_mfma_f32_16x16x32_bf16 v[36:39], v[184:187], v[144:147], v[36:39]
	ds_read_b128 v[220:223], v242 offset:18496
	s_waitcnt vmcnt(13)
	ds_write_b128 v240, v[116:119] offset:9216
	global_load_dwordx4 v[108:111], v[72:73], off offset:1408
	v_mfma_f32_16x16x32_bf16 v[40:43], v[184:187], v[148:151], v[40:43]
	ds_read_b128 v[224:227], v242 offset:20800
	s_waitcnt lgkmcnt(8)
	v_mfma_f32_16x16x32_bf16 v[20:23], v[176:179], v[152:155], v[20:23]
	ds_read_b128 v[164:167], v241 offset:2368
	v_mfma_f32_16x16x32_bf16 v[28:31], v[180:183], v[152:155], v[28:31]
	v_mfma_f32_16x16x32_bf16 v[4:7], v[184:187], v[152:155], v[4:7]
	ds_read_b128 v[228:231], v242 offset:23104
	s_waitcnt lgkmcnt(9)
	v_mfma_f32_16x16x32_bf16 v[44:47], v[216:219], v[144:147], v[44:47]
	ds_read_b128 v[168:171], v241 offset:4672
	v_mfma_f32_16x16x32_bf16 v[48:51], v[216:219], v[148:151], v[48:51]
	s_waitcnt vmcnt(13)
	ds_write_b128 v240, v[120:123] offset:13824
	global_load_dwordx4 v[112:115], v[74:75], off offset:1408
	v_mfma_f32_16x16x32_bf16 v[12:15], v[216:219], v[152:155], v[12:15]
	ds_read_b128 v[232:235], v242 offset:25408
	s_waitcnt lgkmcnt(11)
	v_mfma_f32_16x16x32_bf16 v[24:27], v[176:179], v[156:159], v[24:27]
	ds_read_b128 v[172:175], v241 offset:6976
	s_waitcnt vmcnt(13)
	ds_write_b128 v240, v[124:127] offset:18432
	global_load_dwordx4 v[116:119], v[106:107], off offset:1408
	v_mfma_f32_16x16x32_bf16 v[32:35], v[180:183], v[156:159], v[32:35]
	v_mfma_f32_16x16x32_bf16 v[8:11], v[184:187], v[156:159], v[8:11]
	v_mfma_f32_16x16x32_bf16 v[16:19], v[216:219], v[156:159], v[16:19]
	s_waitcnt lgkmcnt(9)
	v_mfma_f32_16x16x32_bf16 v[52:55], v[220:223], v[160:163], v[52:55]
	s_waitcnt lgkmcnt(7)
	v_mfma_f32_16x16x32_bf16 v[60:63], v[224:227], v[160:163], v[60:63]
	s_waitcnt lgkmcnt(6)
	v_mfma_f32_16x16x32_bf16 v[56:59], v[220:223], v[164:167], v[56:59]
	s_waitcnt vmcnt(13)
	ds_write_b128 v240, v[128:131] offset:23040
	global_load_dwordx4 v[120:123], v[188:189], off offset:1408
	v_mfma_f32_16x16x32_bf16 v[64:67], v[224:227], v[164:167], v[64:67]
	s_waitcnt lgkmcnt(6)
	v_mfma_f32_16x16x32_bf16 v[36:39], v[228:231], v[160:163], v[36:39]
	s_waitcnt vmcnt(13)
	ds_write_b128 v240, v[136:139] offset:27648
	global_load_dwordx4 v[124:127], v[104:105], off offset:1408
	v_mfma_f32_16x16x32_bf16 v[40:43], v[228:231], v[164:167], v[40:43]
	s_waitcnt lgkmcnt(6)
	v_mfma_f32_16x16x32_bf16 v[20:23], v[220:223], v[168:171], v[20:23]
	s_waitcnt vmcnt(13)
	ds_write_b128 v240, v[140:143] offset:32256
	global_load_dwordx4 v[128:131], v[214:215], off offset:1408
	v_mfma_f32_16x16x32_bf16 v[28:31], v[224:227], v[168:171], v[28:31]
	v_mfma_f32_16x16x32_bf16 v[4:7], v[228:231], v[168:171], v[4:7]
	global_load_dwordx4 v[136:139], v[236:237], off offset:1408
	s_waitcnt lgkmcnt(5)
	v_mfma_f32_16x16x32_bf16 v[44:47], v[232:235], v[160:163], v[44:47]
	v_mfma_f32_16x16x32_bf16 v[48:51], v[232:235], v[164:167], v[48:51]
	global_load_dwordx4 v[140:143], v[238:239], off offset:1408
	v_mfma_f32_16x16x32_bf16 v[12:15], v[232:235], v[168:171], v[12:15]
	s_waitcnt lgkmcnt(4)
	v_mfma_f32_16x16x32_bf16 v[24:27], v[220:223], v[172:175], v[24:27]
	v_mfma_f32_16x16x32_bf16 v[32:35], v[224:227], v[172:175], v[32:35]
	v_mfma_f32_16x16x32_bf16 v[8:11], v[228:231], v[172:175], v[8:11]
	v_mfma_f32_16x16x32_bf16 v[16:19], v[232:235], v[172:175], v[16:19]
	s_setprio 0
	s_waitcnt lgkmcnt(0)
	s_barrier
	ds_read_b128 v[144:147], v241 offset:36864
	ds_read_b128 v[176:179], v242 offset:55296
	ds_read_b128 v[180:183], v242 offset:57600
	ds_read_b128 v[148:151], v241 offset:39168
	ds_read_b128 v[184:187], v242 offset:59904
	ds_read_b128 v[152:155], v241 offset:41472
	ds_read_b128 v[216:219], v242 offset:62208
	ds_read_b128 v[156:159], v241 offset:43776
	s_setprio 1
	s_waitcnt lgkmcnt(6)
	v_mfma_f32_16x16x32_bf16 v[52:55], v[176:179], v[144:147], v[52:55]
	s_waitcnt vmcnt(15)
	ds_write_b128 v213, v[68:71]
	s_waitcnt lgkmcnt(6)
	v_mfma_f32_16x16x32_bf16 v[60:63], v[180:183], v[144:147], v[60:63]
	s_waitcnt lgkmcnt(5)
	v_mfma_f32_16x16x32_bf16 v[56:59], v[176:179], v[148:151], v[56:59]
	s_waitcnt vmcnt(14)
	ds_write_b128 v213, v[76:79] offset:4608
	v_mfma_f32_16x16x32_bf16 v[64:67], v[180:183], v[148:151], v[64:67]
	ds_read_b128 v[160:163], v241 offset:36928
	s_waitcnt lgkmcnt(6)
	v_mfma_f32_16x16x32_bf16 v[36:39], v[184:187], v[144:147], v[36:39]
	ds_read_b128 v[220:223], v242 offset:55360
	s_waitcnt vmcnt(13)
	ds_write_b128 v213, v[80:83] offset:9216
	v_mfma_f32_16x16x32_bf16 v[40:43], v[184:187], v[148:151], v[40:43]
	ds_read_b128 v[224:227], v242 offset:57664
	s_waitcnt lgkmcnt(8)
	v_mfma_f32_16x16x32_bf16 v[20:23], v[176:179], v[152:155], v[20:23]
	ds_read_b128 v[164:167], v241 offset:39232
	v_mfma_f32_16x16x32_bf16 v[28:31], v[180:183], v[152:155], v[28:31]
	v_mfma_f32_16x16x32_bf16 v[4:7], v[184:187], v[152:155], v[4:7]
	ds_read_b128 v[228:231], v242 offset:59968
	s_waitcnt lgkmcnt(9)
	v_mfma_f32_16x16x32_bf16 v[44:47], v[216:219], v[144:147], v[44:47]
	ds_read_b128 v[168:171], v241 offset:41536
	v_mfma_f32_16x16x32_bf16 v[48:51], v[216:219], v[148:151], v[48:51]
	s_waitcnt vmcnt(12)
	ds_write_b128 v213, v[84:87] offset:13824
	v_mfma_f32_16x16x32_bf16 v[12:15], v[216:219], v[152:155], v[12:15]
	ds_read_b128 v[232:235], v242 offset:62272
	s_waitcnt lgkmcnt(11)
	v_mfma_f32_16x16x32_bf16 v[24:27], v[176:179], v[156:159], v[24:27]
	ds_read_b128 v[172:175], v241 offset:43840
	s_waitcnt vmcnt(11)
	ds_write_b128 v213, v[88:91] offset:18432
	v_mfma_f32_16x16x32_bf16 v[32:35], v[180:183], v[156:159], v[32:35]
	v_mfma_f32_16x16x32_bf16 v[8:11], v[184:187], v[156:159], v[8:11]
	v_mfma_f32_16x16x32_bf16 v[16:19], v[216:219], v[156:159], v[16:19]
	s_waitcnt lgkmcnt(9)
	v_mfma_f32_16x16x32_bf16 v[52:55], v[220:223], v[160:163], v[52:55]
	s_waitcnt lgkmcnt(7)
	v_mfma_f32_16x16x32_bf16 v[60:63], v[224:227], v[160:163], v[60:63]
	s_waitcnt lgkmcnt(6)
	v_mfma_f32_16x16x32_bf16 v[56:59], v[220:223], v[164:167], v[56:59]
	s_waitcnt vmcnt(10)
	ds_write_b128 v213, v[92:95] offset:23040
	v_mfma_f32_16x16x32_bf16 v[64:67], v[224:227], v[164:167], v[64:67]
	s_waitcnt lgkmcnt(6)
	v_mfma_f32_16x16x32_bf16 v[36:39], v[228:231], v[160:163], v[36:39]
	s_waitcnt vmcnt(9)
	ds_write_b128 v213, v[96:99] offset:27648
	v_mfma_f32_16x16x32_bf16 v[40:43], v[228:231], v[164:167], v[40:43]
	s_waitcnt lgkmcnt(6)
	v_mfma_f32_16x16x32_bf16 v[20:23], v[220:223], v[168:171], v[20:23]
	s_waitcnt vmcnt(8)
	ds_write_b128 v213, v[100:103] offset:32256
	v_mfma_f32_16x16x32_bf16 v[28:31], v[224:227], v[168:171], v[28:31]
	v_mfma_f32_16x16x32_bf16 v[4:7], v[228:231], v[168:171], v[4:7]
	s_waitcnt lgkmcnt(5)
	v_mfma_f32_16x16x32_bf16 v[44:47], v[232:235], v[160:163], v[44:47]
	v_mfma_f32_16x16x32_bf16 v[48:51], v[232:235], v[164:167], v[48:51]
	v_mfma_f32_16x16x32_bf16 v[12:15], v[232:235], v[168:171], v[12:15]
	s_waitcnt lgkmcnt(4)
	v_mfma_f32_16x16x32_bf16 v[24:27], v[220:223], v[172:175], v[24:27]
	v_mfma_f32_16x16x32_bf16 v[32:35], v[224:227], v[172:175], v[32:35]
	v_mfma_f32_16x16x32_bf16 v[8:11], v[228:231], v[172:175], v[8:11]
	v_mfma_f32_16x16x32_bf16 v[16:19], v[232:235], v[172:175], v[16:19]
	s_setprio 0
	s_waitcnt lgkmcnt(0)
	s_barrier
	ds_read_b128 v[144:147], v241
	ds_read_b128 v[176:179], v242 offset:18432
	ds_read_b128 v[180:183], v242 offset:20736
	ds_read_b128 v[148:151], v241 offset:2304
	ds_read_b128 v[184:187], v242 offset:23040
	ds_read_b128 v[152:155], v241 offset:4608
	ds_read_b128 v[216:219], v242 offset:25344
	ds_read_b128 v[156:159], v241 offset:6912
	s_setprio 1
	s_waitcnt lgkmcnt(6)
	v_mfma_f32_16x16x32_bf16 v[52:55], v[176:179], v[144:147], v[52:55]
	s_waitcnt vmcnt(7)
	ds_write_b128 v240, v[108:111]
	s_waitcnt lgkmcnt(6)
	v_mfma_f32_16x16x32_bf16 v[60:63], v[180:183], v[144:147], v[60:63]
	s_waitcnt lgkmcnt(5)
	v_mfma_f32_16x16x32_bf16 v[56:59], v[176:179], v[148:151], v[56:59]
	s_waitcnt vmcnt(6)
	ds_write_b128 v240, v[112:115] offset:4608
	v_mfma_f32_16x16x32_bf16 v[64:67], v[180:183], v[148:151], v[64:67]
	ds_read_b128 v[160:163], v241 offset:64
	s_waitcnt lgkmcnt(6)
	v_mfma_f32_16x16x32_bf16 v[36:39], v[184:187], v[144:147], v[36:39]
	ds_read_b128 v[220:223], v242 offset:18496
	s_waitcnt vmcnt(5)
	ds_write_b128 v240, v[116:119] offset:9216
	v_mfma_f32_16x16x32_bf16 v[40:43], v[184:187], v[148:151], v[40:43]
	ds_read_b128 v[224:227], v242 offset:20800
	s_waitcnt lgkmcnt(8)
	v_mfma_f32_16x16x32_bf16 v[20:23], v[176:179], v[152:155], v[20:23]
	ds_read_b128 v[164:167], v241 offset:2368
	v_mfma_f32_16x16x32_bf16 v[28:31], v[180:183], v[152:155], v[28:31]
	v_mfma_f32_16x16x32_bf16 v[4:7], v[184:187], v[152:155], v[4:7]
	ds_read_b128 v[228:231], v242 offset:23104
	s_waitcnt lgkmcnt(9)
	v_mfma_f32_16x16x32_bf16 v[44:47], v[216:219], v[144:147], v[44:47]
	ds_read_b128 v[168:171], v241 offset:4672
	v_mfma_f32_16x16x32_bf16 v[48:51], v[216:219], v[148:151], v[48:51]
	s_waitcnt vmcnt(4)
	ds_write_b128 v240, v[120:123] offset:13824
	v_mfma_f32_16x16x32_bf16 v[12:15], v[216:219], v[152:155], v[12:15]
	ds_read_b128 v[232:235], v242 offset:25408
	s_waitcnt lgkmcnt(11)
	v_mfma_f32_16x16x32_bf16 v[24:27], v[176:179], v[156:159], v[24:27]
	ds_read_b128 v[172:175], v241 offset:6976
	s_waitcnt vmcnt(3)
	ds_write_b128 v240, v[124:127] offset:18432
	v_mfma_f32_16x16x32_bf16 v[32:35], v[180:183], v[156:159], v[32:35]
	v_mfma_f32_16x16x32_bf16 v[8:11], v[184:187], v[156:159], v[8:11]
	v_mfma_f32_16x16x32_bf16 v[16:19], v[216:219], v[156:159], v[16:19]
	s_waitcnt lgkmcnt(9)
	v_mfma_f32_16x16x32_bf16 v[52:55], v[220:223], v[160:163], v[52:55]
	s_waitcnt lgkmcnt(7)
	v_mfma_f32_16x16x32_bf16 v[60:63], v[224:227], v[160:163], v[60:63]
	s_waitcnt lgkmcnt(6)
	v_mfma_f32_16x16x32_bf16 v[56:59], v[220:223], v[164:167], v[56:59]
	s_waitcnt vmcnt(2)
	ds_write_b128 v240, v[128:131] offset:23040
	v_mfma_f32_16x16x32_bf16 v[64:67], v[224:227], v[164:167], v[64:67]
	s_waitcnt lgkmcnt(6)
	v_mfma_f32_16x16x32_bf16 v[36:39], v[228:231], v[160:163], v[36:39]
	s_waitcnt vmcnt(1)
	ds_write_b128 v240, v[136:139] offset:27648
	v_mfma_f32_16x16x32_bf16 v[40:43], v[228:231], v[164:167], v[40:43]
	s_waitcnt lgkmcnt(6)
	v_mfma_f32_16x16x32_bf16 v[20:23], v[220:223], v[168:171], v[20:23]
	s_waitcnt vmcnt(0)
	ds_write_b128 v240, v[140:143] offset:32256
	v_mfma_f32_16x16x32_bf16 v[28:31], v[224:227], v[168:171], v[28:31]
	v_mfma_f32_16x16x32_bf16 v[4:7], v[228:231], v[168:171], v[4:7]
	s_waitcnt lgkmcnt(5)
	v_mfma_f32_16x16x32_bf16 v[44:47], v[232:235], v[160:163], v[44:47]
	v_mfma_f32_16x16x32_bf16 v[48:51], v[232:235], v[164:167], v[48:51]
	v_mfma_f32_16x16x32_bf16 v[12:15], v[232:235], v[168:171], v[12:15]
	s_waitcnt lgkmcnt(4)
	v_mfma_f32_16x16x32_bf16 v[24:27], v[220:223], v[172:175], v[24:27]
	v_mfma_f32_16x16x32_bf16 v[32:35], v[224:227], v[172:175], v[32:35]
	v_mfma_f32_16x16x32_bf16 v[8:11], v[228:231], v[172:175], v[8:11]
	v_mfma_f32_16x16x32_bf16 v[16:19], v[232:235], v[172:175], v[16:19]
	s_setprio 0
	s_waitcnt lgkmcnt(0)
	s_barrier
	ds_read_b128 v[144:147], v241 offset:36864
	ds_read_b128 v[176:179], v242 offset:55296
	ds_read_b128 v[180:183], v242 offset:57600
	ds_read_b128 v[148:151], v241 offset:39168
	ds_read_b128 v[184:187], v242 offset:59904
	ds_read_b128 v[152:155], v241 offset:41472
	ds_read_b128 v[216:219], v242 offset:62208
	ds_read_b128 v[156:159], v241 offset:43776
	s_setprio 1
	s_waitcnt lgkmcnt(6)
	v_mfma_f32_16x16x32_bf16 v[52:55], v[176:179], v[144:147], v[52:55]
	s_waitcnt lgkmcnt(5)
	v_mfma_f32_16x16x32_bf16 v[60:63], v[180:183], v[144:147], v[60:63]
	s_waitcnt lgkmcnt(4)
	v_mfma_f32_16x16x32_bf16 v[56:59], v[176:179], v[148:151], v[56:59]
	v_mfma_f32_16x16x32_bf16 v[64:67], v[180:183], v[148:151], v[64:67]
	ds_read_b128 v[160:163], v241 offset:36928
	s_waitcnt lgkmcnt(4)
	v_mfma_f32_16x16x32_bf16 v[36:39], v[184:187], v[144:147], v[36:39]
	ds_read_b128 v[220:223], v242 offset:55360
	v_mfma_f32_16x16x32_bf16 v[40:43], v[184:187], v[148:151], v[40:43]
	ds_read_b128 v[224:227], v242 offset:57664
	s_waitcnt lgkmcnt(5)
	v_mfma_f32_16x16x32_bf16 v[20:23], v[176:179], v[152:155], v[20:23]
	ds_read_b128 v[164:167], v241 offset:39232
	v_mfma_f32_16x16x32_bf16 v[28:31], v[180:183], v[152:155], v[28:31]
	v_mfma_f32_16x16x32_bf16 v[4:7], v[184:187], v[152:155], v[4:7]
	ds_read_b128 v[228:231], v242 offset:59968
	s_waitcnt lgkmcnt(6)
	v_mfma_f32_16x16x32_bf16 v[44:47], v[216:219], v[144:147], v[44:47]
	ds_read_b128 v[168:171], v241 offset:41536
	v_mfma_f32_16x16x32_bf16 v[48:51], v[216:219], v[148:151], v[48:51]
	v_mfma_f32_16x16x32_bf16 v[12:15], v[216:219], v[152:155], v[12:15]
	ds_read_b128 v[232:235], v242 offset:62272
	s_waitcnt lgkmcnt(7)
	v_mfma_f32_16x16x32_bf16 v[24:27], v[176:179], v[156:159], v[24:27]
	ds_read_b128 v[172:175], v241 offset:43840
	v_mfma_f32_16x16x32_bf16 v[32:35], v[180:183], v[156:159], v[32:35]
	v_mfma_f32_16x16x32_bf16 v[8:11], v[184:187], v[156:159], v[8:11]
	v_mfma_f32_16x16x32_bf16 v[16:19], v[216:219], v[156:159], v[16:19]
	s_waitcnt lgkmcnt(6)
	v_mfma_f32_16x16x32_bf16 v[52:55], v[220:223], v[160:163], v[52:55]
	s_waitcnt lgkmcnt(5)
	v_mfma_f32_16x16x32_bf16 v[60:63], v[224:227], v[160:163], v[60:63]
	s_waitcnt lgkmcnt(4)
	v_mfma_f32_16x16x32_bf16 v[56:59], v[220:223], v[164:167], v[56:59]
	v_mfma_f32_16x16x32_bf16 v[64:67], v[224:227], v[164:167], v[64:67]
	s_waitcnt lgkmcnt(3)
	v_mfma_f32_16x16x32_bf16 v[36:39], v[228:231], v[160:163], v[36:39]
	v_mfma_f32_16x16x32_bf16 v[40:43], v[228:231], v[164:167], v[40:43]
	s_waitcnt lgkmcnt(2)
	v_mfma_f32_16x16x32_bf16 v[20:23], v[220:223], v[168:171], v[20:23]
	v_mfma_f32_16x16x32_bf16 v[28:31], v[224:227], v[168:171], v[28:31]
	v_mfma_f32_16x16x32_bf16 v[4:7], v[228:231], v[168:171], v[4:7]
	s_waitcnt lgkmcnt(1)
	v_mfma_f32_16x16x32_bf16 v[44:47], v[232:235], v[160:163], v[44:47]
	v_mfma_f32_16x16x32_bf16 v[48:51], v[232:235], v[164:167], v[48:51]
	v_mfma_f32_16x16x32_bf16 v[12:15], v[232:235], v[168:171], v[12:15]
	s_waitcnt lgkmcnt(0)
	v_mfma_f32_16x16x32_bf16 v[24:27], v[220:223], v[172:175], v[24:27]
	v_mfma_f32_16x16x32_bf16 v[32:35], v[224:227], v[172:175], v[32:35]
	v_mfma_f32_16x16x32_bf16 v[8:11], v[228:231], v[172:175], v[8:11]
	v_mfma_f32_16x16x32_bf16 v[16:19], v[232:235], v[172:175], v[16:19]
	s_setprio 0
	s_barrier
	s_nop 7
	s_nop 4
	s_nop 4
	v_permlane16_swap_b32_e32 v52, v56
	v_permlane16_swap_b32_e32 v53, v57
	v_permlane16_swap_b32_e32 v54, v58
	v_permlane16_swap_b32_e32 v55, v59
	v_permlane16_swap_b32_e32 v60, v64
	v_permlane16_swap_b32_e32 v61, v65
	v_permlane16_swap_b32_e32 v62, v66
	v_permlane16_swap_b32_e32 v63, v67
	v_permlane16_swap_b32_e32 v36, v40
	v_permlane16_swap_b32_e32 v37, v41
	v_permlane16_swap_b32_e32 v38, v42
	v_permlane16_swap_b32_e32 v39, v43
	v_permlane16_swap_b32_e32 v44, v48
	v_permlane16_swap_b32_e32 v45, v49
	v_permlane16_swap_b32_e32 v46, v50
	v_permlane16_swap_b32_e32 v47, v51
	v_permlane16_swap_b32_e32 v20, v24
	v_permlane16_swap_b32_e32 v21, v25
	v_permlane16_swap_b32_e32 v22, v26
	v_permlane16_swap_b32_e32 v23, v27
	v_permlane16_swap_b32_e32 v28, v32
	v_permlane16_swap_b32_e32 v29, v33
	v_permlane16_swap_b32_e32 v30, v34
	v_permlane16_swap_b32_e32 v31, v35
	v_permlane16_swap_b32_e32 v4, v8
	v_permlane16_swap_b32_e32 v5, v9
	v_permlane16_swap_b32_e32 v6, v10
	v_permlane16_swap_b32_e32 v7, v11
	v_permlane16_swap_b32_e32 v12, v16
	v_permlane16_swap_b32_e32 v13, v17
	v_permlane16_swap_b32_e32 v14, v18
	v_permlane16_swap_b32_e32 v15, v19
	s_nop 1
	v_permlane32_swap_b32_e32 v52, v56
	v_permlane32_swap_b32_e32 v53, v57
	v_permlane32_swap_b32_e32 v54, v58
	v_permlane32_swap_b32_e32 v55, v59
	v_permlane32_swap_b32_e32 v60, v64
	v_permlane32_swap_b32_e32 v61, v65
	v_permlane32_swap_b32_e32 v62, v66
	v_permlane32_swap_b32_e32 v63, v67
	v_permlane32_swap_b32_e32 v36, v40
	v_permlane32_swap_b32_e32 v37, v41
	v_permlane32_swap_b32_e32 v38, v42
	v_permlane32_swap_b32_e32 v39, v43
	v_permlane32_swap_b32_e32 v44, v48
	v_permlane32_swap_b32_e32 v45, v49
	v_permlane32_swap_b32_e32 v46, v50
	v_permlane32_swap_b32_e32 v47, v51
	v_permlane32_swap_b32_e32 v20, v24
	v_permlane32_swap_b32_e32 v21, v25
	v_permlane32_swap_b32_e32 v22, v26
	v_permlane32_swap_b32_e32 v23, v27
	v_permlane32_swap_b32_e32 v28, v32
	v_permlane32_swap_b32_e32 v29, v33
	v_permlane32_swap_b32_e32 v30, v34
	v_permlane32_swap_b32_e32 v31, v35
	v_permlane32_swap_b32_e32 v4, v8
	v_permlane32_swap_b32_e32 v5, v9
	v_permlane32_swap_b32_e32 v6, v10
	v_permlane32_swap_b32_e32 v7, v11
	v_permlane32_swap_b32_e32 v12, v16
	v_permlane32_swap_b32_e32 v13, v17
	v_permlane32_swap_b32_e32 v14, v18
	v_permlane32_swap_b32_e32 v15, v19
	s_nop 1
	s_branch .LBB0_574
